# plus non-temporal (nt) policy on read-once streaming loads (P0 f32 inputs, LN rows, epilogue residual operands)
# speedup vs baseline: 1.0086x; 1.0086x over previous
; #define LAS __attribute__((address_space(3)))
; __device__ __forceinline__ int map_gu(int j) { return ((j >> 7) & 1) * FF + ((j >> 8) << 7) + (j & 127); }
; #define ARG(T, i) ((T)ldptr(lds, (i)))
; template <int MAP>
; __device__ __forceinline__ void p0_transpose_item(const float* W, int K, int Nsrc, int rows, bf16_t* WT, LAS float* scr, int item, int lane) {
;     const int nblk = rows / 32, kb = item / nblk, nb = item % nblk, k0 = 64 * kb, n0 = 32 * nb;
;     const int j = n0 + (lane & 31);
;     const int sc = MAP == 0 ? j : (MAP == 1 ? map_gu(j) : map_in(j));
;     float tv[32];
; #pragma unroll
;     for (int i = 0; i < 32; ++i) tv[i] = W[(size_t)(k0 + 2 * i + (lane >> 5)) * Nsrc + sc];
; __global__ void __launch_bounds__(512, 2) fwd_megakernel(Args a) {
;     ...
;             if (r < I_GU) { p0_transpose_item<1>(ARG(const float*, 5), D, NGU, NGU, WGU1, scr, r, lane); continue; } r -= I_GU;
;             if (r < I_GU) { p0_transpose_item<1>(ARG(const float*, 13), D, NGU, NGU, WGU2, scr, r, lane); continue; } r -= I_GU;
;             if (r < I_IN) { p0_transpose_item<2>(ARG(const float*, 7), D, 11776, WIN_ROWS, WIN, scr, r, lane); continue; } r -= I_IN;
;             if (r < I_D) { p0_transpose_item<0>(ARG(const float*, 6), FF, D, D, WD1, scr, r, lane); continue; } r -= I_D;
;             if (r < I_D) { p0_transpose_item<0>(ARG(const float*, 14), FF, D, D, WD2, scr, r, lane); continue; } r -= I_D;
;             if (r < I_SQ) { p0_transpose_item<0>(ARG(const float*, 10), D, D, D, WRO, scr, r, lane); continue; } r -= I_SQ;
;             if (r < I_SQ) { p0_transpose_item<0>(ARG(const float*, 12), D, D, D, WMO, scr, r, lane); continue; } r -= I_SQ;
;             if (r < I_SQ) { p0_transpose_item<0>(ARG(const float*, 15), D, D, D, WPG, scr, r, lane); continue; } r -= I_SQ;
;             if (r < I_AO) { p0_transpose_item<0>(ARG(const float*, 11), 1024, D, D, WAO, scr, r, lane); continue; } r -= I_AO;
;             p0_transpose_item<0>(ARG(const float*, 16), PLE, D, D, WPP, scr, r, lane);
.LBB0_12:
	s_cmpk_gt_i32 s78, 0x2bff
	s_mov_b64 s[12:13], -1
	s_cbranch_scc0 .LBB0_70
	s_cmpk_gt_u32 s78, 0x57ff
	s_cbranch_scc0 .LBB0_67
	s_cmpk_gt_u32 s78, 0x85ff
	s_cbranch_scc0 .LBB0_40
	s_cmpk_gt_u32 s78, 0x9bff
	s_cbranch_scc0 .LBB0_37
	s_cmpk_gt_u32 s78, 0xb1ff
	s_cbranch_scc0 .LBB0_34
	s_cmpk_gt_u32 s78, 0xb9ff
	s_cbranch_scc0 .LBB0_31
	s_cmpk_gt_u32 s78, 0xc1ff
	s_cbranch_scc0 .LBB0_28
	s_cmpk_gt_u32 s78, 0xc9ff
	s_cbranch_scc0 .LBB0_25
	s_cmpk_gt_u32 s78, 0xcdff
	s_cbranch_scc0 .LBB0_22
	v_mov_b32_e32 v4, s22
	ds_read_b32 v4, v4
	v_mov_b32_e32 v26, s23
	ds_read_b32 v26, v26
	s_add_i32 s10, s78, 0xffff3200
	s_and_b32 s10, s10, 0x1fc0
	s_waitcnt lgkmcnt(0)
	v_readfirstlane_b32 s12, v4
	s_add_i32 s79, s16, 0xffe64000
	v_or_b32_e32 v4, s10, v30
	s_and_b32 s79, s79, 0x7e0
	v_lshlrev_b32_e32 v69, 11, v4
	v_or3_b32 v4, s79, v3, v69
	s_waitcnt lgkmcnt(0)
	v_readfirstlane_b32 s13, v26
	v_lshlrev_b32_e32 v4, 2, v4
	s_lshl_b32 s10, s10, 1
	v_lshl_add_u64 v[26:27], s[12:13], 0, v[4:5]
	v_or3_b32 v4, s79, v31, v69
	v_lshlrev_b32_e32 v4, 2, v4
	v_lshl_add_u64 v[70:71], s[12:13], 0, v[4:5]
	v_or3_b32 v4, s79, v32, v69
	v_lshlrev_b32_e32 v4, 2, v4
	v_lshl_add_u64 v[72:73], s[12:13], 0, v[4:5]
	v_or3_b32 v4, s79, v33, v69
	v_lshlrev_b32_e32 v4, 2, v4
	v_lshl_add_u64 v[74:75], s[12:13], 0, v[4:5]
	v_or3_b32 v4, s79, v34, v69
	v_lshlrev_b32_e32 v4, 2, v4
	v_lshl_add_u64 v[76:77], s[12:13], 0, v[4:5]
	v_or3_b32 v4, s79, v35, v69
	v_lshlrev_b32_e32 v4, 2, v4
	v_lshl_add_u64 v[78:79], s[12:13], 0, v[4:5]
	v_or3_b32 v4, s79, v36, v69
	v_lshlrev_b32_e32 v4, 2, v4
	v_lshl_add_u64 v[80:81], s[12:13], 0, v[4:5]
	v_or3_b32 v4, s79, v37, v69
	v_lshlrev_b32_e32 v4, 2, v4
	v_lshl_add_u64 v[82:83], s[12:13], 0, v[4:5]
	v_or3_b32 v4, s79, v38, v69
	v_lshlrev_b32_e32 v4, 2, v4
	flat_load_dword v84, v[26:27] nt
	flat_load_dword v85, v[70:71] nt
	flat_load_dword v86, v[72:73] nt
	flat_load_dword v87, v[74:75] nt
	flat_load_dword v88, v[76:77] nt
	flat_load_dword v89, v[78:79] nt
	flat_load_dword v90, v[80:81] nt
	flat_load_dword v91, v[82:83] nt
	v_lshl_add_u64 v[26:27], s[12:13], 0, v[4:5]
	v_or3_b32 v4, s79, v39, v69
	v_lshlrev_b32_e32 v4, 2, v4
	v_lshl_add_u64 v[70:71], s[12:13], 0, v[4:5]
	v_or3_b32 v4, s79, v40, v69
	v_lshlrev_b32_e32 v4, 2, v4
	v_lshl_add_u64 v[72:73], s[12:13], 0, v[4:5]
	v_or3_b32 v4, s79, v41, v69
	v_lshlrev_b32_e32 v4, 2, v4
	v_lshl_add_u64 v[74:75], s[12:13], 0, v[4:5]
	v_or3_b32 v4, s79, v42, v69
	v_lshlrev_b32_e32 v4, 2, v4
	v_lshl_add_u64 v[76:77], s[12:13], 0, v[4:5]
	v_or3_b32 v4, s79, v43, v69
	v_lshlrev_b32_e32 v4, 2, v4
	v_lshl_add_u64 v[78:79], s[12:13], 0, v[4:5]
	v_or3_b32 v4, s79, v44, v69
	v_lshlrev_b32_e32 v4, 2, v4
	v_lshl_add_u64 v[80:81], s[12:13], 0, v[4:5]
	v_or3_b32 v4, s79, v45, v69
	v_lshlrev_b32_e32 v4, 2, v4
	v_lshl_add_u64 v[82:83], s[12:13], 0, v[4:5]
	v_or3_b32 v4, s79, v46, v69
	v_lshlrev_b32_e32 v4, 2, v4
	flat_load_dword v92, v[26:27] nt
	flat_load_dword v93, v[70:71] nt
	flat_load_dword v94, v[72:73] nt
	flat_load_dword v95, v[74:75] nt
	flat_load_dword v96, v[76:77] nt
	flat_load_dword v97, v[78:79] nt
	flat_load_dword v98, v[80:81] nt
	flat_load_dword v99, v[82:83] nt
	v_lshl_add_u64 v[26:27], s[12:13], 0, v[4:5]
	v_or3_b32 v4, s79, v47, v69
	v_lshlrev_b32_e32 v4, 2, v4
	v_lshl_add_u64 v[70:71], s[12:13], 0, v[4:5]
	v_or3_b32 v4, s79, v48, v69
	v_lshlrev_b32_e32 v4, 2, v4
	v_lshl_add_u64 v[72:73], s[12:13], 0, v[4:5]
	v_or3_b32 v4, s79, v49, v69
	v_lshlrev_b32_e32 v4, 2, v4
	v_lshl_add_u64 v[74:75], s[12:13], 0, v[4:5]
	v_or3_b32 v4, s79, v50, v69
	v_lshlrev_b32_e32 v4, 2, v4
	v_lshl_add_u64 v[76:77], s[12:13], 0, v[4:5]
	v_or3_b32 v4, s79, v51, v69
	v_lshlrev_b32_e32 v4, 2, v4
	v_lshl_add_u64 v[78:79], s[12:13], 0, v[4:5]
	v_or3_b32 v4, s79, v52, v69
	v_lshlrev_b32_e32 v4, 2, v4
	v_lshl_add_u64 v[80:81], s[12:13], 0, v[4:5]
	v_or3_b32 v4, s79, v53, v69
	v_lshlrev_b32_e32 v4, 2, v4
	v_lshl_add_u64 v[82:83], s[12:13], 0, v[4:5]
	v_or3_b32 v4, s79, v54, v69
	v_lshlrev_b32_e32 v4, 2, v4
	flat_load_dword v100, v[26:27] nt
	flat_load_dword v101, v[70:71] nt
	flat_load_dword v102, v[72:73] nt
	flat_load_dword v103, v[74:75] nt
	flat_load_dword v104, v[76:77] nt
	flat_load_dword v105, v[78:79] nt
	flat_load_dword v106, v[80:81] nt
	flat_load_dword v107, v[82:83] nt
	v_lshl_add_u64 v[26:27], s[12:13], 0, v[4:5]
	v_or3_b32 v4, s79, v55, v69
	v_lshlrev_b32_e32 v4, 2, v4
	v_lshl_add_u64 v[70:71], s[12:13], 0, v[4:5]
	v_or3_b32 v4, s79, v56, v69
	v_lshlrev_b32_e32 v4, 2, v4
	v_lshl_add_u64 v[72:73], s[12:13], 0, v[4:5]
	v_or3_b32 v4, s79, v57, v69
	v_lshlrev_b32_e32 v4, 2, v4
	v_lshl_add_u64 v[74:75], s[12:13], 0, v[4:5]
	v_or3_b32 v4, s79, v58, v69
	v_lshlrev_b32_e32 v4, 2, v4
	v_lshl_add_u64 v[76:77], s[12:13], 0, v[4:5]
	v_or3_b32 v4, s79, v59, v69
	v_lshlrev_b32_e32 v4, 2, v4
	v_lshl_add_u64 v[78:79], s[12:13], 0, v[4:5]
	v_or3_b32 v4, s79, v60, v69
	v_lshlrev_b32_e32 v4, 2, v4
	v_lshl_add_u64 v[80:81], s[12:13], 0, v[4:5]
	v_or3_b32 v4, s79, v61, v69
	v_lshlrev_b32_e32 v4, 2, v4
	v_lshl_add_u64 v[82:83], s[12:13], 0, v[4:5]
	flat_load_dword v4, v[26:27] nt
	s_nop 0
	flat_load_dword v26, v[70:71] nt
	flat_load_dword v27, v[72:73] nt
	flat_load_dword v69, v[74:75] nt
	s_nop 0
	flat_load_dword v70, v[76:77] nt
	flat_load_dword v71, v[78:79] nt
	flat_load_dword v72, v[80:81] nt
	flat_load_dword v73, v[82:83] nt
	v_add_u32_e32 v74, 0x400, v62
	s_waitcnt vmcnt(0) lgkmcnt(0)
; #define LAS __attribute__((address_space(3)))
; __device__ __forceinline__ unsigned cvt_pk_bf16(float lo, float hi) { unsigned r; asm volatile("s_nop 1\n\tv_cvt_pk_bf16_f32 %0, %1, %2" : "=v"(r) : "v"(lo), "v"(hi)); return r; }
; #define ARG(T, i) ((T)ldptr(lds, (i)))
; template <int MAP>
; __device__ __forceinline__ void p0_transpose_item(const float* W, int K, int Nsrc, int rows, bf16_t* WT, LAS float* scr, int item, int lane) {
;     ...
; #pragma unroll
;     for (int i = 0; i < 32; ++i) scr[(2 * i + (lane >> 5)) * 33 + (lane & 31)] = tv[i];
;     asm volatile("s_waitcnt lgkmcnt(0)" ::: "memory");
;     const int c = lane & 7;
; #pragma unroll
;     for (int jj = 0; jj < 4; ++jj) { const int n = (lane >> 3) + 8 * jj; const LAS float* s = scr + (8 * c) * 33 + n;
;         u32x4 o; o.x = cvt_pk_bf16(s[0 * 33], s[1 * 33]); o.y = cvt_pk_bf16(s[2 * 33], s[3 * 33]); o.z = cvt_pk_bf16(s[4 * 33], s[5 * 33]); o.w = cvt_pk_bf16(s[6 * 33], s[7 * 33]);
;         *(u32x4*)(WT + (size_t)(n0 + n) * K + k0 + 8 * c) = o; }
;     asm volatile("s_waitcnt lgkmcnt(0)" ::: "memory");
; }
; __global__ void __launch_bounds__(512, 2) fwd_megakernel(Args a) {
;     ...
;             if (r < I_AO) { p0_transpose_item<0>(ARG(const float*, 11), 1024, D, D, WAO, scr, r, lane); continue; } r -= I_AO;
	ds_write2_b32 v62, v84, v85 offset1:66
	ds_write2_b32 v62, v86, v87 offset0:132 offset1:198
	ds_write2_b32 v74, v88, v89 offset0:8 offset1:74
	ds_write2_b32 v74, v90, v91 offset0:140 offset1:206
	v_add_u32_e32 v74, 0x800, v62
	ds_write2_b32 v74, v92, v93 offset0:16 offset1:82
	ds_write2_b32 v74, v94, v95 offset0:148 offset1:214
	v_add_u32_e32 v74, 0xc00, v62
	ds_write2_b32 v74, v96, v97 offset0:24 offset1:90
	ds_write2_b32 v74, v98, v99 offset0:156 offset1:222
	v_add_u32_e32 v74, 0x1000, v62
	ds_write2_b32 v74, v100, v101 offset0:32 offset1:98
	ds_write2_b32 v74, v102, v103 offset0:164 offset1:230
	v_add_u32_e32 v74, 0x1400, v62
	ds_write2_b32 v74, v104, v105 offset0:40 offset1:106
	ds_write2_b32 v74, v106, v107 offset0:172 offset1:238
	v_add_u32_e32 v74, 0x1800, v62
	ds_write2_b32 v74, v4, v26 offset0:48 offset1:114
	ds_write2_b32 v74, v27, v69 offset0:180 offset1:246
	v_add_u32_e32 v4, 0x1c00, v62
	ds_write2_b32 v4, v70, v71 offset0:56 offset1:122
	ds_write2_b32 v4, v72, v73 offset0:188 offset1:254
	s_waitcnt lgkmcnt(0)
	ds_read2_b32 v[26:27], v63 offset1:33
	s_waitcnt lgkmcnt(0)
	s_nop 1
	v_cvt_pk_bf16_f32 v70, v26, v27
	ds_read2_b32 v[26:27], v63 offset0:66 offset1:99
	s_waitcnt lgkmcnt(0)
	s_nop 1
	v_cvt_pk_bf16_f32 v71, v26, v27
	ds_read2_b32 v[26:27], v63 offset0:132 offset1:165
	v_or_b32_e32 v4, s79, v29
	s_waitcnt lgkmcnt(0)
	s_nop 1
	v_cvt_pk_bf16_f32 v72, v26, v27
	ds_read2_b32 v[26:27], v63 offset0:198 offset1:231
	v_lshl_add_u64 v[74:75], v[8:9], 0, s[10:11]
	v_lshlrev_b32_e32 v4, 9, v4
	s_waitcnt lgkmcnt(0)
	s_nop 1
	v_cvt_pk_bf16_f32 v73, v26, v27
	v_lshl_add_u64 v[26:27], v[74:75], 0, v[4:5]
	flat_store_dwordx4 v[26:27], v[70:73]
	ds_read2_b32 v[26:27], v63 offset0:8 offset1:41
	v_or_b32_e32 v4, s79, v64
	s_waitcnt lgkmcnt(0)
	s_nop 1
	v_cvt_pk_bf16_f32 v70, v26, v27
	ds_read2_b32 v[26:27], v63 offset0:74 offset1:107
	s_waitcnt lgkmcnt(0)
	s_nop 1
	v_cvt_pk_bf16_f32 v71, v26, v27
	ds_read2_b32 v[26:27], v63 offset0:140 offset1:173
	s_waitcnt lgkmcnt(0)
	s_nop 1
	v_cvt_pk_bf16_f32 v72, v26, v27
	ds_read2_b32 v[26:27], v63 offset0:206 offset1:239
	v_lshlrev_b32_e32 v4, 9, v4
	s_waitcnt lgkmcnt(0)
	s_nop 1
	v_cvt_pk_bf16_f32 v73, v26, v27
	v_lshl_add_u64 v[26:27], v[74:75], 0, v[4:5]
	flat_store_dwordx4 v[26:27], v[70:73]
	ds_read2_b32 v[26:27], v63 offset0:16 offset1:49
	v_or_b32_e32 v4, s79, v65
	s_waitcnt lgkmcnt(0)
	s_nop 1
	v_cvt_pk_bf16_f32 v70, v26, v27
	ds_read2_b32 v[26:27], v63 offset0:82 offset1:115
	s_waitcnt lgkmcnt(0)
	s_nop 1
	v_cvt_pk_bf16_f32 v71, v26, v27
	ds_read2_b32 v[26:27], v63 offset0:148 offset1:181
	s_waitcnt lgkmcnt(0)
	s_nop 1
	v_cvt_pk_bf16_f32 v72, v26, v27
	ds_read2_b32 v[26:27], v63 offset0:214 offset1:247
	v_lshlrev_b32_e32 v4, 9, v4
	s_waitcnt lgkmcnt(0)
	s_nop 1
	v_cvt_pk_bf16_f32 v73, v26, v27
	v_lshl_add_u64 v[26:27], v[74:75], 0, v[4:5]
	flat_store_dwordx4 v[26:27], v[70:73]
	ds_read2_b32 v[26:27], v63 offset0:24 offset1:57
	v_or_b32_e32 v4, s79, v66
	s_waitcnt lgkmcnt(0)
	s_nop 1
	v_cvt_pk_bf16_f32 v70, v26, v27
	ds_read2_b32 v[26:27], v63 offset0:90 offset1:123
	s_waitcnt lgkmcnt(0)
	s_nop 1
	v_cvt_pk_bf16_f32 v71, v26, v27
	ds_read2_b32 v[26:27], v63 offset0:156 offset1:189
	s_waitcnt lgkmcnt(0)
	s_nop 1
	v_cvt_pk_bf16_f32 v72, v26, v27
	ds_read2_b32 v[26:27], v63 offset0:222 offset1:255
	v_lshlrev_b32_e32 v4, 9, v4
	s_waitcnt lgkmcnt(0)
	s_nop 1
	v_cvt_pk_bf16_f32 v73, v26, v27
	v_lshl_add_u64 v[26:27], v[74:75], 0, v[4:5]
	flat_store_dwordx4 v[26:27], v[70:73]
	s_waitcnt lgkmcnt(0)
	s_mov_b64 s[12:13], 0
.LBB0_22:
	s_andn2_b64 vcc, exec, s[12:13]
	s_cbranch_vccnz .LBB0_24
	v_mov_b32_e32 v4, s24
	ds_read_b32 v4, v4
	v_mov_b32_e32 v26, s25
	ds_read_b32 v26, v26
	s_add_i32 s10, s78, 0xffff3600
	s_and_b32 s10, s10, 0x1fc0
	s_waitcnt lgkmcnt(0)
	v_readfirstlane_b32 s12, v4
	s_add_i32 s79, s16, 0xffe6c000
	v_or_b32_e32 v4, s10, v30
	s_and_b32 s79, s79, 0x7e0
	v_lshlrev_b32_e32 v69, 11, v4
	v_or3_b32 v4, s79, v3, v69
	v_readfirstlane_b32 s13, v26
	v_lshlrev_b32_e32 v4, 2, v4
	s_lshl_b32 s10, s10, 1
	v_lshl_add_u64 v[26:27], s[12:13], 0, v[4:5]
	v_or3_b32 v4, s79, v31, v69
	v_lshlrev_b32_e32 v4, 2, v4
	v_lshl_add_u64 v[70:71], s[12:13], 0, v[4:5]
	v_or3_b32 v4, s79, v32, v69
	v_lshlrev_b32_e32 v4, 2, v4
	v_lshl_add_u64 v[72:73], s[12:13], 0, v[4:5]
	v_or3_b32 v4, s79, v33, v69
	v_lshlrev_b32_e32 v4, 2, v4
	v_lshl_add_u64 v[74:75], s[12:13], 0, v[4:5]
	v_or3_b32 v4, s79, v34, v69
	v_lshlrev_b32_e32 v4, 2, v4
	v_lshl_add_u64 v[76:77], s[12:13], 0, v[4:5]
	v_or3_b32 v4, s79, v35, v69
	v_lshlrev_b32_e32 v4, 2, v4
	v_lshl_add_u64 v[78:79], s[12:13], 0, v[4:5]
	v_or3_b32 v4, s79, v36, v69
	v_lshlrev_b32_e32 v4, 2, v4
	v_lshl_add_u64 v[80:81], s[12:13], 0, v[4:5]
	v_or3_b32 v4, s79, v37, v69
	v_lshlrev_b32_e32 v4, 2, v4
	v_lshl_add_u64 v[82:83], s[12:13], 0, v[4:5]
	v_or3_b32 v4, s79, v38, v69
	v_lshlrev_b32_e32 v4, 2, v4
	flat_load_dword v84, v[26:27] nt
	flat_load_dword v85, v[70:71] nt
	flat_load_dword v86, v[72:73] nt
	flat_load_dword v87, v[74:75] nt
	flat_load_dword v88, v[76:77] nt
	flat_load_dword v89, v[78:79] nt
	flat_load_dword v90, v[80:81] nt
	flat_load_dword v91, v[82:83] nt
	v_lshl_add_u64 v[26:27], s[12:13], 0, v[4:5]
	v_or3_b32 v4, s79, v39, v69
	v_lshlrev_b32_e32 v4, 2, v4
	v_lshl_add_u64 v[70:71], s[12:13], 0, v[4:5]
	v_or3_b32 v4, s79, v40, v69
	v_lshlrev_b32_e32 v4, 2, v4
	v_lshl_add_u64 v[72:73], s[12:13], 0, v[4:5]
	v_or3_b32 v4, s79, v41, v69
	v_lshlrev_b32_e32 v4, 2, v4
	v_lshl_add_u64 v[74:75], s[12:13], 0, v[4:5]
	v_or3_b32 v4, s79, v42, v69
	v_lshlrev_b32_e32 v4, 2, v4
	v_lshl_add_u64 v[76:77], s[12:13], 0, v[4:5]
	v_or3_b32 v4, s79, v43, v69
	v_lshlrev_b32_e32 v4, 2, v4
; #define LAS __attribute__((address_space(3)))
; __device__ __forceinline__ unsigned cvt_pk_bf16(float lo, float hi) { unsigned r; asm volatile("s_nop 1\n\tv_cvt_pk_bf16_f32 %0, %1, %2" : "=v"(r) : "v"(lo), "v"(hi)); return r; }
; template <int MAP>
; __device__ __forceinline__ void p0_transpose_item(const float* W, int K, int Nsrc, int rows, bf16_t* WT, LAS float* scr, int item, int lane) {
;     ...
;     for (int i = 0; i < 32; ++i) tv[i] = W[(size_t)(k0 + 2 * i + (lane >> 5)) * Nsrc + sc];
; #pragma unroll
;     for (int i = 0; i < 32; ++i) scr[(2 * i + (lane >> 5)) * 33 + (lane & 31)] = tv[i];
;     asm volatile("s_waitcnt lgkmcnt(0)" ::: "memory");
;     const int c = lane & 7;
; #pragma unroll
;     for (int jj = 0; jj < 4; ++jj) { const int n = (lane >> 3) + 8 * jj; const LAS float* s = scr + (8 * c) * 33 + n;
;         u32x4 o; o.x = cvt_pk_bf16(s[0 * 33], s[1 * 33]); o.y = cvt_pk_bf16(s[2 * 33], s[3 * 33]); o.z = cvt_pk_bf16(s[4 * 33], s[5 * 33]); o.w = cvt_pk_bf16(s[6 * 33], s[7 * 33]);
;         *(u32x4*)(WT + (size_t)(n0 + n) * K + k0 + 8 * c) = o; }
	v_lshl_add_u64 v[78:79], s[12:13], 0, v[4:5]
	v_or3_b32 v4, s79, v44, v69
	v_lshlrev_b32_e32 v4, 2, v4
	v_lshl_add_u64 v[80:81], s[12:13], 0, v[4:5]
	v_or3_b32 v4, s79, v45, v69
	v_lshlrev_b32_e32 v4, 2, v4
	v_lshl_add_u64 v[82:83], s[12:13], 0, v[4:5]
	v_or3_b32 v4, s79, v46, v69
	v_lshlrev_b32_e32 v4, 2, v4
	flat_load_dword v92, v[26:27] nt
	flat_load_dword v93, v[70:71] nt
	flat_load_dword v94, v[72:73] nt
	flat_load_dword v95, v[74:75] nt
	flat_load_dword v96, v[76:77] nt
	flat_load_dword v97, v[78:79] nt
	flat_load_dword v98, v[80:81] nt
	flat_load_dword v99, v[82:83] nt
	v_lshl_add_u64 v[26:27], s[12:13], 0, v[4:5]
	v_or3_b32 v4, s79, v47, v69
	v_lshlrev_b32_e32 v4, 2, v4
	v_lshl_add_u64 v[70:71], s[12:13], 0, v[4:5]
	v_or3_b32 v4, s79, v48, v69
	v_lshlrev_b32_e32 v4, 2, v4
	v_lshl_add_u64 v[72:73], s[12:13], 0, v[4:5]
	v_or3_b32 v4, s79, v49, v69
	v_lshlrev_b32_e32 v4, 2, v4
	v_lshl_add_u64 v[74:75], s[12:13], 0, v[4:5]
	v_or3_b32 v4, s79, v50, v69
	v_lshlrev_b32_e32 v4, 2, v4
	v_lshl_add_u64 v[76:77], s[12:13], 0, v[4:5]
	v_or3_b32 v4, s79, v51, v69
	v_lshlrev_b32_e32 v4, 2, v4
	v_lshl_add_u64 v[78:79], s[12:13], 0, v[4:5]
	v_or3_b32 v4, s79, v52, v69
	v_lshlrev_b32_e32 v4, 2, v4
	v_lshl_add_u64 v[80:81], s[12:13], 0, v[4:5]
	v_or3_b32 v4, s79, v53, v69
	v_lshlrev_b32_e32 v4, 2, v4
	v_lshl_add_u64 v[82:83], s[12:13], 0, v[4:5]
	v_or3_b32 v4, s79, v54, v69
	v_lshlrev_b32_e32 v4, 2, v4
	flat_load_dword v100, v[26:27] nt
	flat_load_dword v101, v[70:71] nt
	flat_load_dword v102, v[72:73] nt
	flat_load_dword v103, v[74:75] nt
	flat_load_dword v104, v[76:77] nt
	flat_load_dword v105, v[78:79] nt
	flat_load_dword v106, v[80:81] nt
	flat_load_dword v107, v[82:83] nt
	v_lshl_add_u64 v[26:27], s[12:13], 0, v[4:5]
	v_or3_b32 v4, s79, v55, v69
	v_lshlrev_b32_e32 v4, 2, v4
	v_lshl_add_u64 v[70:71], s[12:13], 0, v[4:5]
	v_or3_b32 v4, s79, v56, v69
	v_lshlrev_b32_e32 v4, 2, v4
	v_lshl_add_u64 v[72:73], s[12:13], 0, v[4:5]
	v_or3_b32 v4, s79, v57, v69
	v_lshlrev_b32_e32 v4, 2, v4
	v_lshl_add_u64 v[74:75], s[12:13], 0, v[4:5]
	v_or3_b32 v4, s79, v58, v69
	v_lshlrev_b32_e32 v4, 2, v4
	v_lshl_add_u64 v[76:77], s[12:13], 0, v[4:5]
	v_or3_b32 v4, s79, v59, v69
	v_lshlrev_b32_e32 v4, 2, v4
	v_lshl_add_u64 v[78:79], s[12:13], 0, v[4:5]
	v_or3_b32 v4, s79, v60, v69
	v_lshlrev_b32_e32 v4, 2, v4
	v_lshl_add_u64 v[80:81], s[12:13], 0, v[4:5]
	v_or3_b32 v4, s79, v61, v69
	v_lshlrev_b32_e32 v4, 2, v4
	v_lshl_add_u64 v[82:83], s[12:13], 0, v[4:5]
	flat_load_dword v4, v[26:27] nt
	s_nop 0
	flat_load_dword v26, v[70:71] nt
	flat_load_dword v27, v[72:73] nt
	flat_load_dword v69, v[74:75] nt
	s_nop 0
	flat_load_dword v70, v[76:77] nt
	flat_load_dword v71, v[78:79] nt
	flat_load_dword v72, v[80:81] nt
	flat_load_dword v73, v[82:83] nt
	v_add_u32_e32 v74, 0x400, v62
	s_waitcnt vmcnt(0) lgkmcnt(0)
	ds_write2_b32 v62, v84, v85 offset1:66
	ds_write2_b32 v62, v86, v87 offset0:132 offset1:198
	ds_write2_b32 v74, v88, v89 offset0:8 offset1:74
	ds_write2_b32 v74, v90, v91 offset0:140 offset1:206
	v_add_u32_e32 v74, 0x800, v62
	ds_write2_b32 v74, v92, v93 offset0:16 offset1:82
	ds_write2_b32 v74, v94, v95 offset0:148 offset1:214
	v_add_u32_e32 v74, 0xc00, v62
	ds_write2_b32 v74, v96, v97 offset0:24 offset1:90
	ds_write2_b32 v74, v98, v99 offset0:156 offset1:222
	v_add_u32_e32 v74, 0x1000, v62
	ds_write2_b32 v74, v100, v101 offset0:32 offset1:98
	ds_write2_b32 v74, v102, v103 offset0:164 offset1:230
	v_add_u32_e32 v74, 0x1400, v62
	ds_write2_b32 v74, v104, v105 offset0:40 offset1:106
	ds_write2_b32 v74, v106, v107 offset0:172 offset1:238
	v_add_u32_e32 v74, 0x1800, v62
	ds_write2_b32 v74, v4, v26 offset0:48 offset1:114
	ds_write2_b32 v74, v27, v69 offset0:180 offset1:246
	v_add_u32_e32 v4, 0x1c00, v62
	ds_write2_b32 v4, v70, v71 offset0:56 offset1:122
	ds_write2_b32 v4, v72, v73 offset0:188 offset1:254
	s_waitcnt lgkmcnt(0)
	ds_read2_b32 v[26:27], v63 offset1:33
	s_waitcnt lgkmcnt(0)
	s_nop 1
	v_cvt_pk_bf16_f32 v70, v26, v27
	ds_read2_b32 v[26:27], v63 offset0:66 offset1:99
	s_waitcnt lgkmcnt(0)
	s_nop 1
	v_cvt_pk_bf16_f32 v71, v26, v27
	ds_read2_b32 v[26:27], v63 offset0:132 offset1:165
	v_or_b32_e32 v4, s79, v29
	s_waitcnt lgkmcnt(0)
	s_nop 1
	v_cvt_pk_bf16_f32 v72, v26, v27
	ds_read2_b32 v[26:27], v63 offset0:198 offset1:231
	v_lshl_add_u64 v[74:75], v[10:11], 0, s[10:11]
	v_lshlrev_b32_e32 v4, 11, v4
	s_waitcnt lgkmcnt(0)
	s_nop 1
	v_cvt_pk_bf16_f32 v73, v26, v27
	v_lshl_add_u64 v[26:27], v[74:75], 0, v[4:5]
	flat_store_dwordx4 v[26:27], v[70:73]
	ds_read2_b32 v[26:27], v63 offset0:8 offset1:41
	v_or_b32_e32 v4, s79, v64
	s_waitcnt lgkmcnt(0)
	s_nop 1
	v_cvt_pk_bf16_f32 v70, v26, v27
	ds_read2_b32 v[26:27], v63 offset0:74 offset1:107
	s_waitcnt lgkmcnt(0)
	s_nop 1
	v_cvt_pk_bf16_f32 v71, v26, v27
	ds_read2_b32 v[26:27], v63 offset0:140 offset1:173
	s_waitcnt lgkmcnt(0)
	s_nop 1
	v_cvt_pk_bf16_f32 v72, v26, v27
	ds_read2_b32 v[26:27], v63 offset0:206 offset1:239
	v_lshlrev_b32_e32 v4, 11, v4
	s_waitcnt lgkmcnt(0)
	s_nop 1
	v_cvt_pk_bf16_f32 v73, v26, v27
	v_lshl_add_u64 v[26:27], v[74:75], 0, v[4:5]
	flat_store_dwordx4 v[26:27], v[70:73]
	ds_read2_b32 v[26:27], v63 offset0:16 offset1:49
	v_or_b32_e32 v4, s79, v65
	s_waitcnt lgkmcnt(0)
	s_nop 1
	v_cvt_pk_bf16_f32 v70, v26, v27
	ds_read2_b32 v[26:27], v63 offset0:82 offset1:115
	s_waitcnt lgkmcnt(0)
	s_nop 1
	v_cvt_pk_bf16_f32 v71, v26, v27
	ds_read2_b32 v[26:27], v63 offset0:148 offset1:181
	s_waitcnt lgkmcnt(0)
	s_nop 1
	v_cvt_pk_bf16_f32 v72, v26, v27
	ds_read2_b32 v[26:27], v63 offset0:214 offset1:247
	v_lshlrev_b32_e32 v4, 11, v4
	s_waitcnt lgkmcnt(0)
	s_nop 1
	v_cvt_pk_bf16_f32 v73, v26, v27
	v_lshl_add_u64 v[26:27], v[74:75], 0, v[4:5]
	flat_store_dwordx4 v[26:27], v[70:73]
	ds_read2_b32 v[26:27], v63 offset0:24 offset1:57
	v_or_b32_e32 v4, s79, v66
	s_waitcnt lgkmcnt(0)
	s_nop 1
	v_cvt_pk_bf16_f32 v70, v26, v27
	ds_read2_b32 v[26:27], v63 offset0:90 offset1:123
	s_waitcnt lgkmcnt(0)
	s_nop 1
	v_cvt_pk_bf16_f32 v71, v26, v27
	ds_read2_b32 v[26:27], v63 offset0:156 offset1:189
	s_waitcnt lgkmcnt(0)
	s_nop 1
	v_cvt_pk_bf16_f32 v72, v26, v27
	ds_read2_b32 v[26:27], v63 offset0:222 offset1:255
	v_lshlrev_b32_e32 v4, 11, v4
	s_waitcnt lgkmcnt(0)
	s_nop 1
	v_cvt_pk_bf16_f32 v73, v26, v27
	v_lshl_add_u64 v[26:27], v[74:75], 0, v[4:5]
	flat_store_dwordx4 v[26:27], v[70:73]
	s_waitcnt lgkmcnt(0)

; __device__ __forceinline__ int map_gu(int j) { return ((j >> 7) & 1) * FF + ((j >> 8) << 7) + (j & 127); }
; template <int MAP>
; __device__ __forceinline__ void p0_transpose_item(const float* W, int K, int Nsrc, int rows, bf16_t* WT, LAS float* scr, int item, int lane) {
;     const int nblk = rows / 32, kb = item / nblk, nb = item % nblk, k0 = 64 * kb, n0 = 32 * nb;
;     const int j = n0 + (lane & 31);
;     const int sc = MAP == 0 ? j : (MAP == 1 ? map_gu(j) : map_in(j));
;     float tv[32];
; #pragma unroll
;     for (int i = 0; i < 32; ++i) tv[i] = W[(size_t)(k0 + 2 * i + (lane >> 5)) * Nsrc + sc];
; #pragma unroll
;     for (int i = 0; i < 32; ++i) scr[(2 * i + (lane >> 5)) * 33 + (lane & 31)] = tv[i];
.LBB0_25:
	s_andn2_b64 vcc, exec, s[12:13]
	s_cbranch_vccnz .LBB0_27
	v_mov_b32_e32 v4, s26
	ds_read_b32 v4, v4
	v_mov_b32_e32 v26, s27
	ds_read_b32 v26, v26
	s_add_i32 s10, s78, 0xffff3e00
	s_and_b32 s10, s10, 0x1fc0
	s_waitcnt lgkmcnt(0)
	v_readfirstlane_b32 s12, v4
	s_add_i32 s79, s16, 0xffe7c000
	v_or_b32_e32 v4, s10, v30
	s_and_b32 s79, s79, 0x7e0
	v_lshlrev_b32_e32 v69, 11, v4
	v_or3_b32 v4, s79, v3, v69
	v_readfirstlane_b32 s13, v26
	v_lshlrev_b32_e32 v4, 2, v4
	s_lshl_b32 s10, s10, 1
	v_lshl_add_u64 v[26:27], s[12:13], 0, v[4:5]
	v_or3_b32 v4, s79, v31, v69
	v_lshlrev_b32_e32 v4, 2, v4
	v_lshl_add_u64 v[70:71], s[12:13], 0, v[4:5]
	v_or3_b32 v4, s79, v32, v69
	v_lshlrev_b32_e32 v4, 2, v4
	v_lshl_add_u64 v[72:73], s[12:13], 0, v[4:5]
	v_or3_b32 v4, s79, v33, v69
	v_lshlrev_b32_e32 v4, 2, v4
	v_lshl_add_u64 v[74:75], s[12:13], 0, v[4:5]
	v_or3_b32 v4, s79, v34, v69
	v_lshlrev_b32_e32 v4, 2, v4
	v_lshl_add_u64 v[76:77], s[12:13], 0, v[4:5]
	v_or3_b32 v4, s79, v35, v69
	v_lshlrev_b32_e32 v4, 2, v4
	v_lshl_add_u64 v[78:79], s[12:13], 0, v[4:5]
	v_or3_b32 v4, s79, v36, v69
	v_lshlrev_b32_e32 v4, 2, v4
	v_lshl_add_u64 v[80:81], s[12:13], 0, v[4:5]
	v_or3_b32 v4, s79, v37, v69
	v_lshlrev_b32_e32 v4, 2, v4
	v_lshl_add_u64 v[82:83], s[12:13], 0, v[4:5]
	v_or3_b32 v4, s79, v38, v69
	v_lshlrev_b32_e32 v4, 2, v4
	flat_load_dword v84, v[26:27] nt
	flat_load_dword v85, v[70:71] nt
	flat_load_dword v86, v[72:73] nt
	flat_load_dword v87, v[74:75] nt
	flat_load_dword v88, v[76:77] nt
	flat_load_dword v89, v[78:79] nt
	flat_load_dword v90, v[80:81] nt
	flat_load_dword v91, v[82:83] nt
	v_lshl_add_u64 v[26:27], s[12:13], 0, v[4:5]
	v_or3_b32 v4, s79, v39, v69
	v_lshlrev_b32_e32 v4, 2, v4
	v_lshl_add_u64 v[70:71], s[12:13], 0, v[4:5]
	v_or3_b32 v4, s79, v40, v69
	v_lshlrev_b32_e32 v4, 2, v4
	v_lshl_add_u64 v[72:73], s[12:13], 0, v[4:5]
	v_or3_b32 v4, s79, v41, v69
	v_lshlrev_b32_e32 v4, 2, v4
	v_lshl_add_u64 v[74:75], s[12:13], 0, v[4:5]
	v_or3_b32 v4, s79, v42, v69
	v_lshlrev_b32_e32 v4, 2, v4
	v_lshl_add_u64 v[76:77], s[12:13], 0, v[4:5]
	v_or3_b32 v4, s79, v43, v69
	v_lshlrev_b32_e32 v4, 2, v4
	v_lshl_add_u64 v[78:79], s[12:13], 0, v[4:5]
	v_or3_b32 v4, s79, v44, v69
	v_lshlrev_b32_e32 v4, 2, v4
	v_lshl_add_u64 v[80:81], s[12:13], 0, v[4:5]
	v_or3_b32 v4, s79, v45, v69
	v_lshlrev_b32_e32 v4, 2, v4
	v_lshl_add_u64 v[82:83], s[12:13], 0, v[4:5]
	v_or3_b32 v4, s79, v46, v69
	v_lshlrev_b32_e32 v4, 2, v4
	flat_load_dword v92, v[26:27] nt
	flat_load_dword v93, v[70:71] nt
	flat_load_dword v94, v[72:73] nt
	flat_load_dword v95, v[74:75] nt
	flat_load_dword v96, v[76:77] nt
	flat_load_dword v97, v[78:79] nt
	flat_load_dword v98, v[80:81] nt
	flat_load_dword v99, v[82:83] nt
	v_lshl_add_u64 v[26:27], s[12:13], 0, v[4:5]
	v_or3_b32 v4, s79, v47, v69
	v_lshlrev_b32_e32 v4, 2, v4
	v_lshl_add_u64 v[70:71], s[12:13], 0, v[4:5]
	v_or3_b32 v4, s79, v48, v69
	v_lshlrev_b32_e32 v4, 2, v4
	v_lshl_add_u64 v[72:73], s[12:13], 0, v[4:5]
	v_or3_b32 v4, s79, v49, v69
	v_lshlrev_b32_e32 v4, 2, v4
	v_lshl_add_u64 v[74:75], s[12:13], 0, v[4:5]
	v_or3_b32 v4, s79, v50, v69
	v_lshlrev_b32_e32 v4, 2, v4
	v_lshl_add_u64 v[76:77], s[12:13], 0, v[4:5]
	v_or3_b32 v4, s79, v51, v69
	v_lshlrev_b32_e32 v4, 2, v4
	v_lshl_add_u64 v[78:79], s[12:13], 0, v[4:5]
	v_or3_b32 v4, s79, v52, v69
	v_lshlrev_b32_e32 v4, 2, v4
	v_lshl_add_u64 v[80:81], s[12:13], 0, v[4:5]
	v_or3_b32 v4, s79, v53, v69
	v_lshlrev_b32_e32 v4, 2, v4
	v_lshl_add_u64 v[82:83], s[12:13], 0, v[4:5]
	v_or3_b32 v4, s79, v54, v69
	v_lshlrev_b32_e32 v4, 2, v4
	flat_load_dword v100, v[26:27] nt
	flat_load_dword v101, v[70:71] nt
	flat_load_dword v102, v[72:73] nt
	flat_load_dword v103, v[74:75] nt
	flat_load_dword v104, v[76:77] nt
	flat_load_dword v105, v[78:79] nt
	flat_load_dword v106, v[80:81] nt
	flat_load_dword v107, v[82:83] nt
	v_lshl_add_u64 v[26:27], s[12:13], 0, v[4:5]
	v_or3_b32 v4, s79, v55, v69
	v_lshlrev_b32_e32 v4, 2, v4
	v_lshl_add_u64 v[70:71], s[12:13], 0, v[4:5]
	v_or3_b32 v4, s79, v56, v69
	v_lshlrev_b32_e32 v4, 2, v4
	v_lshl_add_u64 v[72:73], s[12:13], 0, v[4:5]
	v_or3_b32 v4, s79, v57, v69
	v_lshlrev_b32_e32 v4, 2, v4
	v_lshl_add_u64 v[74:75], s[12:13], 0, v[4:5]
	v_or3_b32 v4, s79, v58, v69
	v_lshlrev_b32_e32 v4, 2, v4
	v_lshl_add_u64 v[76:77], s[12:13], 0, v[4:5]
	v_or3_b32 v4, s79, v59, v69
	v_lshlrev_b32_e32 v4, 2, v4
	v_lshl_add_u64 v[78:79], s[12:13], 0, v[4:5]
	v_or3_b32 v4, s79, v60, v69
	v_lshlrev_b32_e32 v4, 2, v4
	v_lshl_add_u64 v[80:81], s[12:13], 0, v[4:5]
	v_or3_b32 v4, s79, v61, v69
	v_lshlrev_b32_e32 v4, 2, v4
	v_lshl_add_u64 v[82:83], s[12:13], 0, v[4:5]
	flat_load_dword v4, v[26:27] nt
	s_nop 0
	flat_load_dword v26, v[70:71] nt
	flat_load_dword v27, v[72:73] nt
	flat_load_dword v69, v[74:75] nt
	s_nop 0
	flat_load_dword v70, v[76:77] nt
	flat_load_dword v71, v[78:79] nt
	flat_load_dword v72, v[80:81] nt
	flat_load_dword v73, v[82:83] nt
	v_add_u32_e32 v74, 0x400, v62
	s_waitcnt vmcnt(0) lgkmcnt(0)
; #define LAS __attribute__((address_space(3)))
; __device__ __forceinline__ unsigned cvt_pk_bf16(float lo, float hi) { unsigned r; asm volatile("s_nop 1\n\tv_cvt_pk_bf16_f32 %0, %1, %2" : "=v"(r) : "v"(lo), "v"(hi)); return r; }
; template <int MAP>
; __device__ __forceinline__ void p0_transpose_item(const float* W, int K, int Nsrc, int rows, bf16_t* WT, LAS float* scr, int item, int lane) {
;     ...
;     for (int i = 0; i < 32; ++i) scr[(2 * i + (lane >> 5)) * 33 + (lane & 31)] = tv[i];
;     asm volatile("s_waitcnt lgkmcnt(0)" ::: "memory");
;     const int c = lane & 7;
; #pragma unroll
;     for (int jj = 0; jj < 4; ++jj) { const int n = (lane >> 3) + 8 * jj; const LAS float* s = scr + (8 * c) * 33 + n;
;         u32x4 o; o.x = cvt_pk_bf16(s[0 * 33], s[1 * 33]); o.y = cvt_pk_bf16(s[2 * 33], s[3 * 33]); o.z = cvt_pk_bf16(s[4 * 33], s[5 * 33]); o.w = cvt_pk_bf16(s[6 * 33], s[7 * 33]);
;         *(u32x4*)(WT + (size_t)(n0 + n) * K + k0 + 8 * c) = o; }
;     asm volatile("s_waitcnt lgkmcnt(0)" ::: "memory");
	ds_write2_b32 v62, v84, v85 offset1:66
	ds_write2_b32 v62, v86, v87 offset0:132 offset1:198
	ds_write2_b32 v74, v88, v89 offset0:8 offset1:74
	ds_write2_b32 v74, v90, v91 offset0:140 offset1:206
	v_add_u32_e32 v74, 0x800, v62
	ds_write2_b32 v74, v92, v93 offset0:16 offset1:82
	ds_write2_b32 v74, v94, v95 offset0:148 offset1:214
	v_add_u32_e32 v74, 0xc00, v62
	ds_write2_b32 v74, v96, v97 offset0:24 offset1:90
	ds_write2_b32 v74, v98, v99 offset0:156 offset1:222
	v_add_u32_e32 v74, 0x1000, v62
	ds_write2_b32 v74, v100, v101 offset0:32 offset1:98
	ds_write2_b32 v74, v102, v103 offset0:164 offset1:230
	v_add_u32_e32 v74, 0x1400, v62
	ds_write2_b32 v74, v104, v105 offset0:40 offset1:106
	ds_write2_b32 v74, v106, v107 offset0:172 offset1:238
	v_add_u32_e32 v74, 0x1800, v62
	ds_write2_b32 v74, v4, v26 offset0:48 offset1:114
	ds_write2_b32 v74, v27, v69 offset0:180 offset1:246
	v_add_u32_e32 v4, 0x1c00, v62
	ds_write2_b32 v4, v70, v71 offset0:56 offset1:122
	ds_write2_b32 v4, v72, v73 offset0:188 offset1:254
	s_waitcnt lgkmcnt(0)
	ds_read2_b32 v[26:27], v63 offset1:33
	s_waitcnt lgkmcnt(0)
	s_nop 1
	v_cvt_pk_bf16_f32 v70, v26, v27
	ds_read2_b32 v[26:27], v63 offset0:66 offset1:99
	s_waitcnt lgkmcnt(0)
	s_nop 1
	v_cvt_pk_bf16_f32 v71, v26, v27
	ds_read2_b32 v[26:27], v63 offset0:132 offset1:165
	v_or_b32_e32 v4, s79, v29
	s_waitcnt lgkmcnt(0)
	s_nop 1
	v_cvt_pk_bf16_f32 v72, v26, v27
	ds_read2_b32 v[26:27], v63 offset0:198 offset1:231
	v_lshl_add_u64 v[74:75], v[12:13], 0, s[10:11]
	v_lshlrev_b32_e32 v4, 12, v4
	s_waitcnt lgkmcnt(0)
	s_nop 1
	v_cvt_pk_bf16_f32 v73, v26, v27
	v_lshl_add_u64 v[26:27], v[74:75], 0, v[4:5]
	flat_store_dwordx4 v[26:27], v[70:73]
	ds_read2_b32 v[26:27], v63 offset0:8 offset1:41
	v_or_b32_e32 v4, s79, v64
	s_waitcnt lgkmcnt(0)
	s_nop 1
	v_cvt_pk_bf16_f32 v70, v26, v27
	ds_read2_b32 v[26:27], v63 offset0:74 offset1:107
	s_waitcnt lgkmcnt(0)
	s_nop 1
	v_cvt_pk_bf16_f32 v71, v26, v27
	ds_read2_b32 v[26:27], v63 offset0:140 offset1:173
	s_waitcnt lgkmcnt(0)
	s_nop 1
	v_cvt_pk_bf16_f32 v72, v26, v27
	ds_read2_b32 v[26:27], v63 offset0:206 offset1:239
	v_lshlrev_b32_e32 v4, 12, v4
	s_waitcnt lgkmcnt(0)
	s_nop 1
	v_cvt_pk_bf16_f32 v73, v26, v27
	v_lshl_add_u64 v[26:27], v[74:75], 0, v[4:5]
	flat_store_dwordx4 v[26:27], v[70:73]
	ds_read2_b32 v[26:27], v63 offset0:16 offset1:49
	v_or_b32_e32 v4, s79, v65
	s_waitcnt lgkmcnt(0)
	s_nop 1
	v_cvt_pk_bf16_f32 v70, v26, v27
	ds_read2_b32 v[26:27], v63 offset0:82 offset1:115
	s_waitcnt lgkmcnt(0)
	s_nop 1
	v_cvt_pk_bf16_f32 v71, v26, v27
	ds_read2_b32 v[26:27], v63 offset0:148 offset1:181
	s_waitcnt lgkmcnt(0)
	s_nop 1
	v_cvt_pk_bf16_f32 v72, v26, v27
	ds_read2_b32 v[26:27], v63 offset0:214 offset1:247
	v_lshlrev_b32_e32 v4, 12, v4
	s_waitcnt lgkmcnt(0)
	s_nop 1
	v_cvt_pk_bf16_f32 v73, v26, v27
	v_lshl_add_u64 v[26:27], v[74:75], 0, v[4:5]
	flat_store_dwordx4 v[26:27], v[70:73]
	ds_read2_b32 v[26:27], v63 offset0:24 offset1:57
	v_or_b32_e32 v4, s79, v66
	s_waitcnt lgkmcnt(0)
	s_nop 1
	v_cvt_pk_bf16_f32 v70, v26, v27
	ds_read2_b32 v[26:27], v63 offset0:90 offset1:123
	s_waitcnt lgkmcnt(0)
	s_nop 1
	v_cvt_pk_bf16_f32 v71, v26, v27
	ds_read2_b32 v[26:27], v63 offset0:156 offset1:189
	s_waitcnt lgkmcnt(0)
	s_nop 1
	v_cvt_pk_bf16_f32 v72, v26, v27
	ds_read2_b32 v[26:27], v63 offset0:222 offset1:255
	v_lshlrev_b32_e32 v4, 12, v4
	s_waitcnt lgkmcnt(0)
	s_nop 1
	v_cvt_pk_bf16_f32 v73, v26, v27
	v_lshl_add_u64 v[26:27], v[74:75], 0, v[4:5]
	flat_store_dwordx4 v[26:27], v[70:73]
	s_waitcnt lgkmcnt(0)

; __device__ __forceinline__ int map_gu(int j) { return ((j >> 7) & 1) * FF + ((j >> 8) << 7) + (j & 127); }
; template <int MAP>
; __device__ __forceinline__ void p0_transpose_item(const float* W, int K, int Nsrc, int rows, bf16_t* WT, LAS float* scr, int item, int lane) {
;     const int nblk = rows / 32, kb = item / nblk, nb = item % nblk, k0 = 64 * kb, n0 = 32 * nb;
;     const int j = n0 + (lane & 31);
;     const int sc = MAP == 0 ? j : (MAP == 1 ? map_gu(j) : map_in(j));
;     float tv[32];
; #pragma unroll
;     for (int i = 0; i < 32; ++i) tv[i] = W[(size_t)(k0 + 2 * i + (lane >> 5)) * Nsrc + sc];
; #pragma unroll
;     for (int i = 0; i < 32; ++i) scr[(2 * i + (lane >> 5)) * 33 + (lane & 31)] = tv[i];
.LBB0_28:
	s_andn2_b64 vcc, exec, s[12:13]
	s_cbranch_vccnz .LBB0_30
	v_mov_b32_e32 v4, s28
	ds_read_b32 v4, v4
	v_mov_b32_e32 v26, s29
	ds_read_b32 v26, v26
	s_add_i32 s10, s78, 0xffff4600
	s_and_b32 s10, s10, 0x1fc0
	s_waitcnt lgkmcnt(0)
	v_readfirstlane_b32 s12, v4
	s_add_i32 s79, s16, 0xffe8c000
	v_or_b32_e32 v4, s10, v30
	s_and_b32 s79, s79, 0x7e0
	v_lshlrev_b32_e32 v69, 11, v4
	v_or3_b32 v4, s79, v3, v69
	v_readfirstlane_b32 s13, v26
	v_lshlrev_b32_e32 v4, 2, v4
	s_lshl_b32 s10, s10, 1
	v_lshl_add_u64 v[26:27], s[12:13], 0, v[4:5]
	v_or3_b32 v4, s79, v31, v69
	v_lshlrev_b32_e32 v4, 2, v4
	v_lshl_add_u64 v[70:71], s[12:13], 0, v[4:5]
	v_or3_b32 v4, s79, v32, v69
	v_lshlrev_b32_e32 v4, 2, v4
	v_lshl_add_u64 v[72:73], s[12:13], 0, v[4:5]
	v_or3_b32 v4, s79, v33, v69
	v_lshlrev_b32_e32 v4, 2, v4
	v_lshl_add_u64 v[74:75], s[12:13], 0, v[4:5]
	v_or3_b32 v4, s79, v34, v69
	v_lshlrev_b32_e32 v4, 2, v4
	v_lshl_add_u64 v[76:77], s[12:13], 0, v[4:5]
	v_or3_b32 v4, s79, v35, v69
	v_lshlrev_b32_e32 v4, 2, v4
	v_lshl_add_u64 v[78:79], s[12:13], 0, v[4:5]
	v_or3_b32 v4, s79, v36, v69
	v_lshlrev_b32_e32 v4, 2, v4
	v_lshl_add_u64 v[80:81], s[12:13], 0, v[4:5]
	v_or3_b32 v4, s79, v37, v69
	v_lshlrev_b32_e32 v4, 2, v4
	v_lshl_add_u64 v[82:83], s[12:13], 0, v[4:5]
	v_or3_b32 v4, s79, v38, v69
	v_lshlrev_b32_e32 v4, 2, v4
	flat_load_dword v84, v[26:27] nt
	flat_load_dword v85, v[70:71] nt
	flat_load_dword v86, v[72:73] nt
	flat_load_dword v87, v[74:75] nt
	flat_load_dword v88, v[76:77] nt
	flat_load_dword v89, v[78:79] nt
	flat_load_dword v90, v[80:81] nt
	flat_load_dword v91, v[82:83] nt
	v_lshl_add_u64 v[26:27], s[12:13], 0, v[4:5]
	v_or3_b32 v4, s79, v39, v69
	v_lshlrev_b32_e32 v4, 2, v4
	v_lshl_add_u64 v[70:71], s[12:13], 0, v[4:5]
	v_or3_b32 v4, s79, v40, v69
	v_lshlrev_b32_e32 v4, 2, v4
	v_lshl_add_u64 v[72:73], s[12:13], 0, v[4:5]
	v_or3_b32 v4, s79, v41, v69
	v_lshlrev_b32_e32 v4, 2, v4
	v_lshl_add_u64 v[74:75], s[12:13], 0, v[4:5]
	v_or3_b32 v4, s79, v42, v69
	v_lshlrev_b32_e32 v4, 2, v4
	v_lshl_add_u64 v[76:77], s[12:13], 0, v[4:5]
	v_or3_b32 v4, s79, v43, v69
	v_lshlrev_b32_e32 v4, 2, v4
	v_lshl_add_u64 v[78:79], s[12:13], 0, v[4:5]
	v_or3_b32 v4, s79, v44, v69
	v_lshlrev_b32_e32 v4, 2, v4
	v_lshl_add_u64 v[80:81], s[12:13], 0, v[4:5]
	v_or3_b32 v4, s79, v45, v69
	v_lshlrev_b32_e32 v4, 2, v4
	v_lshl_add_u64 v[82:83], s[12:13], 0, v[4:5]
	v_or3_b32 v4, s79, v46, v69
	v_lshlrev_b32_e32 v4, 2, v4
	flat_load_dword v92, v[26:27] nt
	flat_load_dword v93, v[70:71] nt
	flat_load_dword v94, v[72:73] nt
	flat_load_dword v95, v[74:75] nt
	flat_load_dword v96, v[76:77] nt
	flat_load_dword v97, v[78:79] nt
	flat_load_dword v98, v[80:81] nt
	flat_load_dword v99, v[82:83] nt
	v_lshl_add_u64 v[26:27], s[12:13], 0, v[4:5]
	v_or3_b32 v4, s79, v47, v69
	v_lshlrev_b32_e32 v4, 2, v4
	v_lshl_add_u64 v[70:71], s[12:13], 0, v[4:5]
	v_or3_b32 v4, s79, v48, v69
	v_lshlrev_b32_e32 v4, 2, v4
	v_lshl_add_u64 v[72:73], s[12:13], 0, v[4:5]
	v_or3_b32 v4, s79, v49, v69
	v_lshlrev_b32_e32 v4, 2, v4
	v_lshl_add_u64 v[74:75], s[12:13], 0, v[4:5]
	v_or3_b32 v4, s79, v50, v69
	v_lshlrev_b32_e32 v4, 2, v4
	v_lshl_add_u64 v[76:77], s[12:13], 0, v[4:5]
	v_or3_b32 v4, s79, v51, v69
	v_lshlrev_b32_e32 v4, 2, v4
	v_lshl_add_u64 v[78:79], s[12:13], 0, v[4:5]
	v_or3_b32 v4, s79, v52, v69
	v_lshlrev_b32_e32 v4, 2, v4
	v_lshl_add_u64 v[80:81], s[12:13], 0, v[4:5]
	v_or3_b32 v4, s79, v53, v69
	v_lshlrev_b32_e32 v4, 2, v4
	v_lshl_add_u64 v[82:83], s[12:13], 0, v[4:5]
	v_or3_b32 v4, s79, v54, v69
	v_lshlrev_b32_e32 v4, 2, v4
	flat_load_dword v100, v[26:27] nt
	flat_load_dword v101, v[70:71] nt
	flat_load_dword v102, v[72:73] nt
	flat_load_dword v103, v[74:75] nt
	flat_load_dword v104, v[76:77] nt
	flat_load_dword v105, v[78:79] nt
	flat_load_dword v106, v[80:81] nt
	flat_load_dword v107, v[82:83] nt
	v_lshl_add_u64 v[26:27], s[12:13], 0, v[4:5]
	v_or3_b32 v4, s79, v55, v69
	v_lshlrev_b32_e32 v4, 2, v4
	v_lshl_add_u64 v[70:71], s[12:13], 0, v[4:5]
	v_or3_b32 v4, s79, v56, v69
	v_lshlrev_b32_e32 v4, 2, v4
	v_lshl_add_u64 v[72:73], s[12:13], 0, v[4:5]
	v_or3_b32 v4, s79, v57, v69
	v_lshlrev_b32_e32 v4, 2, v4
	v_lshl_add_u64 v[74:75], s[12:13], 0, v[4:5]
	v_or3_b32 v4, s79, v58, v69
	v_lshlrev_b32_e32 v4, 2, v4
	v_lshl_add_u64 v[76:77], s[12:13], 0, v[4:5]
	v_or3_b32 v4, s79, v59, v69
	v_lshlrev_b32_e32 v4, 2, v4
	v_lshl_add_u64 v[78:79], s[12:13], 0, v[4:5]
	v_or3_b32 v4, s79, v60, v69
	v_lshlrev_b32_e32 v4, 2, v4
	v_lshl_add_u64 v[80:81], s[12:13], 0, v[4:5]
	v_or3_b32 v4, s79, v61, v69
	v_lshlrev_b32_e32 v4, 2, v4
	v_lshl_add_u64 v[82:83], s[12:13], 0, v[4:5]
	flat_load_dword v4, v[26:27] nt
	s_nop 0
	flat_load_dword v26, v[70:71] nt
	flat_load_dword v27, v[72:73] nt
	flat_load_dword v69, v[74:75] nt
	s_nop 0
	flat_load_dword v70, v[76:77] nt
	flat_load_dword v71, v[78:79] nt
	flat_load_dword v72, v[80:81] nt
	flat_load_dword v73, v[82:83] nt
	v_add_u32_e32 v74, 0x400, v62
	s_waitcnt vmcnt(0) lgkmcnt(0)
; #define LAS __attribute__((address_space(3)))
; __device__ __forceinline__ unsigned cvt_pk_bf16(float lo, float hi) { unsigned r; asm volatile("s_nop 1\n\tv_cvt_pk_bf16_f32 %0, %1, %2" : "=v"(r) : "v"(lo), "v"(hi)); return r; }
; template <int MAP>
; __device__ __forceinline__ void p0_transpose_item(const float* W, int K, int Nsrc, int rows, bf16_t* WT, LAS float* scr, int item, int lane) {
;     ...
;     for (int i = 0; i < 32; ++i) scr[(2 * i + (lane >> 5)) * 33 + (lane & 31)] = tv[i];
;     asm volatile("s_waitcnt lgkmcnt(0)" ::: "memory");
;     const int c = lane & 7;
; #pragma unroll
;     for (int jj = 0; jj < 4; ++jj) { const int n = (lane >> 3) + 8 * jj; const LAS float* s = scr + (8 * c) * 33 + n;
;         u32x4 o; o.x = cvt_pk_bf16(s[0 * 33], s[1 * 33]); o.y = cvt_pk_bf16(s[2 * 33], s[3 * 33]); o.z = cvt_pk_bf16(s[4 * 33], s[5 * 33]); o.w = cvt_pk_bf16(s[6 * 33], s[7 * 33]);
;         *(u32x4*)(WT + (size_t)(n0 + n) * K + k0 + 8 * c) = o; }
;     asm volatile("s_waitcnt lgkmcnt(0)" ::: "memory");
	ds_write2_b32 v62, v84, v85 offset1:66
	ds_write2_b32 v62, v86, v87 offset0:132 offset1:198
	ds_write2_b32 v74, v88, v89 offset0:8 offset1:74
	ds_write2_b32 v74, v90, v91 offset0:140 offset1:206
	v_add_u32_e32 v74, 0x800, v62
	ds_write2_b32 v74, v92, v93 offset0:16 offset1:82
	ds_write2_b32 v74, v94, v95 offset0:148 offset1:214
	v_add_u32_e32 v74, 0xc00, v62
	ds_write2_b32 v74, v96, v97 offset0:24 offset1:90
	ds_write2_b32 v74, v98, v99 offset0:156 offset1:222
	v_add_u32_e32 v74, 0x1000, v62
	ds_write2_b32 v74, v100, v101 offset0:32 offset1:98
	ds_write2_b32 v74, v102, v103 offset0:164 offset1:230
	v_add_u32_e32 v74, 0x1400, v62
	ds_write2_b32 v74, v104, v105 offset0:40 offset1:106
	ds_write2_b32 v74, v106, v107 offset0:172 offset1:238
	v_add_u32_e32 v74, 0x1800, v62
	ds_write2_b32 v74, v4, v26 offset0:48 offset1:114
	ds_write2_b32 v74, v27, v69 offset0:180 offset1:246
	v_add_u32_e32 v4, 0x1c00, v62
	ds_write2_b32 v4, v70, v71 offset0:56 offset1:122
	ds_write2_b32 v4, v72, v73 offset0:188 offset1:254
	s_waitcnt lgkmcnt(0)
	ds_read2_b32 v[26:27], v63 offset1:33
	s_waitcnt lgkmcnt(0)
	s_nop 1
	v_cvt_pk_bf16_f32 v70, v26, v27
	ds_read2_b32 v[26:27], v63 offset0:66 offset1:99
	s_waitcnt lgkmcnt(0)
	s_nop 1
	v_cvt_pk_bf16_f32 v71, v26, v27
	ds_read2_b32 v[26:27], v63 offset0:132 offset1:165
	v_or_b32_e32 v4, s79, v29
	s_waitcnt lgkmcnt(0)
	s_nop 1
	v_cvt_pk_bf16_f32 v72, v26, v27
	ds_read2_b32 v[26:27], v63 offset0:198 offset1:231
	v_lshl_add_u64 v[74:75], v[14:15], 0, s[10:11]
	v_lshlrev_b32_e32 v4, 12, v4
	s_waitcnt lgkmcnt(0)
	s_nop 1
	v_cvt_pk_bf16_f32 v73, v26, v27
	v_lshl_add_u64 v[26:27], v[74:75], 0, v[4:5]
	flat_store_dwordx4 v[26:27], v[70:73]
	ds_read2_b32 v[26:27], v63 offset0:8 offset1:41
	v_or_b32_e32 v4, s79, v64
	s_waitcnt lgkmcnt(0)
	s_nop 1
	v_cvt_pk_bf16_f32 v70, v26, v27
	ds_read2_b32 v[26:27], v63 offset0:74 offset1:107
	s_waitcnt lgkmcnt(0)
	s_nop 1
	v_cvt_pk_bf16_f32 v71, v26, v27
	ds_read2_b32 v[26:27], v63 offset0:140 offset1:173
	s_waitcnt lgkmcnt(0)
	s_nop 1
	v_cvt_pk_bf16_f32 v72, v26, v27
	ds_read2_b32 v[26:27], v63 offset0:206 offset1:239
	v_lshlrev_b32_e32 v4, 12, v4
	s_waitcnt lgkmcnt(0)
	s_nop 1
	v_cvt_pk_bf16_f32 v73, v26, v27
	v_lshl_add_u64 v[26:27], v[74:75], 0, v[4:5]
	flat_store_dwordx4 v[26:27], v[70:73]
	ds_read2_b32 v[26:27], v63 offset0:16 offset1:49
	v_or_b32_e32 v4, s79, v65
	s_waitcnt lgkmcnt(0)
	s_nop 1
	v_cvt_pk_bf16_f32 v70, v26, v27
	ds_read2_b32 v[26:27], v63 offset0:82 offset1:115
	s_waitcnt lgkmcnt(0)
	s_nop 1
	v_cvt_pk_bf16_f32 v71, v26, v27
	ds_read2_b32 v[26:27], v63 offset0:148 offset1:181
	s_waitcnt lgkmcnt(0)
	s_nop 1
	v_cvt_pk_bf16_f32 v72, v26, v27
	ds_read2_b32 v[26:27], v63 offset0:214 offset1:247
	v_lshlrev_b32_e32 v4, 12, v4
	s_waitcnt lgkmcnt(0)
	s_nop 1
	v_cvt_pk_bf16_f32 v73, v26, v27
	v_lshl_add_u64 v[26:27], v[74:75], 0, v[4:5]
	flat_store_dwordx4 v[26:27], v[70:73]
	ds_read2_b32 v[26:27], v63 offset0:24 offset1:57
	v_or_b32_e32 v4, s79, v66
	s_waitcnt lgkmcnt(0)
	s_nop 1
	v_cvt_pk_bf16_f32 v70, v26, v27
	ds_read2_b32 v[26:27], v63 offset0:90 offset1:123
	s_waitcnt lgkmcnt(0)
	s_nop 1
	v_cvt_pk_bf16_f32 v71, v26, v27
	ds_read2_b32 v[26:27], v63 offset0:156 offset1:189
	s_waitcnt lgkmcnt(0)
	s_nop 1
	v_cvt_pk_bf16_f32 v72, v26, v27
	ds_read2_b32 v[26:27], v63 offset0:222 offset1:255
	v_lshlrev_b32_e32 v4, 12, v4
	s_waitcnt lgkmcnt(0)
	s_nop 1
	v_cvt_pk_bf16_f32 v73, v26, v27
	v_lshl_add_u64 v[26:27], v[74:75], 0, v[4:5]
	flat_store_dwordx4 v[26:27], v[70:73]
	s_waitcnt lgkmcnt(0)

; __device__ __forceinline__ int map_gu(int j) { return ((j >> 7) & 1) * FF + ((j >> 8) << 7) + (j & 127); }
; template <int MAP>
; __device__ __forceinline__ void p0_transpose_item(const float* W, int K, int Nsrc, int rows, bf16_t* WT, LAS float* scr, int item, int lane) {
;     const int nblk = rows / 32, kb = item / nblk, nb = item % nblk, k0 = 64 * kb, n0 = 32 * nb;
;     const int j = n0 + (lane & 31);
;     const int sc = MAP == 0 ? j : (MAP == 1 ? map_gu(j) : map_in(j));
;     float tv[32];
; #pragma unroll
;     for (int i = 0; i < 32; ++i) tv[i] = W[(size_t)(k0 + 2 * i + (lane >> 5)) * Nsrc + sc];
; #pragma unroll
;     for (int i = 0; i < 32; ++i) scr[(2 * i + (lane >> 5)) * 33 + (lane & 31)] = tv[i];
.LBB0_31:
	s_andn2_b64 vcc, exec, s[12:13]
	s_cbranch_vccnz .LBB0_33
	v_mov_b32_e32 v4, s30
	ds_read_b32 v4, v4
	v_mov_b32_e32 v26, s31
	ds_read_b32 v26, v26
	s_add_i32 s10, s78, 0xffff4e00
	s_and_b32 s10, s10, 0x1fc0
	s_waitcnt lgkmcnt(0)
	v_readfirstlane_b32 s12, v4
	s_add_i32 s79, s16, 0xffe9c000
	v_or_b32_e32 v4, s10, v30
	s_and_b32 s79, s79, 0x7e0
	v_lshlrev_b32_e32 v69, 11, v4
	v_or3_b32 v4, s79, v3, v69
	v_readfirstlane_b32 s13, v26
	v_lshlrev_b32_e32 v4, 2, v4
	s_lshl_b32 s10, s10, 1
	v_lshl_add_u64 v[26:27], s[12:13], 0, v[4:5]
	v_or3_b32 v4, s79, v31, v69
	v_lshlrev_b32_e32 v4, 2, v4
	v_lshl_add_u64 v[70:71], s[12:13], 0, v[4:5]
	v_or3_b32 v4, s79, v32, v69
	v_lshlrev_b32_e32 v4, 2, v4
	v_lshl_add_u64 v[72:73], s[12:13], 0, v[4:5]
	v_or3_b32 v4, s79, v33, v69
	v_lshlrev_b32_e32 v4, 2, v4
	v_lshl_add_u64 v[74:75], s[12:13], 0, v[4:5]
	v_or3_b32 v4, s79, v34, v69
	v_lshlrev_b32_e32 v4, 2, v4
	v_lshl_add_u64 v[76:77], s[12:13], 0, v[4:5]
	v_or3_b32 v4, s79, v35, v69
	v_lshlrev_b32_e32 v4, 2, v4
	v_lshl_add_u64 v[78:79], s[12:13], 0, v[4:5]
	v_or3_b32 v4, s79, v36, v69
	v_lshlrev_b32_e32 v4, 2, v4
	v_lshl_add_u64 v[80:81], s[12:13], 0, v[4:5]
	v_or3_b32 v4, s79, v37, v69
	v_lshlrev_b32_e32 v4, 2, v4
	v_lshl_add_u64 v[82:83], s[12:13], 0, v[4:5]
	v_or3_b32 v4, s79, v38, v69
	v_lshlrev_b32_e32 v4, 2, v4
	flat_load_dword v84, v[26:27] nt
	flat_load_dword v85, v[70:71] nt
	flat_load_dword v86, v[72:73] nt
	flat_load_dword v87, v[74:75] nt
	flat_load_dword v88, v[76:77] nt
	flat_load_dword v89, v[78:79] nt
	flat_load_dword v90, v[80:81] nt
	flat_load_dword v91, v[82:83] nt
	v_lshl_add_u64 v[26:27], s[12:13], 0, v[4:5]
	v_or3_b32 v4, s79, v39, v69
	v_lshlrev_b32_e32 v4, 2, v4
	v_lshl_add_u64 v[70:71], s[12:13], 0, v[4:5]
	v_or3_b32 v4, s79, v40, v69
	v_lshlrev_b32_e32 v4, 2, v4
	v_lshl_add_u64 v[72:73], s[12:13], 0, v[4:5]
	v_or3_b32 v4, s79, v41, v69
	v_lshlrev_b32_e32 v4, 2, v4
	v_lshl_add_u64 v[74:75], s[12:13], 0, v[4:5]
	v_or3_b32 v4, s79, v42, v69
	v_lshlrev_b32_e32 v4, 2, v4
	v_lshl_add_u64 v[76:77], s[12:13], 0, v[4:5]
	v_or3_b32 v4, s79, v43, v69
	v_lshlrev_b32_e32 v4, 2, v4
	v_lshl_add_u64 v[78:79], s[12:13], 0, v[4:5]
	v_or3_b32 v4, s79, v44, v69
	v_lshlrev_b32_e32 v4, 2, v4
	v_lshl_add_u64 v[80:81], s[12:13], 0, v[4:5]
	v_or3_b32 v4, s79, v45, v69
	v_lshlrev_b32_e32 v4, 2, v4
	v_lshl_add_u64 v[82:83], s[12:13], 0, v[4:5]
	v_or3_b32 v4, s79, v46, v69
	v_lshlrev_b32_e32 v4, 2, v4
	flat_load_dword v92, v[26:27] nt
	flat_load_dword v93, v[70:71] nt
	flat_load_dword v94, v[72:73] nt
	flat_load_dword v95, v[74:75] nt
	flat_load_dword v96, v[76:77] nt
	flat_load_dword v97, v[78:79] nt
	flat_load_dword v98, v[80:81] nt
	flat_load_dword v99, v[82:83] nt
	v_lshl_add_u64 v[26:27], s[12:13], 0, v[4:5]
	v_or3_b32 v4, s79, v47, v69
	v_lshlrev_b32_e32 v4, 2, v4
	v_lshl_add_u64 v[70:71], s[12:13], 0, v[4:5]
	v_or3_b32 v4, s79, v48, v69
	v_lshlrev_b32_e32 v4, 2, v4
	v_lshl_add_u64 v[72:73], s[12:13], 0, v[4:5]
	v_or3_b32 v4, s79, v49, v69
	v_lshlrev_b32_e32 v4, 2, v4
	v_lshl_add_u64 v[74:75], s[12:13], 0, v[4:5]
	v_or3_b32 v4, s79, v50, v69
	v_lshlrev_b32_e32 v4, 2, v4
	v_lshl_add_u64 v[76:77], s[12:13], 0, v[4:5]
	v_or3_b32 v4, s79, v51, v69
	v_lshlrev_b32_e32 v4, 2, v4
	v_lshl_add_u64 v[78:79], s[12:13], 0, v[4:5]
	v_or3_b32 v4, s79, v52, v69
	v_lshlrev_b32_e32 v4, 2, v4
	v_lshl_add_u64 v[80:81], s[12:13], 0, v[4:5]
	v_or3_b32 v4, s79, v53, v69
	v_lshlrev_b32_e32 v4, 2, v4
	v_lshl_add_u64 v[82:83], s[12:13], 0, v[4:5]
	v_or3_b32 v4, s79, v54, v69
	v_lshlrev_b32_e32 v4, 2, v4
	flat_load_dword v100, v[26:27] nt
	flat_load_dword v101, v[70:71] nt
	flat_load_dword v102, v[72:73] nt
	flat_load_dword v103, v[74:75] nt
	flat_load_dword v104, v[76:77] nt
	flat_load_dword v105, v[78:79] nt
	flat_load_dword v106, v[80:81] nt
	flat_load_dword v107, v[82:83] nt
	v_lshl_add_u64 v[26:27], s[12:13], 0, v[4:5]
	v_or3_b32 v4, s79, v55, v69
	v_lshlrev_b32_e32 v4, 2, v4
	v_lshl_add_u64 v[70:71], s[12:13], 0, v[4:5]
	v_or3_b32 v4, s79, v56, v69
	v_lshlrev_b32_e32 v4, 2, v4
	v_lshl_add_u64 v[72:73], s[12:13], 0, v[4:5]
	v_or3_b32 v4, s79, v57, v69
	v_lshlrev_b32_e32 v4, 2, v4
	v_lshl_add_u64 v[74:75], s[12:13], 0, v[4:5]
	v_or3_b32 v4, s79, v58, v69
	v_lshlrev_b32_e32 v4, 2, v4
	v_lshl_add_u64 v[76:77], s[12:13], 0, v[4:5]
	v_or3_b32 v4, s79, v59, v69
	v_lshlrev_b32_e32 v4, 2, v4
	v_lshl_add_u64 v[78:79], s[12:13], 0, v[4:5]
	v_or3_b32 v4, s79, v60, v69
	v_lshlrev_b32_e32 v4, 2, v4
	v_lshl_add_u64 v[80:81], s[12:13], 0, v[4:5]
	v_or3_b32 v4, s79, v61, v69
	v_lshlrev_b32_e32 v4, 2, v4
	v_lshl_add_u64 v[82:83], s[12:13], 0, v[4:5]
	flat_load_dword v4, v[26:27] nt
	s_nop 0
	flat_load_dword v26, v[70:71] nt
	flat_load_dword v27, v[72:73] nt
	flat_load_dword v69, v[74:75] nt
	s_nop 0
	flat_load_dword v70, v[76:77] nt
	flat_load_dword v71, v[78:79] nt
	flat_load_dword v72, v[80:81] nt
	flat_load_dword v73, v[82:83] nt
	v_add_u32_e32 v74, 0x400, v62
	s_waitcnt vmcnt(0) lgkmcnt(0)
; #define LAS __attribute__((address_space(3)))
; __device__ __forceinline__ unsigned cvt_pk_bf16(float lo, float hi) { unsigned r; asm volatile("s_nop 1\n\tv_cvt_pk_bf16_f32 %0, %1, %2" : "=v"(r) : "v"(lo), "v"(hi)); return r; }
; template <int MAP>
; __device__ __forceinline__ void p0_transpose_item(const float* W, int K, int Nsrc, int rows, bf16_t* WT, LAS float* scr, int item, int lane) {
;     ...
;     for (int i = 0; i < 32; ++i) scr[(2 * i + (lane >> 5)) * 33 + (lane & 31)] = tv[i];
;     asm volatile("s_waitcnt lgkmcnt(0)" ::: "memory");
;     const int c = lane & 7;
; #pragma unroll
;     for (int jj = 0; jj < 4; ++jj) { const int n = (lane >> 3) + 8 * jj; const LAS float* s = scr + (8 * c) * 33 + n;
;         u32x4 o; o.x = cvt_pk_bf16(s[0 * 33], s[1 * 33]); o.y = cvt_pk_bf16(s[2 * 33], s[3 * 33]); o.z = cvt_pk_bf16(s[4 * 33], s[5 * 33]); o.w = cvt_pk_bf16(s[6 * 33], s[7 * 33]);
;         *(u32x4*)(WT + (size_t)(n0 + n) * K + k0 + 8 * c) = o; }
;     asm volatile("s_waitcnt lgkmcnt(0)" ::: "memory");
	ds_write2_b32 v62, v84, v85 offset1:66
	ds_write2_b32 v62, v86, v87 offset0:132 offset1:198
	ds_write2_b32 v74, v88, v89 offset0:8 offset1:74
	ds_write2_b32 v74, v90, v91 offset0:140 offset1:206
	v_add_u32_e32 v74, 0x800, v62
	ds_write2_b32 v74, v92, v93 offset0:16 offset1:82
	ds_write2_b32 v74, v94, v95 offset0:148 offset1:214
	v_add_u32_e32 v74, 0xc00, v62
	ds_write2_b32 v74, v96, v97 offset0:24 offset1:90
	ds_write2_b32 v74, v98, v99 offset0:156 offset1:222
	v_add_u32_e32 v74, 0x1000, v62
	ds_write2_b32 v74, v100, v101 offset0:32 offset1:98
	ds_write2_b32 v74, v102, v103 offset0:164 offset1:230
	v_add_u32_e32 v74, 0x1400, v62
	ds_write2_b32 v74, v104, v105 offset0:40 offset1:106
	ds_write2_b32 v74, v106, v107 offset0:172 offset1:238
	v_add_u32_e32 v74, 0x1800, v62
	ds_write2_b32 v74, v4, v26 offset0:48 offset1:114
	ds_write2_b32 v74, v27, v69 offset0:180 offset1:246
	v_add_u32_e32 v4, 0x1c00, v62
	ds_write2_b32 v4, v70, v71 offset0:56 offset1:122
	ds_write2_b32 v4, v72, v73 offset0:188 offset1:254
	s_waitcnt lgkmcnt(0)
	ds_read2_b32 v[26:27], v63 offset1:33
	s_waitcnt lgkmcnt(0)
	s_nop 1
	v_cvt_pk_bf16_f32 v70, v26, v27
	ds_read2_b32 v[26:27], v63 offset0:66 offset1:99
	s_waitcnt lgkmcnt(0)
	s_nop 1
	v_cvt_pk_bf16_f32 v71, v26, v27
	ds_read2_b32 v[26:27], v63 offset0:132 offset1:165
	v_or_b32_e32 v4, s79, v29
	s_waitcnt lgkmcnt(0)
	s_nop 1
	v_cvt_pk_bf16_f32 v72, v26, v27
	ds_read2_b32 v[26:27], v63 offset0:198 offset1:231
	v_lshl_add_u64 v[74:75], v[16:17], 0, s[10:11]
	v_lshlrev_b32_e32 v4, 12, v4
	s_waitcnt lgkmcnt(0)
	s_nop 1
	v_cvt_pk_bf16_f32 v73, v26, v27
	v_lshl_add_u64 v[26:27], v[74:75], 0, v[4:5]
	flat_store_dwordx4 v[26:27], v[70:73]
	ds_read2_b32 v[26:27], v63 offset0:8 offset1:41
	v_or_b32_e32 v4, s79, v64
	s_waitcnt lgkmcnt(0)
	s_nop 1
	v_cvt_pk_bf16_f32 v70, v26, v27
	ds_read2_b32 v[26:27], v63 offset0:74 offset1:107
	s_waitcnt lgkmcnt(0)
	s_nop 1
	v_cvt_pk_bf16_f32 v71, v26, v27
	ds_read2_b32 v[26:27], v63 offset0:140 offset1:173
	s_waitcnt lgkmcnt(0)
	s_nop 1
	v_cvt_pk_bf16_f32 v72, v26, v27
	ds_read2_b32 v[26:27], v63 offset0:206 offset1:239
	v_lshlrev_b32_e32 v4, 12, v4
	s_waitcnt lgkmcnt(0)
	s_nop 1
	v_cvt_pk_bf16_f32 v73, v26, v27
	v_lshl_add_u64 v[26:27], v[74:75], 0, v[4:5]
	flat_store_dwordx4 v[26:27], v[70:73]
	ds_read2_b32 v[26:27], v63 offset0:16 offset1:49
	v_or_b32_e32 v4, s79, v65
	s_waitcnt lgkmcnt(0)
	s_nop 1
	v_cvt_pk_bf16_f32 v70, v26, v27
	ds_read2_b32 v[26:27], v63 offset0:82 offset1:115
	s_waitcnt lgkmcnt(0)
	s_nop 1
	v_cvt_pk_bf16_f32 v71, v26, v27
	ds_read2_b32 v[26:27], v63 offset0:148 offset1:181
	s_waitcnt lgkmcnt(0)
	s_nop 1
	v_cvt_pk_bf16_f32 v72, v26, v27
	ds_read2_b32 v[26:27], v63 offset0:214 offset1:247
	v_lshlrev_b32_e32 v4, 12, v4
	s_waitcnt lgkmcnt(0)
	s_nop 1
	v_cvt_pk_bf16_f32 v73, v26, v27
	v_lshl_add_u64 v[26:27], v[74:75], 0, v[4:5]
	flat_store_dwordx4 v[26:27], v[70:73]
	ds_read2_b32 v[26:27], v63 offset0:24 offset1:57
	v_or_b32_e32 v4, s79, v66
	s_waitcnt lgkmcnt(0)
	s_nop 1
	v_cvt_pk_bf16_f32 v70, v26, v27
	ds_read2_b32 v[26:27], v63 offset0:90 offset1:123
	s_waitcnt lgkmcnt(0)
	s_nop 1
	v_cvt_pk_bf16_f32 v71, v26, v27
	ds_read2_b32 v[26:27], v63 offset0:156 offset1:189
	s_waitcnt lgkmcnt(0)
	s_nop 1
	v_cvt_pk_bf16_f32 v72, v26, v27
	ds_read2_b32 v[26:27], v63 offset0:222 offset1:255
	v_lshlrev_b32_e32 v4, 12, v4
	s_waitcnt lgkmcnt(0)
	s_nop 1
	v_cvt_pk_bf16_f32 v73, v26, v27
	v_lshl_add_u64 v[26:27], v[74:75], 0, v[4:5]
	flat_store_dwordx4 v[26:27], v[70:73]
	s_waitcnt lgkmcnt(0)

; __device__ __forceinline__ int map_gu(int j) { return ((j >> 7) & 1) * FF + ((j >> 8) << 7) + (j & 127); }
; template <int MAP>
; __device__ __forceinline__ void p0_transpose_item(const float* W, int K, int Nsrc, int rows, bf16_t* WT, LAS float* scr, int item, int lane) {
;     const int nblk = rows / 32, kb = item / nblk, nb = item % nblk, k0 = 64 * kb, n0 = 32 * nb;
;     const int j = n0 + (lane & 31);
;     const int sc = MAP == 0 ? j : (MAP == 1 ? map_gu(j) : map_in(j));
;     float tv[32];
; #pragma unroll
;     for (int i = 0; i < 32; ++i) tv[i] = W[(size_t)(k0 + 2 * i + (lane >> 5)) * Nsrc + sc];
; #pragma unroll
;     for (int i = 0; i < 32; ++i) scr[(2 * i + (lane >> 5)) * 33 + (lane & 31)] = tv[i];
.LBB0_34:
	s_andn2_b64 vcc, exec, s[12:13]
	s_cbranch_vccnz .LBB0_36
	v_mov_b32_e32 v4, s34
	ds_read_b32 v4, v4
	v_mov_b32_e32 v26, s35
	ds_read_b32 v26, v26
	s_add_i32 s10, s78, 0xffff6400
	s_and_b32 s10, s10, 0x1fc0
	s_waitcnt lgkmcnt(0)
	v_readfirstlane_b32 s12, v4
	s_add_i32 s79, s16, 0xffec8000
	v_or_b32_e32 v4, s10, v30
	s_and_b32 s79, s79, 0x7e0
	v_lshlrev_b32_e32 v69, 11, v4
	v_or3_b32 v4, s79, v3, v69
	v_readfirstlane_b32 s13, v26
	v_lshlrev_b32_e32 v4, 2, v4
	s_lshl_b32 s10, s10, 1
	v_lshl_add_u64 v[26:27], s[12:13], 0, v[4:5]
	v_or3_b32 v4, s79, v31, v69
	v_lshlrev_b32_e32 v4, 2, v4
	v_lshl_add_u64 v[70:71], s[12:13], 0, v[4:5]
	v_or3_b32 v4, s79, v32, v69
	v_lshlrev_b32_e32 v4, 2, v4
	v_lshl_add_u64 v[72:73], s[12:13], 0, v[4:5]
	v_or3_b32 v4, s79, v33, v69
	v_lshlrev_b32_e32 v4, 2, v4
	v_lshl_add_u64 v[74:75], s[12:13], 0, v[4:5]
	v_or3_b32 v4, s79, v34, v69
	v_lshlrev_b32_e32 v4, 2, v4
	v_lshl_add_u64 v[76:77], s[12:13], 0, v[4:5]
	v_or3_b32 v4, s79, v35, v69
	v_lshlrev_b32_e32 v4, 2, v4
	v_lshl_add_u64 v[78:79], s[12:13], 0, v[4:5]
	v_or3_b32 v4, s79, v36, v69
	v_lshlrev_b32_e32 v4, 2, v4
	v_lshl_add_u64 v[80:81], s[12:13], 0, v[4:5]
	v_or3_b32 v4, s79, v37, v69
	v_lshlrev_b32_e32 v4, 2, v4
	v_lshl_add_u64 v[82:83], s[12:13], 0, v[4:5]
	v_or3_b32 v4, s79, v38, v69
	v_lshlrev_b32_e32 v4, 2, v4
	flat_load_dword v84, v[26:27] nt
	flat_load_dword v85, v[70:71] nt
	flat_load_dword v86, v[72:73] nt
	flat_load_dword v87, v[74:75] nt
	flat_load_dword v88, v[76:77] nt
	flat_load_dword v89, v[78:79] nt
	flat_load_dword v90, v[80:81] nt
	flat_load_dword v91, v[82:83] nt
	v_lshl_add_u64 v[26:27], s[12:13], 0, v[4:5]
	v_or3_b32 v4, s79, v39, v69
	v_lshlrev_b32_e32 v4, 2, v4
	v_lshl_add_u64 v[70:71], s[12:13], 0, v[4:5]
	v_or3_b32 v4, s79, v40, v69
	v_lshlrev_b32_e32 v4, 2, v4
	v_lshl_add_u64 v[72:73], s[12:13], 0, v[4:5]
	v_or3_b32 v4, s79, v41, v69
	v_lshlrev_b32_e32 v4, 2, v4
	v_lshl_add_u64 v[74:75], s[12:13], 0, v[4:5]
	v_or3_b32 v4, s79, v42, v69
	v_lshlrev_b32_e32 v4, 2, v4
	v_lshl_add_u64 v[76:77], s[12:13], 0, v[4:5]
	v_or3_b32 v4, s79, v43, v69
	v_lshlrev_b32_e32 v4, 2, v4
	v_lshl_add_u64 v[78:79], s[12:13], 0, v[4:5]
	v_or3_b32 v4, s79, v44, v69
	v_lshlrev_b32_e32 v4, 2, v4
	v_lshl_add_u64 v[80:81], s[12:13], 0, v[4:5]
	v_or3_b32 v4, s79, v45, v69
	v_lshlrev_b32_e32 v4, 2, v4
	v_lshl_add_u64 v[82:83], s[12:13], 0, v[4:5]
	v_or3_b32 v4, s79, v46, v69
	v_lshlrev_b32_e32 v4, 2, v4
	flat_load_dword v92, v[26:27] nt
	flat_load_dword v93, v[70:71] nt
	flat_load_dword v94, v[72:73] nt
	flat_load_dword v95, v[74:75] nt
	flat_load_dword v96, v[76:77] nt
	flat_load_dword v97, v[78:79] nt
	flat_load_dword v98, v[80:81] nt
	flat_load_dword v99, v[82:83] nt
	v_lshl_add_u64 v[26:27], s[12:13], 0, v[4:5]
	v_or3_b32 v4, s79, v47, v69
	v_lshlrev_b32_e32 v4, 2, v4
	v_lshl_add_u64 v[70:71], s[12:13], 0, v[4:5]
	v_or3_b32 v4, s79, v48, v69
	v_lshlrev_b32_e32 v4, 2, v4
	v_lshl_add_u64 v[72:73], s[12:13], 0, v[4:5]
	v_or3_b32 v4, s79, v49, v69
	v_lshlrev_b32_e32 v4, 2, v4
	v_lshl_add_u64 v[74:75], s[12:13], 0, v[4:5]
	v_or3_b32 v4, s79, v50, v69
	v_lshlrev_b32_e32 v4, 2, v4
	v_lshl_add_u64 v[76:77], s[12:13], 0, v[4:5]
	v_or3_b32 v4, s79, v51, v69
	v_lshlrev_b32_e32 v4, 2, v4
	v_lshl_add_u64 v[78:79], s[12:13], 0, v[4:5]
	v_or3_b32 v4, s79, v52, v69
	v_lshlrev_b32_e32 v4, 2, v4
	v_lshl_add_u64 v[80:81], s[12:13], 0, v[4:5]
	v_or3_b32 v4, s79, v53, v69
	v_lshlrev_b32_e32 v4, 2, v4
	v_lshl_add_u64 v[82:83], s[12:13], 0, v[4:5]
	v_or3_b32 v4, s79, v54, v69
	v_lshlrev_b32_e32 v4, 2, v4
	flat_load_dword v100, v[26:27] nt
	flat_load_dword v101, v[70:71] nt
	flat_load_dword v102, v[72:73] nt
	flat_load_dword v103, v[74:75] nt
	flat_load_dword v104, v[76:77] nt
	flat_load_dword v105, v[78:79] nt
	flat_load_dword v106, v[80:81] nt
	flat_load_dword v107, v[82:83] nt
	v_lshl_add_u64 v[26:27], s[12:13], 0, v[4:5]
	v_or3_b32 v4, s79, v55, v69
	v_lshlrev_b32_e32 v4, 2, v4
	v_lshl_add_u64 v[70:71], s[12:13], 0, v[4:5]
	v_or3_b32 v4, s79, v56, v69
	v_lshlrev_b32_e32 v4, 2, v4
	v_lshl_add_u64 v[72:73], s[12:13], 0, v[4:5]
	v_or3_b32 v4, s79, v57, v69
	v_lshlrev_b32_e32 v4, 2, v4
	v_lshl_add_u64 v[74:75], s[12:13], 0, v[4:5]
	v_or3_b32 v4, s79, v58, v69
	v_lshlrev_b32_e32 v4, 2, v4
	v_lshl_add_u64 v[76:77], s[12:13], 0, v[4:5]
	v_or3_b32 v4, s79, v59, v69
	v_lshlrev_b32_e32 v4, 2, v4
	v_lshl_add_u64 v[78:79], s[12:13], 0, v[4:5]
	v_or3_b32 v4, s79, v60, v69
	v_lshlrev_b32_e32 v4, 2, v4
	v_lshl_add_u64 v[80:81], s[12:13], 0, v[4:5]
	v_or3_b32 v4, s79, v61, v69
	v_lshlrev_b32_e32 v4, 2, v4
	v_lshl_add_u64 v[82:83], s[12:13], 0, v[4:5]
	flat_load_dword v4, v[26:27] nt
	s_nop 0
	flat_load_dword v26, v[70:71] nt
	flat_load_dword v27, v[72:73] nt
	flat_load_dword v69, v[74:75] nt
	s_nop 0
	flat_load_dword v70, v[76:77] nt
	flat_load_dword v71, v[78:79] nt
	flat_load_dword v72, v[80:81] nt
	flat_load_dword v73, v[82:83] nt
	v_add_u32_e32 v74, 0x400, v62
	s_waitcnt vmcnt(0) lgkmcnt(0)
; #define LAS __attribute__((address_space(3)))
; __device__ __forceinline__ unsigned cvt_pk_bf16(float lo, float hi) { unsigned r; asm volatile("s_nop 1\n\tv_cvt_pk_bf16_f32 %0, %1, %2" : "=v"(r) : "v"(lo), "v"(hi)); return r; }
; template <int MAP>
; __device__ __forceinline__ void p0_transpose_item(const float* W, int K, int Nsrc, int rows, bf16_t* WT, LAS float* scr, int item, int lane) {
;     ...
;     for (int i = 0; i < 32; ++i) scr[(2 * i + (lane >> 5)) * 33 + (lane & 31)] = tv[i];
;     asm volatile("s_waitcnt lgkmcnt(0)" ::: "memory");
;     const int c = lane & 7;
; #pragma unroll
;     for (int jj = 0; jj < 4; ++jj) { const int n = (lane >> 3) + 8 * jj; const LAS float* s = scr + (8 * c) * 33 + n;
;         u32x4 o; o.x = cvt_pk_bf16(s[0 * 33], s[1 * 33]); o.y = cvt_pk_bf16(s[2 * 33], s[3 * 33]); o.z = cvt_pk_bf16(s[4 * 33], s[5 * 33]); o.w = cvt_pk_bf16(s[6 * 33], s[7 * 33]);
;         *(u32x4*)(WT + (size_t)(n0 + n) * K + k0 + 8 * c) = o; }
;     asm volatile("s_waitcnt lgkmcnt(0)" ::: "memory");
	ds_write2_b32 v62, v84, v85 offset1:66
	ds_write2_b32 v62, v86, v87 offset0:132 offset1:198
	ds_write2_b32 v74, v88, v89 offset0:8 offset1:74
	ds_write2_b32 v74, v90, v91 offset0:140 offset1:206
	v_add_u32_e32 v74, 0x800, v62
	ds_write2_b32 v74, v92, v93 offset0:16 offset1:82
	ds_write2_b32 v74, v94, v95 offset0:148 offset1:214
	v_add_u32_e32 v74, 0xc00, v62
	ds_write2_b32 v74, v96, v97 offset0:24 offset1:90
	ds_write2_b32 v74, v98, v99 offset0:156 offset1:222
	v_add_u32_e32 v74, 0x1000, v62
	ds_write2_b32 v74, v100, v101 offset0:32 offset1:98
	ds_write2_b32 v74, v102, v103 offset0:164 offset1:230
	v_add_u32_e32 v74, 0x1400, v62
	ds_write2_b32 v74, v104, v105 offset0:40 offset1:106
	ds_write2_b32 v74, v106, v107 offset0:172 offset1:238
	v_add_u32_e32 v74, 0x1800, v62
	ds_write2_b32 v74, v4, v26 offset0:48 offset1:114
	ds_write2_b32 v74, v27, v69 offset0:180 offset1:246
	v_add_u32_e32 v4, 0x1c00, v62
	ds_write2_b32 v4, v70, v71 offset0:56 offset1:122
	ds_write2_b32 v4, v72, v73 offset0:188 offset1:254
	s_waitcnt lgkmcnt(0)
	ds_read2_b32 v[26:27], v63 offset1:33
	s_waitcnt lgkmcnt(0)
	s_nop 1
	v_cvt_pk_bf16_f32 v70, v26, v27
	ds_read2_b32 v[26:27], v63 offset0:66 offset1:99
	v_or_b32_e32 v4, s79, v29
	s_waitcnt lgkmcnt(0)
	s_nop 1
	v_cvt_pk_bf16_f32 v71, v26, v27
	ds_read2_b32 v[26:27], v63 offset0:132 offset1:165
	v_mul_u32_u24_e32 v4, 0x1600, v4
	s_waitcnt lgkmcnt(0)
	s_nop 1
	v_cvt_pk_bf16_f32 v72, v26, v27
	ds_read2_b32 v[26:27], v63 offset0:198 offset1:231
	v_lshl_add_u64 v[74:75], v[18:19], 0, s[10:11]
	v_lshlrev_b32_e32 v4, 1, v4
	s_waitcnt lgkmcnt(0)
	s_nop 1
	v_cvt_pk_bf16_f32 v73, v26, v27
	v_lshl_add_u64 v[26:27], v[74:75], 0, v[4:5]
	flat_store_dwordx4 v[26:27], v[70:73]
	ds_read2_b32 v[26:27], v63 offset0:8 offset1:41
	v_or_b32_e32 v4, s79, v64
	s_waitcnt lgkmcnt(0)
	s_nop 1
	v_cvt_pk_bf16_f32 v70, v26, v27
	ds_read2_b32 v[26:27], v63 offset0:74 offset1:107
	s_waitcnt lgkmcnt(0)
	s_nop 1
	v_cvt_pk_bf16_f32 v71, v26, v27
	ds_read2_b32 v[26:27], v63 offset0:140 offset1:173
	v_mul_u32_u24_e32 v4, 0x1600, v4
	s_waitcnt lgkmcnt(0)
	s_nop 1
	v_cvt_pk_bf16_f32 v72, v26, v27
	ds_read2_b32 v[26:27], v63 offset0:206 offset1:239
	v_lshlrev_b32_e32 v4, 1, v4
	s_waitcnt lgkmcnt(0)
	s_nop 1
	v_cvt_pk_bf16_f32 v73, v26, v27
	v_lshl_add_u64 v[26:27], v[74:75], 0, v[4:5]
	flat_store_dwordx4 v[26:27], v[70:73]
	ds_read2_b32 v[26:27], v63 offset0:16 offset1:49
	v_or_b32_e32 v4, s79, v65
	s_waitcnt lgkmcnt(0)
	s_nop 1
	v_cvt_pk_bf16_f32 v70, v26, v27
	ds_read2_b32 v[26:27], v63 offset0:82 offset1:115
	s_waitcnt lgkmcnt(0)
	s_nop 1
	v_cvt_pk_bf16_f32 v71, v26, v27
	ds_read2_b32 v[26:27], v63 offset0:148 offset1:181
	v_mul_u32_u24_e32 v4, 0x1600, v4
	s_waitcnt lgkmcnt(0)
	s_nop 1
	v_cvt_pk_bf16_f32 v72, v26, v27
	ds_read2_b32 v[26:27], v63 offset0:214 offset1:247
	v_lshlrev_b32_e32 v4, 1, v4
	s_waitcnt lgkmcnt(0)
	s_nop 1
	v_cvt_pk_bf16_f32 v73, v26, v27
	v_lshl_add_u64 v[26:27], v[74:75], 0, v[4:5]
	flat_store_dwordx4 v[26:27], v[70:73]
	ds_read2_b32 v[26:27], v63 offset0:24 offset1:57
	v_or_b32_e32 v4, s79, v66
	s_waitcnt lgkmcnt(0)
	s_nop 1
	v_cvt_pk_bf16_f32 v70, v26, v27
	ds_read2_b32 v[26:27], v63 offset0:90 offset1:123
	s_waitcnt lgkmcnt(0)
	s_nop 1
	v_cvt_pk_bf16_f32 v71, v26, v27
	ds_read2_b32 v[26:27], v63 offset0:156 offset1:189
	v_mul_u32_u24_e32 v4, 0x1600, v4
	s_waitcnt lgkmcnt(0)
	s_nop 1
	v_cvt_pk_bf16_f32 v72, v26, v27
	ds_read2_b32 v[26:27], v63 offset0:222 offset1:255
	v_lshlrev_b32_e32 v4, 1, v4
	s_waitcnt lgkmcnt(0)
	s_nop 1
	v_cvt_pk_bf16_f32 v73, v26, v27
	v_lshl_add_u64 v[26:27], v[74:75], 0, v[4:5]
	flat_store_dwordx4 v[26:27], v[70:73]
	s_waitcnt lgkmcnt(0)

; __device__ __forceinline__ int map_gu(int j) { return ((j >> 7) & 1) * FF + ((j >> 8) << 7) + (j & 127); }
; template <int MAP>
; __device__ __forceinline__ void p0_transpose_item(const float* W, int K, int Nsrc, int rows, bf16_t* WT, LAS float* scr, int item, int lane) {
;     const int nblk = rows / 32, kb = item / nblk, nb = item % nblk, k0 = 64 * kb, n0 = 32 * nb;
;     const int j = n0 + (lane & 31);
;     const int sc = MAP == 0 ? j : (MAP == 1 ? map_gu(j) : map_in(j));
;     float tv[32];
; #pragma unroll
;     for (int i = 0; i < 32; ++i) tv[i] = W[(size_t)(k0 + 2 * i + (lane >> 5)) * Nsrc + sc];
; #pragma unroll
;     for (int i = 0; i < 32; ++i) scr[(2 * i + (lane >> 5)) * 33 + (lane & 31)] = tv[i];
.LBB0_37:
	s_andn2_b64 vcc, exec, s[12:13]
	s_cbranch_vccnz .LBB0_39
	v_mov_b32_e32 v4, s36
	ds_read_b32 v4, v4
	v_mov_b32_e32 v26, s37
	ds_read_b32 v26, v26
	s_add_i32 s10, s78, 0xffff7a00
	s_and_b32 s10, s10, 0x1fc0
	s_waitcnt lgkmcnt(0)
	v_readfirstlane_b32 s12, v4
	s_add_i32 s79, s16, 0xffef4000
	v_or_b32_e32 v4, s10, v30
	s_and_b32 s79, s79, 0x7e0
	v_lshlrev_b32_e32 v69, 11, v4
	v_or3_b32 v4, s79, v3, v69
	v_readfirstlane_b32 s13, v26
	v_lshlrev_b32_e32 v4, 2, v4
	s_lshl_b32 s10, s10, 1
	v_lshl_add_u64 v[26:27], s[12:13], 0, v[4:5]
	v_or3_b32 v4, s79, v31, v69
	v_lshlrev_b32_e32 v4, 2, v4
	v_lshl_add_u64 v[70:71], s[12:13], 0, v[4:5]
	v_or3_b32 v4, s79, v32, v69
	v_lshlrev_b32_e32 v4, 2, v4
	v_lshl_add_u64 v[72:73], s[12:13], 0, v[4:5]
	v_or3_b32 v4, s79, v33, v69
	v_lshlrev_b32_e32 v4, 2, v4
	v_lshl_add_u64 v[74:75], s[12:13], 0, v[4:5]
	v_or3_b32 v4, s79, v34, v69
	v_lshlrev_b32_e32 v4, 2, v4
	v_lshl_add_u64 v[76:77], s[12:13], 0, v[4:5]
	v_or3_b32 v4, s79, v35, v69
	v_lshlrev_b32_e32 v4, 2, v4
	v_lshl_add_u64 v[78:79], s[12:13], 0, v[4:5]
	v_or3_b32 v4, s79, v36, v69
	v_lshlrev_b32_e32 v4, 2, v4
	v_lshl_add_u64 v[80:81], s[12:13], 0, v[4:5]
	v_or3_b32 v4, s79, v37, v69
	v_lshlrev_b32_e32 v4, 2, v4
	v_lshl_add_u64 v[82:83], s[12:13], 0, v[4:5]
	v_or3_b32 v4, s79, v38, v69
	v_lshlrev_b32_e32 v4, 2, v4
	flat_load_dword v84, v[26:27] nt
	flat_load_dword v85, v[70:71] nt
	flat_load_dword v86, v[72:73] nt
	flat_load_dword v87, v[74:75] nt
	flat_load_dword v88, v[76:77] nt
	flat_load_dword v89, v[78:79] nt
	flat_load_dword v90, v[80:81] nt
	flat_load_dword v91, v[82:83] nt
	v_lshl_add_u64 v[26:27], s[12:13], 0, v[4:5]
	v_or3_b32 v4, s79, v39, v69
	v_lshlrev_b32_e32 v4, 2, v4
	v_lshl_add_u64 v[70:71], s[12:13], 0, v[4:5]
	v_or3_b32 v4, s79, v40, v69
	v_lshlrev_b32_e32 v4, 2, v4
	v_lshl_add_u64 v[72:73], s[12:13], 0, v[4:5]
	v_or3_b32 v4, s79, v41, v69
	v_lshlrev_b32_e32 v4, 2, v4
	v_lshl_add_u64 v[74:75], s[12:13], 0, v[4:5]
	v_or3_b32 v4, s79, v42, v69
	v_lshlrev_b32_e32 v4, 2, v4
	v_lshl_add_u64 v[76:77], s[12:13], 0, v[4:5]
	v_or3_b32 v4, s79, v43, v69
	v_lshlrev_b32_e32 v4, 2, v4
	v_lshl_add_u64 v[78:79], s[12:13], 0, v[4:5]
	v_or3_b32 v4, s79, v44, v69
	v_lshlrev_b32_e32 v4, 2, v4
	v_lshl_add_u64 v[80:81], s[12:13], 0, v[4:5]
	v_or3_b32 v4, s79, v45, v69
	v_lshlrev_b32_e32 v4, 2, v4
	v_lshl_add_u64 v[82:83], s[12:13], 0, v[4:5]
	v_or3_b32 v4, s79, v46, v69
	v_lshlrev_b32_e32 v4, 2, v4
	flat_load_dword v92, v[26:27] nt
	flat_load_dword v93, v[70:71] nt
	flat_load_dword v94, v[72:73] nt
	flat_load_dword v95, v[74:75] nt
	flat_load_dword v96, v[76:77] nt
	flat_load_dword v97, v[78:79] nt
	flat_load_dword v98, v[80:81] nt
	flat_load_dword v99, v[82:83] nt
	v_lshl_add_u64 v[26:27], s[12:13], 0, v[4:5]
	v_or3_b32 v4, s79, v47, v69
	v_lshlrev_b32_e32 v4, 2, v4
	v_lshl_add_u64 v[70:71], s[12:13], 0, v[4:5]
	v_or3_b32 v4, s79, v48, v69
	v_lshlrev_b32_e32 v4, 2, v4
	v_lshl_add_u64 v[72:73], s[12:13], 0, v[4:5]
	v_or3_b32 v4, s79, v49, v69
	v_lshlrev_b32_e32 v4, 2, v4
	v_lshl_add_u64 v[74:75], s[12:13], 0, v[4:5]
	v_or3_b32 v4, s79, v50, v69
	v_lshlrev_b32_e32 v4, 2, v4
	v_lshl_add_u64 v[76:77], s[12:13], 0, v[4:5]
	v_or3_b32 v4, s79, v51, v69
	v_lshlrev_b32_e32 v4, 2, v4
	v_lshl_add_u64 v[78:79], s[12:13], 0, v[4:5]
	v_or3_b32 v4, s79, v52, v69
	v_lshlrev_b32_e32 v4, 2, v4
	v_lshl_add_u64 v[80:81], s[12:13], 0, v[4:5]
	v_or3_b32 v4, s79, v53, v69
	v_lshlrev_b32_e32 v4, 2, v4
	v_lshl_add_u64 v[82:83], s[12:13], 0, v[4:5]
	v_or3_b32 v4, s79, v54, v69
	v_lshlrev_b32_e32 v4, 2, v4
	flat_load_dword v100, v[26:27] nt
	flat_load_dword v101, v[70:71] nt
	flat_load_dword v102, v[72:73] nt
	flat_load_dword v103, v[74:75] nt
	flat_load_dword v104, v[76:77] nt
	flat_load_dword v105, v[78:79] nt
	flat_load_dword v106, v[80:81] nt
	flat_load_dword v107, v[82:83] nt
	v_lshl_add_u64 v[26:27], s[12:13], 0, v[4:5]
	v_or3_b32 v4, s79, v55, v69
	v_lshlrev_b32_e32 v4, 2, v4
	v_lshl_add_u64 v[70:71], s[12:13], 0, v[4:5]
	v_or3_b32 v4, s79, v56, v69
	v_lshlrev_b32_e32 v4, 2, v4
	v_lshl_add_u64 v[72:73], s[12:13], 0, v[4:5]
	v_or3_b32 v4, s79, v57, v69
	v_lshlrev_b32_e32 v4, 2, v4
	v_lshl_add_u64 v[74:75], s[12:13], 0, v[4:5]
	v_or3_b32 v4, s79, v58, v69
	v_lshlrev_b32_e32 v4, 2, v4
	v_lshl_add_u64 v[76:77], s[12:13], 0, v[4:5]
	v_or3_b32 v4, s79, v59, v69
	v_lshlrev_b32_e32 v4, 2, v4
	v_lshl_add_u64 v[78:79], s[12:13], 0, v[4:5]
	v_or3_b32 v4, s79, v60, v69
	v_lshlrev_b32_e32 v4, 2, v4
	v_lshl_add_u64 v[80:81], s[12:13], 0, v[4:5]
	v_or3_b32 v4, s79, v61, v69
	v_lshlrev_b32_e32 v4, 2, v4
	v_lshl_add_u64 v[82:83], s[12:13], 0, v[4:5]
	flat_load_dword v4, v[26:27] nt
	s_nop 0
	flat_load_dword v26, v[70:71] nt
	flat_load_dword v27, v[72:73] nt
	flat_load_dword v69, v[74:75] nt
	s_nop 0
	flat_load_dword v70, v[76:77] nt
	flat_load_dword v71, v[78:79] nt
	flat_load_dword v72, v[80:81] nt
	flat_load_dword v73, v[82:83] nt
	v_add_u32_e32 v74, 0x400, v62
	s_waitcnt vmcnt(0) lgkmcnt(0)
; #define LAS __attribute__((address_space(3)))
; __device__ __forceinline__ unsigned cvt_pk_bf16(float lo, float hi) { unsigned r; asm volatile("s_nop 1\n\tv_cvt_pk_bf16_f32 %0, %1, %2" : "=v"(r) : "v"(lo), "v"(hi)); return r; }
; template <int MAP>
; __device__ __forceinline__ void p0_transpose_item(const float* W, int K, int Nsrc, int rows, bf16_t* WT, LAS float* scr, int item, int lane) {
;     ...
;     for (int i = 0; i < 32; ++i) scr[(2 * i + (lane >> 5)) * 33 + (lane & 31)] = tv[i];
;     asm volatile("s_waitcnt lgkmcnt(0)" ::: "memory");
;     const int c = lane & 7;
; #pragma unroll
;     for (int jj = 0; jj < 4; ++jj) { const int n = (lane >> 3) + 8 * jj; const LAS float* s = scr + (8 * c) * 33 + n;
;         u32x4 o; o.x = cvt_pk_bf16(s[0 * 33], s[1 * 33]); o.y = cvt_pk_bf16(s[2 * 33], s[3 * 33]); o.z = cvt_pk_bf16(s[4 * 33], s[5 * 33]); o.w = cvt_pk_bf16(s[6 * 33], s[7 * 33]);
;         *(u32x4*)(WT + (size_t)(n0 + n) * K + k0 + 8 * c) = o; }
;     asm volatile("s_waitcnt lgkmcnt(0)" ::: "memory");
	ds_write2_b32 v62, v84, v85 offset1:66
	ds_write2_b32 v62, v86, v87 offset0:132 offset1:198
	ds_write2_b32 v74, v88, v89 offset0:8 offset1:74
	ds_write2_b32 v74, v90, v91 offset0:140 offset1:206
	v_add_u32_e32 v74, 0x800, v62
	ds_write2_b32 v74, v92, v93 offset0:16 offset1:82
	ds_write2_b32 v74, v94, v95 offset0:148 offset1:214
	v_add_u32_e32 v74, 0xc00, v62
	ds_write2_b32 v74, v96, v97 offset0:24 offset1:90
	ds_write2_b32 v74, v98, v99 offset0:156 offset1:222
	v_add_u32_e32 v74, 0x1000, v62
	ds_write2_b32 v74, v100, v101 offset0:32 offset1:98
	ds_write2_b32 v74, v102, v103 offset0:164 offset1:230
	v_add_u32_e32 v74, 0x1400, v62
	ds_write2_b32 v74, v104, v105 offset0:40 offset1:106
	ds_write2_b32 v74, v106, v107 offset0:172 offset1:238
	v_add_u32_e32 v74, 0x1800, v62
	ds_write2_b32 v74, v4, v26 offset0:48 offset1:114
	ds_write2_b32 v74, v27, v69 offset0:180 offset1:246
	v_add_u32_e32 v4, 0x1c00, v62
	ds_write2_b32 v4, v70, v71 offset0:56 offset1:122
	ds_write2_b32 v4, v72, v73 offset0:188 offset1:254
	s_waitcnt lgkmcnt(0)
	ds_read2_b32 v[26:27], v63 offset1:33
	s_waitcnt lgkmcnt(0)
	s_nop 1
	v_cvt_pk_bf16_f32 v70, v26, v27
	ds_read2_b32 v[26:27], v63 offset0:66 offset1:99
	v_or_b32_e32 v4, s79, v29
	s_waitcnt lgkmcnt(0)
	s_nop 1
	v_cvt_pk_bf16_f32 v71, v26, v27
	ds_read2_b32 v[26:27], v63 offset0:132 offset1:165
	v_mul_u32_u24_e32 v4, 0x1600, v4
	s_waitcnt lgkmcnt(0)
	s_nop 1
	v_cvt_pk_bf16_f32 v72, v26, v27
	ds_read2_b32 v[26:27], v63 offset0:198 offset1:231
	v_lshl_add_u64 v[74:75], v[20:21], 0, s[10:11]
	v_lshlrev_b32_e32 v4, 1, v4
	s_waitcnt lgkmcnt(0)
	s_nop 1
	v_cvt_pk_bf16_f32 v73, v26, v27
	v_lshl_add_u64 v[26:27], v[74:75], 0, v[4:5]
	flat_store_dwordx4 v[26:27], v[70:73]
	ds_read2_b32 v[26:27], v63 offset0:8 offset1:41
	v_or_b32_e32 v4, s79, v64
	s_waitcnt lgkmcnt(0)
	s_nop 1
	v_cvt_pk_bf16_f32 v70, v26, v27
	ds_read2_b32 v[26:27], v63 offset0:74 offset1:107
	s_waitcnt lgkmcnt(0)
	s_nop 1
	v_cvt_pk_bf16_f32 v71, v26, v27
	ds_read2_b32 v[26:27], v63 offset0:140 offset1:173
	v_mul_u32_u24_e32 v4, 0x1600, v4
	s_waitcnt lgkmcnt(0)
	s_nop 1
	v_cvt_pk_bf16_f32 v72, v26, v27
	ds_read2_b32 v[26:27], v63 offset0:206 offset1:239
	v_lshlrev_b32_e32 v4, 1, v4
	s_waitcnt lgkmcnt(0)
	s_nop 1
	v_cvt_pk_bf16_f32 v73, v26, v27
	v_lshl_add_u64 v[26:27], v[74:75], 0, v[4:5]
	flat_store_dwordx4 v[26:27], v[70:73]
	ds_read2_b32 v[26:27], v63 offset0:16 offset1:49
	v_or_b32_e32 v4, s79, v65
	s_waitcnt lgkmcnt(0)
	s_nop 1
	v_cvt_pk_bf16_f32 v70, v26, v27
	ds_read2_b32 v[26:27], v63 offset0:82 offset1:115
	s_waitcnt lgkmcnt(0)
	s_nop 1
	v_cvt_pk_bf16_f32 v71, v26, v27
	ds_read2_b32 v[26:27], v63 offset0:148 offset1:181
	v_mul_u32_u24_e32 v4, 0x1600, v4
	s_waitcnt lgkmcnt(0)
	s_nop 1
	v_cvt_pk_bf16_f32 v72, v26, v27
	ds_read2_b32 v[26:27], v63 offset0:214 offset1:247
	v_lshlrev_b32_e32 v4, 1, v4
	s_waitcnt lgkmcnt(0)
	s_nop 1
	v_cvt_pk_bf16_f32 v73, v26, v27
	v_lshl_add_u64 v[26:27], v[74:75], 0, v[4:5]
	flat_store_dwordx4 v[26:27], v[70:73]
	ds_read2_b32 v[26:27], v63 offset0:24 offset1:57
	v_or_b32_e32 v4, s79, v66
	s_waitcnt lgkmcnt(0)
	s_nop 1
	v_cvt_pk_bf16_f32 v70, v26, v27
	ds_read2_b32 v[26:27], v63 offset0:90 offset1:123
	s_waitcnt lgkmcnt(0)
	s_nop 1
	v_cvt_pk_bf16_f32 v71, v26, v27
	ds_read2_b32 v[26:27], v63 offset0:156 offset1:189
	v_mul_u32_u24_e32 v4, 0x1600, v4
	s_waitcnt lgkmcnt(0)
	s_nop 1
	v_cvt_pk_bf16_f32 v72, v26, v27
	ds_read2_b32 v[26:27], v63 offset0:222 offset1:255
	v_lshlrev_b32_e32 v4, 1, v4
	s_waitcnt lgkmcnt(0)
	s_nop 1
	v_cvt_pk_bf16_f32 v73, v26, v27
	v_lshl_add_u64 v[26:27], v[74:75], 0, v[4:5]
	flat_store_dwordx4 v[26:27], v[70:73]
	s_waitcnt lgkmcnt(0)

; __device__ __forceinline__ int map_gu(int j) { return ((j >> 7) & 1) * FF + ((j >> 8) << 7) + (j & 127); }
; template <int MAP>
; __device__ __forceinline__ void p0_transpose_item(const float* W, int K, int Nsrc, int rows, bf16_t* WT, LAS float* scr, int item, int lane) {
;     const int nblk = rows / 32, kb = item / nblk, nb = item % nblk, k0 = 64 * kb, n0 = 32 * nb;
;     const int j = n0 + (lane & 31);
;     const int sc = MAP == 0 ? j : (MAP == 1 ? map_gu(j) : map_in(j));
;     float tv[32];
; #pragma unroll
;     for (int i = 0; i < 32; ++i) tv[i] = W[(size_t)(k0 + 2 * i + (lane >> 5)) * Nsrc + sc];
; #pragma unroll
;     for (int i = 0; i < 32; ++i) scr[(2 * i + (lane >> 5)) * 33 + (lane & 31)] = tv[i];
.LBB0_65:
	v_mov_b32_e32 v70, s10
	s_lshl_b32 s10, s81, 6
	s_and_b32 s10, s10, 0x3fc0
	v_or_b32_e32 v4, s10, v30
	v_mov_b32_e32 v71, s80
	v_ashrrev_i32_e32 v27, 31, v26
	v_mul_u32_u24_e32 v4, 0x2e00, v4
	v_lshl_add_u64 v[26:27], v[26:27], 2, v[70:71]
	v_lshlrev_b32_e32 v4, 2, v4
	v_lshl_add_u64 v[26:27], v[26:27], 0, v[4:5]
	v_add_co_u32_e32 v70, vcc, 0x17000, v26
	s_lshl_b32 s10, s10, 1
	s_nop 0
	v_addc_co_u32_e32 v71, vcc, 0, v27, vcc
	v_add_co_u32_e32 v72, vcc, 0x2e000, v26
	s_nop 1
	v_addc_co_u32_e32 v73, vcc, 0, v27, vcc
	v_add_co_u32_e32 v74, vcc, 0x45000, v26
	s_nop 1
	v_addc_co_u32_e32 v75, vcc, 0, v27, vcc
	v_add_co_u32_e32 v76, vcc, 0x5c000, v26
	s_nop 1
	v_addc_co_u32_e32 v77, vcc, 0, v27, vcc
	v_add_co_u32_e32 v78, vcc, 0x73000, v26
	s_nop 1
	v_addc_co_u32_e32 v79, vcc, 0, v27, vcc
	v_add_co_u32_e32 v80, vcc, 0x8a000, v26
	s_nop 1
	v_addc_co_u32_e32 v81, vcc, 0, v27, vcc
	v_add_co_u32_e32 v82, vcc, 0xa1000, v26
	s_nop 1
	v_addc_co_u32_e32 v83, vcc, 0, v27, vcc
	flat_load_dword v4, v[26:27] nt
	flat_load_dword v69, v[70:71] nt
	flat_load_dword v86, v[72:73] nt
	flat_load_dword v87, v[74:75] nt
	flat_load_dword v88, v[76:77] nt
	flat_load_dword v89, v[78:79] nt
	flat_load_dword v90, v[80:81] nt
	flat_load_dword v91, v[82:83] nt
	v_add_co_u32_e32 v70, vcc, 0xb8000, v26
	s_nop 1
	v_addc_co_u32_e32 v71, vcc, 0, v27, vcc
	v_add_co_u32_e32 v72, vcc, 0xcf000, v26
	s_nop 1
	v_addc_co_u32_e32 v73, vcc, 0, v27, vcc
	v_add_co_u32_e32 v74, vcc, 0xe6000, v26
	s_nop 1
	v_addc_co_u32_e32 v75, vcc, 0, v27, vcc
	v_add_co_u32_e32 v76, vcc, 0xfd000, v26
	s_nop 1
	v_addc_co_u32_e32 v77, vcc, 0, v27, vcc
	v_add_co_u32_e32 v78, vcc, 0x114000, v26
	s_nop 1
	v_addc_co_u32_e32 v79, vcc, 0, v27, vcc
	v_add_co_u32_e32 v80, vcc, 0x12b000, v26
	s_nop 1
	v_addc_co_u32_e32 v81, vcc, 0, v27, vcc
	v_add_co_u32_e32 v82, vcc, 0x142000, v26
	s_nop 1
	v_addc_co_u32_e32 v83, vcc, 0, v27, vcc
	v_add_co_u32_e32 v84, vcc, 0x159000, v26
	s_nop 1
	v_addc_co_u32_e32 v85, vcc, 0, v27, vcc
	flat_load_dword v92, v[70:71] nt
	flat_load_dword v93, v[72:73] nt
	flat_load_dword v94, v[74:75] nt
	flat_load_dword v95, v[76:77] nt
	flat_load_dword v96, v[78:79] nt
	flat_load_dword v97, v[80:81] nt
	flat_load_dword v98, v[82:83] nt
	flat_load_dword v99, v[84:85] nt
	v_add_co_u32_e32 v70, vcc, 0x170000, v26
	s_nop 1
	v_addc_co_u32_e32 v71, vcc, 0, v27, vcc
	v_add_co_u32_e32 v72, vcc, 0x187000, v26
	s_nop 1
	v_addc_co_u32_e32 v73, vcc, 0, v27, vcc
	v_add_co_u32_e32 v74, vcc, 0x19e000, v26
	s_nop 1
	v_addc_co_u32_e32 v75, vcc, 0, v27, vcc
	v_add_co_u32_e32 v76, vcc, 0x1b5000, v26
	s_nop 1
	v_addc_co_u32_e32 v77, vcc, 0, v27, vcc
	v_add_co_u32_e32 v78, vcc, 0x1cc000, v26
	s_nop 1
	v_addc_co_u32_e32 v79, vcc, 0, v27, vcc
	v_add_co_u32_e32 v80, vcc, 0x1e3000, v26
	s_nop 1
	v_addc_co_u32_e32 v81, vcc, 0, v27, vcc
	v_add_co_u32_e32 v82, vcc, 0x1fa000, v26
	s_nop 1
	v_addc_co_u32_e32 v83, vcc, 0, v27, vcc
	v_add_co_u32_e32 v84, vcc, 0x211000, v26
	s_nop 1
	v_addc_co_u32_e32 v85, vcc, 0, v27, vcc
	flat_load_dword v100, v[70:71] nt
	flat_load_dword v101, v[72:73] nt
	flat_load_dword v102, v[74:75] nt
	flat_load_dword v103, v[76:77] nt
	flat_load_dword v104, v[78:79] nt
	flat_load_dword v105, v[80:81] nt
	flat_load_dword v106, v[82:83] nt
	s_nop 0
	flat_load_dword v84, v[84:85] nt
	v_add_co_u32_e32 v70, vcc, 0x228000, v26
	s_nop 1
	v_addc_co_u32_e32 v71, vcc, 0, v27, vcc
	v_add_co_u32_e32 v72, vcc, 0x23f000, v26
	s_nop 1
	v_addc_co_u32_e32 v73, vcc, 0, v27, vcc
	v_add_co_u32_e32 v74, vcc, 0x256000, v26
	s_nop 1
	v_addc_co_u32_e32 v75, vcc, 0, v27, vcc
	v_add_co_u32_e32 v76, vcc, 0x26d000, v26
	s_nop 1
	v_addc_co_u32_e32 v77, vcc, 0, v27, vcc
	v_add_co_u32_e32 v78, vcc, 0x284000, v26
	s_nop 1
	v_addc_co_u32_e32 v79, vcc, 0, v27, vcc
	v_add_co_u32_e32 v80, vcc, 0x29b000, v26
	s_nop 1
	v_addc_co_u32_e32 v81, vcc, 0, v27, vcc
	v_add_co_u32_e32 v82, vcc, 0x2b2000, v26
	s_nop 1
	v_addc_co_u32_e32 v83, vcc, 0, v27, vcc
	v_add_co_u32_e32 v26, vcc, 0x2c9000, v26
	s_nop 1
	v_addc_co_u32_e32 v27, vcc, 0, v27, vcc
	flat_load_dword v70, v[70:71] nt
	s_nop 0
	flat_load_dword v71, v[72:73] nt
	s_nop 0
	flat_load_dword v72, v[74:75] nt
	flat_load_dword v73, v[76:77] nt
	s_nop 0
	flat_load_dword v74, v[78:79] nt
	flat_load_dword v75, v[80:81] nt
	flat_load_dword v76, v[82:83] nt
	s_nop 0
	flat_load_dword v26, v[26:27] nt
	s_waitcnt vmcnt(0) lgkmcnt(0)
; #define LAS __attribute__((address_space(3)))
; __device__ __forceinline__ unsigned cvt_pk_bf16(float lo, float hi) { unsigned r; asm volatile("s_nop 1\n\tv_cvt_pk_bf16_f32 %0, %1, %2" : "=v"(r) : "v"(lo), "v"(hi)); return r; }
; template <int MAP>
; __device__ __forceinline__ void p0_transpose_item(const float* W, int K, int Nsrc, int rows, bf16_t* WT, LAS float* scr, int item, int lane) {
;     ...
;     for (int i = 0; i < 32; ++i) scr[(2 * i + (lane >> 5)) * 33 + (lane & 31)] = tv[i];
;     asm volatile("s_waitcnt lgkmcnt(0)" ::: "memory");
;     const int c = lane & 7;
; #pragma unroll
;     for (int jj = 0; jj < 4; ++jj) { const int n = (lane >> 3) + 8 * jj; const LAS float* s = scr + (8 * c) * 33 + n;
;         u32x4 o; o.x = cvt_pk_bf16(s[0 * 33], s[1 * 33]); o.y = cvt_pk_bf16(s[2 * 33], s[3 * 33]); o.z = cvt_pk_bf16(s[4 * 33], s[5 * 33]); o.w = cvt_pk_bf16(s[6 * 33], s[7 * 33]);
;         *(u32x4*)(WT + (size_t)(n0 + n) * K + k0 + 8 * c) = o; }
;     asm volatile("s_waitcnt lgkmcnt(0)" ::: "memory");
	ds_write2_b32 v62, v4, v69 offset1:66
	ds_write2_b32 v62, v86, v87 offset0:132 offset1:198
	v_add_u32_e32 v4, 0x400, v62
	ds_write2_b32 v4, v88, v89 offset0:8 offset1:74
	ds_write2_b32 v4, v90, v91 offset0:140 offset1:206
	v_add_u32_e32 v4, 0x800, v62
	ds_write2_b32 v4, v92, v93 offset0:16 offset1:82
	ds_write2_b32 v4, v94, v95 offset0:148 offset1:214
	v_add_u32_e32 v4, 0xc00, v62
	ds_write2_b32 v4, v96, v97 offset0:24 offset1:90
	ds_write2_b32 v4, v98, v99 offset0:156 offset1:222
	v_add_u32_e32 v4, 0x1000, v62
	ds_write2_b32 v4, v100, v101 offset0:32 offset1:98
	ds_write2_b32 v4, v102, v103 offset0:164 offset1:230
	v_add_u32_e32 v4, 0x1400, v62
	ds_write2_b32 v4, v104, v105 offset0:40 offset1:106
	ds_write2_b32 v4, v106, v84 offset0:172 offset1:238
	v_add_u32_e32 v4, 0x1800, v62
	ds_write2_b32 v4, v70, v71 offset0:48 offset1:114
	ds_write2_b32 v4, v72, v73 offset0:180 offset1:246
	v_add_u32_e32 v4, 0x1c00, v62
	ds_write2_b32 v4, v74, v75 offset0:56 offset1:122
	ds_write2_b32 v4, v76, v26 offset0:188 offset1:254
	s_waitcnt lgkmcnt(0)
	ds_read2_b32 v[26:27], v63 offset1:33
	s_waitcnt lgkmcnt(0)
	s_nop 1
	v_cvt_pk_bf16_f32 v70, v26, v27
	ds_read2_b32 v[26:27], v63 offset0:66 offset1:99
	s_waitcnt lgkmcnt(0)
	s_nop 1
	v_cvt_pk_bf16_f32 v71, v26, v27
	ds_read2_b32 v[26:27], v63 offset0:132 offset1:165
	v_or_b32_e32 v4, s79, v29
	s_waitcnt lgkmcnt(0)
	s_nop 1
	v_cvt_pk_bf16_f32 v72, v26, v27
	ds_read2_b32 v[26:27], v63 offset0:198 offset1:231
	v_lshl_add_u64 v[74:75], v[22:23], 0, s[10:11]
	v_lshlrev_b32_e32 v4, 12, v4
	s_waitcnt lgkmcnt(0)
	s_nop 1
	v_cvt_pk_bf16_f32 v73, v26, v27
	v_lshl_add_u64 v[26:27], v[74:75], 0, v[4:5]
	flat_store_dwordx4 v[26:27], v[70:73]
	ds_read2_b32 v[26:27], v63 offset0:8 offset1:41
	v_or_b32_e32 v4, s79, v64
	s_waitcnt lgkmcnt(0)
	s_nop 1
	v_cvt_pk_bf16_f32 v70, v26, v27
	ds_read2_b32 v[26:27], v63 offset0:74 offset1:107
	s_waitcnt lgkmcnt(0)
	s_nop 1
	v_cvt_pk_bf16_f32 v71, v26, v27
	ds_read2_b32 v[26:27], v63 offset0:140 offset1:173
	s_waitcnt lgkmcnt(0)
	s_nop 1
	v_cvt_pk_bf16_f32 v72, v26, v27
	ds_read2_b32 v[26:27], v63 offset0:206 offset1:239
	v_lshlrev_b32_e32 v4, 12, v4
	s_waitcnt lgkmcnt(0)
	s_nop 1
	v_cvt_pk_bf16_f32 v73, v26, v27
	v_lshl_add_u64 v[26:27], v[74:75], 0, v[4:5]
	flat_store_dwordx4 v[26:27], v[70:73]
	ds_read2_b32 v[26:27], v63 offset0:16 offset1:49
	v_or_b32_e32 v4, s79, v65
	s_waitcnt lgkmcnt(0)
	s_nop 1
	v_cvt_pk_bf16_f32 v70, v26, v27
	ds_read2_b32 v[26:27], v63 offset0:82 offset1:115
	s_waitcnt lgkmcnt(0)
	s_nop 1
	v_cvt_pk_bf16_f32 v71, v26, v27
	ds_read2_b32 v[26:27], v63 offset0:148 offset1:181
	s_waitcnt lgkmcnt(0)
	s_nop 1
	v_cvt_pk_bf16_f32 v72, v26, v27
	ds_read2_b32 v[26:27], v63 offset0:214 offset1:247
	v_lshlrev_b32_e32 v4, 12, v4
	s_waitcnt lgkmcnt(0)
	s_nop 1
	v_cvt_pk_bf16_f32 v73, v26, v27
	v_lshl_add_u64 v[26:27], v[74:75], 0, v[4:5]
	flat_store_dwordx4 v[26:27], v[70:73]
	ds_read2_b32 v[26:27], v63 offset0:24 offset1:57
	v_or_b32_e32 v4, s79, v66
	s_waitcnt lgkmcnt(0)
	s_nop 1
	v_cvt_pk_bf16_f32 v70, v26, v27
	ds_read2_b32 v[26:27], v63 offset0:90 offset1:123
	s_waitcnt lgkmcnt(0)
	s_nop 1
	v_cvt_pk_bf16_f32 v71, v26, v27
	ds_read2_b32 v[26:27], v63 offset0:156 offset1:189
	s_waitcnt lgkmcnt(0)
	s_nop 1
	v_cvt_pk_bf16_f32 v72, v26, v27
	ds_read2_b32 v[26:27], v63 offset0:222 offset1:255
	v_lshlrev_b32_e32 v4, 12, v4
	s_waitcnt lgkmcnt(0)
	s_nop 1
	v_cvt_pk_bf16_f32 v73, v26, v27
	v_lshl_add_u64 v[26:27], v[74:75], 0, v[4:5]
	flat_store_dwordx4 v[26:27], v[70:73]
	s_waitcnt lgkmcnt(0)

; __device__ __forceinline__ int map_gu(int j) { return ((j >> 7) & 1) * FF + ((j >> 8) << 7) + (j & 127); }
; template <int MAP>
; __device__ __forceinline__ void p0_transpose_item(const float* W, int K, int Nsrc, int rows, bf16_t* WT, LAS float* scr, int item, int lane) {
;     const int nblk = rows / 32, kb = item / nblk, nb = item % nblk, k0 = 64 * kb, n0 = 32 * nb;
;     const int j = n0 + (lane & 31);
;     const int sc = MAP == 0 ? j : (MAP == 1 ? map_gu(j) : map_in(j));
;     float tv[32];
; #pragma unroll
;     for (int i = 0; i < 32; ++i) tv[i] = W[(size_t)(k0 + 2 * i + (lane >> 5)) * Nsrc + sc];
; #pragma unroll
;     for (int i = 0; i < 32; ++i) scr[(2 * i + (lane >> 5)) * 33 + (lane & 31)] = tv[i];
.LBB0_67:
	s_andn2_b64 vcc, exec, s[12:13]
	s_cbranch_vccnz .LBB0_69
	s_add_i32 s12, s78, 0xd400
	s_and_b32 s10, s12, 0xffff
	s_mul_i32 s10, s10, 0xba2f
	s_lshr_b32 s10, s10, 24
	s_mul_i32 s13, s10, 0x160
	v_mov_b32_e32 v4, s45
	s_sub_i32 s13, s12, s13
	ds_read_b32 v4, v4
	v_mov_b32_e32 v26, s46
	s_and_b32 s79, s13, 0xffff
	ds_read_b32 v26, v26
	s_lshl_b32 s12, s79, 5
	s_bfe_i32 s13, s13, 0x10002
	s_lshl_b32 s79, s79, 4
	s_and_b32 s13, s13, 0x1600
	s_and_b32 s79, s79, 0x1f80
	s_add_i32 s13, s13, s79
	s_and_b32 s79, s12, 0x60
	s_or_b32 s13, s13, s79
	s_waitcnt lgkmcnt(0)
	v_readfirstlane_b32 s80, v4
	v_or_b32_e32 v4, s13, v3
	v_readfirstlane_b32 s81, v26
	v_lshl_or_b32 v69, s10, 6, v30
	v_lshlrev_b32_e32 v4, 2, v4
	v_lshl_add_u64 v[26:27], s[80:81], 0, v[4:5]
	v_mul_u32_u24_e32 v4, 0xb000, v69
	v_lshl_add_u64 v[26:27], v[26:27], 0, v[4:5]
	v_add_co_u32_e32 v70, vcc, s15, v26
	s_lshl_b32 s10, s10, 7
	s_nop 0
	v_addc_co_u32_e32 v71, vcc, 0, v27, vcc
	v_add_co_u32_e32 v72, vcc, s47, v26
	s_nop 1
	v_addc_co_u32_e32 v73, vcc, 0, v27, vcc
	v_add_co_u32_e32 v74, vcc, s48, v26
	s_nop 1
	v_addc_co_u32_e32 v75, vcc, 0, v27, vcc
	v_add_co_u32_e32 v76, vcc, s49, v26
	s_nop 1
	v_addc_co_u32_e32 v77, vcc, 0, v27, vcc
	v_add_co_u32_e32 v78, vcc, s50, v26
	s_nop 1
	v_addc_co_u32_e32 v79, vcc, 0, v27, vcc
	v_add_co_u32_e32 v80, vcc, s51, v26
	s_nop 1
	v_addc_co_u32_e32 v81, vcc, 0, v27, vcc
	v_add_co_u32_e32 v82, vcc, s52, v26
	s_nop 1
	v_addc_co_u32_e32 v83, vcc, 0, v27, vcc
	flat_load_dword v4, v[26:27] nt
	flat_load_dword v69, v[70:71] nt
	flat_load_dword v86, v[72:73] nt
	flat_load_dword v87, v[74:75] nt
	flat_load_dword v88, v[76:77] nt
	flat_load_dword v89, v[78:79] nt
	flat_load_dword v90, v[80:81] nt
	flat_load_dword v91, v[82:83] nt
	v_add_co_u32_e32 v70, vcc, s53, v26
	s_nop 1
	v_addc_co_u32_e32 v71, vcc, 0, v27, vcc
	v_add_co_u32_e32 v72, vcc, s54, v26
	s_nop 1
	v_addc_co_u32_e32 v73, vcc, 0, v27, vcc
	v_add_co_u32_e32 v74, vcc, s55, v26
	s_nop 1
	v_addc_co_u32_e32 v75, vcc, 0, v27, vcc
	v_add_co_u32_e32 v76, vcc, s56, v26
	s_nop 1
	v_addc_co_u32_e32 v77, vcc, 0, v27, vcc
	v_add_co_u32_e32 v78, vcc, s57, v26
	s_nop 1
	v_addc_co_u32_e32 v79, vcc, 0, v27, vcc
	v_add_co_u32_e32 v80, vcc, s58, v26
	s_nop 1
	v_addc_co_u32_e32 v81, vcc, 0, v27, vcc
	v_add_co_u32_e32 v82, vcc, s59, v26
	s_nop 1
	v_addc_co_u32_e32 v83, vcc, 0, v27, vcc
	v_add_co_u32_e32 v84, vcc, s60, v26
	s_nop 1
	v_addc_co_u32_e32 v85, vcc, 0, v27, vcc
	flat_load_dword v92, v[70:71] nt
	flat_load_dword v93, v[72:73] nt
	flat_load_dword v94, v[74:75] nt
	flat_load_dword v95, v[76:77] nt
	flat_load_dword v96, v[78:79] nt
	flat_load_dword v97, v[80:81] nt
	flat_load_dword v98, v[82:83] nt
	flat_load_dword v99, v[84:85] nt
	v_add_co_u32_e32 v70, vcc, s61, v26
	s_nop 1
	v_addc_co_u32_e32 v71, vcc, 0, v27, vcc
	v_add_co_u32_e32 v72, vcc, s62, v26
	s_nop 1
	v_addc_co_u32_e32 v73, vcc, 0, v27, vcc
	v_add_co_u32_e32 v74, vcc, s63, v26
	s_nop 1
	v_addc_co_u32_e32 v75, vcc, 0, v27, vcc
	v_add_co_u32_e32 v76, vcc, s64, v26
	s_nop 1
	v_addc_co_u32_e32 v77, vcc, 0, v27, vcc
	v_add_co_u32_e32 v78, vcc, s65, v26
	s_nop 1
	v_addc_co_u32_e32 v79, vcc, 0, v27, vcc
	v_add_co_u32_e32 v80, vcc, s66, v26
	s_nop 1
	v_addc_co_u32_e32 v81, vcc, 0, v27, vcc
	v_add_co_u32_e32 v82, vcc, s67, v26
	s_nop 1
	v_addc_co_u32_e32 v83, vcc, 0, v27, vcc
	v_add_co_u32_e32 v84, vcc, s44, v26
	s_nop 1
	v_addc_co_u32_e32 v85, vcc, 0, v27, vcc
	flat_load_dword v100, v[70:71] nt
	flat_load_dword v101, v[72:73] nt
	flat_load_dword v102, v[74:75] nt
	flat_load_dword v103, v[76:77] nt
	flat_load_dword v104, v[78:79] nt
	flat_load_dword v105, v[80:81] nt
	flat_load_dword v106, v[82:83] nt
	s_nop 0
	flat_load_dword v84, v[84:85] nt
	v_add_co_u32_e32 v70, vcc, s68, v26
	s_nop 1
	v_addc_co_u32_e32 v71, vcc, 0, v27, vcc
	v_add_co_u32_e32 v72, vcc, s69, v26
	s_nop 1
	v_addc_co_u32_e32 v73, vcc, 0, v27, vcc
	v_add_co_u32_e32 v74, vcc, s70, v26
	s_nop 1
	v_addc_co_u32_e32 v75, vcc, 0, v27, vcc
	v_add_co_u32_e32 v76, vcc, s71, v26
	s_nop 1
	v_addc_co_u32_e32 v77, vcc, 0, v27, vcc
	v_add_co_u32_e32 v78, vcc, s72, v26
	s_nop 1
	v_addc_co_u32_e32 v79, vcc, 0, v27, vcc
	v_add_co_u32_e32 v80, vcc, s73, v26
	s_nop 1
	v_addc_co_u32_e32 v81, vcc, 0, v27, vcc
	v_add_co_u32_e32 v82, vcc, s74, v26
	s_nop 1
	v_addc_co_u32_e32 v83, vcc, 0, v27, vcc
	v_add_co_u32_e32 v26, vcc, s75, v26
	s_nop 1
	v_addc_co_u32_e32 v27, vcc, 0, v27, vcc
	flat_load_dword v70, v[70:71] nt
	s_nop 0
	flat_load_dword v71, v[72:73] nt
	s_nop 0
	flat_load_dword v72, v[74:75] nt
	flat_load_dword v73, v[76:77] nt
	s_nop 0
	flat_load_dword v74, v[78:79] nt
	flat_load_dword v75, v[80:81] nt
	flat_load_dword v76, v[82:83] nt
	s_nop 0
	flat_load_dword v26, v[26:27] nt
	s_waitcnt vmcnt(0) lgkmcnt(0)
; #define LAS __attribute__((address_space(3)))
; __device__ __forceinline__ unsigned cvt_pk_bf16(float lo, float hi) { unsigned r; asm volatile("s_nop 1\n\tv_cvt_pk_bf16_f32 %0, %1, %2" : "=v"(r) : "v"(lo), "v"(hi)); return r; }
; template <int MAP>
; __device__ __forceinline__ void p0_transpose_item(const float* W, int K, int Nsrc, int rows, bf16_t* WT, LAS float* scr, int item, int lane) {
;     ...
;     for (int i = 0; i < 32; ++i) scr[(2 * i + (lane >> 5)) * 33 + (lane & 31)] = tv[i];
;     asm volatile("s_waitcnt lgkmcnt(0)" ::: "memory");
;     const int c = lane & 7;
; #pragma unroll
;     for (int jj = 0; jj < 4; ++jj) { const int n = (lane >> 3) + 8 * jj; const LAS float* s = scr + (8 * c) * 33 + n;
;         u32x4 o; o.x = cvt_pk_bf16(s[0 * 33], s[1 * 33]); o.y = cvt_pk_bf16(s[2 * 33], s[3 * 33]); o.z = cvt_pk_bf16(s[4 * 33], s[5 * 33]); o.w = cvt_pk_bf16(s[6 * 33], s[7 * 33]);
;         *(u32x4*)(WT + (size_t)(n0 + n) * K + k0 + 8 * c) = o; }
;     asm volatile("s_waitcnt lgkmcnt(0)" ::: "memory");
	ds_write2_b32 v62, v4, v69 offset1:66
	ds_write2_b32 v62, v86, v87 offset0:132 offset1:198
	v_add_u32_e32 v4, 0x400, v62
	ds_write2_b32 v4, v88, v89 offset0:8 offset1:74
	ds_write2_b32 v4, v90, v91 offset0:140 offset1:206
	v_add_u32_e32 v4, 0x800, v62
	ds_write2_b32 v4, v92, v93 offset0:16 offset1:82
	ds_write2_b32 v4, v94, v95 offset0:148 offset1:214
	v_add_u32_e32 v4, 0xc00, v62
	ds_write2_b32 v4, v96, v97 offset0:24 offset1:90
	ds_write2_b32 v4, v98, v99 offset0:156 offset1:222
	v_add_u32_e32 v4, 0x1000, v62
	ds_write2_b32 v4, v100, v101 offset0:32 offset1:98
	ds_write2_b32 v4, v102, v103 offset0:164 offset1:230
	v_add_u32_e32 v4, 0x1400, v62
	ds_write2_b32 v4, v104, v105 offset0:40 offset1:106
	ds_write2_b32 v4, v106, v84 offset0:172 offset1:238
	v_add_u32_e32 v4, 0x1800, v62
	ds_write2_b32 v4, v70, v71 offset0:48 offset1:114
	ds_write2_b32 v4, v72, v73 offset0:180 offset1:246
	v_add_u32_e32 v4, 0x1c00, v62
	ds_write2_b32 v4, v74, v75 offset0:56 offset1:122
	ds_write2_b32 v4, v76, v26 offset0:188 offset1:254
	s_waitcnt lgkmcnt(0)
	ds_read2_b32 v[26:27], v63 offset1:33
	s_waitcnt lgkmcnt(0)
	s_nop 1
	v_cvt_pk_bf16_f32 v70, v26, v27
	ds_read2_b32 v[26:27], v63 offset0:66 offset1:99
	s_waitcnt lgkmcnt(0)
	s_nop 1
	v_cvt_pk_bf16_f32 v71, v26, v27
	ds_read2_b32 v[26:27], v63 offset0:132 offset1:165
	v_or_b32_e32 v4, s12, v29
	s_waitcnt lgkmcnt(0)
	s_nop 1
	v_cvt_pk_bf16_f32 v72, v26, v27
	ds_read2_b32 v[26:27], v63 offset0:198 offset1:231
	v_lshl_add_u64 v[74:75], v[24:25], 0, s[10:11]
	v_lshlrev_b32_e32 v4, 12, v4
	s_waitcnt lgkmcnt(0)
	s_nop 1
	v_cvt_pk_bf16_f32 v73, v26, v27
	v_lshl_add_u64 v[26:27], v[74:75], 0, v[4:5]
	flat_store_dwordx4 v[26:27], v[70:73]
	ds_read2_b32 v[26:27], v63 offset0:8 offset1:41
	v_or_b32_e32 v4, s12, v64
	s_waitcnt lgkmcnt(0)
	s_nop 1
	v_cvt_pk_bf16_f32 v70, v26, v27
	ds_read2_b32 v[26:27], v63 offset0:74 offset1:107
	s_waitcnt lgkmcnt(0)
	s_nop 1
	v_cvt_pk_bf16_f32 v71, v26, v27
	ds_read2_b32 v[26:27], v63 offset0:140 offset1:173
	s_waitcnt lgkmcnt(0)
	s_nop 1
	v_cvt_pk_bf16_f32 v72, v26, v27
	ds_read2_b32 v[26:27], v63 offset0:206 offset1:239
	v_lshlrev_b32_e32 v4, 12, v4
	s_waitcnt lgkmcnt(0)
	s_nop 1
	v_cvt_pk_bf16_f32 v73, v26, v27
	v_lshl_add_u64 v[26:27], v[74:75], 0, v[4:5]
	flat_store_dwordx4 v[26:27], v[70:73]
	ds_read2_b32 v[26:27], v63 offset0:16 offset1:49
	v_or_b32_e32 v4, s12, v65
	s_waitcnt lgkmcnt(0)
	s_nop 1
	v_cvt_pk_bf16_f32 v70, v26, v27
	ds_read2_b32 v[26:27], v63 offset0:82 offset1:115
	s_waitcnt lgkmcnt(0)
	s_nop 1
	v_cvt_pk_bf16_f32 v71, v26, v27
	ds_read2_b32 v[26:27], v63 offset0:148 offset1:181
	s_waitcnt lgkmcnt(0)
	s_nop 1
	v_cvt_pk_bf16_f32 v72, v26, v27
	ds_read2_b32 v[26:27], v63 offset0:214 offset1:247
	v_lshlrev_b32_e32 v4, 12, v4
	s_waitcnt lgkmcnt(0)
	s_nop 1
	v_cvt_pk_bf16_f32 v73, v26, v27
	v_lshl_add_u64 v[26:27], v[74:75], 0, v[4:5]
	flat_store_dwordx4 v[26:27], v[70:73]
	ds_read2_b32 v[26:27], v63 offset0:24 offset1:57
	v_or_b32_e32 v4, s12, v66
	s_waitcnt lgkmcnt(0)
	s_nop 1
	v_cvt_pk_bf16_f32 v70, v26, v27
	ds_read2_b32 v[26:27], v63 offset0:90 offset1:123
	s_waitcnt lgkmcnt(0)
	s_nop 1
	v_cvt_pk_bf16_f32 v71, v26, v27
	ds_read2_b32 v[26:27], v63 offset0:156 offset1:189
	s_waitcnt lgkmcnt(0)
	s_nop 1
	v_cvt_pk_bf16_f32 v72, v26, v27
	ds_read2_b32 v[26:27], v63 offset0:222 offset1:255
	v_lshlrev_b32_e32 v4, 12, v4
	s_waitcnt lgkmcnt(0)
	s_nop 1
	v_cvt_pk_bf16_f32 v73, v26, v27
	v_lshl_add_u64 v[26:27], v[74:75], 0, v[4:5]
	flat_store_dwordx4 v[26:27], v[70:73]
	s_waitcnt lgkmcnt(0)

; __device__ __forceinline__ int map_gu(int j) { return ((j >> 7) & 1) * FF + ((j >> 8) << 7) + (j & 127); }
; template <int MAP>
; __device__ __forceinline__ void p0_transpose_item(const float* W, int K, int Nsrc, int rows, bf16_t* WT, LAS float* scr, int item, int lane) {
;     const int nblk = rows / 32, kb = item / nblk, nb = item % nblk, k0 = 64 * kb, n0 = 32 * nb;
;     const int j = n0 + (lane & 31);
;     const int sc = MAP == 0 ? j : (MAP == 1 ? map_gu(j) : map_in(j));
;     float tv[32];
; #pragma unroll
;     for (int i = 0; i < 32; ++i) tv[i] = W[(size_t)(k0 + 2 * i + (lane >> 5)) * Nsrc + sc];
; #pragma unroll
;     for (int i = 0; i < 32; ++i) scr[(2 * i + (lane >> 5)) * 33 + (lane & 31)] = tv[i];
.LBB0_70:
	s_andn2_b64 vcc, exec, s[12:13]
	s_cbranch_vccnz .LBB0_11
	v_mov_b32_e32 v4, s76
	ds_read_b32 v4, v4
	v_mov_b32_e32 v26, s77
	ds_read_b32 v26, v26
	s_waitcnt lgkmcnt(0)
	v_readfirstlane_b32 s10, v4
	v_readfirstlane_b32 s12, v26
	s_nop 0
	v_mov_b32_e32 v26, s10
	s_mul_hi_i32 s10, s78, 0x2e8ba2e9
	v_mov_b32_e32 v27, s12
	s_lshr_b32 s12, s10, 31
	s_ashr_i32 s10, s10, 6
	s_add_i32 s10, s10, s12
	s_lshl_b32 s12, s10, 6
	s_mul_i32 s13, s10, 0xffffd400
	s_mulk_i32 s10, 0xea00
	s_add_i32 s79, s16, s13
	s_bfe_i32 s13, s78, 0x10002
	s_add_i32 s10, s18, s10
	s_and_b32 s13, s13, 0x1600
	s_and_b32 s10, s10, 0xffffff80
	s_add_i32 s13, s13, s10
	s_and_b32 s10, s79, 0x60
	s_or_b32 s10, s13, s10
	v_or_b32_e32 v70, s10, v3
	v_or_b32_e32 v4, s12, v30
	v_ashrrev_i32_e32 v71, 31, v70
	v_lshl_add_u64 v[26:27], v[70:71], 2, v[26:27]
	v_or_b32_e32 v69, 2, v4
	v_mad_i64_i32 v[72:73], s[80:81], v69, s14, v[26:27]
	v_or_b32_e32 v69, 4, v4
	v_mad_i64_i32 v[74:75], s[80:81], v69, s14, v[26:27]
	v_or_b32_e32 v69, 6, v4
	v_mad_i64_i32 v[76:77], s[80:81], v69, s14, v[26:27]
	v_or_b32_e32 v69, 8, v4
	v_mad_i64_i32 v[78:79], s[80:81], v69, s14, v[26:27]
	v_or_b32_e32 v69, 10, v4
	v_mad_i64_i32 v[80:81], s[80:81], v69, s14, v[26:27]
	v_or_b32_e32 v69, 12, v4
	v_mad_i64_i32 v[82:83], s[80:81], v69, s14, v[26:27]
	v_or_b32_e32 v69, 14, v4
	v_mad_i64_i32 v[70:71], s[80:81], v4, s14, v[26:27]
	v_mad_i64_i32 v[84:85], s[80:81], v69, s14, v[26:27]
	flat_load_dword v69, v[70:71] nt
	flat_load_dword v86, v[72:73] nt
	flat_load_dword v87, v[74:75] nt
	flat_load_dword v88, v[76:77] nt
	flat_load_dword v89, v[78:79] nt
	flat_load_dword v90, v[80:81] nt
	flat_load_dword v91, v[82:83] nt
	flat_load_dword v92, v[84:85] nt
	v_or_b32_e32 v70, 16, v4
	v_or_b32_e32 v72, 18, v4
	v_or_b32_e32 v74, 20, v4
	v_or_b32_e32 v76, 22, v4
	v_or_b32_e32 v78, 24, v4
	v_or_b32_e32 v80, 26, v4
	v_or_b32_e32 v82, 28, v4
	v_or_b32_e32 v84, 30, v4
	v_mad_i64_i32 v[70:71], s[80:81], v70, s14, v[26:27]
	v_mad_i64_i32 v[72:73], s[80:81], v72, s14, v[26:27]
	v_mad_i64_i32 v[74:75], s[80:81], v74, s14, v[26:27]
	v_mad_i64_i32 v[76:77], s[80:81], v76, s14, v[26:27]
	v_mad_i64_i32 v[78:79], s[80:81], v78, s14, v[26:27]
	v_mad_i64_i32 v[80:81], s[80:81], v80, s14, v[26:27]
	v_mad_i64_i32 v[82:83], s[80:81], v82, s14, v[26:27]
	v_mad_i64_i32 v[84:85], s[80:81], v84, s14, v[26:27]
	flat_load_dword v93, v[70:71] nt
	flat_load_dword v94, v[72:73] nt
	flat_load_dword v95, v[74:75] nt
	flat_load_dword v96, v[76:77] nt
	flat_load_dword v97, v[78:79] nt
	flat_load_dword v98, v[80:81] nt
	flat_load_dword v99, v[82:83] nt
	flat_load_dword v100, v[84:85] nt
	v_or_b32_e32 v70, 32, v4
	v_or_b32_e32 v72, 34, v4
	v_or_b32_e32 v74, 36, v4
	v_or_b32_e32 v76, 38, v4
	v_or_b32_e32 v78, 40, v4
	v_or_b32_e32 v80, 42, v4
	v_or_b32_e32 v82, 44, v4
	v_or_b32_e32 v84, 46, v4
	v_mad_i64_i32 v[70:71], s[80:81], v70, s14, v[26:27]
	v_mad_i64_i32 v[72:73], s[80:81], v72, s14, v[26:27]
	v_mad_i64_i32 v[74:75], s[80:81], v74, s14, v[26:27]
	v_mad_i64_i32 v[76:77], s[80:81], v76, s14, v[26:27]
	v_mad_i64_i32 v[78:79], s[80:81], v78, s14, v[26:27]
	v_mad_i64_i32 v[80:81], s[80:81], v80, s14, v[26:27]
	v_mad_i64_i32 v[82:83], s[80:81], v82, s14, v[26:27]
	v_mad_i64_i32 v[84:85], s[80:81], v84, s14, v[26:27]
	flat_load_dword v101, v[70:71] nt
	flat_load_dword v102, v[72:73] nt
	flat_load_dword v103, v[74:75] nt
	flat_load_dword v104, v[76:77] nt
	flat_load_dword v105, v[78:79] nt
	flat_load_dword v106, v[80:81] nt
	flat_load_dword v107, v[82:83] nt
	s_nop 0
	flat_load_dword v84, v[84:85] nt
	v_or_b32_e32 v70, 48, v4
	v_or_b32_e32 v72, 50, v4
	v_or_b32_e32 v74, 52, v4
	v_or_b32_e32 v76, 54, v4
	v_or_b32_e32 v78, 56, v4
	v_or_b32_e32 v80, 58, v4
	v_or_b32_e32 v82, 60, v4
	v_or_b32_e32 v4, 62, v4
	v_mad_i64_i32 v[70:71], s[80:81], v70, s14, v[26:27]
	v_mad_i64_i32 v[72:73], s[80:81], v72, s14, v[26:27]
	v_mad_i64_i32 v[74:75], s[80:81], v74, s14, v[26:27]
	v_mad_i64_i32 v[76:77], s[80:81], v76, s14, v[26:27]
	v_mad_i64_i32 v[78:79], s[80:81], v78, s14, v[26:27]
	v_mad_i64_i32 v[80:81], s[80:81], v80, s14, v[26:27]
	v_mad_i64_i32 v[82:83], s[80:81], v82, s14, v[26:27]
	v_mad_i64_i32 v[26:27], s[80:81], v4, s14, v[26:27]
	flat_load_dword v4, v[70:71] nt
	s_nop 0
	flat_load_dword v70, v[72:73] nt
	flat_load_dword v71, v[74:75] nt
	s_nop 0
	flat_load_dword v72, v[76:77] nt
	flat_load_dword v73, v[78:79] nt
	flat_load_dword v74, v[80:81] nt
	flat_load_dword v75, v[82:83] nt
	s_nop 0
	flat_load_dword v26, v[26:27] nt
	v_add_u32_e32 v27, 0x400, v62
	s_waitcnt vmcnt(0) lgkmcnt(0)
; #define LAS __attribute__((address_space(3)))
; __device__ __forceinline__ unsigned cvt_pk_bf16(float lo, float hi) { unsigned r; asm volatile("s_nop 1\n\tv_cvt_pk_bf16_f32 %0, %1, %2" : "=v"(r) : "v"(lo), "v"(hi)); return r; }
; template <int MAP>
; __device__ __forceinline__ void p0_transpose_item(const float* W, int K, int Nsrc, int rows, bf16_t* WT, LAS float* scr, int item, int lane) {
;     ...
;     for (int i = 0; i < 32; ++i) scr[(2 * i + (lane >> 5)) * 33 + (lane & 31)] = tv[i];
;     asm volatile("s_waitcnt lgkmcnt(0)" ::: "memory");
;     const int c = lane & 7;
; #pragma unroll
;     for (int jj = 0; jj < 4; ++jj) { const int n = (lane >> 3) + 8 * jj; const LAS float* s = scr + (8 * c) * 33 + n;
;         u32x4 o; o.x = cvt_pk_bf16(s[0 * 33], s[1 * 33]); o.y = cvt_pk_bf16(s[2 * 33], s[3 * 33]); o.z = cvt_pk_bf16(s[4 * 33], s[5 * 33]); o.w = cvt_pk_bf16(s[6 * 33], s[7 * 33]);
;         *(u32x4*)(WT + (size_t)(n0 + n) * K + k0 + 8 * c) = o; }
;     asm volatile("s_waitcnt lgkmcnt(0)" ::: "memory");
	ds_write2_b32 v62, v69, v86 offset1:66
	ds_write2_b32 v62, v87, v88 offset0:132 offset1:198
	ds_write2_b32 v27, v89, v90 offset0:8 offset1:74
	ds_write2_b32 v27, v91, v92 offset0:140 offset1:206
	v_add_u32_e32 v27, 0x800, v62
	ds_write2_b32 v27, v93, v94 offset0:16 offset1:82
	ds_write2_b32 v27, v95, v96 offset0:148 offset1:214
	v_add_u32_e32 v27, 0xc00, v62
	ds_write2_b32 v27, v97, v98 offset0:24 offset1:90
	ds_write2_b32 v27, v99, v100 offset0:156 offset1:222
	v_add_u32_e32 v27, 0x1000, v62
	ds_write2_b32 v27, v101, v102 offset0:32 offset1:98
	ds_write2_b32 v27, v103, v104 offset0:164 offset1:230
	v_add_u32_e32 v27, 0x1400, v62
	ds_write2_b32 v27, v105, v106 offset0:40 offset1:106
	ds_write2_b32 v27, v107, v84 offset0:172 offset1:238
	v_add_u32_e32 v27, 0x1800, v62
	ds_write2_b32 v27, v4, v70 offset0:48 offset1:114
	ds_write2_b32 v27, v71, v72 offset0:180 offset1:246
	v_add_u32_e32 v4, 0x1c00, v62
	ds_write2_b32 v4, v73, v74 offset0:56 offset1:122
	ds_write2_b32 v4, v75, v26 offset0:188 offset1:254
	s_waitcnt lgkmcnt(0)
	ds_read2_b32 v[26:27], v63 offset1:33
	s_waitcnt lgkmcnt(0)
	s_nop 1
	v_cvt_pk_bf16_f32 v70, v26, v27
	ds_read2_b32 v[26:27], v63 offset0:66 offset1:99
	s_waitcnt lgkmcnt(0)
	s_nop 1
	v_cvt_pk_bf16_f32 v71, v26, v27
	ds_read2_b32 v[26:27], v63 offset0:132 offset1:165
	s_waitcnt lgkmcnt(0)
	s_nop 1
	v_cvt_pk_bf16_f32 v72, v26, v27
	ds_read2_b32 v[26:27], v63 offset0:198 offset1:231
	s_waitcnt lgkmcnt(0)
	s_nop 1
	v_cvt_pk_bf16_f32 v73, v26, v27
	v_add_u32_e32 v26, s79, v29
	s_ashr_i32 s13, s12, 31
	v_ashrrev_i32_e32 v27, 31, v26
	v_lshl_add_u64 v[74:75], s[12:13], 1, v[6:7]
	v_lshlrev_b64 v[76:77], 12, v[26:27]
	v_lshl_add_u64 v[76:77], v[74:75], 0, v[76:77]
	flat_store_dwordx4 v[76:77], v[70:73]
	ds_read2_b32 v[70:71], v63 offset0:8 offset1:41
	s_waitcnt lgkmcnt(0)
	s_nop 1
	v_cvt_pk_bf16_f32 v70, v70, v71
	ds_read2_b32 v[72:73], v63 offset0:74 offset1:107
	s_waitcnt lgkmcnt(0)
	s_nop 1
	v_cvt_pk_bf16_f32 v71, v72, v73
	ds_read2_b32 v[72:73], v63 offset0:140 offset1:173
	s_waitcnt lgkmcnt(0)
	s_nop 1
	v_cvt_pk_bf16_f32 v72, v72, v73
	ds_read2_b32 v[76:77], v63 offset0:206 offset1:239
	s_waitcnt lgkmcnt(0)
	s_nop 1
	v_cvt_pk_bf16_f32 v73, v76, v77
	v_add_u32_e32 v76, 8, v26
	v_ashrrev_i32_e32 v77, 31, v76
	v_lshlrev_b64 v[76:77], 12, v[76:77]
	v_lshl_add_u64 v[76:77], v[74:75], 0, v[76:77]
	flat_store_dwordx4 v[76:77], v[70:73]
	ds_read2_b32 v[70:71], v63 offset0:16 offset1:49
	s_waitcnt lgkmcnt(0)
	s_nop 1
	v_cvt_pk_bf16_f32 v70, v70, v71
	ds_read2_b32 v[72:73], v63 offset0:82 offset1:115
	s_waitcnt lgkmcnt(0)
	s_nop 1
	v_cvt_pk_bf16_f32 v71, v72, v73
	ds_read2_b32 v[72:73], v63 offset0:148 offset1:181
	s_waitcnt lgkmcnt(0)
	s_nop 1
	v_cvt_pk_bf16_f32 v72, v72, v73
	ds_read2_b32 v[76:77], v63 offset0:214 offset1:247
	s_waitcnt lgkmcnt(0)
	s_nop 1
	v_cvt_pk_bf16_f32 v73, v76, v77
	v_add_u32_e32 v76, 16, v26
	v_ashrrev_i32_e32 v77, 31, v76
	v_lshlrev_b64 v[76:77], 12, v[76:77]
	v_lshl_add_u64 v[76:77], v[74:75], 0, v[76:77]
	flat_store_dwordx4 v[76:77], v[70:73]
	v_add_u32_e32 v26, 24, v26
	ds_read2_b32 v[70:71], v63 offset0:24 offset1:57
	v_ashrrev_i32_e32 v27, 31, v26
	s_waitcnt lgkmcnt(0)
	s_nop 1
	v_cvt_pk_bf16_f32 v70, v70, v71
	ds_read2_b32 v[72:73], v63 offset0:90 offset1:123
	v_lshlrev_b64 v[26:27], 12, v[26:27]
	s_waitcnt lgkmcnt(0)
	s_nop 1
	v_cvt_pk_bf16_f32 v71, v72, v73
	ds_read2_b32 v[72:73], v63 offset0:156 offset1:189
	v_lshl_add_u64 v[26:27], v[74:75], 0, v[26:27]
	s_waitcnt lgkmcnt(0)
	s_nop 1
	v_cvt_pk_bf16_f32 v72, v72, v73
	ds_read2_b32 v[76:77], v63 offset0:222 offset1:255
	s_waitcnt lgkmcnt(0)
	s_nop 1
	v_cvt_pk_bf16_f32 v73, v76, v77
	flat_store_dwordx4 v[26:27], v[70:73]
	s_waitcnt lgkmcnt(0)
	s_branch .LBB0_11

; __device__ __forceinline__ unsigned cvt_pk_bf16(float lo, float hi) { unsigned r; asm volatile("s_nop 1\n\tv_cvt_pk_bf16_f32 %0, %1, %2" : "=v"(r) : "v"(lo), "v"(hi)); return r; }
; #define ARG(T, i) ((T)ldptr(lds, (i)))
; __global__ void __launch_bounds__(512, 2) fwd_megakernel(Args a) {
;     ...
;         for (int ch = gw; ch < M + M / 8; ch += NGW) {
;             const float* src = ch < M ? ARG(const float*, 0) + (size_t)ch * 2048 : ARG(const float*, 1) + (size_t)(ch - M) * 2048;
;             bf16_t* dst = ch < M ? HB + (size_t)ch * 2048 : PB + (size_t)(ch - M) * 2048;
;             f32x4 v[8];
; #pragma unroll
;             for (int j = 0; j < 8; ++j) v[j] = *((const f32x4*)src + lane + 64 * j);
; #pragma unroll
;             for (int j = 0; j < 8; ++j) { u32x2 wv; wv.x = cvt_pk_bf16(v[j][0], v[j][1]); wv.y = cvt_pk_bf16(v[j][2], v[j][3]); *((u32x2*)dst + lane + 64 * j) = wv; }
;         }
.LBB0_74:
	s_lshl_b64 s[18:19], s[18:19], 13
	s_add_u32 s16, s16, s18
	s_addc_u32 s17, s17, s19
	v_lshl_add_u64 v[24:25], s[16:17], 0, v[4:5]
	flat_load_dwordx4 v[8:11], v[24:25] nt
	flat_load_dwordx4 v[12:15], v[24:25] offset:1024 nt
	flat_load_dwordx4 v[16:19], v[24:25] offset:2048 nt
	flat_load_dwordx4 v[20:23], v[24:25] offset:3072 nt
	v_add_co_u32_e32 v42, vcc, s27, v24
	s_and_b64 s[10:11], s[10:11], exec
	s_nop 0
	v_addc_co_u32_e32 v43, vcc, 0, v25, vcc
	flat_load_dwordx4 v[24:27], v[42:43] nt
	flat_load_dwordx4 v[30:33], v[42:43] offset:1024 nt
	flat_load_dwordx4 v[34:37], v[42:43] offset:2048 nt
	flat_load_dwordx4 v[38:41], v[42:43] offset:3072 nt
	s_cselect_b32 s11, s13, s5
	s_cselect_b32 s10, s12, s4
	s_add_u32 s4, s8, s14
	s_addc_u32 s12, s9, s15
	s_lshl_b64 s[10:11], s[10:11], 12
	s_add_u32 s10, s4, s10
	s_addc_u32 s11, s12, s11
	v_lshl_add_u64 v[42:43], s[10:11], 0, v[6:7]
	s_add_u32 s0, s0, s58
	s_addc_u32 s1, s1, s22
	s_cmp_gt_i32 s0, 0x8fff
	s_waitcnt vmcnt(0) lgkmcnt(0)
	s_nop 1
	v_cvt_pk_bf16_f32 v8, v8, v9
	s_nop 1
	v_cvt_pk_bf16_f32 v9, v10, v11
	flat_store_dwordx2 v[42:43], v[8:9]
	s_nop 1
	v_cvt_pk_bf16_f32 v8, v12, v13
	s_nop 1
	v_cvt_pk_bf16_f32 v9, v14, v15
	flat_store_dwordx2 v[42:43], v[8:9] offset:512
	s_nop 1
	v_cvt_pk_bf16_f32 v8, v16, v17
	s_nop 1
	v_cvt_pk_bf16_f32 v9, v18, v19
	flat_store_dwordx2 v[42:43], v[8:9] offset:1024
	s_nop 1
	v_cvt_pk_bf16_f32 v8, v20, v21
	s_nop 1
	v_cvt_pk_bf16_f32 v9, v22, v23
	flat_store_dwordx2 v[42:43], v[8:9] offset:1536
	s_nop 1
	v_cvt_pk_bf16_f32 v8, v24, v25
	s_nop 1
	v_cvt_pk_bf16_f32 v9, v26, v27
	flat_store_dwordx2 v[42:43], v[8:9] offset:2048
	s_nop 1
	v_cvt_pk_bf16_f32 v8, v30, v31
	s_nop 1
	v_cvt_pk_bf16_f32 v9, v32, v33
	flat_store_dwordx2 v[42:43], v[8:9] offset:2560
	s_nop 1
	v_cvt_pk_bf16_f32 v8, v34, v35
	s_nop 1
	v_cvt_pk_bf16_f32 v9, v36, v37
	flat_store_dwordx2 v[42:43], v[8:9] offset:3072
	s_nop 1
	v_cvt_pk_bf16_f32 v8, v38, v39
	s_nop 1
	v_cvt_pk_bf16_f32 v9, v40, v41
	flat_store_dwordx2 v[42:43], v[8:9] offset:3584
	s_cbranch_scc1 .LBB0_79

; __global__ void __launch_bounds__(512, 2) fwd_megakernel(Args a) {
;     ...
;         for (int row = gw; row < M; row += NGW) {
;             const float ang = (float)posp[row] * invr[lane]; float c, s; sincos_rev(ang, c, s);
;             COSR[(size_t)row * 64 + lane] = c; SINR[(size_t)row * 64 + lane] = s;
;         }
.LBB0_81:
	v_mov_b64_e32 v[6:7], s[4:5]
	flat_load_dword v5, v[6:7] nt
	ds_read_b32 v8, v4
	s_add_i32 s14, s14, s58
	s_add_u32 s4, s4, s10
	v_add_co_u32_e32 v6, vcc, 0x800000, v2
	s_addc_u32 s5, s5, s11
	s_nop 0
	v_addc_co_u32_e32 v7, vcc, 0, v3, vcc
	s_cmpk_gt_i32 s14, 0x7fff
	s_waitcnt vmcnt(0) lgkmcnt(0)
	v_cvt_f32_i32_e32 v5, v5
	v_mul_f32_e32 v5, v8, v5
	v_cvt_f64_f32_e32 v[8:9], v5
	v_mul_f64 v[10:11], v[8:9], s[12:13]
	v_rndne_f64_e32 v[10:11], v[10:11]
	v_fma_f64 v[8:9], v[8:9], s[12:13], -v[10:11]
	v_cvt_f32_f64_e32 v5, v[8:9]
	v_cos_f32_e32 v8, v5
	v_sin_f32_e32 v5, v5
	flat_store_dword v[2:3], v8
	flat_store_dword v[6:7], v5
	v_lshl_add_u64 v[2:3], v[2:3], 0, s[0:1]
	s_cbranch_scc0 .LBB0_81

; __global__ void __launch_bounds__(512, 2) fwd_megakernel(Args a) {
;     ...
;         for (int blk = gw; blk < M / 8; blk += NGW) {
;             const int row = blk * 8 + (lane >> 3), d = lane & 7; float c, s; sincos_rev((float)posp[row] * inva[d], c, s);
;             COSA[(size_t)row * 8 + d] = c; SINA[(size_t)row * 8 + d] = s;
;         }
.LBB0_84:
	v_ashrrev_i32_e32 v5, 31, v4
	v_lshl_add_u64 v[6:7], v[4:5], 2, s[6:7]
	flat_load_dword v6, v[6:7] nt
	ds_read_b32 v8, v3
	s_add_i32 s20, s20, s58
	s_cmpk_gt_i32 s20, 0xfff
	s_waitcnt vmcnt(0) lgkmcnt(0)
	v_cvt_f32_i32_e32 v9, v6
	v_lshlrev_b64 v[6:7], 5, v[4:5]
	v_lshl_or_b32 v6, v2, 2, v6
	v_add_u32_e32 v4, s10, v4
	v_mul_f32_e32 v5, v8, v9
	v_cvt_f64_f32_e32 v[8:9], v5
	v_mul_f64 v[10:11], v[8:9], s[8:9]
	v_rndne_f64_e32 v[10:11], v[10:11]
	v_fma_f64 v[8:9], v[8:9], s[8:9], -v[10:11]
	v_cvt_f32_f64_e32 v5, v[8:9]
	v_cos_f32_e32 v10, v5
	v_sin_f32_e32 v5, v5
	v_lshl_add_u64 v[8:9], s[0:1], 0, v[6:7]
	v_lshl_add_u64 v[6:7], s[4:5], 0, v[6:7]
	flat_store_dword v[8:9], v10
	flat_store_dword v[6:7], v5
	s_cbranch_scc0 .LBB0_84

;     __device__ __forceinline__ void operator()(AccRef acc, const Unit& u, int wr, int wc, int fr, int fq) const {
;     ...
;         for (int ai = 0; ai < 2; ++ai)
; #pragma unroll
;             for (int m = 0; m < 4; ++m) {
;                 const int row = row0 + ai * HALF + m * 16;
;                 const size_t off = (size_t)row * D + col0;
;                 if constexpr (LNRES) {
;                     const f32x2v st = *(const f32x2v*)(stats + 2 * (size_t)row);
;                     const float mean = st.x, rstd = st.y;
; #pragma unroll
;                     for (int bj = 0; bj < 2; ++bj) {
;                         const f32x4 z0 = *(const f32x4*)(res + off + bj * HALF), z1 = *(const f32x4*)(res + off + bj * HALF + 4);
;                         *(f32x4*)(out + off + bj * HALF) = (z0 - mean) * rstd * ga[bj][0] + ba[bj][0] + acc[ai][bj][m][0] * s;
;                         *(f32x4*)(out + off + bj * HALF + 4) = (z1 - mean) * rstd * ga[bj][1] + ba[bj][1] + acc[ai][bj][m][1] * s;
;                     }
;                 } else {
; #pragma unroll
;                     for (int bj = 0; bj < 2; ++bj) {
;                         const f32x4 r0 = *(const f32x4*)(res + off + bj * HALF), r1 = *(const f32x4*)(res + off + bj * HALF + 4);
;                         *(f32x4*)(out + off + bj * HALF) = r0 * alpha + acc[ai][bj][m][0] * s;
;                         *(f32x4*)(out + off + bj * HALF + 4) = r1 * alpha + acc[ai][bj][m][1] * s;
;                     }
.LBB0_225:
	v_mov_b32_e32 v145, v147
	v_mov_b32_e32 v144, v146
	s_lshl_b32 s34, s65, 8
	s_add_i32 s34, s34, s54
	v_add_u32_e32 v144, s34, v144
	s_lshl_b32 s34, s66, 8
	s_or_b32 s34, s34, s55
	v_lshl_add_u32 v152, v145, 3, s34
	v_ashrrev_i32_e32 v145, 31, v144
	v_ashrrev_i32_e32 v153, 31, v152
	v_lshlrev_b64 v[144:145], 11, v[144:145]
	v_lshl_add_u64 v[144:145], v[144:145], 0, v[152:153]
	v_lshlrev_b64 v[144:145], 2, v[144:145]
	s_and_b64 vcc, exec, s[0:1]
	s_mov_b64 s[0:1], -1
	v_lshl_add_u64 v[238:239], s[2:3], 0, v[144:145]
	global_load_dwordx4 v[160:163], v[238:239], off nt
	global_load_dwordx4 v[164:167], v[238:239], off offset:16 nt
	global_load_dwordx4 v[168:171], v[238:239], off offset:512 nt
	global_load_dwordx4 v[172:175], v[238:239], off offset:528 nt
	v_lshl_add_u64 v[224:225], v[144:145], 0, s[18:19]
	v_lshl_add_u64 v[240:241], s[2:3], 0, v[224:225]
	global_load_dwordx4 v[176:179], v[240:241], off nt
	global_load_dwordx4 v[180:183], v[240:241], off offset:16 nt
	global_load_dwordx4 v[184:187], v[240:241], off offset:512 nt
	global_load_dwordx4 v[188:191], v[240:241], off offset:528 nt
	v_lshl_add_u64 v[226:227], v[144:145], 0, s[20:21]
	v_lshl_add_u64 v[242:243], s[2:3], 0, v[226:227]
	global_load_dwordx4 v[192:195], v[242:243], off nt
	global_load_dwordx4 v[196:199], v[242:243], off offset:16 nt
	global_load_dwordx4 v[200:203], v[242:243], off offset:512 nt
	global_load_dwordx4 v[204:207], v[242:243], off offset:528 nt
	v_lshl_add_u64 v[228:229], v[144:145], 0, s[22:23]
	v_lshl_add_u64 v[244:245], s[2:3], 0, v[228:229]
	global_load_dwordx4 v[208:211], v[244:245], off nt
	global_load_dwordx4 v[212:215], v[244:245], off offset:16 nt
	global_load_dwordx4 v[216:219], v[244:245], off offset:512 nt
	global_load_dwordx4 v[220:223], v[244:245], off offset:528 nt
	v_lshl_add_u64 v[152:153], s[6:7], 0, v[144:145]
	s_waitcnt vmcnt(12)
	v_pk_mul_f32 v[162:163], v[162:163], s[16:17] op_sel_hi:[1,0]
	v_pk_mul_f32 v[160:161], v[160:161], s[16:17] op_sel_hi:[1,0]
	v_pk_mul_f32 v[166:167], v[166:167], s[16:17] op_sel_hi:[1,0]
	v_pk_mul_f32 v[164:165], v[164:165], s[16:17] op_sel_hi:[1,0]
	v_pk_mul_f32 v[170:171], v[170:171], s[16:17] op_sel_hi:[1,0]
	v_pk_mul_f32 v[168:169], v[168:169], s[16:17] op_sel_hi:[1,0]
	v_pk_mul_f32 v[174:175], v[174:175], s[16:17] op_sel_hi:[1,0]
	v_pk_mul_f32 v[172:173], v[172:173], s[16:17] op_sel_hi:[1,0]
	v_pk_fma_f32 v[126:127], v[126:127], 0.5, v[162:163] op_sel_hi:[1,0,1]
	v_pk_fma_f32 v[124:125], v[124:125], 0.5, v[160:161] op_sel_hi:[1,0,1]
	v_pk_fma_f32 v[122:123], v[122:123], 0.5, v[166:167] op_sel_hi:[1,0,1]
	v_pk_fma_f32 v[120:121], v[120:121], 0.5, v[164:165] op_sel_hi:[1,0,1]
	v_pk_fma_f32 v[118:119], v[118:119], 0.5, v[170:171] op_sel_hi:[1,0,1]
	v_pk_fma_f32 v[116:117], v[116:117], 0.5, v[168:169] op_sel_hi:[1,0,1]
	v_pk_fma_f32 v[110:111], v[110:111], 0.5, v[174:175] op_sel_hi:[1,0,1]
	v_pk_fma_f32 v[108:109], v[108:109], 0.5, v[172:173] op_sel_hi:[1,0,1]
	global_store_dwordx4 v[152:153], v[124:127], off
	global_store_dwordx4 v[152:153], v[120:123], off offset:16
	global_store_dwordx4 v[152:153], v[116:119], off offset:512
	global_store_dwordx4 v[152:153], v[108:111], off offset:528
	v_lshl_add_u64 v[230:231], v[144:145], 0, s[24:25]
	v_lshl_add_u64 v[246:247], s[2:3], 0, v[230:231]
	global_load_dwordx4 v[160:163], v[246:247], off nt
	global_load_dwordx4 v[164:167], v[246:247], off offset:16 nt
	global_load_dwordx4 v[168:171], v[246:247], off offset:512 nt
	global_load_dwordx4 v[172:175], v[246:247], off offset:528 nt
	v_lshl_add_u64 v[154:155], s[6:7], 0, v[224:225]
	s_waitcnt vmcnt(16)
	v_pk_mul_f32 v[178:179], v[178:179], s[16:17] op_sel_hi:[1,0]
	v_pk_mul_f32 v[176:177], v[176:177], s[16:17] op_sel_hi:[1,0]
	v_pk_mul_f32 v[182:183], v[182:183], s[16:17] op_sel_hi:[1,0]
	v_pk_mul_f32 v[180:181], v[180:181], s[16:17] op_sel_hi:[1,0]
	v_pk_mul_f32 v[186:187], v[186:187], s[16:17] op_sel_hi:[1,0]
	v_pk_mul_f32 v[184:185], v[184:185], s[16:17] op_sel_hi:[1,0]
	v_pk_mul_f32 v[190:191], v[190:191], s[16:17] op_sel_hi:[1,0]
	v_pk_mul_f32 v[188:189], v[188:189], s[16:17] op_sel_hi:[1,0]
	v_pk_fma_f32 v[114:115], v[114:115], 0.5, v[178:179] op_sel_hi:[1,0,1]
	v_pk_fma_f32 v[112:113], v[112:113], 0.5, v[176:177] op_sel_hi:[1,0,1]
	v_pk_fma_f32 v[106:107], v[106:107], 0.5, v[182:183] op_sel_hi:[1,0,1]
	v_pk_fma_f32 v[104:105], v[104:105], 0.5, v[180:181] op_sel_hi:[1,0,1]
	v_pk_fma_f32 v[102:103], v[102:103], 0.5, v[186:187] op_sel_hi:[1,0,1]
	v_pk_fma_f32 v[100:101], v[100:101], 0.5, v[184:185] op_sel_hi:[1,0,1]
	v_pk_fma_f32 v[94:95], v[94:95], 0.5, v[190:191] op_sel_hi:[1,0,1]
	v_pk_fma_f32 v[92:93], v[92:93], 0.5, v[188:189] op_sel_hi:[1,0,1]
	global_store_dwordx4 v[154:155], v[112:115], off
	global_store_dwordx4 v[154:155], v[104:107], off offset:16
	global_store_dwordx4 v[154:155], v[100:103], off offset:512
	global_store_dwordx4 v[154:155], v[92:95], off offset:528
	v_lshl_add_u64 v[232:233], v[144:145], 0, s[26:27]
	v_lshl_add_u64 v[248:249], s[2:3], 0, v[232:233]
	global_load_dwordx4 v[176:179], v[248:249], off nt
	global_load_dwordx4 v[180:183], v[248:249], off offset:16 nt
	global_load_dwordx4 v[184:187], v[248:249], off offset:512 nt
	global_load_dwordx4 v[188:191], v[248:249], off offset:528 nt
	v_lshl_add_u64 v[152:153], s[6:7], 0, v[226:227]
	s_waitcnt vmcnt(20)
;     __device__ __forceinline__ void operator()(AccRef acc, const Unit& u, int wr, int wc, int fr, int fq) const {
;     ...
; #pragma unroll
;                     for (int bj = 0; bj < 2; ++bj) {
;                         const f32x4 r0 = *(const f32x4*)(res + off + bj * HALF), r1 = *(const f32x4*)(res + off + bj * HALF + 4);
;                         *(f32x4*)(out + off + bj * HALF) = r0 * alpha + acc[ai][bj][m][0] * s;
;                         *(f32x4*)(out + off + bj * HALF + 4) = r1 * alpha + acc[ai][bj][m][1] * s;
;                     }
	v_pk_mul_f32 v[194:195], v[194:195], s[16:17] op_sel_hi:[1,0]
	v_pk_mul_f32 v[192:193], v[192:193], s[16:17] op_sel_hi:[1,0]
	v_pk_mul_f32 v[198:199], v[198:199], s[16:17] op_sel_hi:[1,0]
	v_pk_mul_f32 v[196:197], v[196:197], s[16:17] op_sel_hi:[1,0]
	v_pk_mul_f32 v[202:203], v[202:203], s[16:17] op_sel_hi:[1,0]
	v_pk_mul_f32 v[200:201], v[200:201], s[16:17] op_sel_hi:[1,0]
	v_pk_mul_f32 v[206:207], v[206:207], s[16:17] op_sel_hi:[1,0]
	v_pk_mul_f32 v[204:205], v[204:205], s[16:17] op_sel_hi:[1,0]
	v_pk_fma_f32 v[98:99], v[98:99], 0.5, v[194:195] op_sel_hi:[1,0,1]
	v_pk_fma_f32 v[96:97], v[96:97], 0.5, v[192:193] op_sel_hi:[1,0,1]
	v_pk_fma_f32 v[90:91], v[90:91], 0.5, v[198:199] op_sel_hi:[1,0,1]
	v_pk_fma_f32 v[88:89], v[88:89], 0.5, v[196:197] op_sel_hi:[1,0,1]
	v_pk_fma_f32 v[86:87], v[86:87], 0.5, v[202:203] op_sel_hi:[1,0,1]
	v_pk_fma_f32 v[84:85], v[84:85], 0.5, v[200:201] op_sel_hi:[1,0,1]
	v_pk_fma_f32 v[78:79], v[78:79], 0.5, v[206:207] op_sel_hi:[1,0,1]
	v_pk_fma_f32 v[76:77], v[76:77], 0.5, v[204:205] op_sel_hi:[1,0,1]
	global_store_dwordx4 v[152:153], v[96:99], off
	global_store_dwordx4 v[152:153], v[88:91], off offset:16
	global_store_dwordx4 v[152:153], v[84:87], off offset:512
	global_store_dwordx4 v[152:153], v[76:79], off offset:528
	v_lshl_add_u64 v[234:235], v[144:145], 0, s[28:29]
	v_lshl_add_u64 v[250:251], s[2:3], 0, v[234:235]
	global_load_dwordx4 v[192:195], v[250:251], off nt
	global_load_dwordx4 v[196:199], v[250:251], off offset:16 nt
	global_load_dwordx4 v[200:203], v[250:251], off offset:512 nt
	global_load_dwordx4 v[204:207], v[250:251], off offset:528 nt
	v_lshl_add_u64 v[154:155], s[6:7], 0, v[228:229]
	s_waitcnt vmcnt(24)
	v_pk_mul_f32 v[210:211], v[210:211], s[16:17] op_sel_hi:[1,0]
	v_pk_mul_f32 v[208:209], v[208:209], s[16:17] op_sel_hi:[1,0]
	v_pk_mul_f32 v[214:215], v[214:215], s[16:17] op_sel_hi:[1,0]
	v_pk_mul_f32 v[212:213], v[212:213], s[16:17] op_sel_hi:[1,0]
	v_pk_mul_f32 v[218:219], v[218:219], s[16:17] op_sel_hi:[1,0]
	v_pk_mul_f32 v[216:217], v[216:217], s[16:17] op_sel_hi:[1,0]
	v_pk_mul_f32 v[222:223], v[222:223], s[16:17] op_sel_hi:[1,0]
	v_pk_mul_f32 v[220:221], v[220:221], s[16:17] op_sel_hi:[1,0]
	v_pk_fma_f32 v[82:83], v[82:83], 0.5, v[210:211] op_sel_hi:[1,0,1]
	v_pk_fma_f32 v[80:81], v[80:81], 0.5, v[208:209] op_sel_hi:[1,0,1]
	v_pk_fma_f32 v[74:75], v[74:75], 0.5, v[214:215] op_sel_hi:[1,0,1]
	v_pk_fma_f32 v[72:73], v[72:73], 0.5, v[212:213] op_sel_hi:[1,0,1]
	v_pk_fma_f32 v[70:71], v[70:71], 0.5, v[218:219] op_sel_hi:[1,0,1]
	v_pk_fma_f32 v[68:69], v[68:69], 0.5, v[216:217] op_sel_hi:[1,0,1]
	v_pk_fma_f32 v[66:67], v[66:67], 0.5, v[222:223] op_sel_hi:[1,0,1]
	v_pk_fma_f32 v[64:65], v[64:65], 0.5, v[220:221] op_sel_hi:[1,0,1]
	global_store_dwordx4 v[154:155], v[80:83], off
	global_store_dwordx4 v[154:155], v[72:75], off offset:16
	global_store_dwordx4 v[154:155], v[68:71], off offset:512
	global_store_dwordx4 v[154:155], v[64:67], off offset:528
	v_lshl_add_u64 v[236:237], v[144:145], 0, s[8:9]
	v_lshl_add_u64 v[252:253], s[2:3], 0, v[236:237]
	global_load_dwordx4 v[208:211], v[252:253], off nt
	global_load_dwordx4 v[212:215], v[252:253], off offset:16 nt
	global_load_dwordx4 v[216:219], v[252:253], off offset:512 nt
	global_load_dwordx4 v[220:223], v[252:253], off offset:528 nt
	v_lshl_add_u64 v[152:153], s[6:7], 0, v[230:231]
	s_waitcnt vmcnt(24)
	v_pk_mul_f32 v[162:163], v[162:163], s[16:17] op_sel_hi:[1,0]
	v_pk_mul_f32 v[160:161], v[160:161], s[16:17] op_sel_hi:[1,0]
	v_pk_mul_f32 v[166:167], v[166:167], s[16:17] op_sel_hi:[1,0]
	v_pk_mul_f32 v[164:165], v[164:165], s[16:17] op_sel_hi:[1,0]
	v_pk_mul_f32 v[170:171], v[170:171], s[16:17] op_sel_hi:[1,0]
	v_pk_mul_f32 v[168:169], v[168:169], s[16:17] op_sel_hi:[1,0]
	v_pk_mul_f32 v[174:175], v[174:175], s[16:17] op_sel_hi:[1,0]
	v_pk_mul_f32 v[172:173], v[172:173], s[16:17] op_sel_hi:[1,0]
	v_pk_fma_f32 v[62:63], v[62:63], 0.5, v[162:163] op_sel_hi:[1,0,1]
	v_pk_fma_f32 v[60:61], v[60:61], 0.5, v[160:161] op_sel_hi:[1,0,1]
	v_pk_fma_f32 v[58:59], v[58:59], 0.5, v[166:167] op_sel_hi:[1,0,1]
	v_pk_fma_f32 v[56:57], v[56:57], 0.5, v[164:165] op_sel_hi:[1,0,1]
	v_pk_fma_f32 v[54:55], v[54:55], 0.5, v[170:171] op_sel_hi:[1,0,1]
	v_pk_fma_f32 v[52:53], v[52:53], 0.5, v[168:169] op_sel_hi:[1,0,1]
	v_pk_fma_f32 v[46:47], v[46:47], 0.5, v[174:175] op_sel_hi:[1,0,1]
	v_pk_fma_f32 v[44:45], v[44:45], 0.5, v[172:173] op_sel_hi:[1,0,1]
	global_store_dwordx4 v[152:153], v[60:63], off
	global_store_dwordx4 v[152:153], v[56:59], off offset:16
	global_store_dwordx4 v[152:153], v[52:55], off offset:512
	global_store_dwordx4 v[152:153], v[44:47], off offset:528
	v_lshl_add_u64 v[154:155], s[6:7], 0, v[232:233]
	s_waitcnt vmcnt(20)
; #define PG8_BAR __builtin_amdgcn_s_barrier()
; template <class Epi>
; __device__ __forceinline__ void gemm_phase(ldsp lds, const Gemm g, const StaticOrder& S, const Epi& E, int wave0) {
;     ...
;         cur = nxt; cA = nA; cB = nB; ++ui;
;         if (wr == 1) PG8_BAR;
;     __device__ __forceinline__ void operator()(AccRef acc, const Unit& u, int wr, int wc, int fr, int fq) const {
;     ...
;                     for (int bj = 0; bj < 2; ++bj) {
;                         const f32x4 r0 = *(const f32x4*)(res + off + bj * HALF), r1 = *(const f32x4*)(res + off + bj * HALF + 4);
;                         *(f32x4*)(out + off + bj * HALF) = r0 * alpha + acc[ai][bj][m][0] * s;
;                         *(f32x4*)(out + off + bj * HALF + 4) = r1 * alpha + acc[ai][bj][m][1] * s;
;                     }
	v_pk_mul_f32 v[178:179], v[178:179], s[16:17] op_sel_hi:[1,0]
	v_pk_mul_f32 v[176:177], v[176:177], s[16:17] op_sel_hi:[1,0]
	v_pk_mul_f32 v[182:183], v[182:183], s[16:17] op_sel_hi:[1,0]
	v_pk_mul_f32 v[180:181], v[180:181], s[16:17] op_sel_hi:[1,0]
	v_pk_mul_f32 v[186:187], v[186:187], s[16:17] op_sel_hi:[1,0]
	v_pk_mul_f32 v[184:185], v[184:185], s[16:17] op_sel_hi:[1,0]
	v_pk_mul_f32 v[190:191], v[190:191], s[16:17] op_sel_hi:[1,0]
	v_pk_mul_f32 v[188:189], v[188:189], s[16:17] op_sel_hi:[1,0]
	v_pk_fma_f32 v[50:51], v[50:51], 0.5, v[178:179] op_sel_hi:[1,0,1]
	v_pk_fma_f32 v[48:49], v[48:49], 0.5, v[176:177] op_sel_hi:[1,0,1]
	v_pk_fma_f32 v[42:43], v[42:43], 0.5, v[182:183] op_sel_hi:[1,0,1]
	v_pk_fma_f32 v[40:41], v[40:41], 0.5, v[180:181] op_sel_hi:[1,0,1]
	v_pk_fma_f32 v[38:39], v[38:39], 0.5, v[186:187] op_sel_hi:[1,0,1]
	v_pk_fma_f32 v[36:37], v[36:37], 0.5, v[184:185] op_sel_hi:[1,0,1]
	v_pk_fma_f32 v[30:31], v[30:31], 0.5, v[190:191] op_sel_hi:[1,0,1]
	v_pk_fma_f32 v[28:29], v[28:29], 0.5, v[188:189] op_sel_hi:[1,0,1]
	global_store_dwordx4 v[154:155], v[48:51], off
	global_store_dwordx4 v[154:155], v[40:43], off offset:16
	global_store_dwordx4 v[154:155], v[36:39], off offset:512
	global_store_dwordx4 v[154:155], v[28:31], off offset:528
	v_lshl_add_u64 v[152:153], s[6:7], 0, v[234:235]
	s_waitcnt vmcnt(16)
	v_pk_mul_f32 v[194:195], v[194:195], s[16:17] op_sel_hi:[1,0]
	v_pk_mul_f32 v[192:193], v[192:193], s[16:17] op_sel_hi:[1,0]
	v_pk_mul_f32 v[198:199], v[198:199], s[16:17] op_sel_hi:[1,0]
	v_pk_mul_f32 v[196:197], v[196:197], s[16:17] op_sel_hi:[1,0]
	v_pk_mul_f32 v[202:203], v[202:203], s[16:17] op_sel_hi:[1,0]
	v_pk_mul_f32 v[200:201], v[200:201], s[16:17] op_sel_hi:[1,0]
	v_pk_mul_f32 v[206:207], v[206:207], s[16:17] op_sel_hi:[1,0]
	v_pk_mul_f32 v[204:205], v[204:205], s[16:17] op_sel_hi:[1,0]
	v_pk_fma_f32 v[34:35], v[34:35], 0.5, v[194:195] op_sel_hi:[1,0,1]
	v_pk_fma_f32 v[32:33], v[32:33], 0.5, v[192:193] op_sel_hi:[1,0,1]
	v_pk_fma_f32 v[26:27], v[26:27], 0.5, v[198:199] op_sel_hi:[1,0,1]
	v_pk_fma_f32 v[24:25], v[24:25], 0.5, v[196:197] op_sel_hi:[1,0,1]
	v_pk_fma_f32 v[22:23], v[22:23], 0.5, v[202:203] op_sel_hi:[1,0,1]
	v_pk_fma_f32 v[20:21], v[20:21], 0.5, v[200:201] op_sel_hi:[1,0,1]
	v_pk_fma_f32 v[14:15], v[14:15], 0.5, v[206:207] op_sel_hi:[1,0,1]
	v_pk_fma_f32 v[12:13], v[12:13], 0.5, v[204:205] op_sel_hi:[1,0,1]
	global_store_dwordx4 v[152:153], v[32:35], off
	global_store_dwordx4 v[152:153], v[24:27], off offset:16
	global_store_dwordx4 v[152:153], v[20:23], off offset:512
	global_store_dwordx4 v[152:153], v[12:15], off offset:528
	v_lshl_add_u64 v[154:155], s[6:7], 0, v[236:237]
	s_waitcnt vmcnt(12)
	v_pk_mul_f32 v[210:211], v[210:211], s[16:17] op_sel_hi:[1,0]
	v_pk_mul_f32 v[208:209], v[208:209], s[16:17] op_sel_hi:[1,0]
	v_pk_mul_f32 v[214:215], v[214:215], s[16:17] op_sel_hi:[1,0]
	v_pk_mul_f32 v[212:213], v[212:213], s[16:17] op_sel_hi:[1,0]
	v_pk_mul_f32 v[218:219], v[218:219], s[16:17] op_sel_hi:[1,0]
	v_pk_mul_f32 v[216:217], v[216:217], s[16:17] op_sel_hi:[1,0]
	v_pk_mul_f32 v[222:223], v[222:223], s[16:17] op_sel_hi:[1,0]
	v_pk_mul_f32 v[220:221], v[220:221], s[16:17] op_sel_hi:[1,0]
	v_pk_fma_f32 v[18:19], v[18:19], 0.5, v[210:211] op_sel_hi:[1,0,1]
	v_pk_fma_f32 v[16:17], v[16:17], 0.5, v[208:209] op_sel_hi:[1,0,1]
	v_pk_fma_f32 v[10:11], v[10:11], 0.5, v[214:215] op_sel_hi:[1,0,1]
	v_pk_fma_f32 v[8:9], v[8:9], 0.5, v[212:213] op_sel_hi:[1,0,1]
	v_pk_fma_f32 v[6:7], v[6:7], 0.5, v[218:219] op_sel_hi:[1,0,1]
	v_pk_fma_f32 v[4:5], v[4:5], 0.5, v[216:217] op_sel_hi:[1,0,1]
	v_pk_fma_f32 v[2:3], v[2:3], 0.5, v[222:223] op_sel_hi:[1,0,1]
	v_pk_fma_f32 v[0:1], v[0:1], 0.5, v[220:221] op_sel_hi:[1,0,1]
	global_store_dwordx4 v[154:155], v[16:19], off
	global_store_dwordx4 v[154:155], v[8:11], off offset:16
	global_store_dwordx4 v[154:155], v[4:7], off offset:512
	global_store_dwordx4 v[154:155], v[0:3], off offset:528
	s_cbranch_vccnz .LBB0_210
	s_andn2_b64 vcc, exec, s[10:11]
	s_cbranch_vccnz .LBB0_209
	s_barrier
	s_branch .LBB0_209

; __device__ __forceinline__ void ln_phase(float* io, const float* g, const float* b, bf16_t* hb, float* stats, int gw, int NGW, int lane) {
;     ...
;     for (int row = gw; row < M; row += NGW) {
;         f32x4* xr = (f32x4*)(io + (size_t)row * D) + lane;
;         f32x4 v[8]; float s = 0.f;
; #pragma unroll
;         for (int j = 0; j < 8; ++j) { v[j] = xr[64 * j]; s += (v[j][0] + v[j][1]) + (v[j][2] + v[j][3]); }
;         const float mean = wave_sum(s, lane) * (1.f / D); float s2 = 0.f;
; #pragma unroll
;         for (int j = 0; j < 8; ++j) { v[j] = v[j] - mean; s2 += (v[j][0] * v[j][0] + v[j][1] * v[j][1]) + (v[j][2] * v[j][2] + v[j][3] * v[j][3]); }
;         const float rstd = 1.0f / sqrtf(wave_sum(s2, lane) * (1.f / D) + 1e-5f);
.LBB0_275:
	v_add_co_u32_e32 v84, vcc, 0xfffff000, v82
	v_add_co_u32_e64 v86, s[0:1], s3, v82
	s_nop 0
	v_addc_co_u32_e32 v85, vcc, -1, v83, vcc
	v_add_co_u32_e32 v106, vcc, 0xfffff400, v82
	flat_load_dwordx4 v[64:67], v[82:83] nt
	v_addc_co_u32_e64 v87, s[0:1], -1, v83, s[0:1]
	flat_load_dwordx4 v[68:71], v[82:83] offset:1024 nt
	flat_load_dwordx4 v[72:75], v[82:83] offset:2048 nt
	flat_load_dwordx4 v[76:79], v[82:83] offset:3072 nt
	flat_load_dwordx4 v[102:105], v[84:85] nt
	v_addc_co_u32_e32 v107, vcc, -1, v83, vcc
	v_add_co_u32_e64 v88, s[0:1], s10, v82
	flat_load_dwordx4 v[98:101], v[86:87] nt
	s_nop 0
	v_addc_co_u32_e64 v89, s[0:1], -1, v83, s[0:1]
	flat_load_dwordx4 v[106:109], v[106:107] nt
	s_add_i32 s2, s2, s12
	flat_load_dwordx4 v[86:89], v[88:89] nt
	s_cmp_lt_i32 s2, 0x8000
	v_lshl_add_u64 v[82:83], v[82:83], 0, s[6:7]
	s_waitcnt vmcnt(0) lgkmcnt(0)
	v_mov_b32_e32 v111, v66
	v_mov_b32_e32 v113, v67
	v_mov_b32_e32 v114, v69
	v_mov_b32_e32 v115, v70
	v_mov_b32_e32 v116, v68
	v_mov_b32_e32 v117, v71
	v_add_f32_e32 v118, v72, v73
	v_add_f32_e32 v120, v74, v75
	v_mov_b32_e32 v119, v78
	v_mov_b32_e32 v121, v79
	v_pk_add_f32 v[114:115], v[114:115], v[116:117]
	v_pk_add_f32 v[116:117], v[118:119], v[120:121]
	v_mov_b32_e32 v118, v102
	v_mov_b32_e32 v120, v103
	v_mov_b32_e32 v126, v104
	v_mov_b32_e32 v128, v105
	v_mov_b32_e32 v119, v106
	v_mov_b32_e32 v121, v107
	v_mov_b32_e32 v127, v108
	v_mov_b32_e32 v129, v109
	v_mov_b32_e32 v122, v99
	v_mov_b32_e32 v123, v100
	v_mov_b32_e32 v124, v98
	v_mov_b32_e32 v125, v101
	v_pk_add_f32 v[118:119], v[118:119], v[120:121]
	v_pk_add_f32 v[120:121], v[126:127], v[128:129]
	v_add_f32_e32 v110, v86, v87
	v_add_f32_e32 v112, v88, v89
	v_pk_add_f32 v[122:123], v[122:123], v[124:125]
	v_pk_add_f32 v[118:119], v[118:119], v[120:121]
	v_pk_add_f32 v[110:111], v[110:111], v[112:113]
	v_pk_add_f32 v[112:113], v[114:115], v[114:115] op_sel:[0,1] op_sel_hi:[1,0]
	v_pk_add_f32 v[114:115], v[122:123], v[122:123] op_sel:[0,1] op_sel_hi:[1,0]
	v_add_f32_e32 v84, 0, v118
	v_mov_b32_e32 v85, v64
	v_mov_b32_e32 v115, v65
	v_add_f32_e32 v84, v84, v119
	v_pk_add_f32 v[84:85], v[84:85], v[114:115]
	v_mov_b32_e32 v113, v77
	v_pk_add_f32 v[84:85], v[84:85], v[110:111]
	s_nop 0
	v_pk_add_f32 v[84:85], v[84:85], v[84:85] op_sel:[0,1] op_sel_hi:[1,0]
	s_nop 0
	v_mov_b32_e32 v85, v76
	v_pk_add_f32 v[84:85], v[84:85], v[112:113]
	s_nop 0
	v_pk_add_f32 v[84:85], v[84:85], v[116:117]
	s_nop 0
	v_add_f32_e32 v84, v84, v85
	ds_bpermute_b32 v85, v90, v84
	s_waitcnt lgkmcnt(0)
	v_add_f32_e32 v84, v84, v85
	ds_bpermute_b32 v85, v91, v84
	s_waitcnt lgkmcnt(0)
	v_add_f32_e32 v84, v84, v85
	ds_bpermute_b32 v85, v92, v84
	s_waitcnt lgkmcnt(0)
	v_add_f32_e32 v84, v84, v85
	ds_bpermute_b32 v85, v93, v84
	s_waitcnt lgkmcnt(0)
	v_add_f32_e32 v84, v84, v85
	ds_bpermute_b32 v85, v94, v84
	s_waitcnt lgkmcnt(0)
	v_add_f32_e32 v84, v84, v85
	ds_bpermute_b32 v85, v95, v84
	s_waitcnt lgkmcnt(0)
	v_add_f32_e32 v110, v84, v85
	v_fmamk_f32 v85, v110, 0xba000000, v105
	v_fmamk_f32 v103, v110, 0xba000000, v103
	v_fmamk_f32 v105, v110, 0xba000000, v109
	v_fmamk_f32 v107, v110, 0xba000000, v107
	v_fmamk_f32 v84, v110, 0xba000000, v104
	v_fmac_f32_e32 v102, 0xba000000, v110
	v_fmamk_f32 v104, v110, 0xba000000, v108
	v_fmac_f32_e32 v106, 0xba000000, v110
	v_fmamk_f32 v99, v110, 0xba000000, v99
	v_fmamk_f32 v98, v110, 0xba000000, v98
	v_fmamk_f32 v101, v110, 0xba000000, v101
	v_fmac_f32_e32 v100, 0xba000000, v110
	v_fmamk_f32 v87, v110, 0xba000000, v87
	v_fmamk_f32 v86, v110, 0xba000000, v86
	v_fmamk_f32 v89, v110, 0xba000000, v89
	v_fmac_f32_e32 v88, 0xba000000, v110
	v_fmamk_f32 v67, v110, 0xba000000, v67
	v_fmamk_f32 v66, v110, 0xba000000, v66
	v_fmamk_f32 v65, v110, 0xba000000, v65
	v_fmac_f32_e32 v64, 0xba000000, v110
	v_fmamk_f32 v69, v110, 0xba000000, v69
	v_fmamk_f32 v68, v110, 0xba000000, v68
	v_fmamk_f32 v71, v110, 0xba000000, v71
	v_fmac_f32_e32 v70, 0xba000000, v110
	v_fmamk_f32 v73, v110, 0xba000000, v73
	v_fmamk_f32 v72, v110, 0xba000000, v72
	v_fmamk_f32 v75, v110, 0xba000000, v75
	v_fmac_f32_e32 v74, 0xba000000, v110
	v_fmamk_f32 v79, v110, 0xba000000, v79
	v_fmamk_f32 v78, v110, 0xba000000, v78
	v_fmamk_f32 v77, v110, 0xba000000, v77
	v_fmac_f32_e32 v76, 0xba000000, v110
	v_mov_b32_e32 v110, v103
	v_mov_b32_e32 v111, v107
	v_mov_b32_e32 v114, v85
	v_mov_b32_e32 v115, v105
	v_mov_b32_e32 v108, v102
	v_mov_b32_e32 v109, v106
	v_mov_b32_e32 v112, v84
	v_mov_b32_e32 v113, v104
	v_pk_mul_f32 v[116:117], v[100:101], v[100:101]
	v_pk_mul_f32 v[118:119], v[98:99], v[98:99]
	v_pk_mul_f32 v[110:111], v[110:111], v[110:111]
	v_pk_mul_f32 v[114:115], v[114:115], v[114:115]
	v_pk_mov_b32 v[132:133], v[118:119], v[116:117] op_sel:[1,0]
	v_mov_b32_e32 v119, v117
	v_pk_fma_f32 v[108:109], v[108:109], v[108:109], v[110:111]
	v_pk_fma_f32 v[110:111], v[112:113], v[112:113], v[114:115]
	v_mul_f32_e32 v120, v86, v86
	v_mul_f32_e32 v122, v88, v88
	v_pk_add_f32 v[112:113], v[132:133], v[118:119]
	v_pk_add_f32 v[108:109], v[108:109], v[110:111]
	v_pk_fma_f32 v[116:117], v[86:87], v[86:87], v[120:121] op_sel_hi:[1,1,0]
	v_pk_fma_f32 v[120:121], v[88:89], v[88:89], v[122:123] op_sel_hi:[1,1,0]
	v_pk_add_f32 v[110:111], v[112:113], v[112:113] op_sel_hi:[0,1]
	v_pk_add_f32 v[108:109], v[108:109], v[108:109] op_sel_hi:[0,1]
	v_pk_mul_f32 v[124:125], v[70:71], v[70:71]
	v_pk_mul_f32 v[126:127], v[68:69], v[68:69]
	v_mul_f32_e32 v116, v64, v64
	v_mul_f32_e32 v120, v65, v65
	v_mul_f32_e32 v110, v66, v66
	v_mul_f32_e32 v108, v67, v67
	v_pk_mov_b32 v[122:123], v[126:127], v[124:125] op_sel:[1,0]
	v_mov_b32_e32 v127, v125
	v_pk_add_f32 v[112:113], v[116:117], v[120:121]
	v_pk_add_f32 v[108:109], v[110:111], v[108:109]
	v_mul_f32_e32 v128, v72, v72
	v_mul_f32_e32 v130, v74, v74
	v_pk_add_f32 v[114:115], v[122:123], v[126:127]
	v_pk_add_f32 v[108:109], v[112:113], v[108:109]
	v_pk_fma_f32 v[124:125], v[72:73], v[72:73], v[128:129] op_sel_hi:[1,1,0]
	v_pk_fma_f32 v[128:129], v[74:75], v[74:75], v[130:131] op_sel_hi:[1,1,0]
	v_pk_add_f32 v[114:115], v[114:115], v[114:115] op_sel_hi:[0,1]
	v_pk_add_f32 v[108:109], v[108:109], v[108:109] op_sel_hi:[0,1]
	v_mul_f32_e32 v124, v76, v76
	v_mul_f32_e32 v128, v77, v77
	v_mul_f32_e32 v114, v78, v78
	v_mul_f32_e32 v108, v79, v79
	v_pk_add_f32 v[116:117], v[124:125], v[128:129]
	v_pk_add_f32 v[108:109], v[114:115], v[108:109]
	s_nop 0
	v_pk_add_f32 v[108:109], v[116:117], v[108:109]
	s_nop 0
	v_add_f32_e32 v108, v108, v109
	ds_bpermute_b32 v109, v90, v108
	s_waitcnt lgkmcnt(0)
; __device__ __forceinline__ unsigned cvt_pk_bf16(float lo, float hi) { unsigned r; asm volatile("s_nop 1\n\tv_cvt_pk_bf16_f32 %0, %1, %2" : "=v"(r) : "v"(lo), "v"(hi)); return r; }
; __device__ __forceinline__ void ln_phase(float* io, const float* g, const float* b, bf16_t* hb, float* stats, int gw, int NGW, int lane) {
;     ...
;         const float mean = wave_sum(s, lane) * (1.f / D); float s2 = 0.f;
; #pragma unroll
;         for (int j = 0; j < 8; ++j) { v[j] = v[j] - mean; s2 += (v[j][0] * v[j][0] + v[j][1] * v[j][1]) + (v[j][2] * v[j][2] + v[j][3] * v[j][3]); }
;         const float rstd = 1.0f / sqrtf(wave_sum(s2, lane) * (1.f / D) + 1e-5f);
; #pragma unroll
;         for (int j = 0; j < 8; ++j) v[j] = v[j] * rstd * gv[j] + bv[j];
;         if (stats) {
;             u32x2* o8 = (u32x2*)(hb + (size_t)row * D) + lane;
; #pragma unroll
;             for (int j = 0; j < 8; ++j) { u32x2 w; w.x = cvt_pk_bf16(v[j][0], v[j][1]); w.y = cvt_pk_bf16(v[j][2], v[j][3]); o8[64 * j] = w; }
	v_add_f32_e32 v108, v108, v109
	ds_bpermute_b32 v109, v91, v108
	s_waitcnt lgkmcnt(0)
	v_add_f32_e32 v108, v108, v109
	ds_bpermute_b32 v109, v92, v108
	s_waitcnt lgkmcnt(0)
	v_add_f32_e32 v108, v108, v109
	ds_bpermute_b32 v109, v93, v108
	s_waitcnt lgkmcnt(0)
	v_add_f32_e32 v108, v108, v109
	ds_bpermute_b32 v109, v94, v108
	s_waitcnt lgkmcnt(0)
	v_add_f32_e32 v108, v108, v109
	ds_bpermute_b32 v109, v95, v108
	s_waitcnt lgkmcnt(0)
	v_add_f32_e32 v108, v108, v109
	v_fmamk_f32 v108, v108, 0x3a000000, v96
	v_mul_f32_e32 v109, 0x4f800000, v108
	v_cmp_gt_f32_e32 vcc, s11, v108
	s_nop 1
	v_cndmask_b32_e32 v108, v108, v109, vcc
	v_sqrt_f32_e32 v109, v108
	s_nop 0
	v_add_u32_e32 v110, -1, v109
	v_add_u32_e32 v111, 1, v109
	v_fma_f32 v112, -v110, v109, v108
	v_fma_f32 v113, -v111, v109, v108
	v_cmp_ge_f32_e64 s[0:1], 0, v112
	s_nop 1
	v_cndmask_b32_e64 v109, v109, v110, s[0:1]
	v_cmp_lt_f32_e64 s[0:1], 0, v113
	s_nop 1
	v_cndmask_b32_e64 v109, v109, v111, s[0:1]
	v_mul_f32_e32 v110, 0x37800000, v109
	v_cndmask_b32_e32 v109, v109, v110, vcc
	v_cmp_class_f32_e32 vcc, v108, v97
	s_nop 1
	v_cndmask_b32_e32 v108, v109, v108, vcc
	v_div_scale_f32 v109, s[0:1], v108, v108, 1.0
	v_rcp_f32_e32 v111, v109
	v_div_scale_f32 v110, vcc, 1.0, v108, 1.0
	v_fma_f32 v112, -v109, v111, 1.0
	v_fmac_f32_e32 v111, v112, v111
	v_mul_f32_e32 v112, v110, v111
	v_fma_f32 v113, -v109, v112, v110
	v_fmac_f32_e32 v112, v113, v111
	v_fma_f32 v109, -v109, v112, v110
	v_div_fmas_f32 v109, v109, v111, v112
	v_div_fixup_f32 v108, v109, v108, 1.0
	v_pk_mul_f32 v[84:85], v[84:85], v[108:109] op_sel_hi:[1,0]
	v_pk_mul_f32 v[102:103], v[102:103], v[108:109] op_sel_hi:[1,0]
	v_pk_mul_f32 v[104:105], v[104:105], v[108:109] op_sel_hi:[1,0]
	v_pk_mul_f32 v[106:107], v[106:107], v[108:109] op_sel_hi:[1,0]
	v_pk_fma_f32 v[102:103], v[0:1], v[102:103], v[8:9]
	v_pk_fma_f32 v[84:85], v[2:3], v[84:85], v[10:11]
	v_pk_mul_f32 v[100:101], v[100:101], v[108:109] op_sel_hi:[1,0]
	v_pk_mul_f32 v[98:99], v[98:99], v[108:109] op_sel_hi:[1,0]
	v_pk_mul_f32 v[64:65], v[64:65], v[108:109] op_sel_hi:[1,0]
	v_pk_fma_f32 v[106:107], v[4:5], v[106:107], v[12:13]
	v_pk_fma_f32 v[104:105], v[6:7], v[104:105], v[14:15]
	s_nop 1
	v_cvt_pk_bf16_f32 v102, v102, v103
	s_nop 1
	v_cvt_pk_bf16_f32 v103, v84, v85
	flat_store_dwordx2 v[80:81], v[102:103]
	s_nop 1
	v_cvt_pk_bf16_f32 v84, v106, v107
	s_nop 1
	v_cvt_pk_bf16_f32 v85, v104, v105
	v_pk_mul_f32 v[88:89], v[88:89], v[108:109] op_sel_hi:[1,0]
	v_pk_mul_f32 v[86:87], v[86:87], v[108:109] op_sel_hi:[1,0]
	v_pk_mul_f32 v[66:67], v[66:67], v[108:109] op_sel_hi:[1,0]
	v_pk_fma_f32 v[98:99], v[16:17], v[98:99], v[24:25]
	v_pk_fma_f32 v[100:101], v[18:19], v[100:101], v[26:27]
	v_pk_fma_f32 v[64:65], v[32:33], v[64:65], v[40:41]
	flat_store_dwordx2 v[80:81], v[84:85] offset:512
	s_nop 1
	v_cvt_pk_bf16_f32 v84, v98, v99
	s_nop 1
	v_cvt_pk_bf16_f32 v85, v100, v101
	v_pk_mul_f32 v[70:71], v[70:71], v[108:109] op_sel_hi:[1,0]
	v_pk_mul_f32 v[68:69], v[68:69], v[108:109] op_sel_hi:[1,0]
	v_pk_fma_f32 v[86:87], v[20:21], v[86:87], v[28:29]
	v_pk_fma_f32 v[88:89], v[22:23], v[88:89], v[30:31]
	v_pk_fma_f32 v[66:67], v[34:35], v[66:67], v[42:43]
	flat_store_dwordx2 v[80:81], v[84:85] offset:1024
	s_nop 1
	v_cvt_pk_bf16_f32 v84, v86, v87
	s_nop 1
	v_cvt_pk_bf16_f32 v85, v88, v89
	flat_store_dwordx2 v[80:81], v[84:85] offset:1536
	s_nop 1
	v_cvt_pk_bf16_f32 v64, v64, v65
	s_nop 1
	v_cvt_pk_bf16_f32 v65, v66, v67
	v_pk_mul_f32 v[74:75], v[74:75], v[108:109] op_sel_hi:[1,0]
	v_pk_mul_f32 v[72:73], v[72:73], v[108:109] op_sel_hi:[1,0]
	v_pk_fma_f32 v[68:69], v[36:37], v[68:69], v[44:45]
	v_pk_fma_f32 v[70:71], v[38:39], v[70:71], v[46:47]
	flat_store_dwordx2 v[80:81], v[64:65] offset:2048
	s_nop 1
	v_cvt_pk_bf16_f32 v64, v68, v69
	s_nop 1
	v_cvt_pk_bf16_f32 v65, v70, v71
	v_pk_mul_f32 v[78:79], v[78:79], v[108:109] op_sel_hi:[1,0]
	v_pk_mul_f32 v[76:77], v[76:77], v[108:109] op_sel_hi:[1,0]
	v_pk_fma_f32 v[72:73], v[48:49], v[72:73], v[56:57]
	v_pk_fma_f32 v[74:75], v[50:51], v[74:75], v[58:59]
	flat_store_dwordx2 v[80:81], v[64:65] offset:2560
	s_nop 1
	v_cvt_pk_bf16_f32 v64, v72, v73
	s_nop 1
	v_cvt_pk_bf16_f32 v65, v74, v75
	v_pk_fma_f32 v[76:77], v[52:53], v[76:77], v[60:61]
	v_pk_fma_f32 v[78:79], v[54:55], v[78:79], v[62:63]
	flat_store_dwordx2 v[80:81], v[64:65] offset:3072
	s_nop 1
	v_cvt_pk_bf16_f32 v64, v76, v77
	s_nop 1
	v_cvt_pk_bf16_f32 v65, v78, v79
	flat_store_dwordx2 v[80:81], v[64:65] offset:3584
	v_lshl_add_u64 v[80:81], v[80:81], 0, s[4:5]
	s_cbranch_scc1 .LBB0_275
	v_writelane_b32 v254, s12, 4
	s_nop 1
	v_writelane_b32 v254, s13, 5

; __device__ __forceinline__ float bf_lo(unsigned u) { return __uint_as_float(u << 16); }
; __device__ __forceinline__ float bf_hi(unsigned u) { return __uint_as_float(u & 0xffff0000u); }
; __device__ __forceinline__ u32x4 pack8(f32x4 a, f32x4 b) { u32x4 w; w.x = cvt_pk_bf16(a[0], a[1]); w.y = cvt_pk_bf16(a[2], a[3]); w.z = cvt_pk_bf16(b[0], b[1]); w.w = cvt_pk_bf16(b[2], b[3]); return w; }
;     __device__ __forceinline__ void operator()(AccRef acc, const Unit& u, int wr, int wc, int fr, int fq) const {
;     ...
;             for (int m = 0; m < 4; ++m) {
;                 const size_t off = (size_t)(row0 + ai * HALF + m * 16) * 2048 + col0;
; #pragma unroll
;                 for (int bj = 0; bj < 2; ++bj) {
;                     const u32x4 gv = *(const u32x4*)(G + off + bj * HALF);
;                     f32x4 v0 = acc[ai][bj][m][0], v1 = acc[ai][bj][m][1];
;                     v0[0] *= bf_lo(gv.x); v0[1] *= bf_hi(gv.x); v0[2] *= bf_lo(gv.y); v0[3] *= bf_hi(gv.y);
;                     v1[0] *= bf_lo(gv.z); v1[1] *= bf_hi(gv.z); v1[2] *= bf_lo(gv.w); v1[3] *= bf_hi(gv.w);
;                     if (ADD) {
;                         const u32x4 tv = *(const u32x4*)(T + off + bj * HALF);
;                         v0[0] += bf_lo(tv.x); v0[1] += bf_hi(tv.x); v0[2] += bf_lo(tv.y); v0[3] += bf_hi(tv.y);
;                         v1[0] += bf_lo(tv.z); v1[1] += bf_hi(tv.z); v1[2] += bf_lo(tv.w); v1[3] += bf_hi(tv.w);
;                     }
;                     *(u32x4*)(T + off + bj * HALF) = pack8(v0, v1);
.LBB0_692:
	v_mov_b32_e32 v144, v146
	v_mov_b32_e32 v145, v147
	s_lshl_b32 s25, s34, 8
	s_add_i32 s25, s25, s55
	v_add_u32_e32 v144, s25, v144
	s_lshl_b32 s25, s68, 8
	s_or_b32 s25, s25, s56
	v_lshl_add_u32 v152, v145, 3, s25
	v_ashrrev_i32_e32 v145, 31, v144
	v_lshlrev_b64 v[144:145], 12, v[144:145]
	v_ashrrev_i32_e32 v153, 31, v152
	v_lshl_add_u64 v[144:145], s[6:7], 0, v[144:145]
	v_lshl_add_u64 v[144:145], v[152:153], 1, v[144:145]
	flat_load_dwordx4 v[152:155], v[144:145] nt
	s_waitcnt vmcnt(0) lgkmcnt(0)
	v_lshlrev_b32_e32 v156, 16, v152
	v_and_b32_e32 v152, 0xffff0000, v152
	v_lshlrev_b32_e32 v157, 16, v153
	v_and_b32_e32 v153, 0xffff0000, v153
	v_lshlrev_b32_e32 v159, 16, v155
	v_and_b32_e32 v155, 0xffff0000, v155
	v_lshlrev_b32_e32 v158, 16, v154
	v_and_b32_e32 v154, 0xffff0000, v154
	v_mul_f32_e32 v124, v124, v156
	v_mul_f32_e32 v125, v125, v152
	v_mul_f32_e32 v126, v126, v157
	v_mul_f32_e32 v127, v127, v153
	v_mul_f32_e32 v123, v123, v155
	v_mul_f32_e32 v152, v120, v158
	v_mul_f32_e32 v153, v121, v154
	v_mul_f32_e32 v154, v122, v159
	s_nop 1
	v_cvt_pk_bf16_f32 v120, v124, v125
	s_nop 1
	v_cvt_pk_bf16_f32 v121, v126, v127
	s_nop 1
	v_cvt_pk_bf16_f32 v122, v152, v153
	s_nop 1
	v_cvt_pk_bf16_f32 v123, v154, v123
	flat_load_dwordx4 v[124:127], v[144:145] offset:256 nt
	v_add_co_u32_e32 v152, vcc, s54, v144
	flat_store_dwordx4 v[144:145], v[120:123]
	s_nop 0
	v_addc_co_u32_e32 v153, vcc, 0, v145, vcc
	s_waitcnt vmcnt(0) lgkmcnt(0)
	v_lshlrev_b32_e32 v120, 16, v124
	v_and_b32_e32 v121, 0xffff0000, v124
	v_lshlrev_b32_e32 v122, 16, v125
	v_and_b32_e32 v123, 0xffff0000, v125
	v_lshlrev_b32_e32 v124, 16, v126
	v_and_b32_e32 v125, 0xffff0000, v126
	v_lshlrev_b32_e32 v126, 16, v127
	v_and_b32_e32 v127, 0xffff0000, v127
	v_mul_f32_e32 v116, v116, v120
	v_mul_f32_e32 v117, v117, v121
	v_mul_f32_e32 v118, v118, v122
	v_mul_f32_e32 v119, v119, v123
	v_mul_f32_e32 v111, v111, v127
	v_mul_f32_e32 v120, v108, v124
	v_mul_f32_e32 v121, v109, v125
	v_mul_f32_e32 v122, v110, v126
	s_nop 1
	v_cvt_pk_bf16_f32 v108, v116, v117
	s_nop 1
	v_cvt_pk_bf16_f32 v109, v118, v119
	s_nop 1
	v_cvt_pk_bf16_f32 v110, v120, v121
	s_nop 1
	v_cvt_pk_bf16_f32 v111, v122, v111
	flat_load_dwordx4 v[116:119], v[152:153] nt
	v_lshl_add_u64 v[120:121], v[144:145], 0, s[12:13]
	flat_store_dwordx4 v[144:145], v[108:111] offset:256
	s_waitcnt vmcnt(0) lgkmcnt(0)
	s_nop 0
	v_lshlrev_b32_e32 v108, 16, v116
	v_and_b32_e32 v109, 0xffff0000, v116
	v_lshlrev_b32_e32 v110, 16, v117
	v_and_b32_e32 v111, 0xffff0000, v117
	v_lshlrev_b32_e32 v116, 16, v118
	v_and_b32_e32 v117, 0xffff0000, v118
	v_lshlrev_b32_e32 v118, 16, v119
	v_and_b32_e32 v119, 0xffff0000, v119
	v_mul_f32_e32 v108, v112, v108
	v_mul_f32_e32 v109, v113, v109
	v_mul_f32_e32 v110, v114, v110
	v_mul_f32_e32 v111, v115, v111
	v_mul_f32_e32 v107, v107, v119
	v_mul_f32_e32 v112, v104, v116
	v_mul_f32_e32 v113, v105, v117
	v_mul_f32_e32 v114, v106, v118
	s_nop 1
	v_cvt_pk_bf16_f32 v104, v108, v109
	s_nop 1
	v_cvt_pk_bf16_f32 v105, v110, v111
	s_nop 1
	v_cvt_pk_bf16_f32 v106, v112, v113
	s_nop 1
	v_cvt_pk_bf16_f32 v107, v114, v107
	flat_load_dwordx4 v[108:111], v[120:121] offset:256 nt
	v_add_co_u32_e32 v112, vcc, s62, v144
	flat_store_dwordx4 v[152:153], v[104:107]
	s_nop 0
	v_addc_co_u32_e32 v113, vcc, 0, v145, vcc
	s_waitcnt vmcnt(0) lgkmcnt(0)
	v_lshlrev_b32_e32 v104, 16, v108
	v_and_b32_e32 v105, 0xffff0000, v108
	v_lshlrev_b32_e32 v106, 16, v109
	v_and_b32_e32 v107, 0xffff0000, v109
	v_lshlrev_b32_e32 v108, 16, v110
	v_and_b32_e32 v109, 0xffff0000, v110
	v_lshlrev_b32_e32 v110, 16, v111
	v_and_b32_e32 v111, 0xffff0000, v111
	v_mul_f32_e32 v100, v100, v104
	v_mul_f32_e32 v101, v101, v105
	v_mul_f32_e32 v102, v102, v106
	v_mul_f32_e32 v103, v103, v107
	v_mul_f32_e32 v95, v95, v111
	v_mul_f32_e32 v104, v92, v108
	v_mul_f32_e32 v105, v93, v109
	v_mul_f32_e32 v106, v94, v110
	s_nop 1
	v_cvt_pk_bf16_f32 v92, v100, v101
	s_nop 1
	v_cvt_pk_bf16_f32 v93, v102, v103
	s_nop 1
	v_cvt_pk_bf16_f32 v94, v104, v105
	s_nop 1
	v_cvt_pk_bf16_f32 v95, v106, v95
	flat_load_dwordx4 v[100:103], v[112:113] nt
	v_lshl_add_u64 v[104:105], v[144:145], 0, s[14:15]
	flat_store_dwordx4 v[120:121], v[92:95] offset:256
	s_waitcnt vmcnt(0) lgkmcnt(0)
	s_nop 0
	v_lshlrev_b32_e32 v92, 16, v100
	v_and_b32_e32 v93, 0xffff0000, v100
	v_lshlrev_b32_e32 v94, 16, v101
	v_and_b32_e32 v95, 0xffff0000, v101
	v_lshlrev_b32_e32 v100, 16, v102
	v_and_b32_e32 v101, 0xffff0000, v102
	v_lshlrev_b32_e32 v102, 16, v103
	v_and_b32_e32 v103, 0xffff0000, v103
	v_mul_f32_e32 v92, v96, v92
	v_mul_f32_e32 v93, v97, v93
	v_mul_f32_e32 v94, v98, v94
	v_mul_f32_e32 v95, v99, v95
	v_mul_f32_e32 v91, v91, v103
	v_mul_f32_e32 v96, v88, v100
	v_mul_f32_e32 v97, v89, v101
	v_mul_f32_e32 v98, v90, v102
	s_nop 1
	v_cvt_pk_bf16_f32 v88, v92, v93
	s_nop 1
	v_cvt_pk_bf16_f32 v89, v94, v95
	s_nop 1
	v_cvt_pk_bf16_f32 v90, v96, v97
	s_nop 1
	v_cvt_pk_bf16_f32 v91, v98, v91
	flat_load_dwordx4 v[92:95], v[104:105] offset:256 nt
	v_add_co_u32_e32 v96, vcc, s63, v144
	flat_store_dwordx4 v[112:113], v[88:91]
	s_nop 0
	v_addc_co_u32_e32 v97, vcc, 0, v145, vcc
	s_waitcnt vmcnt(0) lgkmcnt(0)
	v_lshlrev_b32_e32 v88, 16, v92
	v_and_b32_e32 v89, 0xffff0000, v92
	v_lshlrev_b32_e32 v90, 16, v93
	v_and_b32_e32 v91, 0xffff0000, v93
	v_lshlrev_b32_e32 v92, 16, v94
	v_and_b32_e32 v93, 0xffff0000, v94
	v_lshlrev_b32_e32 v94, 16, v95
	v_and_b32_e32 v95, 0xffff0000, v95
	v_mul_f32_e32 v84, v84, v88
	v_mul_f32_e32 v85, v85, v89
	v_mul_f32_e32 v86, v86, v90
	v_mul_f32_e32 v87, v87, v91
	v_mul_f32_e32 v79, v79, v95
	v_mul_f32_e32 v88, v76, v92
	v_mul_f32_e32 v89, v77, v93
	v_mul_f32_e32 v90, v78, v94
	s_nop 1
	v_cvt_pk_bf16_f32 v76, v84, v85
	s_nop 1
	v_cvt_pk_bf16_f32 v77, v86, v87
	s_nop 1
	v_cvt_pk_bf16_f32 v78, v88, v89
	s_nop 1
	v_cvt_pk_bf16_f32 v79, v90, v79
	flat_load_dwordx4 v[84:87], v[96:97] nt
	v_lshl_add_u64 v[88:89], v[144:145], 0, s[16:17]
	flat_store_dwordx4 v[104:105], v[76:79] offset:256
	s_waitcnt vmcnt(0) lgkmcnt(0)
; __device__ __forceinline__ float bf_lo(unsigned u) { return __uint_as_float(u << 16); }
; __device__ __forceinline__ float bf_hi(unsigned u) { return __uint_as_float(u & 0xffff0000u); }
; __device__ __forceinline__ u32x4 pack8(f32x4 a, f32x4 b) { u32x4 w; w.x = cvt_pk_bf16(a[0], a[1]); w.y = cvt_pk_bf16(a[2], a[3]); w.z = cvt_pk_bf16(b[0], b[1]); w.w = cvt_pk_bf16(b[2], b[3]); return w; }
;     __device__ __forceinline__ void operator()(AccRef acc, const Unit& u, int wr, int wc, int fr, int fq) const {
;     ...
;             for (int m = 0; m < 4; ++m) {
;                 const size_t off = (size_t)(row0 + ai * HALF + m * 16) * 2048 + col0;
; #pragma unroll
;                 for (int bj = 0; bj < 2; ++bj) {
;                     const u32x4 gv = *(const u32x4*)(G + off + bj * HALF);
;                     f32x4 v0 = acc[ai][bj][m][0], v1 = acc[ai][bj][m][1];
;                     v0[0] *= bf_lo(gv.x); v0[1] *= bf_hi(gv.x); v0[2] *= bf_lo(gv.y); v0[3] *= bf_hi(gv.y);
;                     v1[0] *= bf_lo(gv.z); v1[1] *= bf_hi(gv.z); v1[2] *= bf_lo(gv.w); v1[3] *= bf_hi(gv.w);
;                     if (ADD) {
;                         const u32x4 tv = *(const u32x4*)(T + off + bj * HALF);
;                         v0[0] += bf_lo(tv.x); v0[1] += bf_hi(tv.x); v0[2] += bf_lo(tv.y); v0[3] += bf_hi(tv.y);
;                         v1[0] += bf_lo(tv.z); v1[1] += bf_hi(tv.z); v1[2] += bf_lo(tv.w); v1[3] += bf_hi(tv.w);
;                     }
;                     *(u32x4*)(T + off + bj * HALF) = pack8(v0, v1);
;                 }
	s_nop 0
	v_lshlrev_b32_e32 v76, 16, v84
	v_and_b32_e32 v77, 0xffff0000, v84
	v_lshlrev_b32_e32 v78, 16, v85
	v_and_b32_e32 v79, 0xffff0000, v85
	v_lshlrev_b32_e32 v84, 16, v86
	v_and_b32_e32 v85, 0xffff0000, v86
	v_lshlrev_b32_e32 v86, 16, v87
	v_and_b32_e32 v87, 0xffff0000, v87
	v_mul_f32_e32 v76, v80, v76
	v_mul_f32_e32 v77, v81, v77
	v_mul_f32_e32 v78, v82, v78
	v_mul_f32_e32 v79, v83, v79
	v_mul_f32_e32 v75, v75, v87
	v_mul_f32_e32 v80, v72, v84
	v_mul_f32_e32 v81, v73, v85
	v_mul_f32_e32 v82, v74, v86
	s_nop 1
	v_cvt_pk_bf16_f32 v72, v76, v77
	s_nop 1
	v_cvt_pk_bf16_f32 v73, v78, v79
	s_nop 1
	v_cvt_pk_bf16_f32 v74, v80, v81
	s_nop 1
	v_cvt_pk_bf16_f32 v75, v82, v75
	flat_load_dwordx4 v[76:79], v[88:89] offset:256 nt
	v_add_co_u32_e32 v80, vcc, s64, v144
	flat_store_dwordx4 v[96:97], v[72:75]
	s_nop 0
	v_addc_co_u32_e32 v81, vcc, 0, v145, vcc
	s_waitcnt vmcnt(0) lgkmcnt(0)
	v_lshlrev_b32_e32 v72, 16, v76
	v_and_b32_e32 v73, 0xffff0000, v76
	v_lshlrev_b32_e32 v74, 16, v77
	v_and_b32_e32 v75, 0xffff0000, v77
	v_lshlrev_b32_e32 v76, 16, v78
	v_and_b32_e32 v77, 0xffff0000, v78
	v_lshlrev_b32_e32 v78, 16, v79
	v_and_b32_e32 v79, 0xffff0000, v79
	v_mul_f32_e32 v68, v68, v72
	v_mul_f32_e32 v69, v69, v73
	v_mul_f32_e32 v70, v70, v74
	v_mul_f32_e32 v71, v71, v75
	v_mul_f32_e32 v67, v67, v79
	v_mul_f32_e32 v72, v64, v76
	v_mul_f32_e32 v73, v65, v77
	v_mul_f32_e32 v74, v66, v78
	s_nop 1
	v_cvt_pk_bf16_f32 v64, v68, v69
	s_nop 1
	v_cvt_pk_bf16_f32 v65, v70, v71
	s_nop 1
	v_cvt_pk_bf16_f32 v66, v72, v73
	s_nop 1
	v_cvt_pk_bf16_f32 v67, v74, v67
	flat_load_dwordx4 v[68:71], v[80:81] nt
	v_lshl_add_u64 v[72:73], v[144:145], 0, s[2:3]
	flat_store_dwordx4 v[88:89], v[64:67] offset:256
	s_waitcnt vmcnt(0) lgkmcnt(0)
	s_nop 0
	v_lshlrev_b32_e32 v64, 16, v68
	v_and_b32_e32 v65, 0xffff0000, v68
	v_lshlrev_b32_e32 v66, 16, v69
	v_and_b32_e32 v67, 0xffff0000, v69
	v_lshlrev_b32_e32 v68, 16, v70
	v_and_b32_e32 v69, 0xffff0000, v70
	v_lshlrev_b32_e32 v70, 16, v71
	v_and_b32_e32 v71, 0xffff0000, v71
	v_mul_f32_e32 v60, v60, v64
	v_mul_f32_e32 v61, v61, v65
	v_mul_f32_e32 v62, v62, v66
	v_mul_f32_e32 v63, v63, v67
	v_mul_f32_e32 v59, v59, v71
	v_mul_f32_e32 v64, v56, v68
	v_mul_f32_e32 v65, v57, v69
	v_mul_f32_e32 v66, v58, v70
	s_nop 1
	v_cvt_pk_bf16_f32 v56, v60, v61
	s_nop 1
	v_cvt_pk_bf16_f32 v57, v62, v63
	s_nop 1
	v_cvt_pk_bf16_f32 v58, v64, v65
	s_nop 1
	v_cvt_pk_bf16_f32 v59, v66, v59
	flat_load_dwordx4 v[60:63], v[72:73] offset:256 nt
	v_add_co_u32_e32 v64, vcc, s65, v144
	flat_store_dwordx4 v[80:81], v[56:59]
	s_nop 0
	v_addc_co_u32_e32 v65, vcc, 0, v145, vcc
	s_waitcnt vmcnt(0) lgkmcnt(0)
	v_lshlrev_b32_e32 v56, 16, v60
	v_and_b32_e32 v57, 0xffff0000, v60
	v_lshlrev_b32_e32 v58, 16, v61
	v_and_b32_e32 v59, 0xffff0000, v61
	v_lshlrev_b32_e32 v60, 16, v62
	v_and_b32_e32 v61, 0xffff0000, v62
	v_lshlrev_b32_e32 v62, 16, v63
	v_and_b32_e32 v63, 0xffff0000, v63
	v_mul_f32_e32 v52, v52, v56
	v_mul_f32_e32 v53, v53, v57
	v_mul_f32_e32 v54, v54, v58
	v_mul_f32_e32 v55, v55, v59
	v_mul_f32_e32 v47, v47, v63
	v_mul_f32_e32 v56, v44, v60
	v_mul_f32_e32 v57, v45, v61
	v_mul_f32_e32 v58, v46, v62
	s_nop 1
	v_cvt_pk_bf16_f32 v44, v52, v53
	s_nop 1
	v_cvt_pk_bf16_f32 v45, v54, v55
	s_nop 1
	v_cvt_pk_bf16_f32 v46, v56, v57
	s_nop 1
	v_cvt_pk_bf16_f32 v47, v58, v47
	flat_load_dwordx4 v[52:55], v[64:65] nt
	v_lshl_add_u64 v[56:57], v[144:145], 0, s[18:19]
	flat_store_dwordx4 v[72:73], v[44:47] offset:256
	s_waitcnt vmcnt(0) lgkmcnt(0)
	s_nop 0
	v_lshlrev_b32_e32 v44, 16, v52
	v_and_b32_e32 v45, 0xffff0000, v52
	v_lshlrev_b32_e32 v46, 16, v53
	v_and_b32_e32 v47, 0xffff0000, v53
	v_lshlrev_b32_e32 v52, 16, v54
	v_and_b32_e32 v53, 0xffff0000, v54
	v_lshlrev_b32_e32 v54, 16, v55
	v_and_b32_e32 v55, 0xffff0000, v55
	v_mul_f32_e32 v44, v48, v44
	v_mul_f32_e32 v45, v49, v45
	v_mul_f32_e32 v46, v50, v46
	v_mul_f32_e32 v47, v51, v47
	v_mul_f32_e32 v43, v43, v55
	v_mul_f32_e32 v48, v40, v52
	v_mul_f32_e32 v49, v41, v53
	v_mul_f32_e32 v50, v42, v54
	s_nop 1
	v_cvt_pk_bf16_f32 v40, v44, v45
	s_nop 1
	v_cvt_pk_bf16_f32 v41, v46, v47
	s_nop 1
	v_cvt_pk_bf16_f32 v42, v48, v49
	s_nop 1
	v_cvt_pk_bf16_f32 v43, v50, v43
	flat_load_dwordx4 v[44:47], v[56:57] offset:256 nt
	v_add_co_u32_e32 v48, vcc, s66, v144
	flat_store_dwordx4 v[64:65], v[40:43]
	s_nop 0
	v_addc_co_u32_e32 v49, vcc, 0, v145, vcc
	s_waitcnt vmcnt(0) lgkmcnt(0)
; __device__ __forceinline__ float bf_lo(unsigned u) { return __uint_as_float(u << 16); }
; __device__ __forceinline__ float bf_hi(unsigned u) { return __uint_as_float(u & 0xffff0000u); }
; __device__ __forceinline__ u32x4 pack8(f32x4 a, f32x4 b) { u32x4 w; w.x = cvt_pk_bf16(a[0], a[1]); w.y = cvt_pk_bf16(a[2], a[3]); w.z = cvt_pk_bf16(b[0], b[1]); w.w = cvt_pk_bf16(b[2], b[3]); return w; }
; #define PG8_BAR __builtin_amdgcn_s_barrier()
; template <class Epi>
; __device__ __forceinline__ void gemm_phase(ldsp lds, const Gemm g, const StaticOrder& S, const Epi& E, int wave0) {
;     ...
;         if (wr == 1) PG8_BAR;
;     __device__ __forceinline__ void operator()(AccRef acc, const Unit& u, int wr, int wc, int fr, int fq) const {
;     ...
;             for (int m = 0; m < 4; ++m) {
;                 const size_t off = (size_t)(row0 + ai * HALF + m * 16) * 2048 + col0;
; #pragma unroll
;                 for (int bj = 0; bj < 2; ++bj) {
;                     const u32x4 gv = *(const u32x4*)(G + off + bj * HALF);
;                     f32x4 v0 = acc[ai][bj][m][0], v1 = acc[ai][bj][m][1];
;                     v0[0] *= bf_lo(gv.x); v0[1] *= bf_hi(gv.x); v0[2] *= bf_lo(gv.y); v0[3] *= bf_hi(gv.y);
;                     v1[0] *= bf_lo(gv.z); v1[1] *= bf_hi(gv.z); v1[2] *= bf_lo(gv.w); v1[3] *= bf_hi(gv.w);
;                     if (ADD) {
;                         const u32x4 tv = *(const u32x4*)(T + off + bj * HALF);
;                         v0[0] += bf_lo(tv.x); v0[1] += bf_hi(tv.x); v0[2] += bf_lo(tv.y); v0[3] += bf_hi(tv.y);
;                         v1[0] += bf_lo(tv.z); v1[1] += bf_hi(tv.z); v1[2] += bf_lo(tv.w); v1[3] += bf_hi(tv.w);
;                     }
;                     *(u32x4*)(T + off + bj * HALF) = pack8(v0, v1);
;                 }
	v_lshlrev_b32_e32 v40, 16, v44
	v_and_b32_e32 v41, 0xffff0000, v44
	v_lshlrev_b32_e32 v42, 16, v45
	v_and_b32_e32 v43, 0xffff0000, v45
	v_lshlrev_b32_e32 v44, 16, v46
	v_and_b32_e32 v45, 0xffff0000, v46
	v_lshlrev_b32_e32 v46, 16, v47
	v_and_b32_e32 v47, 0xffff0000, v47
	v_mul_f32_e32 v36, v36, v40
	v_mul_f32_e32 v37, v37, v41
	v_mul_f32_e32 v38, v38, v42
	v_mul_f32_e32 v39, v39, v43
	v_mul_f32_e32 v31, v31, v47
	v_mul_f32_e32 v40, v28, v44
	v_mul_f32_e32 v41, v29, v45
	v_mul_f32_e32 v42, v30, v46
	s_nop 1
	v_cvt_pk_bf16_f32 v28, v36, v37
	s_nop 1
	v_cvt_pk_bf16_f32 v29, v38, v39
	s_nop 1
	v_cvt_pk_bf16_f32 v30, v40, v41
	s_nop 1
	v_cvt_pk_bf16_f32 v31, v42, v31
	flat_load_dwordx4 v[36:39], v[48:49] nt
	v_lshl_add_u64 v[40:41], v[144:145], 0, s[20:21]
	flat_store_dwordx4 v[56:57], v[28:31] offset:256
	s_waitcnt vmcnt(0) lgkmcnt(0)
	s_nop 0
	v_lshlrev_b32_e32 v28, 16, v36
	v_and_b32_e32 v29, 0xffff0000, v36
	v_lshlrev_b32_e32 v30, 16, v37
	v_and_b32_e32 v31, 0xffff0000, v37
	v_lshlrev_b32_e32 v36, 16, v38
	v_and_b32_e32 v37, 0xffff0000, v38
	v_lshlrev_b32_e32 v38, 16, v39
	v_and_b32_e32 v39, 0xffff0000, v39
	v_mul_f32_e32 v28, v32, v28
	v_mul_f32_e32 v29, v33, v29
	v_mul_f32_e32 v30, v34, v30
	v_mul_f32_e32 v31, v35, v31
	v_mul_f32_e32 v27, v27, v39
	v_mul_f32_e32 v32, v24, v36
	v_mul_f32_e32 v33, v25, v37
	v_mul_f32_e32 v34, v26, v38
	s_nop 1
	v_cvt_pk_bf16_f32 v24, v28, v29
	s_nop 1
	v_cvt_pk_bf16_f32 v25, v30, v31
	s_nop 1
	v_cvt_pk_bf16_f32 v26, v32, v33
	s_nop 1
	v_cvt_pk_bf16_f32 v27, v34, v27
	flat_load_dwordx4 v[28:31], v[40:41] offset:256 nt
	v_add_co_u32_e32 v32, vcc, s67, v144
	flat_store_dwordx4 v[48:49], v[24:27]
	s_nop 0
	v_addc_co_u32_e32 v33, vcc, 0, v145, vcc
	s_andn2_b64 vcc, exec, s[0:1]
	s_mov_b64 s[0:1], -1
	s_waitcnt vmcnt(0) lgkmcnt(0)
	v_lshlrev_b32_e32 v24, 16, v28
	v_and_b32_e32 v25, 0xffff0000, v28
	v_lshlrev_b32_e32 v26, 16, v29
	v_and_b32_e32 v27, 0xffff0000, v29
	v_lshlrev_b32_e32 v28, 16, v30
	v_and_b32_e32 v29, 0xffff0000, v30
	v_lshlrev_b32_e32 v30, 16, v31
	v_and_b32_e32 v31, 0xffff0000, v31
	v_mul_f32_e32 v20, v20, v24
	v_mul_f32_e32 v21, v21, v25
	v_mul_f32_e32 v22, v22, v26
	v_mul_f32_e32 v23, v23, v27
	v_mul_f32_e32 v15, v15, v31
	v_mul_f32_e32 v24, v12, v28
	v_mul_f32_e32 v25, v13, v29
	v_mul_f32_e32 v26, v14, v30
	s_nop 1
	v_cvt_pk_bf16_f32 v12, v20, v21
	s_nop 1
	v_cvt_pk_bf16_f32 v13, v22, v23
	s_nop 1
	v_cvt_pk_bf16_f32 v14, v24, v25
	s_nop 1
	v_cvt_pk_bf16_f32 v15, v26, v15
	flat_load_dwordx4 v[20:23], v[32:33] nt
	v_lshl_add_u64 v[24:25], v[144:145], 0, s[22:23]
	flat_store_dwordx4 v[40:41], v[12:15] offset:256
	s_waitcnt vmcnt(0) lgkmcnt(0)
	s_nop 0
	v_lshlrev_b32_e32 v12, 16, v20
	v_and_b32_e32 v13, 0xffff0000, v20
	v_lshlrev_b32_e32 v14, 16, v21
	v_and_b32_e32 v15, 0xffff0000, v21
	v_lshlrev_b32_e32 v20, 16, v22
	v_and_b32_e32 v21, 0xffff0000, v22
	v_lshlrev_b32_e32 v22, 16, v23
	v_and_b32_e32 v23, 0xffff0000, v23
	v_mul_f32_e32 v12, v16, v12
	v_mul_f32_e32 v13, v17, v13
	v_mul_f32_e32 v14, v18, v14
	v_mul_f32_e32 v15, v19, v15
	v_mul_f32_e32 v11, v11, v23
	v_mul_f32_e32 v16, v8, v20
	v_mul_f32_e32 v17, v9, v21
	v_mul_f32_e32 v18, v10, v22
	s_nop 1
	v_cvt_pk_bf16_f32 v8, v12, v13
	s_nop 1
	v_cvt_pk_bf16_f32 v9, v14, v15
	s_nop 1
	v_cvt_pk_bf16_f32 v10, v16, v17
	s_nop 1
	v_cvt_pk_bf16_f32 v11, v18, v11
	flat_load_dwordx4 v[12:15], v[24:25] offset:256 nt
	s_nop 0
	flat_store_dwordx4 v[32:33], v[8:11]
	s_waitcnt vmcnt(0) lgkmcnt(0)
	s_nop 0
	v_lshlrev_b32_e32 v8, 16, v12
	v_and_b32_e32 v9, 0xffff0000, v12
	v_lshlrev_b32_e32 v10, 16, v13
	v_and_b32_e32 v11, 0xffff0000, v13
	v_lshlrev_b32_e32 v12, 16, v14
	v_and_b32_e32 v13, 0xffff0000, v14
	v_lshlrev_b32_e32 v14, 16, v15
	v_and_b32_e32 v15, 0xffff0000, v15
	v_mul_f32_e32 v3, v3, v15
	v_mul_f32_e32 v4, v4, v8
	v_mul_f32_e32 v5, v5, v9
	v_mul_f32_e32 v6, v6, v10
	v_mul_f32_e32 v7, v7, v11
	v_mul_f32_e32 v8, v0, v12
	v_mul_f32_e32 v9, v1, v13
	v_mul_f32_e32 v10, v2, v14
	s_nop 1
	v_cvt_pk_bf16_f32 v0, v4, v5
	s_nop 1
	v_cvt_pk_bf16_f32 v1, v6, v7
	s_nop 1
	v_cvt_pk_bf16_f32 v2, v8, v9
	s_nop 1
	v_cvt_pk_bf16_f32 v3, v10, v3
	flat_store_dwordx4 v[24:25], v[0:3] offset:256
	s_cbranch_vccnz .LBB0_681
	s_andn2_b64 vcc, exec, s[4:5]
	s_cbranch_vccnz .LBB0_680
	s_barrier
	s_branch .LBB0_680

; __device__ __forceinline__ float bf_lo(unsigned u) { return __uint_as_float(u << 16); }
; __device__ __forceinline__ float bf_hi(unsigned u) { return __uint_as_float(u & 0xffff0000u); }
; __device__ __forceinline__ u32x4 pack8(f32x4 a, f32x4 b) { u32x4 w; w.x = cvt_pk_bf16(a[0], a[1]); w.y = cvt_pk_bf16(a[2], a[3]); w.z = cvt_pk_bf16(b[0], b[1]); w.w = cvt_pk_bf16(b[2], b[3]); return w; }
;     __device__ __forceinline__ void operator()(AccRef acc, const Unit& u, int wr, int wc, int fr, int fq) const {
;     ...
;             for (int m = 0; m < 4; ++m) {
;                 const size_t off = (size_t)(row0 + ai * HALF + m * 16) * 2048 + col0;
; #pragma unroll
;                 for (int bj = 0; bj < 2; ++bj) {
;                     const u32x4 gv = *(const u32x4*)(G + off + bj * HALF);
;                     f32x4 v0 = acc[ai][bj][m][0], v1 = acc[ai][bj][m][1];
;                     v0[0] *= bf_lo(gv.x); v0[1] *= bf_hi(gv.x); v0[2] *= bf_lo(gv.y); v0[3] *= bf_hi(gv.y);
;                     v1[0] *= bf_lo(gv.z); v1[1] *= bf_hi(gv.z); v1[2] *= bf_lo(gv.w); v1[3] *= bf_hi(gv.w);
;                     if (ADD) {
;                         const u32x4 tv = *(const u32x4*)(T + off + bj * HALF);
;                         v0[0] += bf_lo(tv.x); v0[1] += bf_hi(tv.x); v0[2] += bf_lo(tv.y); v0[3] += bf_hi(tv.y);
;                         v1[0] += bf_lo(tv.z); v1[1] += bf_hi(tv.z); v1[2] += bf_lo(tv.w); v1[3] += bf_hi(tv.w);
;                     }
;                     *(u32x4*)(T + off + bj * HALF) = pack8(v0, v1);
;                 }
.LBB0_716:
	v_mov_b32_e32 v144, v146
	v_mov_b32_e32 v145, v147
	s_lshl_b32 s27, s36, 8
	s_add_i32 s27, s27, s54
	v_add_u32_e32 v144, s27, v144
	s_lshl_b32 s27, s61, 8
	s_or_b32 s27, s27, s55
	v_lshl_add_u32 v152, v145, 3, s27
	v_ashrrev_i32_e32 v145, 31, v144
	v_ashrrev_i32_e32 v153, 31, v152
	v_lshlrev_b64 v[144:145], 11, v[144:145]
	v_lshl_add_u64 v[144:145], v[144:145], 0, v[152:153]
	v_lshlrev_b64 v[144:145], 1, v[144:145]
	v_lshl_add_u64 v[160:161], s[4:5], 0, v[144:145]
	v_lshl_add_u64 v[162:163], s[6:7], 0, v[144:145]
	flat_load_dwordx4 v[152:155], v[160:161] nt
	flat_load_dwordx4 v[156:159], v[162:163] nt
	s_andn2_b64 vcc, exec, s[0:1]
	s_mov_b64 s[0:1], -1
	s_waitcnt vmcnt(0) lgkmcnt(0)
	v_lshlrev_b32_e32 v164, 16, v152
	v_and_b32_e32 v152, 0xffff0000, v152
	v_lshlrev_b32_e32 v165, 16, v153
	v_and_b32_e32 v153, 0xffff0000, v153
	v_lshlrev_b32_e32 v166, 16, v154
	v_and_b32_e32 v154, 0xffff0000, v154
	v_lshlrev_b32_e32 v167, 16, v155
	v_and_b32_e32 v155, 0xffff0000, v155
	v_lshlrev_b32_e32 v168, 16, v156
	v_and_b32_e32 v156, 0xffff0000, v156
	v_lshlrev_b32_e32 v169, 16, v157
	v_and_b32_e32 v157, 0xffff0000, v157
	v_lshlrev_b32_e32 v170, 16, v158
	v_and_b32_e32 v158, 0xffff0000, v158
	v_lshlrev_b32_e32 v171, 16, v159
	v_and_b32_e32 v159, 0xffff0000, v159
	v_fmac_f32_e32 v168, v124, v164
	v_fmac_f32_e32 v156, v125, v152
	v_fmac_f32_e32 v169, v126, v165
	v_fmac_f32_e32 v157, v127, v153
	v_fmac_f32_e32 v170, v120, v166
	v_fmac_f32_e32 v158, v121, v154
	v_fmac_f32_e32 v171, v122, v167
	v_fmac_f32_e32 v159, v123, v155
	s_nop 1
	v_cvt_pk_bf16_f32 v120, v168, v156
	s_nop 1
	v_cvt_pk_bf16_f32 v121, v169, v157
	s_nop 1
	v_cvt_pk_bf16_f32 v122, v170, v158
	s_nop 1
	v_cvt_pk_bf16_f32 v123, v171, v159
	flat_load_dwordx4 v[124:127], v[160:161] offset:256 nt
	flat_load_dwordx4 v[152:155], v[162:163] offset:256 nt
	v_lshl_add_u64 v[156:157], v[144:145], 0, s[12:13]
	flat_store_dwordx4 v[162:163], v[120:123]
	v_lshl_add_u64 v[158:159], s[4:5], 0, v[156:157]
	s_waitcnt vmcnt(0) lgkmcnt(0)
	v_lshlrev_b32_e32 v160, 16, v152
	v_lshlrev_b32_e32 v120, 16, v124
	v_and_b32_e32 v121, 0xffff0000, v124
	v_lshlrev_b32_e32 v122, 16, v125
	v_and_b32_e32 v123, 0xffff0000, v125
	v_lshlrev_b32_e32 v124, 16, v126
	v_and_b32_e32 v125, 0xffff0000, v126
	v_lshlrev_b32_e32 v126, 16, v127
	v_and_b32_e32 v127, 0xffff0000, v127
	v_and_b32_e32 v152, 0xffff0000, v152
	v_lshlrev_b32_e32 v161, 16, v153
	v_and_b32_e32 v153, 0xffff0000, v153
	v_lshlrev_b32_e32 v164, 16, v154
	v_and_b32_e32 v154, 0xffff0000, v154
	v_lshlrev_b32_e32 v165, 16, v155
	v_and_b32_e32 v155, 0xffff0000, v155
	v_fmac_f32_e32 v160, v116, v120
	v_fmac_f32_e32 v152, v117, v121
	v_fmac_f32_e32 v161, v118, v122
	v_fmac_f32_e32 v153, v119, v123
	v_fmac_f32_e32 v164, v112, v124
	v_fmac_f32_e32 v154, v113, v125
	v_fmac_f32_e32 v165, v114, v126
	v_fmac_f32_e32 v155, v115, v127
	s_nop 1
	v_cvt_pk_bf16_f32 v112, v160, v152
	s_nop 1
	v_cvt_pk_bf16_f32 v113, v161, v153
	s_nop 1
	v_cvt_pk_bf16_f32 v114, v164, v154
	s_nop 1
	v_cvt_pk_bf16_f32 v115, v165, v155
	flat_store_dwordx4 v[162:163], v[112:115] offset:256
	v_lshl_add_u64 v[120:121], s[6:7], 0, v[156:157]
	flat_load_dwordx4 v[112:115], v[158:159] nt
	flat_load_dwordx4 v[116:119], v[120:121] nt
	s_waitcnt vmcnt(0) lgkmcnt(0)
	v_lshlrev_b32_e32 v122, 16, v112
	v_and_b32_e32 v112, 0xffff0000, v112
	v_lshlrev_b32_e32 v123, 16, v113
	v_and_b32_e32 v113, 0xffff0000, v113
	v_lshlrev_b32_e32 v124, 16, v114
	v_and_b32_e32 v114, 0xffff0000, v114
	v_lshlrev_b32_e32 v125, 16, v115
	v_and_b32_e32 v115, 0xffff0000, v115
	v_lshlrev_b32_e32 v126, 16, v116
	v_and_b32_e32 v116, 0xffff0000, v116
	v_lshlrev_b32_e32 v127, 16, v117
	v_and_b32_e32 v117, 0xffff0000, v117
	v_lshlrev_b32_e32 v152, 16, v118
	v_and_b32_e32 v118, 0xffff0000, v118
	v_lshlrev_b32_e32 v153, 16, v119
	v_and_b32_e32 v119, 0xffff0000, v119
	v_fmac_f32_e32 v126, v108, v122
	v_fmac_f32_e32 v116, v109, v112
	v_fmac_f32_e32 v127, v110, v123
	v_fmac_f32_e32 v117, v111, v113
	v_fmac_f32_e32 v152, v104, v124
	v_fmac_f32_e32 v118, v105, v114
	v_fmac_f32_e32 v153, v106, v125
	v_fmac_f32_e32 v119, v107, v115
	s_nop 1
	v_cvt_pk_bf16_f32 v104, v126, v116
	s_nop 1
	v_cvt_pk_bf16_f32 v105, v127, v117
	s_nop 1
	v_cvt_pk_bf16_f32 v106, v152, v118
	s_nop 1
	v_cvt_pk_bf16_f32 v107, v153, v119
	flat_load_dwordx4 v[108:111], v[158:159] offset:256 nt
	flat_load_dwordx4 v[112:115], v[120:121] offset:256 nt
	v_lshl_add_u64 v[116:117], v[144:145], 0, s[14:15]
	flat_store_dwordx4 v[120:121], v[104:107]
	v_lshl_add_u64 v[118:119], s[4:5], 0, v[116:117]
	s_waitcnt vmcnt(0) lgkmcnt(0)
	v_lshlrev_b32_e32 v122, 16, v112
	v_lshlrev_b32_e32 v104, 16, v108
	v_and_b32_e32 v105, 0xffff0000, v108
	v_lshlrev_b32_e32 v106, 16, v109
	v_and_b32_e32 v107, 0xffff0000, v109
	v_lshlrev_b32_e32 v108, 16, v110
	v_and_b32_e32 v109, 0xffff0000, v110
	v_lshlrev_b32_e32 v110, 16, v111
	v_and_b32_e32 v111, 0xffff0000, v111
	v_and_b32_e32 v112, 0xffff0000, v112
	v_lshlrev_b32_e32 v123, 16, v113
	v_and_b32_e32 v113, 0xffff0000, v113
	v_lshlrev_b32_e32 v124, 16, v114
	v_and_b32_e32 v114, 0xffff0000, v114
	v_lshlrev_b32_e32 v125, 16, v115
	v_and_b32_e32 v115, 0xffff0000, v115
	v_fmac_f32_e32 v122, v100, v104
	v_fmac_f32_e32 v112, v101, v105
	v_fmac_f32_e32 v123, v102, v106
	v_fmac_f32_e32 v113, v103, v107
	v_fmac_f32_e32 v124, v96, v108
	v_fmac_f32_e32 v114, v97, v109
	v_fmac_f32_e32 v125, v98, v110
	v_fmac_f32_e32 v115, v99, v111
	s_nop 1
	v_cvt_pk_bf16_f32 v96, v122, v112
	s_nop 1
	v_cvt_pk_bf16_f32 v97, v123, v113
	s_nop 1
	v_cvt_pk_bf16_f32 v98, v124, v114
	s_nop 1
	v_cvt_pk_bf16_f32 v99, v125, v115
	flat_store_dwordx4 v[120:121], v[96:99] offset:256
	v_lshl_add_u64 v[104:105], s[6:7], 0, v[116:117]
	flat_load_dwordx4 v[96:99], v[118:119] nt
	flat_load_dwordx4 v[100:103], v[104:105] nt
	s_waitcnt vmcnt(0) lgkmcnt(0)
; __device__ __forceinline__ float bf_lo(unsigned u) { return __uint_as_float(u << 16); }
; __device__ __forceinline__ float bf_hi(unsigned u) { return __uint_as_float(u & 0xffff0000u); }
; __device__ __forceinline__ u32x4 pack8(f32x4 a, f32x4 b) { u32x4 w; w.x = cvt_pk_bf16(a[0], a[1]); w.y = cvt_pk_bf16(a[2], a[3]); w.z = cvt_pk_bf16(b[0], b[1]); w.w = cvt_pk_bf16(b[2], b[3]); return w; }
;     __device__ __forceinline__ void operator()(AccRef acc, const Unit& u, int wr, int wc, int fr, int fq) const {
;     ...
;                 for (int bj = 0; bj < 2; ++bj) {
;                     const u32x4 gv = *(const u32x4*)(G + off + bj * HALF);
;                     f32x4 v0 = acc[ai][bj][m][0], v1 = acc[ai][bj][m][1];
;                     v0[0] *= bf_lo(gv.x); v0[1] *= bf_hi(gv.x); v0[2] *= bf_lo(gv.y); v0[3] *= bf_hi(gv.y);
;                     v1[0] *= bf_lo(gv.z); v1[1] *= bf_hi(gv.z); v1[2] *= bf_lo(gv.w); v1[3] *= bf_hi(gv.w);
;                     if (ADD) {
;                         const u32x4 tv = *(const u32x4*)(T + off + bj * HALF);
;                         v0[0] += bf_lo(tv.x); v0[1] += bf_hi(tv.x); v0[2] += bf_lo(tv.y); v0[3] += bf_hi(tv.y);
;                         v1[0] += bf_lo(tv.z); v1[1] += bf_hi(tv.z); v1[2] += bf_lo(tv.w); v1[3] += bf_hi(tv.w);
;                     }
;                     *(u32x4*)(T + off + bj * HALF) = pack8(v0, v1);
	v_lshlrev_b32_e32 v106, 16, v96
	v_and_b32_e32 v96, 0xffff0000, v96
	v_lshlrev_b32_e32 v107, 16, v97
	v_and_b32_e32 v97, 0xffff0000, v97
	v_lshlrev_b32_e32 v108, 16, v98
	v_and_b32_e32 v98, 0xffff0000, v98
	v_lshlrev_b32_e32 v109, 16, v99
	v_and_b32_e32 v99, 0xffff0000, v99
	v_lshlrev_b32_e32 v110, 16, v100
	v_and_b32_e32 v100, 0xffff0000, v100
	v_lshlrev_b32_e32 v111, 16, v101
	v_and_b32_e32 v101, 0xffff0000, v101
	v_lshlrev_b32_e32 v112, 16, v102
	v_and_b32_e32 v102, 0xffff0000, v102
	v_lshlrev_b32_e32 v113, 16, v103
	v_and_b32_e32 v103, 0xffff0000, v103
	v_fmac_f32_e32 v110, v92, v106
	v_fmac_f32_e32 v100, v93, v96
	v_fmac_f32_e32 v111, v94, v107
	v_fmac_f32_e32 v101, v95, v97
	v_fmac_f32_e32 v112, v88, v108
	v_fmac_f32_e32 v102, v89, v98
	v_fmac_f32_e32 v113, v90, v109
	v_fmac_f32_e32 v103, v91, v99
	s_nop 1
	v_cvt_pk_bf16_f32 v88, v110, v100
	s_nop 1
	v_cvt_pk_bf16_f32 v89, v111, v101
	s_nop 1
	v_cvt_pk_bf16_f32 v90, v112, v102
	s_nop 1
	v_cvt_pk_bf16_f32 v91, v113, v103
	flat_load_dwordx4 v[92:95], v[118:119] offset:256 nt
	flat_load_dwordx4 v[96:99], v[104:105] offset:256 nt
	v_lshl_add_u64 v[100:101], v[144:145], 0, s[16:17]
	flat_store_dwordx4 v[104:105], v[88:91]
	v_lshl_add_u64 v[102:103], s[4:5], 0, v[100:101]
	s_waitcnt vmcnt(0) lgkmcnt(0)
	v_lshlrev_b32_e32 v106, 16, v96
	v_lshlrev_b32_e32 v88, 16, v92
	v_and_b32_e32 v89, 0xffff0000, v92
	v_lshlrev_b32_e32 v90, 16, v93
	v_and_b32_e32 v91, 0xffff0000, v93
	v_lshlrev_b32_e32 v92, 16, v94
	v_and_b32_e32 v93, 0xffff0000, v94
	v_lshlrev_b32_e32 v94, 16, v95
	v_and_b32_e32 v95, 0xffff0000, v95
	v_and_b32_e32 v96, 0xffff0000, v96
	v_lshlrev_b32_e32 v107, 16, v97
	v_and_b32_e32 v97, 0xffff0000, v97
	v_lshlrev_b32_e32 v108, 16, v98
	v_and_b32_e32 v98, 0xffff0000, v98
	v_lshlrev_b32_e32 v109, 16, v99
	v_and_b32_e32 v99, 0xffff0000, v99
	v_fmac_f32_e32 v106, v84, v88
	v_fmac_f32_e32 v96, v85, v89
	v_fmac_f32_e32 v107, v86, v90
	v_fmac_f32_e32 v97, v87, v91
	v_fmac_f32_e32 v108, v80, v92
	v_fmac_f32_e32 v98, v81, v93
	v_fmac_f32_e32 v109, v82, v94
	v_fmac_f32_e32 v99, v83, v95
	s_nop 1
	v_cvt_pk_bf16_f32 v80, v106, v96
	s_nop 1
	v_cvt_pk_bf16_f32 v81, v107, v97
	s_nop 1
	v_cvt_pk_bf16_f32 v82, v108, v98
	s_nop 1
	v_cvt_pk_bf16_f32 v83, v109, v99
	flat_store_dwordx4 v[104:105], v[80:83] offset:256
	v_lshl_add_u64 v[88:89], s[6:7], 0, v[100:101]
	flat_load_dwordx4 v[80:83], v[102:103] nt
	flat_load_dwordx4 v[84:87], v[88:89] nt
	s_waitcnt vmcnt(0) lgkmcnt(0)
	v_lshlrev_b32_e32 v90, 16, v80
	v_and_b32_e32 v80, 0xffff0000, v80
	v_lshlrev_b32_e32 v91, 16, v81
	v_and_b32_e32 v81, 0xffff0000, v81
	v_lshlrev_b32_e32 v92, 16, v82
	v_and_b32_e32 v82, 0xffff0000, v82
	v_lshlrev_b32_e32 v93, 16, v83
	v_and_b32_e32 v83, 0xffff0000, v83
	v_lshlrev_b32_e32 v94, 16, v84
	v_and_b32_e32 v84, 0xffff0000, v84
	v_lshlrev_b32_e32 v95, 16, v85
	v_and_b32_e32 v85, 0xffff0000, v85
	v_lshlrev_b32_e32 v96, 16, v86
	v_and_b32_e32 v86, 0xffff0000, v86
	v_lshlrev_b32_e32 v97, 16, v87
	v_and_b32_e32 v87, 0xffff0000, v87
	v_fmac_f32_e32 v94, v76, v90
	v_fmac_f32_e32 v84, v77, v80
	v_fmac_f32_e32 v95, v78, v91
	v_fmac_f32_e32 v85, v79, v81
	v_fmac_f32_e32 v96, v72, v92
	v_fmac_f32_e32 v86, v73, v82
	v_fmac_f32_e32 v97, v74, v93
	v_fmac_f32_e32 v87, v75, v83
	s_nop 1
	v_cvt_pk_bf16_f32 v72, v94, v84
	s_nop 1
	v_cvt_pk_bf16_f32 v73, v95, v85
	s_nop 1
	v_cvt_pk_bf16_f32 v74, v96, v86
	s_nop 1
	v_cvt_pk_bf16_f32 v75, v97, v87
	flat_load_dwordx4 v[76:79], v[102:103] offset:256 nt
	flat_load_dwordx4 v[80:83], v[88:89] offset:256 nt
	v_lshl_add_u64 v[84:85], v[144:145], 0, s[18:19]
	flat_store_dwordx4 v[88:89], v[72:75]
	v_lshl_add_u64 v[86:87], s[4:5], 0, v[84:85]
	s_waitcnt vmcnt(0) lgkmcnt(0)
	v_lshlrev_b32_e32 v90, 16, v80
	v_lshlrev_b32_e32 v72, 16, v76
	v_and_b32_e32 v73, 0xffff0000, v76
	v_lshlrev_b32_e32 v74, 16, v77
	v_and_b32_e32 v75, 0xffff0000, v77
	v_lshlrev_b32_e32 v76, 16, v78
	v_and_b32_e32 v77, 0xffff0000, v78
	v_lshlrev_b32_e32 v78, 16, v79
	v_and_b32_e32 v79, 0xffff0000, v79
	v_and_b32_e32 v80, 0xffff0000, v80
	v_lshlrev_b32_e32 v91, 16, v81
	v_and_b32_e32 v81, 0xffff0000, v81
	v_lshlrev_b32_e32 v92, 16, v82
	v_and_b32_e32 v82, 0xffff0000, v82
	v_lshlrev_b32_e32 v93, 16, v83
	v_and_b32_e32 v83, 0xffff0000, v83
	v_fmac_f32_e32 v90, v68, v72
	v_fmac_f32_e32 v80, v69, v73
	v_fmac_f32_e32 v91, v70, v74
	v_fmac_f32_e32 v81, v71, v75
	v_fmac_f32_e32 v92, v64, v76
	v_fmac_f32_e32 v82, v65, v77
	v_fmac_f32_e32 v93, v66, v78
	v_fmac_f32_e32 v83, v67, v79
	s_nop 1
	v_cvt_pk_bf16_f32 v64, v90, v80
	s_nop 1
	v_cvt_pk_bf16_f32 v65, v91, v81
	s_nop 1
	v_cvt_pk_bf16_f32 v66, v92, v82
	s_nop 1
	v_cvt_pk_bf16_f32 v67, v93, v83
	flat_store_dwordx4 v[88:89], v[64:67] offset:256
	v_lshl_add_u64 v[72:73], s[6:7], 0, v[84:85]
	flat_load_dwordx4 v[64:67], v[86:87] nt
	flat_load_dwordx4 v[68:71], v[72:73] nt
	s_waitcnt vmcnt(0) lgkmcnt(0)
	v_lshlrev_b32_e32 v74, 16, v64
	v_and_b32_e32 v64, 0xffff0000, v64
	v_lshlrev_b32_e32 v75, 16, v65
	v_and_b32_e32 v65, 0xffff0000, v65
	v_lshlrev_b32_e32 v76, 16, v66
	v_and_b32_e32 v66, 0xffff0000, v66
	v_lshlrev_b32_e32 v77, 16, v67
	v_and_b32_e32 v67, 0xffff0000, v67
	v_lshlrev_b32_e32 v78, 16, v68
	v_and_b32_e32 v68, 0xffff0000, v68
	v_lshlrev_b32_e32 v79, 16, v69
	v_and_b32_e32 v69, 0xffff0000, v69
	v_lshlrev_b32_e32 v80, 16, v70
	v_and_b32_e32 v70, 0xffff0000, v70
	v_lshlrev_b32_e32 v81, 16, v71
	v_and_b32_e32 v71, 0xffff0000, v71
	v_fmac_f32_e32 v78, v60, v74
	v_fmac_f32_e32 v68, v61, v64
	v_fmac_f32_e32 v79, v62, v75
	v_fmac_f32_e32 v69, v63, v65
	v_fmac_f32_e32 v80, v56, v76
	v_fmac_f32_e32 v70, v57, v66
	v_fmac_f32_e32 v81, v58, v77
	v_fmac_f32_e32 v71, v59, v67
	s_nop 1
	v_cvt_pk_bf16_f32 v56, v78, v68
	s_nop 1
	v_cvt_pk_bf16_f32 v57, v79, v69
	s_nop 1
	v_cvt_pk_bf16_f32 v58, v80, v70
	s_nop 1
	v_cvt_pk_bf16_f32 v59, v81, v71
	flat_load_dwordx4 v[60:63], v[86:87] offset:256 nt
	flat_load_dwordx4 v[64:67], v[72:73] offset:256 nt
	v_lshl_add_u64 v[68:69], v[144:145], 0, s[20:21]
	flat_store_dwordx4 v[72:73], v[56:59]
	v_lshl_add_u64 v[70:71], s[4:5], 0, v[68:69]
	s_waitcnt vmcnt(0) lgkmcnt(0)
; __device__ __forceinline__ float bf_lo(unsigned u) { return __uint_as_float(u << 16); }
; __device__ __forceinline__ float bf_hi(unsigned u) { return __uint_as_float(u & 0xffff0000u); }
; __device__ __forceinline__ u32x4 pack8(f32x4 a, f32x4 b) { u32x4 w; w.x = cvt_pk_bf16(a[0], a[1]); w.y = cvt_pk_bf16(a[2], a[3]); w.z = cvt_pk_bf16(b[0], b[1]); w.w = cvt_pk_bf16(b[2], b[3]); return w; }
;     __device__ __forceinline__ void operator()(AccRef acc, const Unit& u, int wr, int wc, int fr, int fq) const {
;     ...
;                 for (int bj = 0; bj < 2; ++bj) {
;                     const u32x4 gv = *(const u32x4*)(G + off + bj * HALF);
;                     f32x4 v0 = acc[ai][bj][m][0], v1 = acc[ai][bj][m][1];
;                     v0[0] *= bf_lo(gv.x); v0[1] *= bf_hi(gv.x); v0[2] *= bf_lo(gv.y); v0[3] *= bf_hi(gv.y);
;                     v1[0] *= bf_lo(gv.z); v1[1] *= bf_hi(gv.z); v1[2] *= bf_lo(gv.w); v1[3] *= bf_hi(gv.w);
;                     if (ADD) {
;                         const u32x4 tv = *(const u32x4*)(T + off + bj * HALF);
;                         v0[0] += bf_lo(tv.x); v0[1] += bf_hi(tv.x); v0[2] += bf_lo(tv.y); v0[3] += bf_hi(tv.y);
;                         v1[0] += bf_lo(tv.z); v1[1] += bf_hi(tv.z); v1[2] += bf_lo(tv.w); v1[3] += bf_hi(tv.w);
;                     }
;                     *(u32x4*)(T + off + bj * HALF) = pack8(v0, v1);
	v_lshlrev_b32_e32 v74, 16, v64
	v_lshlrev_b32_e32 v56, 16, v60
	v_and_b32_e32 v57, 0xffff0000, v60
	v_lshlrev_b32_e32 v58, 16, v61
	v_and_b32_e32 v59, 0xffff0000, v61
	v_lshlrev_b32_e32 v60, 16, v62
	v_and_b32_e32 v61, 0xffff0000, v62
	v_lshlrev_b32_e32 v62, 16, v63
	v_and_b32_e32 v63, 0xffff0000, v63
	v_and_b32_e32 v64, 0xffff0000, v64
	v_lshlrev_b32_e32 v75, 16, v65
	v_and_b32_e32 v65, 0xffff0000, v65
	v_lshlrev_b32_e32 v76, 16, v66
	v_and_b32_e32 v66, 0xffff0000, v66
	v_lshlrev_b32_e32 v77, 16, v67
	v_and_b32_e32 v67, 0xffff0000, v67
	v_fmac_f32_e32 v74, v52, v56
	v_fmac_f32_e32 v64, v53, v57
	v_fmac_f32_e32 v75, v54, v58
	v_fmac_f32_e32 v65, v55, v59
	v_fmac_f32_e32 v76, v48, v60
	v_fmac_f32_e32 v66, v49, v61
	v_fmac_f32_e32 v77, v50, v62
	v_fmac_f32_e32 v67, v51, v63
	s_nop 1
	v_cvt_pk_bf16_f32 v48, v74, v64
	s_nop 1
	v_cvt_pk_bf16_f32 v49, v75, v65
	s_nop 1
	v_cvt_pk_bf16_f32 v50, v76, v66
	s_nop 1
	v_cvt_pk_bf16_f32 v51, v77, v67
	flat_store_dwordx4 v[72:73], v[48:51] offset:256
	v_lshl_add_u64 v[56:57], s[6:7], 0, v[68:69]
	flat_load_dwordx4 v[48:51], v[70:71] nt
	flat_load_dwordx4 v[52:55], v[56:57] nt
	s_waitcnt vmcnt(0) lgkmcnt(0)
	v_lshlrev_b32_e32 v58, 16, v48
	v_and_b32_e32 v48, 0xffff0000, v48
	v_lshlrev_b32_e32 v59, 16, v49
	v_and_b32_e32 v49, 0xffff0000, v49
	v_lshlrev_b32_e32 v60, 16, v50
	v_and_b32_e32 v50, 0xffff0000, v50
	v_lshlrev_b32_e32 v61, 16, v51
	v_and_b32_e32 v51, 0xffff0000, v51
	v_lshlrev_b32_e32 v62, 16, v52
	v_and_b32_e32 v52, 0xffff0000, v52
	v_lshlrev_b32_e32 v63, 16, v53
	v_and_b32_e32 v53, 0xffff0000, v53
	v_lshlrev_b32_e32 v64, 16, v54
	v_and_b32_e32 v54, 0xffff0000, v54
	v_lshlrev_b32_e32 v65, 16, v55
	v_and_b32_e32 v55, 0xffff0000, v55
	v_fmac_f32_e32 v62, v44, v58
	v_fmac_f32_e32 v52, v45, v48
	v_fmac_f32_e32 v63, v46, v59
	v_fmac_f32_e32 v53, v47, v49
	v_fmac_f32_e32 v64, v40, v60
	v_fmac_f32_e32 v54, v41, v50
	v_fmac_f32_e32 v65, v42, v61
	v_fmac_f32_e32 v55, v43, v51
	s_nop 1
	v_cvt_pk_bf16_f32 v40, v62, v52
	s_nop 1
	v_cvt_pk_bf16_f32 v41, v63, v53
	s_nop 1
	v_cvt_pk_bf16_f32 v42, v64, v54
	s_nop 1
	v_cvt_pk_bf16_f32 v43, v65, v55
	flat_load_dwordx4 v[44:47], v[70:71] offset:256 nt
	flat_load_dwordx4 v[48:51], v[56:57] offset:256 nt
	v_lshl_add_u64 v[52:53], v[144:145], 0, s[22:23]
	flat_store_dwordx4 v[56:57], v[40:43]
	v_lshl_add_u64 v[54:55], s[4:5], 0, v[52:53]
	s_waitcnt vmcnt(0) lgkmcnt(0)
	v_lshlrev_b32_e32 v58, 16, v48
	v_lshlrev_b32_e32 v40, 16, v44
	v_and_b32_e32 v41, 0xffff0000, v44
	v_lshlrev_b32_e32 v42, 16, v45
	v_and_b32_e32 v43, 0xffff0000, v45
	v_lshlrev_b32_e32 v44, 16, v46
	v_and_b32_e32 v45, 0xffff0000, v46
	v_lshlrev_b32_e32 v46, 16, v47
	v_and_b32_e32 v47, 0xffff0000, v47
	v_and_b32_e32 v48, 0xffff0000, v48
	v_lshlrev_b32_e32 v59, 16, v49
	v_and_b32_e32 v49, 0xffff0000, v49
	v_lshlrev_b32_e32 v60, 16, v50
	v_and_b32_e32 v50, 0xffff0000, v50
	v_lshlrev_b32_e32 v61, 16, v51
	v_and_b32_e32 v51, 0xffff0000, v51
	v_fmac_f32_e32 v58, v36, v40
	v_fmac_f32_e32 v48, v37, v41
	v_fmac_f32_e32 v59, v38, v42
	v_fmac_f32_e32 v49, v39, v43
	v_fmac_f32_e32 v60, v32, v44
	v_fmac_f32_e32 v50, v33, v45
	v_fmac_f32_e32 v61, v34, v46
	v_fmac_f32_e32 v51, v35, v47
	s_nop 1
	v_cvt_pk_bf16_f32 v32, v58, v48
	s_nop 1
	v_cvt_pk_bf16_f32 v33, v59, v49
	s_nop 1
	v_cvt_pk_bf16_f32 v34, v60, v50
	s_nop 1
	v_cvt_pk_bf16_f32 v35, v61, v51
	flat_store_dwordx4 v[56:57], v[32:35] offset:256
	v_lshl_add_u64 v[40:41], s[6:7], 0, v[52:53]
	flat_load_dwordx4 v[32:35], v[54:55] nt
	flat_load_dwordx4 v[36:39], v[40:41] nt
	s_waitcnt vmcnt(0) lgkmcnt(0)
; __device__ __forceinline__ float bf_lo(unsigned u) { return __uint_as_float(u << 16); }
; __device__ __forceinline__ float bf_hi(unsigned u) { return __uint_as_float(u & 0xffff0000u); }
; __device__ __forceinline__ u32x4 pack8(f32x4 a, f32x4 b) { u32x4 w; w.x = cvt_pk_bf16(a[0], a[1]); w.y = cvt_pk_bf16(a[2], a[3]); w.z = cvt_pk_bf16(b[0], b[1]); w.w = cvt_pk_bf16(b[2], b[3]); return w; }
; #define PG8_BAR __builtin_amdgcn_s_barrier()
; template <class Epi>
; __device__ __forceinline__ void gemm_phase(ldsp lds, const Gemm g, const StaticOrder& S, const Epi& E, int wave0) {
;     ...
;         if (wr == 1) PG8_BAR;
;     __device__ __forceinline__ void operator()(AccRef acc, const Unit& u, int wr, int wc, int fr, int fq) const {
;     ...
;                 for (int bj = 0; bj < 2; ++bj) {
;                     const u32x4 gv = *(const u32x4*)(G + off + bj * HALF);
;                     f32x4 v0 = acc[ai][bj][m][0], v1 = acc[ai][bj][m][1];
;                     v0[0] *= bf_lo(gv.x); v0[1] *= bf_hi(gv.x); v0[2] *= bf_lo(gv.y); v0[3] *= bf_hi(gv.y);
;                     v1[0] *= bf_lo(gv.z); v1[1] *= bf_hi(gv.z); v1[2] *= bf_lo(gv.w); v1[3] *= bf_hi(gv.w);
;                     if (ADD) {
;                         const u32x4 tv = *(const u32x4*)(T + off + bj * HALF);
;                         v0[0] += bf_lo(tv.x); v0[1] += bf_hi(tv.x); v0[2] += bf_lo(tv.y); v0[3] += bf_hi(tv.y);
;                         v1[0] += bf_lo(tv.z); v1[1] += bf_hi(tv.z); v1[2] += bf_lo(tv.w); v1[3] += bf_hi(tv.w);
;                     }
;                     *(u32x4*)(T + off + bj * HALF) = pack8(v0, v1);
	v_lshlrev_b32_e32 v42, 16, v32
	v_and_b32_e32 v32, 0xffff0000, v32
	v_lshlrev_b32_e32 v43, 16, v33
	v_and_b32_e32 v33, 0xffff0000, v33
	v_lshlrev_b32_e32 v44, 16, v34
	v_and_b32_e32 v34, 0xffff0000, v34
	v_lshlrev_b32_e32 v45, 16, v35
	v_and_b32_e32 v35, 0xffff0000, v35
	v_lshlrev_b32_e32 v46, 16, v36
	v_and_b32_e32 v36, 0xffff0000, v36
	v_lshlrev_b32_e32 v47, 16, v37
	v_and_b32_e32 v37, 0xffff0000, v37
	v_lshlrev_b32_e32 v48, 16, v38
	v_and_b32_e32 v38, 0xffff0000, v38
	v_lshlrev_b32_e32 v49, 16, v39
	v_and_b32_e32 v39, 0xffff0000, v39
	v_fmac_f32_e32 v46, v28, v42
	v_fmac_f32_e32 v36, v29, v32
	v_fmac_f32_e32 v47, v30, v43
	v_fmac_f32_e32 v37, v31, v33
	v_fmac_f32_e32 v48, v24, v44
	v_fmac_f32_e32 v38, v25, v34
	v_fmac_f32_e32 v49, v26, v45
	v_fmac_f32_e32 v39, v27, v35
	s_nop 1
	v_cvt_pk_bf16_f32 v24, v46, v36
	s_nop 1
	v_cvt_pk_bf16_f32 v25, v47, v37
	s_nop 1
	v_cvt_pk_bf16_f32 v26, v48, v38
	s_nop 1
	v_cvt_pk_bf16_f32 v27, v49, v39
	flat_load_dwordx4 v[28:31], v[54:55] offset:256 nt
	flat_load_dwordx4 v[32:35], v[40:41] offset:256 nt
	v_lshl_add_u64 v[36:37], v[144:145], 0, s[24:25]
	flat_store_dwordx4 v[40:41], v[24:27]
	v_lshl_add_u64 v[38:39], s[4:5], 0, v[36:37]
	s_waitcnt vmcnt(0) lgkmcnt(0)
	v_lshlrev_b32_e32 v42, 16, v32
	v_lshlrev_b32_e32 v24, 16, v28
	v_and_b32_e32 v25, 0xffff0000, v28
	v_lshlrev_b32_e32 v26, 16, v29
	v_and_b32_e32 v27, 0xffff0000, v29
	v_lshlrev_b32_e32 v28, 16, v30
	v_and_b32_e32 v29, 0xffff0000, v30
	v_lshlrev_b32_e32 v30, 16, v31
	v_and_b32_e32 v31, 0xffff0000, v31
	v_and_b32_e32 v32, 0xffff0000, v32
	v_lshlrev_b32_e32 v43, 16, v33
	v_and_b32_e32 v33, 0xffff0000, v33
	v_lshlrev_b32_e32 v44, 16, v34
	v_and_b32_e32 v34, 0xffff0000, v34
	v_lshlrev_b32_e32 v45, 16, v35
	v_and_b32_e32 v35, 0xffff0000, v35
	v_fmac_f32_e32 v42, v20, v24
	v_fmac_f32_e32 v32, v21, v25
	v_fmac_f32_e32 v43, v22, v26
	v_fmac_f32_e32 v33, v23, v27
	v_fmac_f32_e32 v44, v16, v28
	v_fmac_f32_e32 v34, v17, v29
	v_fmac_f32_e32 v45, v18, v30
	v_fmac_f32_e32 v35, v19, v31
	s_nop 1
	v_cvt_pk_bf16_f32 v16, v42, v32
	s_nop 1
	v_cvt_pk_bf16_f32 v17, v43, v33
	s_nop 1
	v_cvt_pk_bf16_f32 v18, v44, v34
	s_nop 1
	v_cvt_pk_bf16_f32 v19, v45, v35
	flat_store_dwordx4 v[40:41], v[16:19] offset:256
	v_lshl_add_u64 v[24:25], s[6:7], 0, v[36:37]
	flat_load_dwordx4 v[16:19], v[38:39] nt
	flat_load_dwordx4 v[20:23], v[24:25] nt
	s_waitcnt vmcnt(0) lgkmcnt(0)
	v_lshlrev_b32_e32 v26, 16, v16
	v_and_b32_e32 v16, 0xffff0000, v16
	v_lshlrev_b32_e32 v27, 16, v17
	v_and_b32_e32 v17, 0xffff0000, v17
	v_lshlrev_b32_e32 v28, 16, v18
	v_and_b32_e32 v18, 0xffff0000, v18
	v_lshlrev_b32_e32 v29, 16, v19
	v_and_b32_e32 v19, 0xffff0000, v19
	v_lshlrev_b32_e32 v30, 16, v20
	v_and_b32_e32 v20, 0xffff0000, v20
	v_lshlrev_b32_e32 v31, 16, v21
	v_and_b32_e32 v21, 0xffff0000, v21
	v_lshlrev_b32_e32 v32, 16, v22
	v_and_b32_e32 v22, 0xffff0000, v22
	v_lshlrev_b32_e32 v33, 16, v23
	v_and_b32_e32 v23, 0xffff0000, v23
	v_fmac_f32_e32 v30, v12, v26
	v_fmac_f32_e32 v20, v13, v16
	v_fmac_f32_e32 v31, v14, v27
	v_fmac_f32_e32 v21, v15, v17
	v_fmac_f32_e32 v32, v8, v28
	v_fmac_f32_e32 v22, v9, v18
	v_fmac_f32_e32 v33, v10, v29
	v_fmac_f32_e32 v23, v11, v19
	s_nop 1
	v_cvt_pk_bf16_f32 v8, v30, v20
	s_nop 1
	v_cvt_pk_bf16_f32 v9, v31, v21
	s_nop 1
	v_cvt_pk_bf16_f32 v10, v32, v22
	s_nop 1
	v_cvt_pk_bf16_f32 v11, v33, v23
	flat_load_dwordx4 v[12:15], v[38:39] offset:256 nt
	flat_load_dwordx4 v[16:19], v[24:25] offset:256 nt
	s_waitcnt vmcnt(0) lgkmcnt(0)
	v_lshlrev_b32_e32 v20, 16, v16
	flat_store_dwordx4 v[24:25], v[8:11]
	v_and_b32_e32 v16, 0xffff0000, v16
	v_lshlrev_b32_e32 v21, 16, v17
	v_lshlrev_b32_e32 v8, 16, v12
	v_and_b32_e32 v9, 0xffff0000, v12
	v_lshlrev_b32_e32 v10, 16, v13
	v_and_b32_e32 v11, 0xffff0000, v13
	v_lshlrev_b32_e32 v12, 16, v14
	v_and_b32_e32 v13, 0xffff0000, v14
	v_lshlrev_b32_e32 v14, 16, v15
	v_and_b32_e32 v15, 0xffff0000, v15
	v_and_b32_e32 v17, 0xffff0000, v17
	v_lshlrev_b32_e32 v22, 16, v18
	v_and_b32_e32 v18, 0xffff0000, v18
	v_lshlrev_b32_e32 v23, 16, v19
	v_and_b32_e32 v19, 0xffff0000, v19
	v_fmac_f32_e32 v20, v4, v8
	v_fmac_f32_e32 v16, v5, v9
	v_fmac_f32_e32 v21, v6, v10
	v_fmac_f32_e32 v17, v7, v11
	v_fmac_f32_e32 v22, v0, v12
	v_fmac_f32_e32 v18, v1, v13
	v_fmac_f32_e32 v23, v2, v14
	v_fmac_f32_e32 v19, v3, v15
	s_nop 1
	v_cvt_pk_bf16_f32 v0, v20, v16
	s_nop 1
	v_cvt_pk_bf16_f32 v1, v21, v17
	s_nop 1
	v_cvt_pk_bf16_f32 v2, v22, v18
	s_nop 1
	v_cvt_pk_bf16_f32 v3, v23, v19
	flat_store_dwordx4 v[24:25], v[0:3] offset:256
	s_cbranch_vccnz .LBB0_705
	s_andn2_b64 vcc, exec, s[2:3]
	s_cbranch_vccnz .LBB0_704
	s_barrier
	s_branch .LBB0_704

; __device__ __forceinline__ float bf_lo(unsigned u) { return __uint_as_float(u << 16); }
; __device__ __forceinline__ float bf_hi(unsigned u) { return __uint_as_float(u & 0xffff0000u); }
;     __device__ __forceinline__ void operator()(AccRef acc, const Unit& u, int wr, int wc, int fr, int fq) const {
;     ...
;         for (int ai = 0; ai < 2; ++ai)
; #pragma unroll
;             for (int m = 0; m < 4; ++m) {
;                 const size_t off = (size_t)(row0 + ai * HALF + m * 16) * D + col0;
; #pragma unroll
;                 for (int bj = 0; bj < 2; ++bj) {
;                     const u32x4 hv = *(const u32x4*)(hb + off + bj * HALF);
;                     f32x4 r0, r1;
;                     r0[0] = bf_lo(hv.x); r0[1] = bf_hi(hv.x); r0[2] = bf_lo(hv.y); r0[3] = bf_hi(hv.y); r1[0] = bf_lo(hv.z); r1[1] = bf_hi(hv.z); r1[2] = bf_lo(hv.w); r1[3] = bf_hi(hv.w);
;                     *(f32x4*)(out + off + bj * HALF) = r0 * alpha + acc[ai][bj][m][0] * s;
;                     *(f32x4*)(out + off + bj * HALF + 4) = r1 * alpha + acc[ai][bj][m][1] * s;
;                 }
;                 if (m == 3) asm volatile("" ::: "memory");
.LBB0_784:
	v_mov_b32_e32 v144, v147
	v_mov_b32_e32 v145, v146
	s_lshl_b32 s29, s38, 8
	s_add_i32 s29, s29, s57
	v_add_u32_e32 v144, s29, v144
	s_lshl_b32 s29, s64, 8
	s_or_b32 s29, s29, s58
	v_lshl_add_u32 v152, v145, 3, s29
	v_ashrrev_i32_e32 v145, 31, v144
	v_ashrrev_i32_e32 v153, 31, v152
	v_lshlrev_b64 v[144:145], 11, v[144:145]
	v_lshl_add_u64 v[144:145], v[144:145], 0, v[152:153]
	s_andn2_b64 vcc, exec, s[0:1]
	s_mov_b64 s[0:1], -1
	v_lshl_add_u64 v[238:239], v[144:145], 1, s[6:7]
	global_load_dwordx4 v[160:163], v[238:239], off nt
	global_load_dwordx4 v[164:167], v[238:239], off offset:256 nt
	v_lshl_add_u64 v[224:225], v[144:145], 0, s[14:15]
	v_lshl_add_u64 v[240:241], v[224:225], 1, s[6:7]
	global_load_dwordx4 v[168:171], v[240:241], off nt
	global_load_dwordx4 v[172:175], v[240:241], off offset:256 nt
	v_lshl_add_u64 v[226:227], v[144:145], 0, s[16:17]
	v_lshl_add_u64 v[242:243], v[226:227], 1, s[6:7]
	global_load_dwordx4 v[176:179], v[242:243], off nt
	global_load_dwordx4 v[180:183], v[242:243], off offset:256 nt
	v_lshl_add_u64 v[228:229], v[144:145], 0, s[18:19]
	v_lshl_add_u64 v[244:245], v[228:229], 1, s[6:7]
	global_load_dwordx4 v[184:187], v[244:245], off nt
	global_load_dwordx4 v[188:191], v[244:245], off offset:256 nt
	v_lshl_add_u64 v[230:231], v[144:145], 0, s[20:21]
	v_lshl_add_u64 v[246:247], v[230:231], 1, s[6:7]
	global_load_dwordx4 v[192:195], v[246:247], off nt
	global_load_dwordx4 v[196:199], v[246:247], off offset:256 nt
	v_lshl_add_u64 v[232:233], v[144:145], 0, s[22:23]
	v_lshl_add_u64 v[248:249], v[232:233], 1, s[6:7]
	global_load_dwordx4 v[200:203], v[248:249], off nt
	global_load_dwordx4 v[204:207], v[248:249], off offset:256 nt
	v_lshl_add_u64 v[234:235], v[144:145], 0, s[24:25]
	v_lshl_add_u64 v[250:251], v[234:235], 1, s[6:7]
	global_load_dwordx4 v[208:211], v[250:251], off nt
	global_load_dwordx4 v[212:215], v[250:251], off offset:256 nt
	v_lshl_add_u64 v[236:237], v[144:145], 0, s[26:27]
	v_lshl_add_u64 v[252:253], v[236:237], 1, s[6:7]
	global_load_dwordx4 v[216:219], v[252:253], off nt
	global_load_dwordx4 v[220:223], v[252:253], off offset:256 nt
	v_lshl_add_u64 v[152:153], v[144:145], 2, s[2:3]
	s_waitcnt vmcnt(15)
	v_lshlrev_b32_e32 v156, 16, v160
	v_and_b32_e32 v157, 0xffff0000, v160
	v_lshlrev_b32_e32 v160, 16, v161
	v_and_b32_e32 v161, 0xffff0000, v161
	v_lshlrev_b32_e32 v158, 16, v162
	v_and_b32_e32 v159, 0xffff0000, v162
	v_lshlrev_b32_e32 v162, 16, v163
	v_and_b32_e32 v163, 0xffff0000, v163
	v_pk_fma_f32 v[126:127], v[160:161], s[12:13], v[126:127] op_sel_hi:[1,0,1]
	v_pk_fma_f32 v[124:125], v[156:157], s[12:13], v[124:125] op_sel_hi:[1,0,1]
	v_pk_fma_f32 v[122:123], v[162:163], s[12:13], v[122:123] op_sel_hi:[1,0,1]
	v_pk_fma_f32 v[120:121], v[158:159], s[12:13], v[120:121] op_sel_hi:[1,0,1]
	global_store_dwordx4 v[152:153], v[124:127], off
	global_store_dwordx4 v[152:153], v[120:123], off offset:16
	s_waitcnt vmcnt(16)
	v_lshlrev_b32_e32 v156, 16, v164
	v_and_b32_e32 v157, 0xffff0000, v164
	v_lshlrev_b32_e32 v164, 16, v165
	v_and_b32_e32 v165, 0xffff0000, v165
	v_lshlrev_b32_e32 v158, 16, v166
	v_and_b32_e32 v159, 0xffff0000, v166
	v_lshlrev_b32_e32 v166, 16, v167
	v_and_b32_e32 v167, 0xffff0000, v167
	v_pk_fma_f32 v[118:119], v[164:165], s[12:13], v[118:119] op_sel_hi:[1,0,1]
	v_pk_fma_f32 v[116:117], v[156:157], s[12:13], v[116:117] op_sel_hi:[1,0,1]
	v_pk_fma_f32 v[114:115], v[166:167], s[12:13], v[114:115] op_sel_hi:[1,0,1]
	v_pk_fma_f32 v[112:113], v[158:159], s[12:13], v[112:113] op_sel_hi:[1,0,1]
	global_store_dwordx4 v[152:153], v[116:119], off offset:512
	global_store_dwordx4 v[152:153], v[112:115], off offset:528
	v_lshl_add_u64 v[154:155], v[224:225], 2, s[2:3]
	s_waitcnt vmcnt(17)
	v_lshlrev_b32_e32 v156, 16, v168
	v_and_b32_e32 v157, 0xffff0000, v168
	v_lshlrev_b32_e32 v168, 16, v169
	v_and_b32_e32 v169, 0xffff0000, v169
	v_lshlrev_b32_e32 v158, 16, v170
	v_and_b32_e32 v159, 0xffff0000, v170
	v_lshlrev_b32_e32 v170, 16, v171
	v_and_b32_e32 v171, 0xffff0000, v171
	v_pk_fma_f32 v[110:111], v[168:169], s[12:13], v[110:111] op_sel_hi:[1,0,1]
	v_pk_fma_f32 v[108:109], v[156:157], s[12:13], v[108:109] op_sel_hi:[1,0,1]
	v_pk_fma_f32 v[106:107], v[170:171], s[12:13], v[106:107] op_sel_hi:[1,0,1]
	v_pk_fma_f32 v[104:105], v[158:159], s[12:13], v[104:105] op_sel_hi:[1,0,1]
	global_store_dwordx4 v[154:155], v[108:111], off
	global_store_dwordx4 v[154:155], v[104:107], off offset:16
	s_waitcnt vmcnt(18)
	v_lshlrev_b32_e32 v156, 16, v172
	v_and_b32_e32 v157, 0xffff0000, v172
	v_lshlrev_b32_e32 v172, 16, v173
	v_and_b32_e32 v173, 0xffff0000, v173
	v_lshlrev_b32_e32 v158, 16, v174
	v_and_b32_e32 v159, 0xffff0000, v174
	v_lshlrev_b32_e32 v174, 16, v175
	v_and_b32_e32 v175, 0xffff0000, v175
	v_pk_fma_f32 v[102:103], v[172:173], s[12:13], v[102:103] op_sel_hi:[1,0,1]
	v_pk_fma_f32 v[100:101], v[156:157], s[12:13], v[100:101] op_sel_hi:[1,0,1]
	v_pk_fma_f32 v[98:99], v[174:175], s[12:13], v[98:99] op_sel_hi:[1,0,1]
	v_pk_fma_f32 v[96:97], v[158:159], s[12:13], v[96:97] op_sel_hi:[1,0,1]
	global_store_dwordx4 v[154:155], v[100:103], off offset:512
	global_store_dwordx4 v[154:155], v[96:99], off offset:528
	v_lshl_add_u64 v[152:153], v[226:227], 2, s[2:3]
	s_waitcnt vmcnt(19)
	v_lshlrev_b32_e32 v156, 16, v176
	v_and_b32_e32 v157, 0xffff0000, v176
	v_lshlrev_b32_e32 v176, 16, v177
	v_and_b32_e32 v177, 0xffff0000, v177
	v_lshlrev_b32_e32 v158, 16, v178
	v_and_b32_e32 v159, 0xffff0000, v178
	v_lshlrev_b32_e32 v178, 16, v179
	v_and_b32_e32 v179, 0xffff0000, v179
	v_pk_fma_f32 v[94:95], v[176:177], s[12:13], v[94:95] op_sel_hi:[1,0,1]
	v_pk_fma_f32 v[92:93], v[156:157], s[12:13], v[92:93] op_sel_hi:[1,0,1]
	v_pk_fma_f32 v[90:91], v[178:179], s[12:13], v[90:91] op_sel_hi:[1,0,1]
	v_pk_fma_f32 v[88:89], v[158:159], s[12:13], v[88:89] op_sel_hi:[1,0,1]
	global_store_dwordx4 v[152:153], v[92:95], off
	global_store_dwordx4 v[152:153], v[88:91], off offset:16
	s_waitcnt vmcnt(20)
; __device__ __forceinline__ float bf_lo(unsigned u) { return __uint_as_float(u << 16); }
; __device__ __forceinline__ float bf_hi(unsigned u) { return __uint_as_float(u & 0xffff0000u); }
;     __device__ __forceinline__ void operator()(AccRef acc, const Unit& u, int wr, int wc, int fr, int fq) const {
;     ...
;                 for (int bj = 0; bj < 2; ++bj) {
;                     const u32x4 hv = *(const u32x4*)(hb + off + bj * HALF);
;                     f32x4 r0, r1;
;                     r0[0] = bf_lo(hv.x); r0[1] = bf_hi(hv.x); r0[2] = bf_lo(hv.y); r0[3] = bf_hi(hv.y); r1[0] = bf_lo(hv.z); r1[1] = bf_hi(hv.z); r1[2] = bf_lo(hv.w); r1[3] = bf_hi(hv.w);
;                     *(f32x4*)(out + off + bj * HALF) = r0 * alpha + acc[ai][bj][m][0] * s;
;                     *(f32x4*)(out + off + bj * HALF + 4) = r1 * alpha + acc[ai][bj][m][1] * s;
;                 }
	v_lshlrev_b32_e32 v156, 16, v180
	v_and_b32_e32 v157, 0xffff0000, v180
	v_lshlrev_b32_e32 v180, 16, v181
	v_and_b32_e32 v181, 0xffff0000, v181
	v_lshlrev_b32_e32 v158, 16, v182
	v_and_b32_e32 v159, 0xffff0000, v182
	v_lshlrev_b32_e32 v182, 16, v183
	v_and_b32_e32 v183, 0xffff0000, v183
	v_pk_fma_f32 v[86:87], v[180:181], s[12:13], v[86:87] op_sel_hi:[1,0,1]
	v_pk_fma_f32 v[84:85], v[156:157], s[12:13], v[84:85] op_sel_hi:[1,0,1]
	v_pk_fma_f32 v[82:83], v[182:183], s[12:13], v[82:83] op_sel_hi:[1,0,1]
	v_pk_fma_f32 v[80:81], v[158:159], s[12:13], v[80:81] op_sel_hi:[1,0,1]
	global_store_dwordx4 v[152:153], v[84:87], off offset:512
	global_store_dwordx4 v[152:153], v[80:83], off offset:528
	v_lshl_add_u64 v[154:155], v[228:229], 2, s[2:3]
	s_waitcnt vmcnt(21)
	v_lshlrev_b32_e32 v156, 16, v184
	v_and_b32_e32 v157, 0xffff0000, v184
	v_lshlrev_b32_e32 v184, 16, v185
	v_and_b32_e32 v185, 0xffff0000, v185
	v_lshlrev_b32_e32 v158, 16, v186
	v_and_b32_e32 v159, 0xffff0000, v186
	v_lshlrev_b32_e32 v186, 16, v187
	v_and_b32_e32 v187, 0xffff0000, v187
	v_pk_fma_f32 v[78:79], v[184:185], s[12:13], v[78:79] op_sel_hi:[1,0,1]
	v_pk_fma_f32 v[76:77], v[156:157], s[12:13], v[76:77] op_sel_hi:[1,0,1]
	v_pk_fma_f32 v[74:75], v[186:187], s[12:13], v[74:75] op_sel_hi:[1,0,1]
	v_pk_fma_f32 v[72:73], v[158:159], s[12:13], v[72:73] op_sel_hi:[1,0,1]
	global_store_dwordx4 v[154:155], v[76:79], off
	global_store_dwordx4 v[154:155], v[72:75], off offset:16
	s_waitcnt vmcnt(22)
	v_lshlrev_b32_e32 v156, 16, v188
	v_and_b32_e32 v157, 0xffff0000, v188
	v_lshlrev_b32_e32 v188, 16, v189
	v_and_b32_e32 v189, 0xffff0000, v189
	v_lshlrev_b32_e32 v158, 16, v190
	v_and_b32_e32 v159, 0xffff0000, v190
	v_lshlrev_b32_e32 v190, 16, v191
	v_and_b32_e32 v191, 0xffff0000, v191
	v_pk_fma_f32 v[70:71], v[188:189], s[12:13], v[70:71] op_sel_hi:[1,0,1]
	v_pk_fma_f32 v[68:69], v[156:157], s[12:13], v[68:69] op_sel_hi:[1,0,1]
	v_pk_fma_f32 v[66:67], v[190:191], s[12:13], v[66:67] op_sel_hi:[1,0,1]
	v_pk_fma_f32 v[64:65], v[158:159], s[12:13], v[64:65] op_sel_hi:[1,0,1]
	global_store_dwordx4 v[154:155], v[68:71], off offset:512
	global_store_dwordx4 v[154:155], v[64:67], off offset:528
	v_lshl_add_u64 v[152:153], v[230:231], 2, s[2:3]
	s_waitcnt vmcnt(23)
	v_lshlrev_b32_e32 v156, 16, v192
	v_and_b32_e32 v157, 0xffff0000, v192
	v_lshlrev_b32_e32 v192, 16, v193
	v_and_b32_e32 v193, 0xffff0000, v193
	v_lshlrev_b32_e32 v158, 16, v194
	v_and_b32_e32 v159, 0xffff0000, v194
	v_lshlrev_b32_e32 v194, 16, v195
	v_and_b32_e32 v195, 0xffff0000, v195
	v_pk_fma_f32 v[62:63], v[192:193], s[12:13], v[62:63] op_sel_hi:[1,0,1]
	v_pk_fma_f32 v[60:61], v[156:157], s[12:13], v[60:61] op_sel_hi:[1,0,1]
	v_pk_fma_f32 v[58:59], v[194:195], s[12:13], v[58:59] op_sel_hi:[1,0,1]
	v_pk_fma_f32 v[56:57], v[158:159], s[12:13], v[56:57] op_sel_hi:[1,0,1]
	global_store_dwordx4 v[152:153], v[60:63], off
	global_store_dwordx4 v[152:153], v[56:59], off offset:16
	s_waitcnt vmcnt(24)
	v_lshlrev_b32_e32 v156, 16, v196
	v_and_b32_e32 v157, 0xffff0000, v196
	v_lshlrev_b32_e32 v196, 16, v197
	v_and_b32_e32 v197, 0xffff0000, v197
	v_lshlrev_b32_e32 v158, 16, v198
	v_and_b32_e32 v159, 0xffff0000, v198
	v_lshlrev_b32_e32 v198, 16, v199
	v_and_b32_e32 v199, 0xffff0000, v199
	v_pk_fma_f32 v[54:55], v[196:197], s[12:13], v[54:55] op_sel_hi:[1,0,1]
	v_pk_fma_f32 v[52:53], v[156:157], s[12:13], v[52:53] op_sel_hi:[1,0,1]
	v_pk_fma_f32 v[50:51], v[198:199], s[12:13], v[50:51] op_sel_hi:[1,0,1]
	v_pk_fma_f32 v[48:49], v[158:159], s[12:13], v[48:49] op_sel_hi:[1,0,1]
	global_store_dwordx4 v[152:153], v[52:55], off offset:512
	global_store_dwordx4 v[152:153], v[48:51], off offset:528
	v_lshl_add_u64 v[154:155], v[232:233], 2, s[2:3]
	s_waitcnt vmcnt(25)
	v_lshlrev_b32_e32 v156, 16, v200
	v_and_b32_e32 v157, 0xffff0000, v200
	v_lshlrev_b32_e32 v200, 16, v201
	v_and_b32_e32 v201, 0xffff0000, v201
	v_lshlrev_b32_e32 v158, 16, v202
	v_and_b32_e32 v159, 0xffff0000, v202
	v_lshlrev_b32_e32 v202, 16, v203
	v_and_b32_e32 v203, 0xffff0000, v203
	v_pk_fma_f32 v[46:47], v[200:201], s[12:13], v[46:47] op_sel_hi:[1,0,1]
	v_pk_fma_f32 v[44:45], v[156:157], s[12:13], v[44:45] op_sel_hi:[1,0,1]
	v_pk_fma_f32 v[42:43], v[202:203], s[12:13], v[42:43] op_sel_hi:[1,0,1]
	v_pk_fma_f32 v[40:41], v[158:159], s[12:13], v[40:41] op_sel_hi:[1,0,1]
	global_store_dwordx4 v[154:155], v[44:47], off
	global_store_dwordx4 v[154:155], v[40:43], off offset:16
	s_waitcnt vmcnt(26)
; __device__ __forceinline__ float bf_lo(unsigned u) { return __uint_as_float(u << 16); }
; __device__ __forceinline__ float bf_hi(unsigned u) { return __uint_as_float(u & 0xffff0000u); }
; #define PG8_BAR __builtin_amdgcn_s_barrier()
; template <class Epi>
; __device__ __forceinline__ void gemm_phase(ldsp lds, const Gemm g, const StaticOrder& S, const Epi& E, int wave0) {
;     ...
;         if (wr == 1) PG8_BAR;
;     __device__ __forceinline__ void operator()(AccRef acc, const Unit& u, int wr, int wc, int fr, int fq) const {
;     ...
;                 for (int bj = 0; bj < 2; ++bj) {
;                     const u32x4 hv = *(const u32x4*)(hb + off + bj * HALF);
;                     f32x4 r0, r1;
;                     r0[0] = bf_lo(hv.x); r0[1] = bf_hi(hv.x); r0[2] = bf_lo(hv.y); r0[3] = bf_hi(hv.y); r1[0] = bf_lo(hv.z); r1[1] = bf_hi(hv.z); r1[2] = bf_lo(hv.w); r1[3] = bf_hi(hv.w);
;                     *(f32x4*)(out + off + bj * HALF) = r0 * alpha + acc[ai][bj][m][0] * s;
;                     *(f32x4*)(out + off + bj * HALF + 4) = r1 * alpha + acc[ai][bj][m][1] * s;
;                 }
;                 if (m == 3) asm volatile("" ::: "memory");
	v_lshlrev_b32_e32 v156, 16, v204
	v_and_b32_e32 v157, 0xffff0000, v204
	v_lshlrev_b32_e32 v204, 16, v205
	v_and_b32_e32 v205, 0xffff0000, v205
	v_lshlrev_b32_e32 v158, 16, v206
	v_and_b32_e32 v159, 0xffff0000, v206
	v_lshlrev_b32_e32 v206, 16, v207
	v_and_b32_e32 v207, 0xffff0000, v207
	v_pk_fma_f32 v[38:39], v[204:205], s[12:13], v[38:39] op_sel_hi:[1,0,1]
	v_pk_fma_f32 v[36:37], v[156:157], s[12:13], v[36:37] op_sel_hi:[1,0,1]
	v_pk_fma_f32 v[34:35], v[206:207], s[12:13], v[34:35] op_sel_hi:[1,0,1]
	v_pk_fma_f32 v[32:33], v[158:159], s[12:13], v[32:33] op_sel_hi:[1,0,1]
	global_store_dwordx4 v[154:155], v[36:39], off offset:512
	global_store_dwordx4 v[154:155], v[32:35], off offset:528
	v_lshl_add_u64 v[152:153], v[234:235], 2, s[2:3]
	s_waitcnt vmcnt(27)
	v_lshlrev_b32_e32 v156, 16, v208
	v_and_b32_e32 v157, 0xffff0000, v208
	v_lshlrev_b32_e32 v208, 16, v209
	v_and_b32_e32 v209, 0xffff0000, v209
	v_lshlrev_b32_e32 v158, 16, v210
	v_and_b32_e32 v159, 0xffff0000, v210
	v_lshlrev_b32_e32 v210, 16, v211
	v_and_b32_e32 v211, 0xffff0000, v211
	v_pk_fma_f32 v[30:31], v[208:209], s[12:13], v[30:31] op_sel_hi:[1,0,1]
	v_pk_fma_f32 v[28:29], v[156:157], s[12:13], v[28:29] op_sel_hi:[1,0,1]
	v_pk_fma_f32 v[26:27], v[210:211], s[12:13], v[26:27] op_sel_hi:[1,0,1]
	v_pk_fma_f32 v[24:25], v[158:159], s[12:13], v[24:25] op_sel_hi:[1,0,1]
	global_store_dwordx4 v[152:153], v[28:31], off
	global_store_dwordx4 v[152:153], v[24:27], off offset:16
	s_waitcnt vmcnt(28)
	v_lshlrev_b32_e32 v156, 16, v212
	v_and_b32_e32 v157, 0xffff0000, v212
	v_lshlrev_b32_e32 v212, 16, v213
	v_and_b32_e32 v213, 0xffff0000, v213
	v_lshlrev_b32_e32 v158, 16, v214
	v_and_b32_e32 v159, 0xffff0000, v214
	v_lshlrev_b32_e32 v214, 16, v215
	v_and_b32_e32 v215, 0xffff0000, v215
	v_pk_fma_f32 v[22:23], v[212:213], s[12:13], v[22:23] op_sel_hi:[1,0,1]
	v_pk_fma_f32 v[20:21], v[156:157], s[12:13], v[20:21] op_sel_hi:[1,0,1]
	v_pk_fma_f32 v[18:19], v[214:215], s[12:13], v[18:19] op_sel_hi:[1,0,1]
	v_pk_fma_f32 v[16:17], v[158:159], s[12:13], v[16:17] op_sel_hi:[1,0,1]
	global_store_dwordx4 v[152:153], v[20:23], off offset:512
	global_store_dwordx4 v[152:153], v[16:19], off offset:528
	v_lshl_add_u64 v[154:155], v[236:237], 2, s[2:3]
	s_waitcnt vmcnt(29)
	v_lshlrev_b32_e32 v156, 16, v216
	v_and_b32_e32 v157, 0xffff0000, v216
	v_lshlrev_b32_e32 v216, 16, v217
	v_and_b32_e32 v217, 0xffff0000, v217
	v_lshlrev_b32_e32 v158, 16, v218
	v_and_b32_e32 v159, 0xffff0000, v218
	v_lshlrev_b32_e32 v218, 16, v219
	v_and_b32_e32 v219, 0xffff0000, v219
	v_pk_fma_f32 v[14:15], v[216:217], s[12:13], v[14:15] op_sel_hi:[1,0,1]
	v_pk_fma_f32 v[12:13], v[156:157], s[12:13], v[12:13] op_sel_hi:[1,0,1]
	v_pk_fma_f32 v[10:11], v[218:219], s[12:13], v[10:11] op_sel_hi:[1,0,1]
	v_pk_fma_f32 v[8:9], v[158:159], s[12:13], v[8:9] op_sel_hi:[1,0,1]
	global_store_dwordx4 v[154:155], v[12:15], off
	global_store_dwordx4 v[154:155], v[8:11], off offset:16
	s_waitcnt vmcnt(30)
	v_lshlrev_b32_e32 v156, 16, v220
	v_and_b32_e32 v157, 0xffff0000, v220
	v_lshlrev_b32_e32 v220, 16, v221
	v_and_b32_e32 v221, 0xffff0000, v221
	v_lshlrev_b32_e32 v158, 16, v222
	v_and_b32_e32 v159, 0xffff0000, v222
	v_lshlrev_b32_e32 v222, 16, v223
	v_and_b32_e32 v223, 0xffff0000, v223
	v_pk_fma_f32 v[6:7], v[220:221], s[12:13], v[6:7] op_sel_hi:[1,0,1]
	v_pk_fma_f32 v[4:5], v[156:157], s[12:13], v[4:5] op_sel_hi:[1,0,1]
	v_pk_fma_f32 v[2:3], v[222:223], s[12:13], v[2:3] op_sel_hi:[1,0,1]
	v_pk_fma_f32 v[0:1], v[158:159], s[12:13], v[0:1] op_sel_hi:[1,0,1]
	global_store_dwordx4 v[154:155], v[4:7], off offset:512
	global_store_dwordx4 v[154:155], v[0:3], off offset:528
	s_cbranch_vccnz .LBB0_773
	s_andn2_b64 vcc, exec, s[4:5]
	s_cbranch_vccnz .LBB0_772
	s_barrier
	s_branch .LBB0_772

; __device__ __forceinline__ void ln_phase(float* io, const float* g, const float* b, bf16_t* hb, float* stats, int gw, int NGW, int lane) {
;     ...
;     for (int row = gw; row < M; row += NGW) {
;         f32x4* xr = (f32x4*)(io + (size_t)row * D) + lane;
;         f32x4 v[8]; float s = 0.f;
; #pragma unroll
;         for (int j = 0; j < 8; ++j) { v[j] = xr[64 * j]; s += (v[j][0] + v[j][1]) + (v[j][2] + v[j][3]); }
;         const float mean = wave_sum(s, lane) * (1.f / D); float s2 = 0.f;
; #pragma unroll
;         for (int j = 0; j < 8; ++j) { v[j] = v[j] - mean; s2 += (v[j][0] * v[j][0] + v[j][1] * v[j][1]) + (v[j][2] * v[j][2] + v[j][3] * v[j][3]); }
;         const float rstd = 1.0f / sqrtf(wave_sum(s2, lane) * (1.f / D) + 1e-5f);
.LBB0_834:
	v_add_co_u32_e32 v84, vcc, 0xfffff000, v82
	v_add_co_u32_e64 v86, s[0:1], s3, v82
	s_nop 0
	v_addc_co_u32_e32 v85, vcc, -1, v83, vcc
	v_add_co_u32_e32 v106, vcc, 0xfffff400, v82
	flat_load_dwordx4 v[64:67], v[82:83] nt
	v_addc_co_u32_e64 v87, s[0:1], -1, v83, s[0:1]
	flat_load_dwordx4 v[68:71], v[82:83] offset:1024 nt
	flat_load_dwordx4 v[72:75], v[82:83] offset:2048 nt
	flat_load_dwordx4 v[76:79], v[82:83] offset:3072 nt
	flat_load_dwordx4 v[102:105], v[84:85] nt
	v_addc_co_u32_e32 v107, vcc, -1, v83, vcc
	v_add_co_u32_e64 v88, s[0:1], s10, v82
	flat_load_dwordx4 v[98:101], v[86:87] nt
	s_nop 0
	v_addc_co_u32_e64 v89, s[0:1], -1, v83, s[0:1]
	flat_load_dwordx4 v[106:109], v[106:107] nt
	s_add_i32 s2, s2, s58
	flat_load_dwordx4 v[86:89], v[88:89] nt
	s_cmp_lt_i32 s2, 0x8000
	v_lshl_add_u64 v[82:83], v[82:83], 0, s[6:7]
	s_waitcnt vmcnt(0) lgkmcnt(0)
	v_mov_b32_e32 v111, v66
	v_mov_b32_e32 v113, v67
	v_mov_b32_e32 v114, v69
	v_mov_b32_e32 v115, v70
	v_mov_b32_e32 v116, v68
	v_mov_b32_e32 v117, v71
	v_add_f32_e32 v118, v72, v73
	v_add_f32_e32 v120, v74, v75
	v_mov_b32_e32 v119, v78
	v_mov_b32_e32 v121, v79
	v_pk_add_f32 v[114:115], v[114:115], v[116:117]
	v_pk_add_f32 v[116:117], v[118:119], v[120:121]
	v_mov_b32_e32 v118, v102
	v_mov_b32_e32 v120, v103
	v_mov_b32_e32 v126, v104
	v_mov_b32_e32 v128, v105
	v_mov_b32_e32 v119, v106
	v_mov_b32_e32 v121, v107
	v_mov_b32_e32 v127, v108
	v_mov_b32_e32 v129, v109
	v_mov_b32_e32 v122, v99
	v_mov_b32_e32 v123, v100
	v_mov_b32_e32 v124, v98
	v_mov_b32_e32 v125, v101
	v_pk_add_f32 v[118:119], v[118:119], v[120:121]
	v_pk_add_f32 v[120:121], v[126:127], v[128:129]
	v_add_f32_e32 v110, v86, v87
	v_add_f32_e32 v112, v88, v89
	v_pk_add_f32 v[122:123], v[122:123], v[124:125]
	v_pk_add_f32 v[118:119], v[118:119], v[120:121]
	v_pk_add_f32 v[110:111], v[110:111], v[112:113]
	v_pk_add_f32 v[112:113], v[114:115], v[114:115] op_sel:[0,1] op_sel_hi:[1,0]
	v_pk_add_f32 v[114:115], v[122:123], v[122:123] op_sel:[0,1] op_sel_hi:[1,0]
	v_add_f32_e32 v84, 0, v118
	v_mov_b32_e32 v85, v64
	v_mov_b32_e32 v115, v65
	v_add_f32_e32 v84, v84, v119
	v_pk_add_f32 v[84:85], v[84:85], v[114:115]
	v_mov_b32_e32 v113, v77
	v_pk_add_f32 v[84:85], v[84:85], v[110:111]
	s_nop 0
	v_pk_add_f32 v[84:85], v[84:85], v[84:85] op_sel:[0,1] op_sel_hi:[1,0]
	s_nop 0
	v_mov_b32_e32 v85, v76
	v_pk_add_f32 v[84:85], v[84:85], v[112:113]
	s_nop 0
	v_pk_add_f32 v[84:85], v[84:85], v[116:117]
	s_nop 0
	v_add_f32_e32 v84, v84, v85
	ds_bpermute_b32 v85, v90, v84
	s_waitcnt lgkmcnt(0)
	v_add_f32_e32 v84, v84, v85
	ds_bpermute_b32 v85, v91, v84
	s_waitcnt lgkmcnt(0)
	v_add_f32_e32 v84, v84, v85
	ds_bpermute_b32 v85, v92, v84
	s_waitcnt lgkmcnt(0)
	v_add_f32_e32 v84, v84, v85
	ds_bpermute_b32 v85, v93, v84
	s_waitcnt lgkmcnt(0)
	v_add_f32_e32 v84, v84, v85
	ds_bpermute_b32 v85, v94, v84
	s_waitcnt lgkmcnt(0)
	v_add_f32_e32 v84, v84, v85
	ds_bpermute_b32 v85, v95, v84
	s_waitcnt lgkmcnt(0)
	v_add_f32_e32 v110, v84, v85
	v_fmamk_f32 v85, v110, 0xba000000, v105
	v_fmamk_f32 v103, v110, 0xba000000, v103
	v_fmamk_f32 v105, v110, 0xba000000, v109
	v_fmamk_f32 v107, v110, 0xba000000, v107
	v_fmamk_f32 v84, v110, 0xba000000, v104
	v_fmac_f32_e32 v102, 0xba000000, v110
	v_fmamk_f32 v104, v110, 0xba000000, v108
	v_fmac_f32_e32 v106, 0xba000000, v110
	v_fmamk_f32 v99, v110, 0xba000000, v99
	v_fmamk_f32 v98, v110, 0xba000000, v98
	v_fmamk_f32 v101, v110, 0xba000000, v101
	v_fmac_f32_e32 v100, 0xba000000, v110
	v_fmamk_f32 v87, v110, 0xba000000, v87
	v_fmamk_f32 v86, v110, 0xba000000, v86
	v_fmamk_f32 v89, v110, 0xba000000, v89
	v_fmac_f32_e32 v88, 0xba000000, v110
	v_fmamk_f32 v67, v110, 0xba000000, v67
	v_fmamk_f32 v66, v110, 0xba000000, v66
	v_fmamk_f32 v65, v110, 0xba000000, v65
	v_fmac_f32_e32 v64, 0xba000000, v110
	v_fmamk_f32 v69, v110, 0xba000000, v69
	v_fmamk_f32 v68, v110, 0xba000000, v68
	v_fmamk_f32 v71, v110, 0xba000000, v71
	v_fmac_f32_e32 v70, 0xba000000, v110
	v_fmamk_f32 v73, v110, 0xba000000, v73
	v_fmamk_f32 v72, v110, 0xba000000, v72
	v_fmamk_f32 v75, v110, 0xba000000, v75
	v_fmac_f32_e32 v74, 0xba000000, v110
	v_fmamk_f32 v79, v110, 0xba000000, v79
	v_fmamk_f32 v78, v110, 0xba000000, v78
	v_fmamk_f32 v77, v110, 0xba000000, v77
	v_fmac_f32_e32 v76, 0xba000000, v110
	v_mov_b32_e32 v110, v103
	v_mov_b32_e32 v111, v107
	v_mov_b32_e32 v114, v85
	v_mov_b32_e32 v115, v105
	v_mov_b32_e32 v108, v102
	v_mov_b32_e32 v109, v106
	v_mov_b32_e32 v112, v84
	v_mov_b32_e32 v113, v104
	v_pk_mul_f32 v[116:117], v[100:101], v[100:101]
	v_pk_mul_f32 v[118:119], v[98:99], v[98:99]
	v_pk_mul_f32 v[110:111], v[110:111], v[110:111]
	v_pk_mul_f32 v[114:115], v[114:115], v[114:115]
	v_pk_mov_b32 v[132:133], v[118:119], v[116:117] op_sel:[1,0]
	v_mov_b32_e32 v119, v117
	v_pk_fma_f32 v[108:109], v[108:109], v[108:109], v[110:111]
	v_pk_fma_f32 v[110:111], v[112:113], v[112:113], v[114:115]
	v_mul_f32_e32 v120, v86, v86
	v_mul_f32_e32 v122, v88, v88
	v_pk_add_f32 v[112:113], v[132:133], v[118:119]
	v_pk_add_f32 v[108:109], v[108:109], v[110:111]
	v_pk_fma_f32 v[116:117], v[86:87], v[86:87], v[120:121] op_sel_hi:[1,1,0]
	v_pk_fma_f32 v[120:121], v[88:89], v[88:89], v[122:123] op_sel_hi:[1,1,0]
	v_pk_add_f32 v[110:111], v[112:113], v[112:113] op_sel_hi:[0,1]
	v_pk_add_f32 v[108:109], v[108:109], v[108:109] op_sel_hi:[0,1]
	v_pk_mul_f32 v[124:125], v[70:71], v[70:71]
	v_pk_mul_f32 v[126:127], v[68:69], v[68:69]
	v_mul_f32_e32 v116, v64, v64
	v_mul_f32_e32 v120, v65, v65
	v_mul_f32_e32 v110, v66, v66
	v_mul_f32_e32 v108, v67, v67
	v_pk_mov_b32 v[122:123], v[126:127], v[124:125] op_sel:[1,0]
	v_mov_b32_e32 v127, v125
	v_pk_add_f32 v[112:113], v[116:117], v[120:121]
	v_pk_add_f32 v[108:109], v[110:111], v[108:109]
	v_mul_f32_e32 v128, v72, v72
	v_mul_f32_e32 v130, v74, v74
	v_pk_add_f32 v[114:115], v[122:123], v[126:127]
	v_pk_add_f32 v[108:109], v[112:113], v[108:109]
	v_pk_fma_f32 v[124:125], v[72:73], v[72:73], v[128:129] op_sel_hi:[1,1,0]
	v_pk_fma_f32 v[128:129], v[74:75], v[74:75], v[130:131] op_sel_hi:[1,1,0]
	v_pk_add_f32 v[114:115], v[114:115], v[114:115] op_sel_hi:[0,1]
	v_pk_add_f32 v[108:109], v[108:109], v[108:109] op_sel_hi:[0,1]
	v_mul_f32_e32 v124, v76, v76
	v_mul_f32_e32 v128, v77, v77
	v_mul_f32_e32 v114, v78, v78
	v_mul_f32_e32 v108, v79, v79
	v_pk_add_f32 v[116:117], v[124:125], v[128:129]
	v_pk_add_f32 v[108:109], v[114:115], v[108:109]
	s_nop 0
	v_pk_add_f32 v[108:109], v[116:117], v[108:109]
	s_nop 0
	v_add_f32_e32 v108, v108, v109
	ds_bpermute_b32 v109, v90, v108
	s_waitcnt lgkmcnt(0)
; __device__ __forceinline__ unsigned cvt_pk_bf16(float lo, float hi) { unsigned r; asm volatile("s_nop 1\n\tv_cvt_pk_bf16_f32 %0, %1, %2" : "=v"(r) : "v"(lo), "v"(hi)); return r; }
; __device__ __forceinline__ void ln_phase(float* io, const float* g, const float* b, bf16_t* hb, float* stats, int gw, int NGW, int lane) {
;     ...
;         const float mean = wave_sum(s, lane) * (1.f / D); float s2 = 0.f;
; #pragma unroll
;         for (int j = 0; j < 8; ++j) { v[j] = v[j] - mean; s2 += (v[j][0] * v[j][0] + v[j][1] * v[j][1]) + (v[j][2] * v[j][2] + v[j][3] * v[j][3]); }
;         const float rstd = 1.0f / sqrtf(wave_sum(s2, lane) * (1.f / D) + 1e-5f);
; #pragma unroll
;         for (int j = 0; j < 8; ++j) v[j] = v[j] * rstd * gv[j] + bv[j];
;         if (stats) {
;             u32x2* o8 = (u32x2*)(hb + (size_t)row * D) + lane;
; #pragma unroll
;             for (int j = 0; j < 8; ++j) { u32x2 w; w.x = cvt_pk_bf16(v[j][0], v[j][1]); w.y = cvt_pk_bf16(v[j][2], v[j][3]); o8[64 * j] = w; }
	v_add_f32_e32 v108, v108, v109
	ds_bpermute_b32 v109, v91, v108
	s_waitcnt lgkmcnt(0)
	v_add_f32_e32 v108, v108, v109
	ds_bpermute_b32 v109, v92, v108
	s_waitcnt lgkmcnt(0)
	v_add_f32_e32 v108, v108, v109
	ds_bpermute_b32 v109, v93, v108
	s_waitcnt lgkmcnt(0)
	v_add_f32_e32 v108, v108, v109
	ds_bpermute_b32 v109, v94, v108
	s_waitcnt lgkmcnt(0)
	v_add_f32_e32 v108, v108, v109
	ds_bpermute_b32 v109, v95, v108
	s_waitcnt lgkmcnt(0)
	v_add_f32_e32 v108, v108, v109
	v_fmamk_f32 v108, v108, 0x3a000000, v96
	v_mul_f32_e32 v109, 0x4f800000, v108
	v_cmp_gt_f32_e32 vcc, s11, v108
	s_nop 1
	v_cndmask_b32_e32 v108, v108, v109, vcc
	v_sqrt_f32_e32 v109, v108
	s_nop 0
	v_add_u32_e32 v110, -1, v109
	v_add_u32_e32 v111, 1, v109
	v_fma_f32 v112, -v110, v109, v108
	v_fma_f32 v113, -v111, v109, v108
	v_cmp_ge_f32_e64 s[0:1], 0, v112
	s_nop 1
	v_cndmask_b32_e64 v109, v109, v110, s[0:1]
	v_cmp_lt_f32_e64 s[0:1], 0, v113
	s_nop 1
	v_cndmask_b32_e64 v109, v109, v111, s[0:1]
	v_mul_f32_e32 v110, 0x37800000, v109
	v_cndmask_b32_e32 v109, v109, v110, vcc
	v_cmp_class_f32_e32 vcc, v108, v97
	s_nop 1
	v_cndmask_b32_e32 v108, v109, v108, vcc
	v_div_scale_f32 v109, s[0:1], v108, v108, 1.0
	v_rcp_f32_e32 v111, v109
	v_div_scale_f32 v110, vcc, 1.0, v108, 1.0
	v_fma_f32 v112, -v109, v111, 1.0
	v_fmac_f32_e32 v111, v112, v111
	v_mul_f32_e32 v112, v110, v111
	v_fma_f32 v113, -v109, v112, v110
	v_fmac_f32_e32 v112, v113, v111
	v_fma_f32 v109, -v109, v112, v110
	v_div_fmas_f32 v109, v109, v111, v112
	v_div_fixup_f32 v108, v109, v108, 1.0
	v_pk_mul_f32 v[84:85], v[84:85], v[108:109] op_sel_hi:[1,0]
	v_pk_mul_f32 v[102:103], v[102:103], v[108:109] op_sel_hi:[1,0]
	v_pk_mul_f32 v[104:105], v[104:105], v[108:109] op_sel_hi:[1,0]
	v_pk_mul_f32 v[106:107], v[106:107], v[108:109] op_sel_hi:[1,0]
	v_pk_fma_f32 v[102:103], v[0:1], v[102:103], v[4:5]
	v_pk_fma_f32 v[84:85], v[2:3], v[84:85], v[6:7]
	v_pk_mul_f32 v[100:101], v[100:101], v[108:109] op_sel_hi:[1,0]
	v_pk_mul_f32 v[98:99], v[98:99], v[108:109] op_sel_hi:[1,0]
	v_pk_mul_f32 v[64:65], v[64:65], v[108:109] op_sel_hi:[1,0]
	v_pk_fma_f32 v[106:107], v[8:9], v[106:107], v[16:17]
	v_pk_fma_f32 v[104:105], v[10:11], v[104:105], v[18:19]
	s_nop 1
	v_cvt_pk_bf16_f32 v102, v102, v103
	s_nop 1
	v_cvt_pk_bf16_f32 v103, v84, v85
	flat_store_dwordx2 v[80:81], v[102:103]
	s_nop 1
	v_cvt_pk_bf16_f32 v84, v106, v107
	s_nop 1
	v_cvt_pk_bf16_f32 v85, v104, v105
	v_pk_mul_f32 v[88:89], v[88:89], v[108:109] op_sel_hi:[1,0]
	v_pk_mul_f32 v[86:87], v[86:87], v[108:109] op_sel_hi:[1,0]
	v_pk_mul_f32 v[66:67], v[66:67], v[108:109] op_sel_hi:[1,0]
	v_pk_fma_f32 v[98:99], v[12:13], v[98:99], v[20:21]
	v_pk_fma_f32 v[100:101], v[14:15], v[100:101], v[22:23]
	v_pk_fma_f32 v[64:65], v[32:33], v[64:65], v[40:41]
	flat_store_dwordx2 v[80:81], v[84:85] offset:512
	s_nop 1
	v_cvt_pk_bf16_f32 v84, v98, v99
	s_nop 1
	v_cvt_pk_bf16_f32 v85, v100, v101
	v_pk_mul_f32 v[70:71], v[70:71], v[108:109] op_sel_hi:[1,0]
	v_pk_mul_f32 v[68:69], v[68:69], v[108:109] op_sel_hi:[1,0]
	v_pk_fma_f32 v[86:87], v[24:25], v[86:87], v[28:29]
	v_pk_fma_f32 v[88:89], v[26:27], v[88:89], v[30:31]
	v_pk_fma_f32 v[66:67], v[34:35], v[66:67], v[42:43]
	flat_store_dwordx2 v[80:81], v[84:85] offset:1024
	s_nop 1
	v_cvt_pk_bf16_f32 v84, v86, v87
	s_nop 1
	v_cvt_pk_bf16_f32 v85, v88, v89
	flat_store_dwordx2 v[80:81], v[84:85] offset:1536
	s_nop 1
	v_cvt_pk_bf16_f32 v64, v64, v65
	s_nop 1
	v_cvt_pk_bf16_f32 v65, v66, v67
	v_pk_mul_f32 v[74:75], v[74:75], v[108:109] op_sel_hi:[1,0]
	v_pk_mul_f32 v[72:73], v[72:73], v[108:109] op_sel_hi:[1,0]
	v_pk_fma_f32 v[68:69], v[36:37], v[68:69], v[44:45]
	v_pk_fma_f32 v[70:71], v[38:39], v[70:71], v[46:47]
	flat_store_dwordx2 v[80:81], v[64:65] offset:2048
	s_nop 1
	v_cvt_pk_bf16_f32 v64, v68, v69
	s_nop 1
	v_cvt_pk_bf16_f32 v65, v70, v71
	v_pk_mul_f32 v[78:79], v[78:79], v[108:109] op_sel_hi:[1,0]
	v_pk_mul_f32 v[76:77], v[76:77], v[108:109] op_sel_hi:[1,0]
	v_pk_fma_f32 v[72:73], v[48:49], v[72:73], v[56:57]
	v_pk_fma_f32 v[74:75], v[50:51], v[74:75], v[58:59]
	flat_store_dwordx2 v[80:81], v[64:65] offset:2560
	s_nop 1
	v_cvt_pk_bf16_f32 v64, v72, v73
	s_nop 1
	v_cvt_pk_bf16_f32 v65, v74, v75
	v_pk_fma_f32 v[76:77], v[52:53], v[76:77], v[60:61]
	v_pk_fma_f32 v[78:79], v[54:55], v[78:79], v[62:63]
	flat_store_dwordx2 v[80:81], v[64:65] offset:3072
	s_nop 1
	v_cvt_pk_bf16_f32 v64, v76, v77
	s_nop 1
	v_cvt_pk_bf16_f32 v65, v78, v79
	flat_store_dwordx2 v[80:81], v[64:65] offset:3584
	v_lshl_add_u64 v[80:81], v[80:81], 0, s[4:5]
	s_cbranch_scc1 .LBB0_834
	v_readlane_b32 s59, v254, 0

; __device__ __forceinline__ float bf_lo(unsigned u) { return __uint_as_float(u << 16); }
; __device__ __forceinline__ float bf_hi(unsigned u) { return __uint_as_float(u & 0xffff0000u); }
;     __device__ __forceinline__ void operator()(AccRef acc, const Unit& u, int wr, int wc, int fr, int fq) const {
;     ...
;         for (int ai = 0; ai < 2; ++ai)
; #pragma unroll
;             for (int m = 0; m < 4; ++m) {
;                 const size_t off = (size_t)(row0 + ai * HALF + m * 16) * D + col0;
; #pragma unroll
;                 for (int bj = 0; bj < 2; ++bj) {
;                     const u32x4 hv = *(const u32x4*)(hb + off + bj * HALF);
;                     f32x4 r0, r1;
;                     r0[0] = bf_lo(hv.x); r0[1] = bf_hi(hv.x); r0[2] = bf_lo(hv.y); r0[3] = bf_hi(hv.y); r1[0] = bf_lo(hv.z); r1[1] = bf_hi(hv.z); r1[2] = bf_lo(hv.w); r1[3] = bf_hi(hv.w);
;                     *(f32x4*)(out + off + bj * HALF) = r0 * alpha + acc[ai][bj][m][0] * s;
;                     *(f32x4*)(out + off + bj * HALF + 4) = r1 * alpha + acc[ai][bj][m][1] * s;
;                 }
;                 if (m == 3) asm volatile("" ::: "memory");
.LBB0_964:
	v_mov_b32_e32 v144, v147
	v_mov_b32_e32 v145, v146
	s_lshl_b32 s34, s63, 8
	s_add_i32 s34, s34, s54
	v_add_u32_e32 v144, s34, v144
	s_lshl_b32 s34, s64, 8
	s_or_b32 s34, s34, s55
	v_lshl_add_u32 v152, v145, 3, s34
	v_ashrrev_i32_e32 v145, 31, v144
	v_ashrrev_i32_e32 v153, 31, v152
	v_lshlrev_b64 v[144:145], 11, v[144:145]
	v_lshl_add_u64 v[144:145], v[144:145], 0, v[152:153]
	s_and_b64 vcc, exec, s[0:1]
	s_mov_b64 s[0:1], -1
	v_lshl_add_u64 v[238:239], v[144:145], 1, s[8:9]
	global_load_dwordx4 v[160:163], v[238:239], off nt
	global_load_dwordx4 v[164:167], v[238:239], off offset:256 nt
	v_lshl_add_u64 v[224:225], v[144:145], 0, s[16:17]
	v_lshl_add_u64 v[240:241], v[224:225], 1, s[8:9]
	global_load_dwordx4 v[168:171], v[240:241], off nt
	global_load_dwordx4 v[172:175], v[240:241], off offset:256 nt
	v_lshl_add_u64 v[226:227], v[144:145], 0, s[18:19]
	v_lshl_add_u64 v[242:243], v[226:227], 1, s[8:9]
	global_load_dwordx4 v[176:179], v[242:243], off nt
	global_load_dwordx4 v[180:183], v[242:243], off offset:256 nt
	v_lshl_add_u64 v[228:229], v[144:145], 0, s[20:21]
	v_lshl_add_u64 v[244:245], v[228:229], 1, s[8:9]
	global_load_dwordx4 v[184:187], v[244:245], off nt
	global_load_dwordx4 v[188:191], v[244:245], off offset:256 nt
	v_lshl_add_u64 v[230:231], v[144:145], 0, s[22:23]
	v_lshl_add_u64 v[246:247], v[230:231], 1, s[8:9]
	global_load_dwordx4 v[192:195], v[246:247], off nt
	global_load_dwordx4 v[196:199], v[246:247], off offset:256 nt
	v_lshl_add_u64 v[232:233], v[144:145], 0, s[24:25]
	v_lshl_add_u64 v[248:249], v[232:233], 1, s[8:9]
	global_load_dwordx4 v[200:203], v[248:249], off nt
	global_load_dwordx4 v[204:207], v[248:249], off offset:256 nt
	v_lshl_add_u64 v[234:235], v[144:145], 0, s[26:27]
	v_lshl_add_u64 v[250:251], v[234:235], 1, s[8:9]
	global_load_dwordx4 v[208:211], v[250:251], off nt
	global_load_dwordx4 v[212:215], v[250:251], off offset:256 nt
	v_lshl_add_u64 v[236:237], v[144:145], 0, s[28:29]
	v_lshl_add_u64 v[252:253], v[236:237], 1, s[8:9]
	global_load_dwordx4 v[216:219], v[252:253], off nt
	global_load_dwordx4 v[220:223], v[252:253], off offset:256 nt
	v_lshl_add_u64 v[152:153], v[144:145], 2, s[2:3]
	s_waitcnt vmcnt(15)
	v_lshlrev_b32_e32 v156, 16, v160
	v_and_b32_e32 v157, 0xffff0000, v160
	v_lshlrev_b32_e32 v160, 16, v161
	v_and_b32_e32 v161, 0xffff0000, v161
	v_lshlrev_b32_e32 v158, 16, v162
	v_and_b32_e32 v159, 0xffff0000, v162
	v_lshlrev_b32_e32 v162, 16, v163
	v_and_b32_e32 v163, 0xffff0000, v163
	v_pk_mul_f32 v[156:157], v[156:157], s[14:15] op_sel_hi:[1,0]
	v_pk_mul_f32 v[160:161], v[160:161], s[14:15] op_sel_hi:[1,0]
	v_pk_mul_f32 v[158:159], v[158:159], s[14:15] op_sel_hi:[1,0]
	v_pk_mul_f32 v[162:163], v[162:163], s[14:15] op_sel_hi:[1,0]
	v_pk_fma_f32 v[126:127], v[126:127], 0.5, v[160:161] op_sel_hi:[1,0,1]
	v_pk_fma_f32 v[124:125], v[124:125], 0.5, v[156:157] op_sel_hi:[1,0,1]
	v_pk_fma_f32 v[122:123], v[122:123], 0.5, v[162:163] op_sel_hi:[1,0,1]
	v_pk_fma_f32 v[120:121], v[120:121], 0.5, v[158:159] op_sel_hi:[1,0,1]
	global_store_dwordx4 v[152:153], v[124:127], off
	global_store_dwordx4 v[152:153], v[120:123], off offset:16
	s_waitcnt vmcnt(16)
	v_lshlrev_b32_e32 v156, 16, v164
	v_and_b32_e32 v157, 0xffff0000, v164
	v_lshlrev_b32_e32 v164, 16, v165
	v_and_b32_e32 v165, 0xffff0000, v165
	v_lshlrev_b32_e32 v158, 16, v166
	v_and_b32_e32 v159, 0xffff0000, v166
	v_lshlrev_b32_e32 v166, 16, v167
	v_and_b32_e32 v167, 0xffff0000, v167
	v_pk_mul_f32 v[156:157], v[156:157], s[14:15] op_sel_hi:[1,0]
	v_pk_mul_f32 v[164:165], v[164:165], s[14:15] op_sel_hi:[1,0]
	v_pk_mul_f32 v[158:159], v[158:159], s[14:15] op_sel_hi:[1,0]
	v_pk_mul_f32 v[166:167], v[166:167], s[14:15] op_sel_hi:[1,0]
	v_pk_fma_f32 v[118:119], v[118:119], 0.5, v[164:165] op_sel_hi:[1,0,1]
	v_pk_fma_f32 v[116:117], v[116:117], 0.5, v[156:157] op_sel_hi:[1,0,1]
	v_pk_fma_f32 v[114:115], v[114:115], 0.5, v[166:167] op_sel_hi:[1,0,1]
	v_pk_fma_f32 v[112:113], v[112:113], 0.5, v[158:159] op_sel_hi:[1,0,1]
	global_store_dwordx4 v[152:153], v[116:119], off offset:512
	global_store_dwordx4 v[152:153], v[112:115], off offset:528
	v_lshl_add_u64 v[154:155], v[224:225], 2, s[2:3]
	s_waitcnt vmcnt(17)
	v_lshlrev_b32_e32 v156, 16, v168
	v_and_b32_e32 v157, 0xffff0000, v168
	v_lshlrev_b32_e32 v168, 16, v169
	v_and_b32_e32 v169, 0xffff0000, v169
	v_lshlrev_b32_e32 v158, 16, v170
	v_and_b32_e32 v159, 0xffff0000, v170
	v_lshlrev_b32_e32 v170, 16, v171
	v_and_b32_e32 v171, 0xffff0000, v171
	v_pk_mul_f32 v[156:157], v[156:157], s[14:15] op_sel_hi:[1,0]
	v_pk_mul_f32 v[168:169], v[168:169], s[14:15] op_sel_hi:[1,0]
	v_pk_mul_f32 v[158:159], v[158:159], s[14:15] op_sel_hi:[1,0]
	v_pk_mul_f32 v[170:171], v[170:171], s[14:15] op_sel_hi:[1,0]
	v_pk_fma_f32 v[110:111], v[110:111], 0.5, v[168:169] op_sel_hi:[1,0,1]
	v_pk_fma_f32 v[108:109], v[108:109], 0.5, v[156:157] op_sel_hi:[1,0,1]
	v_pk_fma_f32 v[106:107], v[106:107], 0.5, v[170:171] op_sel_hi:[1,0,1]
	v_pk_fma_f32 v[104:105], v[104:105], 0.5, v[158:159] op_sel_hi:[1,0,1]
	global_store_dwordx4 v[154:155], v[108:111], off
	global_store_dwordx4 v[154:155], v[104:107], off offset:16
	s_waitcnt vmcnt(18)
; __device__ __forceinline__ float bf_lo(unsigned u) { return __uint_as_float(u << 16); }
; __device__ __forceinline__ float bf_hi(unsigned u) { return __uint_as_float(u & 0xffff0000u); }
;     __device__ __forceinline__ void operator()(AccRef acc, const Unit& u, int wr, int wc, int fr, int fq) const {
;     ...
;                 for (int bj = 0; bj < 2; ++bj) {
;                     const u32x4 hv = *(const u32x4*)(hb + off + bj * HALF);
;                     f32x4 r0, r1;
;                     r0[0] = bf_lo(hv.x); r0[1] = bf_hi(hv.x); r0[2] = bf_lo(hv.y); r0[3] = bf_hi(hv.y); r1[0] = bf_lo(hv.z); r1[1] = bf_hi(hv.z); r1[2] = bf_lo(hv.w); r1[3] = bf_hi(hv.w);
;                     *(f32x4*)(out + off + bj * HALF) = r0 * alpha + acc[ai][bj][m][0] * s;
;                     *(f32x4*)(out + off + bj * HALF + 4) = r1 * alpha + acc[ai][bj][m][1] * s;
;                 }
	v_lshlrev_b32_e32 v156, 16, v172
	v_and_b32_e32 v157, 0xffff0000, v172
	v_lshlrev_b32_e32 v172, 16, v173
	v_and_b32_e32 v173, 0xffff0000, v173
	v_lshlrev_b32_e32 v158, 16, v174
	v_and_b32_e32 v159, 0xffff0000, v174
	v_lshlrev_b32_e32 v174, 16, v175
	v_and_b32_e32 v175, 0xffff0000, v175
	v_pk_mul_f32 v[156:157], v[156:157], s[14:15] op_sel_hi:[1,0]
	v_pk_mul_f32 v[172:173], v[172:173], s[14:15] op_sel_hi:[1,0]
	v_pk_mul_f32 v[158:159], v[158:159], s[14:15] op_sel_hi:[1,0]
	v_pk_mul_f32 v[174:175], v[174:175], s[14:15] op_sel_hi:[1,0]
	v_pk_fma_f32 v[102:103], v[102:103], 0.5, v[172:173] op_sel_hi:[1,0,1]
	v_pk_fma_f32 v[100:101], v[100:101], 0.5, v[156:157] op_sel_hi:[1,0,1]
	v_pk_fma_f32 v[98:99], v[98:99], 0.5, v[174:175] op_sel_hi:[1,0,1]
	v_pk_fma_f32 v[96:97], v[96:97], 0.5, v[158:159] op_sel_hi:[1,0,1]
	global_store_dwordx4 v[154:155], v[100:103], off offset:512
	global_store_dwordx4 v[154:155], v[96:99], off offset:528
	v_lshl_add_u64 v[152:153], v[226:227], 2, s[2:3]
	s_waitcnt vmcnt(19)
	v_lshlrev_b32_e32 v156, 16, v176
	v_and_b32_e32 v157, 0xffff0000, v176
	v_lshlrev_b32_e32 v176, 16, v177
	v_and_b32_e32 v177, 0xffff0000, v177
	v_lshlrev_b32_e32 v158, 16, v178
	v_and_b32_e32 v159, 0xffff0000, v178
	v_lshlrev_b32_e32 v178, 16, v179
	v_and_b32_e32 v179, 0xffff0000, v179
	v_pk_mul_f32 v[156:157], v[156:157], s[14:15] op_sel_hi:[1,0]
	v_pk_mul_f32 v[176:177], v[176:177], s[14:15] op_sel_hi:[1,0]
	v_pk_mul_f32 v[158:159], v[158:159], s[14:15] op_sel_hi:[1,0]
	v_pk_mul_f32 v[178:179], v[178:179], s[14:15] op_sel_hi:[1,0]
	v_pk_fma_f32 v[94:95], v[94:95], 0.5, v[176:177] op_sel_hi:[1,0,1]
	v_pk_fma_f32 v[92:93], v[92:93], 0.5, v[156:157] op_sel_hi:[1,0,1]
	v_pk_fma_f32 v[90:91], v[90:91], 0.5, v[178:179] op_sel_hi:[1,0,1]
	v_pk_fma_f32 v[88:89], v[88:89], 0.5, v[158:159] op_sel_hi:[1,0,1]
	global_store_dwordx4 v[152:153], v[92:95], off
	global_store_dwordx4 v[152:153], v[88:91], off offset:16
	s_waitcnt vmcnt(20)
	v_lshlrev_b32_e32 v156, 16, v180
	v_and_b32_e32 v157, 0xffff0000, v180
	v_lshlrev_b32_e32 v180, 16, v181
	v_and_b32_e32 v181, 0xffff0000, v181
	v_lshlrev_b32_e32 v158, 16, v182
	v_and_b32_e32 v159, 0xffff0000, v182
	v_lshlrev_b32_e32 v182, 16, v183
	v_and_b32_e32 v183, 0xffff0000, v183
	v_pk_mul_f32 v[156:157], v[156:157], s[14:15] op_sel_hi:[1,0]
	v_pk_mul_f32 v[180:181], v[180:181], s[14:15] op_sel_hi:[1,0]
	v_pk_mul_f32 v[158:159], v[158:159], s[14:15] op_sel_hi:[1,0]
	v_pk_mul_f32 v[182:183], v[182:183], s[14:15] op_sel_hi:[1,0]
	v_pk_fma_f32 v[86:87], v[86:87], 0.5, v[180:181] op_sel_hi:[1,0,1]
	v_pk_fma_f32 v[84:85], v[84:85], 0.5, v[156:157] op_sel_hi:[1,0,1]
	v_pk_fma_f32 v[82:83], v[82:83], 0.5, v[182:183] op_sel_hi:[1,0,1]
	v_pk_fma_f32 v[80:81], v[80:81], 0.5, v[158:159] op_sel_hi:[1,0,1]
	global_store_dwordx4 v[152:153], v[84:87], off offset:512
	global_store_dwordx4 v[152:153], v[80:83], off offset:528
	v_lshl_add_u64 v[154:155], v[228:229], 2, s[2:3]
	s_waitcnt vmcnt(21)
	v_lshlrev_b32_e32 v156, 16, v184
	v_and_b32_e32 v157, 0xffff0000, v184
	v_lshlrev_b32_e32 v184, 16, v185
	v_and_b32_e32 v185, 0xffff0000, v185
	v_lshlrev_b32_e32 v158, 16, v186
	v_and_b32_e32 v159, 0xffff0000, v186
	v_lshlrev_b32_e32 v186, 16, v187
	v_and_b32_e32 v187, 0xffff0000, v187
	v_pk_mul_f32 v[156:157], v[156:157], s[14:15] op_sel_hi:[1,0]
	v_pk_mul_f32 v[184:185], v[184:185], s[14:15] op_sel_hi:[1,0]
	v_pk_mul_f32 v[158:159], v[158:159], s[14:15] op_sel_hi:[1,0]
	v_pk_mul_f32 v[186:187], v[186:187], s[14:15] op_sel_hi:[1,0]
	v_pk_fma_f32 v[78:79], v[78:79], 0.5, v[184:185] op_sel_hi:[1,0,1]
	v_pk_fma_f32 v[76:77], v[76:77], 0.5, v[156:157] op_sel_hi:[1,0,1]
	v_pk_fma_f32 v[74:75], v[74:75], 0.5, v[186:187] op_sel_hi:[1,0,1]
	v_pk_fma_f32 v[72:73], v[72:73], 0.5, v[158:159] op_sel_hi:[1,0,1]
	global_store_dwordx4 v[154:155], v[76:79], off
	global_store_dwordx4 v[154:155], v[72:75], off offset:16
	s_waitcnt vmcnt(22)
	v_lshlrev_b32_e32 v156, 16, v188
	v_and_b32_e32 v157, 0xffff0000, v188
	v_lshlrev_b32_e32 v188, 16, v189
	v_and_b32_e32 v189, 0xffff0000, v189
	v_lshlrev_b32_e32 v158, 16, v190
	v_and_b32_e32 v159, 0xffff0000, v190
	v_lshlrev_b32_e32 v190, 16, v191
	v_and_b32_e32 v191, 0xffff0000, v191
	v_pk_mul_f32 v[156:157], v[156:157], s[14:15] op_sel_hi:[1,0]
	v_pk_mul_f32 v[188:189], v[188:189], s[14:15] op_sel_hi:[1,0]
	v_pk_mul_f32 v[158:159], v[158:159], s[14:15] op_sel_hi:[1,0]
	v_pk_mul_f32 v[190:191], v[190:191], s[14:15] op_sel_hi:[1,0]
	v_pk_fma_f32 v[70:71], v[70:71], 0.5, v[188:189] op_sel_hi:[1,0,1]
	v_pk_fma_f32 v[68:69], v[68:69], 0.5, v[156:157] op_sel_hi:[1,0,1]
	v_pk_fma_f32 v[66:67], v[66:67], 0.5, v[190:191] op_sel_hi:[1,0,1]
	v_pk_fma_f32 v[64:65], v[64:65], 0.5, v[158:159] op_sel_hi:[1,0,1]
	global_store_dwordx4 v[154:155], v[68:71], off offset:512
	global_store_dwordx4 v[154:155], v[64:67], off offset:528
	v_lshl_add_u64 v[152:153], v[230:231], 2, s[2:3]
	s_waitcnt vmcnt(23)
	v_lshlrev_b32_e32 v156, 16, v192
	v_and_b32_e32 v157, 0xffff0000, v192
	v_lshlrev_b32_e32 v192, 16, v193
	v_and_b32_e32 v193, 0xffff0000, v193
	v_lshlrev_b32_e32 v158, 16, v194
	v_and_b32_e32 v159, 0xffff0000, v194
	v_lshlrev_b32_e32 v194, 16, v195
	v_and_b32_e32 v195, 0xffff0000, v195
	v_pk_mul_f32 v[156:157], v[156:157], s[14:15] op_sel_hi:[1,0]
	v_pk_mul_f32 v[192:193], v[192:193], s[14:15] op_sel_hi:[1,0]
	v_pk_mul_f32 v[158:159], v[158:159], s[14:15] op_sel_hi:[1,0]
	v_pk_mul_f32 v[194:195], v[194:195], s[14:15] op_sel_hi:[1,0]
	v_pk_fma_f32 v[62:63], v[62:63], 0.5, v[192:193] op_sel_hi:[1,0,1]
	v_pk_fma_f32 v[60:61], v[60:61], 0.5, v[156:157] op_sel_hi:[1,0,1]
	v_pk_fma_f32 v[58:59], v[58:59], 0.5, v[194:195] op_sel_hi:[1,0,1]
	v_pk_fma_f32 v[56:57], v[56:57], 0.5, v[158:159] op_sel_hi:[1,0,1]
	global_store_dwordx4 v[152:153], v[60:63], off
	global_store_dwordx4 v[152:153], v[56:59], off offset:16
	s_waitcnt vmcnt(24)
; __device__ __forceinline__ float bf_lo(unsigned u) { return __uint_as_float(u << 16); }
; __device__ __forceinline__ float bf_hi(unsigned u) { return __uint_as_float(u & 0xffff0000u); }
; #define PG8_BAR __builtin_amdgcn_s_barrier()
; template <class Epi>
; __device__ __forceinline__ void gemm_phase(ldsp lds, const Gemm g, const StaticOrder& S, const Epi& E, int wave0) {
;     ...
;         if (wr == 1) PG8_BAR;
;     __device__ __forceinline__ void operator()(AccRef acc, const Unit& u, int wr, int wc, int fr, int fq) const {
;     ...
;                 for (int bj = 0; bj < 2; ++bj) {
;                     const u32x4 hv = *(const u32x4*)(hb + off + bj * HALF);
;                     f32x4 r0, r1;
;                     r0[0] = bf_lo(hv.x); r0[1] = bf_hi(hv.x); r0[2] = bf_lo(hv.y); r0[3] = bf_hi(hv.y); r1[0] = bf_lo(hv.z); r1[1] = bf_hi(hv.z); r1[2] = bf_lo(hv.w); r1[3] = bf_hi(hv.w);
;                     *(f32x4*)(out + off + bj * HALF) = r0 * alpha + acc[ai][bj][m][0] * s;
;                     *(f32x4*)(out + off + bj * HALF + 4) = r1 * alpha + acc[ai][bj][m][1] * s;
;                 }
;                 if (m == 3) asm volatile("" ::: "memory");
	v_lshlrev_b32_e32 v156, 16, v196
	v_and_b32_e32 v157, 0xffff0000, v196
	v_lshlrev_b32_e32 v196, 16, v197
	v_and_b32_e32 v197, 0xffff0000, v197
	v_lshlrev_b32_e32 v158, 16, v198
	v_and_b32_e32 v159, 0xffff0000, v198
	v_lshlrev_b32_e32 v198, 16, v199
	v_and_b32_e32 v199, 0xffff0000, v199
	v_pk_mul_f32 v[156:157], v[156:157], s[14:15] op_sel_hi:[1,0]
	v_pk_mul_f32 v[196:197], v[196:197], s[14:15] op_sel_hi:[1,0]
	v_pk_mul_f32 v[158:159], v[158:159], s[14:15] op_sel_hi:[1,0]
	v_pk_mul_f32 v[198:199], v[198:199], s[14:15] op_sel_hi:[1,0]
	v_pk_fma_f32 v[54:55], v[54:55], 0.5, v[196:197] op_sel_hi:[1,0,1]
	v_pk_fma_f32 v[52:53], v[52:53], 0.5, v[156:157] op_sel_hi:[1,0,1]
	v_pk_fma_f32 v[50:51], v[50:51], 0.5, v[198:199] op_sel_hi:[1,0,1]
	v_pk_fma_f32 v[48:49], v[48:49], 0.5, v[158:159] op_sel_hi:[1,0,1]
	global_store_dwordx4 v[152:153], v[52:55], off offset:512
	global_store_dwordx4 v[152:153], v[48:51], off offset:528
	v_lshl_add_u64 v[154:155], v[232:233], 2, s[2:3]
	s_waitcnt vmcnt(25)
	v_lshlrev_b32_e32 v156, 16, v200
	v_and_b32_e32 v157, 0xffff0000, v200
	v_lshlrev_b32_e32 v200, 16, v201
	v_and_b32_e32 v201, 0xffff0000, v201
	v_lshlrev_b32_e32 v158, 16, v202
	v_and_b32_e32 v159, 0xffff0000, v202
	v_lshlrev_b32_e32 v202, 16, v203
	v_and_b32_e32 v203, 0xffff0000, v203
	v_pk_mul_f32 v[156:157], v[156:157], s[14:15] op_sel_hi:[1,0]
	v_pk_mul_f32 v[200:201], v[200:201], s[14:15] op_sel_hi:[1,0]
	v_pk_mul_f32 v[158:159], v[158:159], s[14:15] op_sel_hi:[1,0]
	v_pk_mul_f32 v[202:203], v[202:203], s[14:15] op_sel_hi:[1,0]
	v_pk_fma_f32 v[46:47], v[46:47], 0.5, v[200:201] op_sel_hi:[1,0,1]
	v_pk_fma_f32 v[44:45], v[44:45], 0.5, v[156:157] op_sel_hi:[1,0,1]
	v_pk_fma_f32 v[42:43], v[42:43], 0.5, v[202:203] op_sel_hi:[1,0,1]
	v_pk_fma_f32 v[40:41], v[40:41], 0.5, v[158:159] op_sel_hi:[1,0,1]
	global_store_dwordx4 v[154:155], v[44:47], off
	global_store_dwordx4 v[154:155], v[40:43], off offset:16
	s_waitcnt vmcnt(26)
	v_lshlrev_b32_e32 v156, 16, v204
	v_and_b32_e32 v157, 0xffff0000, v204
	v_lshlrev_b32_e32 v204, 16, v205
	v_and_b32_e32 v205, 0xffff0000, v205
	v_lshlrev_b32_e32 v158, 16, v206
	v_and_b32_e32 v159, 0xffff0000, v206
	v_lshlrev_b32_e32 v206, 16, v207
	v_and_b32_e32 v207, 0xffff0000, v207
	v_pk_mul_f32 v[156:157], v[156:157], s[14:15] op_sel_hi:[1,0]
	v_pk_mul_f32 v[204:205], v[204:205], s[14:15] op_sel_hi:[1,0]
	v_pk_mul_f32 v[158:159], v[158:159], s[14:15] op_sel_hi:[1,0]
	v_pk_mul_f32 v[206:207], v[206:207], s[14:15] op_sel_hi:[1,0]
	v_pk_fma_f32 v[38:39], v[38:39], 0.5, v[204:205] op_sel_hi:[1,0,1]
	v_pk_fma_f32 v[36:37], v[36:37], 0.5, v[156:157] op_sel_hi:[1,0,1]
	v_pk_fma_f32 v[34:35], v[34:35], 0.5, v[206:207] op_sel_hi:[1,0,1]
	v_pk_fma_f32 v[32:33], v[32:33], 0.5, v[158:159] op_sel_hi:[1,0,1]
	global_store_dwordx4 v[154:155], v[36:39], off offset:512
	global_store_dwordx4 v[154:155], v[32:35], off offset:528
	v_lshl_add_u64 v[152:153], v[234:235], 2, s[2:3]
	s_waitcnt vmcnt(27)
	v_lshlrev_b32_e32 v156, 16, v208
	v_and_b32_e32 v157, 0xffff0000, v208
	v_lshlrev_b32_e32 v208, 16, v209
	v_and_b32_e32 v209, 0xffff0000, v209
	v_lshlrev_b32_e32 v158, 16, v210
	v_and_b32_e32 v159, 0xffff0000, v210
	v_lshlrev_b32_e32 v210, 16, v211
	v_and_b32_e32 v211, 0xffff0000, v211
	v_pk_mul_f32 v[156:157], v[156:157], s[14:15] op_sel_hi:[1,0]
	v_pk_mul_f32 v[208:209], v[208:209], s[14:15] op_sel_hi:[1,0]
	v_pk_mul_f32 v[158:159], v[158:159], s[14:15] op_sel_hi:[1,0]
	v_pk_mul_f32 v[210:211], v[210:211], s[14:15] op_sel_hi:[1,0]
	v_pk_fma_f32 v[30:31], v[30:31], 0.5, v[208:209] op_sel_hi:[1,0,1]
	v_pk_fma_f32 v[28:29], v[28:29], 0.5, v[156:157] op_sel_hi:[1,0,1]
	v_pk_fma_f32 v[26:27], v[26:27], 0.5, v[210:211] op_sel_hi:[1,0,1]
	v_pk_fma_f32 v[24:25], v[24:25], 0.5, v[158:159] op_sel_hi:[1,0,1]
	global_store_dwordx4 v[152:153], v[28:31], off
	global_store_dwordx4 v[152:153], v[24:27], off offset:16
	s_waitcnt vmcnt(28)
	v_lshlrev_b32_e32 v156, 16, v212
	v_and_b32_e32 v157, 0xffff0000, v212
	v_lshlrev_b32_e32 v212, 16, v213
	v_and_b32_e32 v213, 0xffff0000, v213
	v_lshlrev_b32_e32 v158, 16, v214
	v_and_b32_e32 v159, 0xffff0000, v214
	v_lshlrev_b32_e32 v214, 16, v215
	v_and_b32_e32 v215, 0xffff0000, v215
	v_pk_mul_f32 v[156:157], v[156:157], s[14:15] op_sel_hi:[1,0]
	v_pk_mul_f32 v[212:213], v[212:213], s[14:15] op_sel_hi:[1,0]
	v_pk_mul_f32 v[158:159], v[158:159], s[14:15] op_sel_hi:[1,0]
	v_pk_mul_f32 v[214:215], v[214:215], s[14:15] op_sel_hi:[1,0]
	v_pk_fma_f32 v[22:23], v[22:23], 0.5, v[212:213] op_sel_hi:[1,0,1]
	v_pk_fma_f32 v[20:21], v[20:21], 0.5, v[156:157] op_sel_hi:[1,0,1]
	v_pk_fma_f32 v[18:19], v[18:19], 0.5, v[214:215] op_sel_hi:[1,0,1]
	v_pk_fma_f32 v[16:17], v[16:17], 0.5, v[158:159] op_sel_hi:[1,0,1]
	global_store_dwordx4 v[152:153], v[20:23], off offset:512
	global_store_dwordx4 v[152:153], v[16:19], off offset:528
	v_lshl_add_u64 v[154:155], v[236:237], 2, s[2:3]
	s_waitcnt vmcnt(29)
	v_lshlrev_b32_e32 v156, 16, v216
	v_and_b32_e32 v157, 0xffff0000, v216
	v_lshlrev_b32_e32 v216, 16, v217
	v_and_b32_e32 v217, 0xffff0000, v217
	v_lshlrev_b32_e32 v158, 16, v218
	v_and_b32_e32 v159, 0xffff0000, v218
	v_lshlrev_b32_e32 v218, 16, v219
	v_and_b32_e32 v219, 0xffff0000, v219
	v_pk_mul_f32 v[156:157], v[156:157], s[14:15] op_sel_hi:[1,0]
	v_pk_mul_f32 v[216:217], v[216:217], s[14:15] op_sel_hi:[1,0]
	v_pk_mul_f32 v[158:159], v[158:159], s[14:15] op_sel_hi:[1,0]
	v_pk_mul_f32 v[218:219], v[218:219], s[14:15] op_sel_hi:[1,0]
	v_pk_fma_f32 v[14:15], v[14:15], 0.5, v[216:217] op_sel_hi:[1,0,1]
	v_pk_fma_f32 v[12:13], v[12:13], 0.5, v[156:157] op_sel_hi:[1,0,1]
	v_pk_fma_f32 v[10:11], v[10:11], 0.5, v[218:219] op_sel_hi:[1,0,1]
	v_pk_fma_f32 v[8:9], v[8:9], 0.5, v[158:159] op_sel_hi:[1,0,1]
	global_store_dwordx4 v[154:155], v[12:15], off
	global_store_dwordx4 v[154:155], v[8:11], off offset:16
	s_waitcnt vmcnt(30)
	v_lshlrev_b32_e32 v156, 16, v220
	v_and_b32_e32 v157, 0xffff0000, v220
	v_lshlrev_b32_e32 v220, 16, v221
	v_and_b32_e32 v221, 0xffff0000, v221
	v_lshlrev_b32_e32 v158, 16, v222
	v_and_b32_e32 v159, 0xffff0000, v222
	v_lshlrev_b32_e32 v222, 16, v223
	v_and_b32_e32 v223, 0xffff0000, v223
	v_pk_mul_f32 v[156:157], v[156:157], s[14:15] op_sel_hi:[1,0]
	v_pk_mul_f32 v[220:221], v[220:221], s[14:15] op_sel_hi:[1,0]
	v_pk_mul_f32 v[158:159], v[158:159], s[14:15] op_sel_hi:[1,0]
	v_pk_mul_f32 v[222:223], v[222:223], s[14:15] op_sel_hi:[1,0]
	v_pk_fma_f32 v[6:7], v[6:7], 0.5, v[220:221] op_sel_hi:[1,0,1]
	v_pk_fma_f32 v[4:5], v[4:5], 0.5, v[156:157] op_sel_hi:[1,0,1]
	v_pk_fma_f32 v[2:3], v[2:3], 0.5, v[222:223] op_sel_hi:[1,0,1]
	v_pk_fma_f32 v[0:1], v[0:1], 0.5, v[158:159] op_sel_hi:[1,0,1]
	global_store_dwordx4 v[154:155], v[4:7], off offset:512
	global_store_dwordx4 v[154:155], v[0:3], off offset:528
	s_cbranch_vccnz .LBB0_949
	s_andn2_b64 vcc, exec, s[6:7]
	s_cbranch_vccnz .LBB0_948
	s_barrier
	s_branch .LBB0_948

; __device__ __forceinline__ void ln_phase(float* io, const float* g, const float* b, bf16_t* hb, float* stats, int gw, int NGW, int lane) {
;     ...
;     for (int row = gw; row < M; row += NGW) {
;         f32x4* xr = (f32x4*)(io + (size_t)row * D) + lane;
;         f32x4 v[8]; float s = 0.f;
; #pragma unroll
;         for (int j = 0; j < 8; ++j) { v[j] = xr[64 * j]; s += (v[j][0] + v[j][1]) + (v[j][2] + v[j][3]); }
;         const float mean = wave_sum(s, lane) * (1.f / D); float s2 = 0.f;
; #pragma unroll
;         for (int j = 0; j < 8; ++j) { v[j] = v[j] - mean; s2 += (v[j][0] * v[j][0] + v[j][1] * v[j][1]) + (v[j][2] * v[j][2] + v[j][3] * v[j][3]); }
;         const float rstd = 1.0f / sqrtf(wave_sum(s2, lane) * (1.f / D) + 1e-5f);
.LBB0_1036:
	v_add_co_u32_e32 v84, vcc, 0xfffff000, v82
	v_add_co_u32_e64 v86, s[0:1], s3, v82
	s_nop 0
	v_addc_co_u32_e32 v85, vcc, -1, v83, vcc
	v_add_co_u32_e32 v106, vcc, 0xfffff400, v82
	flat_load_dwordx4 v[64:67], v[82:83] nt
	v_addc_co_u32_e64 v87, s[0:1], -1, v83, s[0:1]
	flat_load_dwordx4 v[68:71], v[82:83] offset:1024 nt
	flat_load_dwordx4 v[72:75], v[82:83] offset:2048 nt
	flat_load_dwordx4 v[76:79], v[82:83] offset:3072 nt
	flat_load_dwordx4 v[102:105], v[84:85] nt
	v_addc_co_u32_e32 v107, vcc, -1, v83, vcc
	v_add_co_u32_e64 v88, s[0:1], s8, v82
	flat_load_dwordx4 v[98:101], v[86:87] nt
	s_nop 0
	v_addc_co_u32_e64 v89, s[0:1], -1, v83, s[0:1]
	flat_load_dwordx4 v[106:109], v[106:107] nt
	s_add_i32 s2, s2, s58
	flat_load_dwordx4 v[86:89], v[88:89] nt
	s_cmp_lt_i32 s2, 0x8000
	v_lshl_add_u64 v[82:83], v[82:83], 0, s[6:7]
	s_waitcnt vmcnt(0) lgkmcnt(0)
	v_mov_b32_e32 v111, v66
	v_mov_b32_e32 v113, v67
	v_mov_b32_e32 v114, v69
	v_mov_b32_e32 v115, v70
	v_mov_b32_e32 v116, v68
	v_mov_b32_e32 v117, v71
	v_add_f32_e32 v118, v72, v73
	v_add_f32_e32 v120, v74, v75
	v_mov_b32_e32 v119, v78
	v_mov_b32_e32 v121, v79
	v_pk_add_f32 v[114:115], v[114:115], v[116:117]
	v_pk_add_f32 v[116:117], v[118:119], v[120:121]
	v_mov_b32_e32 v118, v102
	v_mov_b32_e32 v120, v103
	v_mov_b32_e32 v126, v104
	v_mov_b32_e32 v128, v105
	v_mov_b32_e32 v119, v106
	v_mov_b32_e32 v121, v107
	v_mov_b32_e32 v127, v108
	v_mov_b32_e32 v129, v109
	v_mov_b32_e32 v122, v99
	v_mov_b32_e32 v123, v100
	v_mov_b32_e32 v124, v98
	v_mov_b32_e32 v125, v101
	v_pk_add_f32 v[118:119], v[118:119], v[120:121]
	v_pk_add_f32 v[120:121], v[126:127], v[128:129]
	v_add_f32_e32 v110, v86, v87
	v_add_f32_e32 v112, v88, v89
	v_pk_add_f32 v[122:123], v[122:123], v[124:125]
	v_pk_add_f32 v[118:119], v[118:119], v[120:121]
	v_pk_add_f32 v[110:111], v[110:111], v[112:113]
	v_pk_add_f32 v[112:113], v[114:115], v[114:115] op_sel:[0,1] op_sel_hi:[1,0]
	v_pk_add_f32 v[114:115], v[122:123], v[122:123] op_sel:[0,1] op_sel_hi:[1,0]
	v_add_f32_e32 v84, 0, v118
	v_mov_b32_e32 v85, v64
	v_mov_b32_e32 v115, v65
	v_add_f32_e32 v84, v84, v119
	v_pk_add_f32 v[84:85], v[84:85], v[114:115]
	v_mov_b32_e32 v113, v77
	v_pk_add_f32 v[84:85], v[84:85], v[110:111]
	s_nop 0
	v_pk_add_f32 v[84:85], v[84:85], v[84:85] op_sel:[0,1] op_sel_hi:[1,0]
	s_nop 0
	v_mov_b32_e32 v85, v76
	v_pk_add_f32 v[84:85], v[84:85], v[112:113]
	s_nop 0
	v_pk_add_f32 v[84:85], v[84:85], v[116:117]
	s_nop 0
	v_add_f32_e32 v84, v84, v85
	ds_bpermute_b32 v85, v90, v84
	s_waitcnt lgkmcnt(0)
	v_add_f32_e32 v84, v84, v85
	ds_bpermute_b32 v85, v91, v84
	s_waitcnt lgkmcnt(0)
	v_add_f32_e32 v84, v84, v85
	ds_bpermute_b32 v85, v92, v84
	s_waitcnt lgkmcnt(0)
	v_add_f32_e32 v84, v84, v85
	ds_bpermute_b32 v85, v93, v84
	s_waitcnt lgkmcnt(0)
	v_add_f32_e32 v84, v84, v85
	ds_bpermute_b32 v85, v94, v84
	s_waitcnt lgkmcnt(0)
	v_add_f32_e32 v84, v84, v85
	ds_bpermute_b32 v85, v95, v84
	s_waitcnt lgkmcnt(0)
	v_add_f32_e32 v110, v84, v85
	v_fmamk_f32 v85, v110, 0xba000000, v105
	v_fmamk_f32 v103, v110, 0xba000000, v103
	v_fmamk_f32 v105, v110, 0xba000000, v109
	v_fmamk_f32 v107, v110, 0xba000000, v107
	v_fmamk_f32 v84, v110, 0xba000000, v104
	v_fmac_f32_e32 v102, 0xba000000, v110
	v_fmamk_f32 v104, v110, 0xba000000, v108
	v_fmac_f32_e32 v106, 0xba000000, v110
	v_fmamk_f32 v99, v110, 0xba000000, v99
	v_fmamk_f32 v98, v110, 0xba000000, v98
	v_fmamk_f32 v101, v110, 0xba000000, v101
	v_fmac_f32_e32 v100, 0xba000000, v110
	v_fmamk_f32 v87, v110, 0xba000000, v87
	v_fmamk_f32 v86, v110, 0xba000000, v86
	v_fmamk_f32 v89, v110, 0xba000000, v89
	v_fmac_f32_e32 v88, 0xba000000, v110
	v_fmamk_f32 v67, v110, 0xba000000, v67
	v_fmamk_f32 v66, v110, 0xba000000, v66
	v_fmamk_f32 v65, v110, 0xba000000, v65
	v_fmac_f32_e32 v64, 0xba000000, v110
	v_fmamk_f32 v69, v110, 0xba000000, v69
	v_fmamk_f32 v68, v110, 0xba000000, v68
	v_fmamk_f32 v71, v110, 0xba000000, v71
	v_fmac_f32_e32 v70, 0xba000000, v110
	v_fmamk_f32 v73, v110, 0xba000000, v73
	v_fmamk_f32 v72, v110, 0xba000000, v72
	v_fmamk_f32 v75, v110, 0xba000000, v75
	v_fmac_f32_e32 v74, 0xba000000, v110
	v_fmamk_f32 v79, v110, 0xba000000, v79
	v_fmamk_f32 v78, v110, 0xba000000, v78
	v_fmamk_f32 v77, v110, 0xba000000, v77
	v_fmac_f32_e32 v76, 0xba000000, v110
	v_mov_b32_e32 v110, v103
	v_mov_b32_e32 v111, v107
	v_mov_b32_e32 v114, v85
	v_mov_b32_e32 v115, v105
	v_mov_b32_e32 v108, v102
	v_mov_b32_e32 v109, v106
	v_mov_b32_e32 v112, v84
	v_mov_b32_e32 v113, v104
	v_pk_mul_f32 v[116:117], v[100:101], v[100:101]
	v_pk_mul_f32 v[118:119], v[98:99], v[98:99]
	v_pk_mul_f32 v[110:111], v[110:111], v[110:111]
	v_pk_mul_f32 v[114:115], v[114:115], v[114:115]
	v_pk_mov_b32 v[132:133], v[118:119], v[116:117] op_sel:[1,0]
	v_mov_b32_e32 v119, v117
	v_pk_fma_f32 v[108:109], v[108:109], v[108:109], v[110:111]
	v_pk_fma_f32 v[110:111], v[112:113], v[112:113], v[114:115]
	v_mul_f32_e32 v120, v86, v86
	v_mul_f32_e32 v122, v88, v88
	v_pk_add_f32 v[112:113], v[132:133], v[118:119]
	v_pk_add_f32 v[108:109], v[108:109], v[110:111]
	v_pk_fma_f32 v[116:117], v[86:87], v[86:87], v[120:121] op_sel_hi:[1,1,0]
	v_pk_fma_f32 v[120:121], v[88:89], v[88:89], v[122:123] op_sel_hi:[1,1,0]
	v_pk_add_f32 v[110:111], v[112:113], v[112:113] op_sel_hi:[0,1]
	v_pk_add_f32 v[108:109], v[108:109], v[108:109] op_sel_hi:[0,1]
	v_pk_mul_f32 v[124:125], v[70:71], v[70:71]
	v_pk_mul_f32 v[126:127], v[68:69], v[68:69]
	v_mul_f32_e32 v116, v64, v64
	v_mul_f32_e32 v120, v65, v65
	v_mul_f32_e32 v110, v66, v66
	v_mul_f32_e32 v108, v67, v67
	v_pk_mov_b32 v[122:123], v[126:127], v[124:125] op_sel:[1,0]
	v_mov_b32_e32 v127, v125
	v_pk_add_f32 v[112:113], v[116:117], v[120:121]
	v_pk_add_f32 v[108:109], v[110:111], v[108:109]
	v_mul_f32_e32 v128, v72, v72
	v_mul_f32_e32 v130, v74, v74
	v_pk_add_f32 v[114:115], v[122:123], v[126:127]
	v_pk_add_f32 v[108:109], v[112:113], v[108:109]
	v_pk_fma_f32 v[124:125], v[72:73], v[72:73], v[128:129] op_sel_hi:[1,1,0]
	v_pk_fma_f32 v[128:129], v[74:75], v[74:75], v[130:131] op_sel_hi:[1,1,0]
	v_pk_add_f32 v[114:115], v[114:115], v[114:115] op_sel_hi:[0,1]
	v_pk_add_f32 v[108:109], v[108:109], v[108:109] op_sel_hi:[0,1]
	v_mul_f32_e32 v124, v76, v76
	v_mul_f32_e32 v128, v77, v77
	v_mul_f32_e32 v114, v78, v78
	v_mul_f32_e32 v108, v79, v79
	v_pk_add_f32 v[116:117], v[124:125], v[128:129]
	v_pk_add_f32 v[108:109], v[114:115], v[108:109]
	s_nop 0
	v_pk_add_f32 v[108:109], v[116:117], v[108:109]
	s_nop 0
	v_add_f32_e32 v108, v108, v109
	ds_bpermute_b32 v109, v90, v108
	s_waitcnt lgkmcnt(0)
; __device__ __forceinline__ unsigned cvt_pk_bf16(float lo, float hi) { unsigned r; asm volatile("s_nop 1\n\tv_cvt_pk_bf16_f32 %0, %1, %2" : "=v"(r) : "v"(lo), "v"(hi)); return r; }
; __device__ __forceinline__ void ln_phase(float* io, const float* g, const float* b, bf16_t* hb, float* stats, int gw, int NGW, int lane) {
;     ...
;         const float mean = wave_sum(s, lane) * (1.f / D); float s2 = 0.f;
; #pragma unroll
;         for (int j = 0; j < 8; ++j) { v[j] = v[j] - mean; s2 += (v[j][0] * v[j][0] + v[j][1] * v[j][1]) + (v[j][2] * v[j][2] + v[j][3] * v[j][3]); }
;         const float rstd = 1.0f / sqrtf(wave_sum(s2, lane) * (1.f / D) + 1e-5f);
; #pragma unroll
;         for (int j = 0; j < 8; ++j) v[j] = v[j] * rstd * gv[j] + bv[j];
;         if (stats) {
;             u32x2* o8 = (u32x2*)(hb + (size_t)row * D) + lane;
; #pragma unroll
;             for (int j = 0; j < 8; ++j) { u32x2 w; w.x = cvt_pk_bf16(v[j][0], v[j][1]); w.y = cvt_pk_bf16(v[j][2], v[j][3]); o8[64 * j] = w; }
	v_add_f32_e32 v108, v108, v109
	ds_bpermute_b32 v109, v91, v108
	s_waitcnt lgkmcnt(0)
	v_add_f32_e32 v108, v108, v109
	ds_bpermute_b32 v109, v92, v108
	s_waitcnt lgkmcnt(0)
	v_add_f32_e32 v108, v108, v109
	ds_bpermute_b32 v109, v93, v108
	s_waitcnt lgkmcnt(0)
	v_add_f32_e32 v108, v108, v109
	ds_bpermute_b32 v109, v94, v108
	s_waitcnt lgkmcnt(0)
	v_add_f32_e32 v108, v108, v109
	ds_bpermute_b32 v109, v95, v108
	s_waitcnt lgkmcnt(0)
	v_add_f32_e32 v108, v108, v109
	v_fmamk_f32 v108, v108, 0x3a000000, v96
	v_mul_f32_e32 v109, 0x4f800000, v108
	v_cmp_gt_f32_e32 vcc, s9, v108
	s_nop 1
	v_cndmask_b32_e32 v108, v108, v109, vcc
	v_sqrt_f32_e32 v109, v108
	s_nop 0
	v_add_u32_e32 v110, -1, v109
	v_add_u32_e32 v111, 1, v109
	v_fma_f32 v112, -v110, v109, v108
	v_fma_f32 v113, -v111, v109, v108
	v_cmp_ge_f32_e64 s[0:1], 0, v112
	s_nop 1
	v_cndmask_b32_e64 v109, v109, v110, s[0:1]
	v_cmp_lt_f32_e64 s[0:1], 0, v113
	s_nop 1
	v_cndmask_b32_e64 v109, v109, v111, s[0:1]
	v_mul_f32_e32 v110, 0x37800000, v109
	v_cndmask_b32_e32 v109, v109, v110, vcc
	v_cmp_class_f32_e32 vcc, v108, v97
	s_nop 1
	v_cndmask_b32_e32 v108, v109, v108, vcc
	v_div_scale_f32 v109, s[0:1], v108, v108, 1.0
	v_rcp_f32_e32 v111, v109
	v_div_scale_f32 v110, vcc, 1.0, v108, 1.0
	v_fma_f32 v112, -v109, v111, 1.0
	v_fmac_f32_e32 v111, v112, v111
	v_mul_f32_e32 v112, v110, v111
	v_fma_f32 v113, -v109, v112, v110
	v_fmac_f32_e32 v112, v113, v111
	v_fma_f32 v109, -v109, v112, v110
	v_div_fmas_f32 v109, v109, v111, v112
	v_div_fixup_f32 v108, v109, v108, 1.0
	v_pk_mul_f32 v[84:85], v[84:85], v[108:109] op_sel_hi:[1,0]
	v_pk_mul_f32 v[102:103], v[102:103], v[108:109] op_sel_hi:[1,0]
	v_pk_mul_f32 v[104:105], v[104:105], v[108:109] op_sel_hi:[1,0]
	v_pk_mul_f32 v[106:107], v[106:107], v[108:109] op_sel_hi:[1,0]
	v_pk_fma_f32 v[102:103], v[0:1], v[102:103], v[4:5]
	v_pk_fma_f32 v[84:85], v[2:3], v[84:85], v[6:7]
	v_pk_mul_f32 v[100:101], v[100:101], v[108:109] op_sel_hi:[1,0]
	v_pk_mul_f32 v[98:99], v[98:99], v[108:109] op_sel_hi:[1,0]
	v_pk_mul_f32 v[64:65], v[64:65], v[108:109] op_sel_hi:[1,0]
	v_pk_fma_f32 v[106:107], v[8:9], v[106:107], v[16:17]
	v_pk_fma_f32 v[104:105], v[10:11], v[104:105], v[18:19]
	s_nop 1
	v_cvt_pk_bf16_f32 v102, v102, v103
	s_nop 1
	v_cvt_pk_bf16_f32 v103, v84, v85
	flat_store_dwordx2 v[80:81], v[102:103]
	s_nop 1
	v_cvt_pk_bf16_f32 v84, v106, v107
	s_nop 1
	v_cvt_pk_bf16_f32 v85, v104, v105
	v_pk_mul_f32 v[88:89], v[88:89], v[108:109] op_sel_hi:[1,0]
	v_pk_mul_f32 v[86:87], v[86:87], v[108:109] op_sel_hi:[1,0]
	v_pk_mul_f32 v[66:67], v[66:67], v[108:109] op_sel_hi:[1,0]
	v_pk_fma_f32 v[98:99], v[12:13], v[98:99], v[20:21]
	v_pk_fma_f32 v[100:101], v[14:15], v[100:101], v[22:23]
	v_pk_fma_f32 v[64:65], v[32:33], v[64:65], v[40:41]
	flat_store_dwordx2 v[80:81], v[84:85] offset:512
	s_nop 1
	v_cvt_pk_bf16_f32 v84, v98, v99
	s_nop 1
	v_cvt_pk_bf16_f32 v85, v100, v101
	v_pk_mul_f32 v[70:71], v[70:71], v[108:109] op_sel_hi:[1,0]
	v_pk_mul_f32 v[68:69], v[68:69], v[108:109] op_sel_hi:[1,0]
	v_pk_fma_f32 v[86:87], v[24:25], v[86:87], v[28:29]
	v_pk_fma_f32 v[88:89], v[26:27], v[88:89], v[30:31]
	v_pk_fma_f32 v[66:67], v[34:35], v[66:67], v[42:43]
	flat_store_dwordx2 v[80:81], v[84:85] offset:1024
	s_nop 1
	v_cvt_pk_bf16_f32 v84, v86, v87
	s_nop 1
	v_cvt_pk_bf16_f32 v85, v88, v89
	flat_store_dwordx2 v[80:81], v[84:85] offset:1536
	s_nop 1
	v_cvt_pk_bf16_f32 v64, v64, v65
	s_nop 1
	v_cvt_pk_bf16_f32 v65, v66, v67
	v_pk_mul_f32 v[74:75], v[74:75], v[108:109] op_sel_hi:[1,0]
	v_pk_mul_f32 v[72:73], v[72:73], v[108:109] op_sel_hi:[1,0]
	v_pk_fma_f32 v[68:69], v[36:37], v[68:69], v[44:45]
	v_pk_fma_f32 v[70:71], v[38:39], v[70:71], v[46:47]
	flat_store_dwordx2 v[80:81], v[64:65] offset:2048
	s_nop 1
	v_cvt_pk_bf16_f32 v64, v68, v69
	s_nop 1
	v_cvt_pk_bf16_f32 v65, v70, v71
	v_pk_mul_f32 v[78:79], v[78:79], v[108:109] op_sel_hi:[1,0]
	v_pk_mul_f32 v[76:77], v[76:77], v[108:109] op_sel_hi:[1,0]
	v_pk_fma_f32 v[72:73], v[48:49], v[72:73], v[56:57]
	v_pk_fma_f32 v[74:75], v[50:51], v[74:75], v[58:59]
	flat_store_dwordx2 v[80:81], v[64:65] offset:2560
	s_nop 1
	v_cvt_pk_bf16_f32 v64, v72, v73
	s_nop 1
	v_cvt_pk_bf16_f32 v65, v74, v75
	v_pk_fma_f32 v[76:77], v[52:53], v[76:77], v[60:61]
	v_pk_fma_f32 v[78:79], v[54:55], v[78:79], v[62:63]
	flat_store_dwordx2 v[80:81], v[64:65] offset:3072
	s_nop 1
	v_cvt_pk_bf16_f32 v64, v76, v77
	s_nop 1
	v_cvt_pk_bf16_f32 v65, v78, v79
	flat_store_dwordx2 v[80:81], v[64:65] offset:3584
	v_lshl_add_u64 v[80:81], v[80:81], 0, s[4:5]
	s_cbranch_scc1 .LBB0_1036
	v_readlane_b32 s59, v254, 0

; __device__ __forceinline__ float bf_lo(unsigned u) { return __uint_as_float(u << 16); }
; __device__ __forceinline__ float bf_hi(unsigned u) { return __uint_as_float(u & 0xffff0000u); }
; __device__ __forceinline__ float fsigmoid(float x) { return __builtin_amdgcn_rcpf(1.0f + __builtin_amdgcn_exp2f(-LOG2E * x)); }
;     __device__ __forceinline__ void operator()(AccRef acc, const Unit& u, int wr, int wc, int fr, int fq) const {
;     ...
; #pragma unroll
;                 for (int bj = 0; bj < 2; ++bj) {
;                     const u32x4 pv = *(const u32x4*)(pp + off + bj * HALF);
;                     const u32x4 hv = *(const u32x4*)(hb + off + bj * HALF);
;                     f32x4 r0, r1;
;                     r0[0] = bf_lo(hv.x); r0[1] = bf_hi(hv.x); r0[2] = bf_lo(hv.y); r0[3] = bf_hi(hv.y); r1[0] = bf_lo(hv.z); r1[1] = bf_hi(hv.z); r1[2] = bf_lo(hv.w); r1[3] = bf_hi(hv.w);
;                     const f32x4 a0 = acc[ai][bj][m][0], a1 = acc[ai][bj][m][1];
;                     f32x4 o0, o1;
;                     o0[0] = r0[0] * alpha + fsigmoid(a0[0]) * bf_lo(pv.x); o0[1] = r0[1] * alpha + fsigmoid(a0[1]) * bf_hi(pv.x);
;                     o0[2] = r0[2] * alpha + fsigmoid(a0[2]) * bf_lo(pv.y); o0[3] = r0[3] * alpha + fsigmoid(a0[3]) * bf_hi(pv.y);
;                     o1[0] = r1[0] * alpha + fsigmoid(a1[0]) * bf_lo(pv.z); o1[1] = r1[1] * alpha + fsigmoid(a1[1]) * bf_hi(pv.z);
;                     o1[2] = r1[2] * alpha + fsigmoid(a1[2]) * bf_lo(pv.w); o1[3] = r1[3] * alpha + fsigmoid(a1[3]) * bf_hi(pv.w);
;                     *(f32x4*)(out + off + bj * HALF) = o0; *(f32x4*)(out + off + bj * HALF + 4) = o1;
.LBB0_1102:
	v_mov_b32_e32 v144, v146
	v_mov_b32_e32 v145, v147
	s_lshl_b32 s31, s40, 8
	s_add_i32 s31, s31, s57
	v_add_u32_e32 v144, s31, v144
	s_lshl_b32 s31, s64, 8
	s_or_b32 s31, s31, s58
	v_lshl_add_u32 v152, v145, 3, s31
	v_ashrrev_i32_e32 v145, 31, v144
	v_ashrrev_i32_e32 v153, 31, v152
	v_lshlrev_b64 v[144:145], 11, v[144:145]
	v_lshl_add_u64 v[144:145], v[144:145], 0, v[152:153]
	v_lshlrev_b64 v[156:157], 1, v[144:145]
	v_lshl_add_u64 v[160:161], s[4:5], 0, v[156:157]
	flat_load_dwordx4 v[152:155], v[160:161] nt
	v_lshl_add_u64 v[162:163], s[8:9], 0, v[156:157]
	flat_load_dwordx4 v[156:159], v[162:163] nt
	v_mul_f32_e32 v124, 0xbfb8aa3b, v124
	v_mul_f32_e32 v125, 0xbfb8aa3b, v125
	v_mul_f32_e32 v126, 0xbfb8aa3b, v126
	v_mul_f32_e32 v127, 0xbfb8aa3b, v127
	v_mul_f32_e32 v120, 0xbfb8aa3b, v120
	v_mul_f32_e32 v121, 0xbfb8aa3b, v121
	v_mul_f32_e32 v122, 0xbfb8aa3b, v122
	v_mul_f32_e32 v123, 0xbfb8aa3b, v123
	v_exp_f32_e32 v124, v124
	v_exp_f32_e32 v125, v125
	v_exp_f32_e32 v126, v126
	v_exp_f32_e32 v127, v127
	v_exp_f32_e32 v120, v120
	v_exp_f32_e32 v121, v121
	v_exp_f32_e32 v122, v122
	v_exp_f32_e32 v123, v123
	v_add_f32_e32 v124, 1.0, v124
	v_add_f32_e32 v125, 1.0, v125
	v_add_f32_e32 v126, 1.0, v126
	v_add_f32_e32 v127, 1.0, v127
	v_add_f32_e32 v164, 1.0, v120
	v_add_f32_e32 v165, 1.0, v121
	v_add_f32_e32 v166, 1.0, v122
	v_add_f32_e32 v167, 1.0, v123
	v_rcp_f32_e32 v120, v124
	v_rcp_f32_e32 v121, v125
	v_rcp_f32_e32 v122, v126
	v_rcp_f32_e32 v123, v127
	v_rcp_f32_e32 v124, v164
	v_rcp_f32_e32 v125, v165
	v_rcp_f32_e32 v126, v166
	v_rcp_f32_e32 v127, v167
	v_lshl_add_u64 v[164:165], v[144:145], 2, s[2:3]
	v_mul_f32_e32 v116, 0xbfb8aa3b, v116
	v_mul_f32_e32 v117, 0xbfb8aa3b, v117
	v_mul_f32_e32 v118, 0xbfb8aa3b, v118
	v_mul_f32_e32 v119, 0xbfb8aa3b, v119
	v_mul_f32_e32 v112, 0xbfb8aa3b, v112
	v_mul_f32_e32 v113, 0xbfb8aa3b, v113
	v_mul_f32_e32 v114, 0xbfb8aa3b, v114
	v_mul_f32_e32 v115, 0xbfb8aa3b, v115
	v_exp_f32_e32 v116, v116
	v_exp_f32_e32 v117, v117
	v_exp_f32_e32 v118, v118
	v_exp_f32_e32 v119, v119
	v_exp_f32_e32 v112, v112
	v_exp_f32_e32 v113, v113
	v_exp_f32_e32 v114, v114
	v_exp_f32_e32 v115, v115
	v_add_f32_e32 v116, 1.0, v116
	v_add_f32_e32 v117, 1.0, v117
	v_add_f32_e32 v118, 1.0, v118
	v_add_f32_e32 v119, 1.0, v119
	v_mul_f32_e32 v108, 0xbfb8aa3b, v108
	v_mul_f32_e32 v109, 0xbfb8aa3b, v109
	v_mul_f32_e32 v110, 0xbfb8aa3b, v110
	v_mul_f32_e32 v111, 0xbfb8aa3b, v111
	v_mul_f32_e32 v104, 0xbfb8aa3b, v104
	v_mul_f32_e32 v105, 0xbfb8aa3b, v105
	v_mul_f32_e32 v106, 0xbfb8aa3b, v106
	v_mul_f32_e32 v107, 0xbfb8aa3b, v107
	v_exp_f32_e32 v108, v108
	v_exp_f32_e32 v109, v109
	v_exp_f32_e32 v110, v110
	v_exp_f32_e32 v111, v111
	v_exp_f32_e32 v104, v104
	v_exp_f32_e32 v105, v105
	v_exp_f32_e32 v106, v106
	v_exp_f32_e32 v107, v107
	v_add_f32_e32 v108, 1.0, v108
	v_add_f32_e32 v109, 1.0, v109
	v_add_f32_e32 v110, 1.0, v110
	v_add_f32_e32 v111, 1.0, v111
	v_mul_f32_e32 v100, 0xbfb8aa3b, v100
	v_mul_f32_e32 v101, 0xbfb8aa3b, v101
	v_mul_f32_e32 v102, 0xbfb8aa3b, v102
	v_mul_f32_e32 v103, 0xbfb8aa3b, v103
	s_waitcnt vmcnt(0) lgkmcnt(0)
	v_lshlrev_b32_e32 v166, 16, v152
	v_and_b32_e32 v167, 0xffff0000, v152
	v_lshlrev_b32_e32 v152, 16, v153
	v_and_b32_e32 v153, 0xffff0000, v153
	v_lshlrev_b32_e32 v168, 16, v156
	v_and_b32_e32 v169, 0xffff0000, v156
	v_lshlrev_b32_e32 v156, 16, v157
	v_and_b32_e32 v157, 0xffff0000, v157
	v_lshlrev_b32_e32 v170, 16, v154
	v_and_b32_e32 v171, 0xffff0000, v154
	v_lshlrev_b32_e32 v154, 16, v155
	v_and_b32_e32 v155, 0xffff0000, v155
	v_pk_mul_f32 v[166:167], v[166:167], s[14:15] op_sel_hi:[1,0]
	v_pk_mul_f32 v[152:153], v[152:153], s[14:15] op_sel_hi:[1,0]
	v_lshlrev_b32_e32 v172, 16, v158
	v_and_b32_e32 v173, 0xffff0000, v158
	v_lshlrev_b32_e32 v158, 16, v159
	v_and_b32_e32 v159, 0xffff0000, v159
	v_pk_mul_f32 v[170:171], v[170:171], s[14:15] op_sel_hi:[1,0]
	v_pk_mul_f32 v[154:155], v[154:155], s[14:15] op_sel_hi:[1,0]
	v_pk_fma_f32 v[120:121], v[120:121], v[168:169], v[166:167]
	v_pk_fma_f32 v[122:123], v[122:123], v[156:157], v[152:153]
	v_pk_fma_f32 v[124:125], v[124:125], v[172:173], v[170:171]
	v_pk_fma_f32 v[126:127], v[126:127], v[158:159], v[154:155]
	flat_store_dwordx4 v[164:165], v[120:123]
	flat_store_dwordx4 v[164:165], v[124:127] offset:16
	flat_load_dwordx4 v[120:123], v[160:161] offset:256 nt
	s_nop 0
	flat_load_dwordx4 v[124:127], v[162:163] offset:256 nt
	v_add_f32_e32 v152, 1.0, v112
	v_add_f32_e32 v153, 1.0, v113
	v_add_f32_e32 v154, 1.0, v114
	v_add_f32_e32 v155, 1.0, v115
	v_rcp_f32_e32 v112, v116
	v_rcp_f32_e32 v113, v117
	v_rcp_f32_e32 v114, v118
	v_rcp_f32_e32 v115, v119
	v_rcp_f32_e32 v116, v152
	v_rcp_f32_e32 v117, v153
	v_rcp_f32_e32 v118, v154
	v_rcp_f32_e32 v119, v155
	v_lshl_add_u64 v[152:153], v[144:145], 0, s[16:17]
	v_lshlrev_b64 v[154:155], 1, v[152:153]
	v_lshl_add_u64 v[156:157], s[4:5], 0, v[154:155]
	v_mul_f32_e32 v96, 0xbfb8aa3b, v96
	v_mul_f32_e32 v97, 0xbfb8aa3b, v97
	v_mul_f32_e32 v98, 0xbfb8aa3b, v98
	v_mul_f32_e32 v99, 0xbfb8aa3b, v99
	v_exp_f32_e32 v100, v100
	v_exp_f32_e32 v101, v101
	v_exp_f32_e32 v102, v102
	v_exp_f32_e32 v103, v103
	v_exp_f32_e32 v96, v96
	v_exp_f32_e32 v97, v97
	v_exp_f32_e32 v98, v98
	v_exp_f32_e32 v99, v99
	v_add_f32_e32 v100, 1.0, v100
	v_add_f32_e32 v101, 1.0, v101
	v_add_f32_e32 v102, 1.0, v102
	v_add_f32_e32 v103, 1.0, v103
	v_mul_f32_e32 v92, 0xbfb8aa3b, v92
	v_mul_f32_e32 v93, 0xbfb8aa3b, v93
	v_mul_f32_e32 v94, 0xbfb8aa3b, v94
	v_mul_f32_e32 v95, 0xbfb8aa3b, v95
	v_mul_f32_e32 v88, 0xbfb8aa3b, v88
	v_mul_f32_e32 v89, 0xbfb8aa3b, v89
	v_mul_f32_e32 v90, 0xbfb8aa3b, v90
	v_mul_f32_e32 v91, 0xbfb8aa3b, v91
	v_exp_f32_e32 v92, v92
	v_exp_f32_e32 v93, v93
	v_exp_f32_e32 v94, v94
	v_exp_f32_e32 v95, v95
	v_exp_f32_e32 v88, v88
	v_exp_f32_e32 v89, v89
	v_exp_f32_e32 v90, v90
	v_exp_f32_e32 v91, v91
	v_add_f32_e32 v92, 1.0, v92
	v_add_f32_e32 v93, 1.0, v93
	v_add_f32_e32 v94, 1.0, v94
	v_add_f32_e32 v95, 1.0, v95
	v_mul_f32_e32 v84, 0xbfb8aa3b, v84
	v_mul_f32_e32 v85, 0xbfb8aa3b, v85
	v_mul_f32_e32 v86, 0xbfb8aa3b, v86
	v_mul_f32_e32 v87, 0xbfb8aa3b, v87
	v_mul_f32_e32 v80, 0xbfb8aa3b, v80
	v_mul_f32_e32 v81, 0xbfb8aa3b, v81
	v_mul_f32_e32 v82, 0xbfb8aa3b, v82
	v_mul_f32_e32 v83, 0xbfb8aa3b, v83
	v_exp_f32_e32 v84, v84
	v_exp_f32_e32 v85, v85
	v_exp_f32_e32 v86, v86
	v_exp_f32_e32 v87, v87
	v_exp_f32_e32 v80, v80
	v_exp_f32_e32 v81, v81
	v_exp_f32_e32 v82, v82
	v_exp_f32_e32 v83, v83
	v_add_f32_e32 v84, 1.0, v84
	v_add_f32_e32 v85, 1.0, v85
	v_add_f32_e32 v86, 1.0, v86
	v_add_f32_e32 v87, 1.0, v87
	v_mul_f32_e32 v76, 0xbfb8aa3b, v76
	v_mul_f32_e32 v77, 0xbfb8aa3b, v77
	v_mul_f32_e32 v78, 0xbfb8aa3b, v78
	v_mul_f32_e32 v79, 0xbfb8aa3b, v79
	v_mul_f32_e32 v72, 0xbfb8aa3b, v72
	v_mul_f32_e32 v73, 0xbfb8aa3b, v73
	v_mul_f32_e32 v74, 0xbfb8aa3b, v74
	s_waitcnt vmcnt(0) lgkmcnt(0)
; __device__ __forceinline__ float bf_lo(unsigned u) { return __uint_as_float(u << 16); }
; __device__ __forceinline__ float bf_hi(unsigned u) { return __uint_as_float(u & 0xffff0000u); }
; __device__ __forceinline__ float fsigmoid(float x) { return __builtin_amdgcn_rcpf(1.0f + __builtin_amdgcn_exp2f(-LOG2E * x)); }
;     __device__ __forceinline__ void operator()(AccRef acc, const Unit& u, int wr, int wc, int fr, int fq) const {
;     ...
;                 for (int bj = 0; bj < 2; ++bj) {
;                     const u32x4 pv = *(const u32x4*)(pp + off + bj * HALF);
;                     const u32x4 hv = *(const u32x4*)(hb + off + bj * HALF);
;                     f32x4 r0, r1;
;                     r0[0] = bf_lo(hv.x); r0[1] = bf_hi(hv.x); r0[2] = bf_lo(hv.y); r0[3] = bf_hi(hv.y); r1[0] = bf_lo(hv.z); r1[1] = bf_hi(hv.z); r1[2] = bf_lo(hv.w); r1[3] = bf_hi(hv.w);
;                     const f32x4 a0 = acc[ai][bj][m][0], a1 = acc[ai][bj][m][1];
;                     f32x4 o0, o1;
;                     o0[0] = r0[0] * alpha + fsigmoid(a0[0]) * bf_lo(pv.x); o0[1] = r0[1] * alpha + fsigmoid(a0[1]) * bf_hi(pv.x);
;                     o0[2] = r0[2] * alpha + fsigmoid(a0[2]) * bf_lo(pv.y); o0[3] = r0[3] * alpha + fsigmoid(a0[3]) * bf_hi(pv.y);
;                     o1[0] = r1[0] * alpha + fsigmoid(a1[0]) * bf_lo(pv.z); o1[1] = r1[1] * alpha + fsigmoid(a1[1]) * bf_hi(pv.z);
;                     o1[2] = r1[2] * alpha + fsigmoid(a1[2]) * bf_lo(pv.w); o1[3] = r1[3] * alpha + fsigmoid(a1[3]) * bf_hi(pv.w);
;                     *(f32x4*)(out + off + bj * HALF) = o0; *(f32x4*)(out + off + bj * HALF + 4) = o1;
	v_lshlrev_b32_e32 v158, 16, v120
	v_and_b32_e32 v159, 0xffff0000, v120
	v_lshlrev_b32_e32 v120, 16, v121
	v_and_b32_e32 v121, 0xffff0000, v121
	v_lshlrev_b32_e32 v160, 16, v124
	v_and_b32_e32 v161, 0xffff0000, v124
	v_lshlrev_b32_e32 v124, 16, v125
	v_and_b32_e32 v125, 0xffff0000, v125
	v_lshlrev_b32_e32 v162, 16, v122
	v_and_b32_e32 v163, 0xffff0000, v122
	v_lshlrev_b32_e32 v122, 16, v123
	v_and_b32_e32 v123, 0xffff0000, v123
	v_pk_mul_f32 v[158:159], v[158:159], s[14:15] op_sel_hi:[1,0]
	v_pk_mul_f32 v[120:121], v[120:121], s[14:15] op_sel_hi:[1,0]
	v_lshlrev_b32_e32 v166, 16, v126
	v_and_b32_e32 v167, 0xffff0000, v126
	v_lshlrev_b32_e32 v126, 16, v127
	v_and_b32_e32 v127, 0xffff0000, v127
	v_pk_mul_f32 v[162:163], v[162:163], s[14:15] op_sel_hi:[1,0]
	v_pk_mul_f32 v[122:123], v[122:123], s[14:15] op_sel_hi:[1,0]
	v_pk_fma_f32 v[112:113], v[112:113], v[160:161], v[158:159]
	v_pk_fma_f32 v[114:115], v[114:115], v[124:125], v[120:121]
	v_pk_fma_f32 v[116:117], v[116:117], v[166:167], v[162:163]
	v_pk_fma_f32 v[118:119], v[118:119], v[126:127], v[122:123]
	flat_store_dwordx4 v[164:165], v[112:115] offset:512
	flat_store_dwordx4 v[164:165], v[116:119] offset:528
	flat_load_dwordx4 v[112:115], v[156:157] nt
	v_lshl_add_u64 v[120:121], s[8:9], 0, v[154:155]
	flat_load_dwordx4 v[116:119], v[120:121] nt
	v_add_f32_e32 v122, 1.0, v104
	v_add_f32_e32 v123, 1.0, v105
	v_add_f32_e32 v124, 1.0, v106
	v_add_f32_e32 v125, 1.0, v107
	v_rcp_f32_e32 v104, v108
	v_rcp_f32_e32 v105, v109
	v_rcp_f32_e32 v106, v110
	v_rcp_f32_e32 v107, v111
	v_rcp_f32_e32 v108, v122
	v_rcp_f32_e32 v109, v123
	v_rcp_f32_e32 v110, v124
	v_rcp_f32_e32 v111, v125
	v_lshl_add_u64 v[122:123], v[152:153], 2, s[2:3]
	v_mul_f32_e32 v75, 0xbfb8aa3b, v75
	v_exp_f32_e32 v76, v76
	v_exp_f32_e32 v77, v77
	v_exp_f32_e32 v78, v78
	v_exp_f32_e32 v79, v79
	v_exp_f32_e32 v72, v72
	v_exp_f32_e32 v73, v73
	v_exp_f32_e32 v74, v74
	v_exp_f32_e32 v75, v75
	v_add_f32_e32 v76, 1.0, v76
	v_add_f32_e32 v77, 1.0, v77
	v_add_f32_e32 v78, 1.0, v78
	v_add_f32_e32 v79, 1.0, v79
	v_mul_f32_e32 v68, 0xbfb8aa3b, v68
	v_mul_f32_e32 v69, 0xbfb8aa3b, v69
	v_mul_f32_e32 v70, 0xbfb8aa3b, v70
	v_mul_f32_e32 v71, 0xbfb8aa3b, v71
	v_mul_f32_e32 v64, 0xbfb8aa3b, v64
	v_mul_f32_e32 v65, 0xbfb8aa3b, v65
	v_mul_f32_e32 v66, 0xbfb8aa3b, v66
	v_mul_f32_e32 v67, 0xbfb8aa3b, v67
	v_exp_f32_e32 v68, v68
	v_exp_f32_e32 v69, v69
	v_exp_f32_e32 v70, v70
	v_exp_f32_e32 v71, v71
	v_exp_f32_e32 v64, v64
	v_exp_f32_e32 v65, v65
	v_exp_f32_e32 v66, v66
	v_exp_f32_e32 v67, v67
	v_add_f32_e32 v68, 1.0, v68
	v_add_f32_e32 v69, 1.0, v69
	v_add_f32_e32 v70, 1.0, v70
	v_add_f32_e32 v71, 1.0, v71
	v_mul_f32_e32 v60, 0xbfb8aa3b, v60
	v_mul_f32_e32 v61, 0xbfb8aa3b, v61
	v_mul_f32_e32 v62, 0xbfb8aa3b, v62
	v_mul_f32_e32 v63, 0xbfb8aa3b, v63
	v_mul_f32_e32 v56, 0xbfb8aa3b, v56
	v_mul_f32_e32 v57, 0xbfb8aa3b, v57
	v_mul_f32_e32 v58, 0xbfb8aa3b, v58
	v_mul_f32_e32 v59, 0xbfb8aa3b, v59
	v_exp_f32_e32 v60, v60
	v_exp_f32_e32 v61, v61
	v_exp_f32_e32 v62, v62
	v_exp_f32_e32 v63, v63
	v_exp_f32_e32 v56, v56
	v_exp_f32_e32 v57, v57
	v_exp_f32_e32 v58, v58
	v_exp_f32_e32 v59, v59
	v_add_f32_e32 v60, 1.0, v60
	v_add_f32_e32 v61, 1.0, v61
	v_add_f32_e32 v62, 1.0, v62
	v_add_f32_e32 v63, 1.0, v63
	v_mul_f32_e32 v52, 0xbfb8aa3b, v52
	v_mul_f32_e32 v53, 0xbfb8aa3b, v53
	v_mul_f32_e32 v54, 0xbfb8aa3b, v54
	v_mul_f32_e32 v55, 0xbfb8aa3b, v55
	v_mul_f32_e32 v48, 0xbfb8aa3b, v48
	v_mul_f32_e32 v49, 0xbfb8aa3b, v49
	v_mul_f32_e32 v50, 0xbfb8aa3b, v50
	v_mul_f32_e32 v51, 0xbfb8aa3b, v51
	v_exp_f32_e32 v52, v52
	v_exp_f32_e32 v53, v53
	v_exp_f32_e32 v54, v54
	s_waitcnt vmcnt(0) lgkmcnt(0)
	v_lshlrev_b32_e32 v124, 16, v112
	v_and_b32_e32 v125, 0xffff0000, v112
	v_lshlrev_b32_e32 v112, 16, v113
	v_and_b32_e32 v113, 0xffff0000, v113
	v_lshlrev_b32_e32 v126, 16, v116
	v_and_b32_e32 v127, 0xffff0000, v116
	v_lshlrev_b32_e32 v116, 16, v117
	v_and_b32_e32 v117, 0xffff0000, v117
	v_lshlrev_b32_e32 v152, 16, v114
	v_and_b32_e32 v153, 0xffff0000, v114
	v_lshlrev_b32_e32 v114, 16, v115
	v_and_b32_e32 v115, 0xffff0000, v115
	v_pk_mul_f32 v[124:125], v[124:125], s[14:15] op_sel_hi:[1,0]
	v_pk_mul_f32 v[112:113], v[112:113], s[14:15] op_sel_hi:[1,0]
	v_lshlrev_b32_e32 v154, 16, v118
	v_and_b32_e32 v155, 0xffff0000, v118
	v_lshlrev_b32_e32 v118, 16, v119
	v_and_b32_e32 v119, 0xffff0000, v119
	v_pk_mul_f32 v[152:153], v[152:153], s[14:15] op_sel_hi:[1,0]
	v_pk_mul_f32 v[114:115], v[114:115], s[14:15] op_sel_hi:[1,0]
	v_pk_fma_f32 v[104:105], v[104:105], v[126:127], v[124:125]
	v_pk_fma_f32 v[106:107], v[106:107], v[116:117], v[112:113]
	v_pk_fma_f32 v[108:109], v[108:109], v[154:155], v[152:153]
	v_pk_fma_f32 v[110:111], v[110:111], v[118:119], v[114:115]
	flat_store_dwordx4 v[122:123], v[104:107]
	flat_store_dwordx4 v[122:123], v[108:111] offset:16
	flat_load_dwordx4 v[104:107], v[156:157] offset:256 nt
	s_nop 0
	flat_load_dwordx4 v[108:111], v[120:121] offset:256 nt
	v_add_f32_e32 v112, 1.0, v96
	v_add_f32_e32 v113, 1.0, v97
	v_add_f32_e32 v114, 1.0, v98
	v_add_f32_e32 v115, 1.0, v99
	v_rcp_f32_e32 v96, v100
	v_rcp_f32_e32 v97, v101
	v_rcp_f32_e32 v98, v102
	v_rcp_f32_e32 v99, v103
	v_rcp_f32_e32 v100, v112
	v_rcp_f32_e32 v101, v113
	v_rcp_f32_e32 v102, v114
	v_rcp_f32_e32 v103, v115
	v_lshl_add_u64 v[112:113], v[144:145], 0, s[18:19]
	v_lshlrev_b64 v[114:115], 1, v[112:113]
	v_lshl_add_u64 v[116:117], s[4:5], 0, v[114:115]
	v_exp_f32_e32 v55, v55
	v_exp_f32_e32 v48, v48
	v_exp_f32_e32 v49, v49
	v_exp_f32_e32 v50, v50
	v_exp_f32_e32 v51, v51
	v_add_f32_e32 v52, 1.0, v52
	v_add_f32_e32 v53, 1.0, v53
	v_add_f32_e32 v54, 1.0, v54
	v_add_f32_e32 v55, 1.0, v55
	v_mul_f32_e32 v44, 0xbfb8aa3b, v44
; __device__ __forceinline__ float bf_lo(unsigned u) { return __uint_as_float(u << 16); }
; __device__ __forceinline__ float bf_hi(unsigned u) { return __uint_as_float(u & 0xffff0000u); }
; __device__ __forceinline__ float fsigmoid(float x) { return __builtin_amdgcn_rcpf(1.0f + __builtin_amdgcn_exp2f(-LOG2E * x)); }
;     __device__ __forceinline__ void operator()(AccRef acc, const Unit& u, int wr, int wc, int fr, int fq) const {
;     ...
;                 for (int bj = 0; bj < 2; ++bj) {
;                     const u32x4 pv = *(const u32x4*)(pp + off + bj * HALF);
;                     const u32x4 hv = *(const u32x4*)(hb + off + bj * HALF);
;                     f32x4 r0, r1;
;                     r0[0] = bf_lo(hv.x); r0[1] = bf_hi(hv.x); r0[2] = bf_lo(hv.y); r0[3] = bf_hi(hv.y); r1[0] = bf_lo(hv.z); r1[1] = bf_hi(hv.z); r1[2] = bf_lo(hv.w); r1[3] = bf_hi(hv.w);
;                     const f32x4 a0 = acc[ai][bj][m][0], a1 = acc[ai][bj][m][1];
;                     f32x4 o0, o1;
;                     o0[0] = r0[0] * alpha + fsigmoid(a0[0]) * bf_lo(pv.x); o0[1] = r0[1] * alpha + fsigmoid(a0[1]) * bf_hi(pv.x);
;                     o0[2] = r0[2] * alpha + fsigmoid(a0[2]) * bf_lo(pv.y); o0[3] = r0[3] * alpha + fsigmoid(a0[3]) * bf_hi(pv.y);
;                     o1[0] = r1[0] * alpha + fsigmoid(a1[0]) * bf_lo(pv.z); o1[1] = r1[1] * alpha + fsigmoid(a1[1]) * bf_hi(pv.z);
;                     o1[2] = r1[2] * alpha + fsigmoid(a1[2]) * bf_lo(pv.w); o1[3] = r1[3] * alpha + fsigmoid(a1[3]) * bf_hi(pv.w);
;                     *(f32x4*)(out + off + bj * HALF) = o0; *(f32x4*)(out + off + bj * HALF + 4) = o1;
	v_mul_f32_e32 v45, 0xbfb8aa3b, v45
	v_mul_f32_e32 v46, 0xbfb8aa3b, v46
	v_mul_f32_e32 v47, 0xbfb8aa3b, v47
	v_mul_f32_e32 v40, 0xbfb8aa3b, v40
	v_mul_f32_e32 v41, 0xbfb8aa3b, v41
	v_mul_f32_e32 v42, 0xbfb8aa3b, v42
	v_mul_f32_e32 v43, 0xbfb8aa3b, v43
	v_exp_f32_e32 v44, v44
	v_exp_f32_e32 v45, v45
	v_exp_f32_e32 v46, v46
	v_exp_f32_e32 v47, v47
	v_exp_f32_e32 v40, v40
	v_exp_f32_e32 v41, v41
	v_exp_f32_e32 v42, v42
	v_exp_f32_e32 v43, v43
	v_add_f32_e32 v44, 1.0, v44
	v_add_f32_e32 v45, 1.0, v45
	v_add_f32_e32 v46, 1.0, v46
	v_add_f32_e32 v47, 1.0, v47
	v_mul_f32_e32 v36, 0xbfb8aa3b, v36
	v_mul_f32_e32 v37, 0xbfb8aa3b, v37
	v_mul_f32_e32 v38, 0xbfb8aa3b, v38
	v_mul_f32_e32 v39, 0xbfb8aa3b, v39
	v_mul_f32_e32 v32, 0xbfb8aa3b, v32
	v_mul_f32_e32 v33, 0xbfb8aa3b, v33
	v_mul_f32_e32 v34, 0xbfb8aa3b, v34
	v_mul_f32_e32 v35, 0xbfb8aa3b, v35
	v_exp_f32_e32 v36, v36
	v_exp_f32_e32 v37, v37
	v_exp_f32_e32 v38, v38
	v_exp_f32_e32 v39, v39
	v_exp_f32_e32 v32, v32
	v_exp_f32_e32 v33, v33
	v_exp_f32_e32 v34, v34
	v_exp_f32_e32 v35, v35
	v_add_f32_e32 v36, 1.0, v36
	v_add_f32_e32 v37, 1.0, v37
	v_add_f32_e32 v38, 1.0, v38
	v_add_f32_e32 v39, 1.0, v39
	v_mul_f32_e32 v28, 0xbfb8aa3b, v28
	v_mul_f32_e32 v29, 0xbfb8aa3b, v29
	v_mul_f32_e32 v30, 0xbfb8aa3b, v30
	v_mul_f32_e32 v31, 0xbfb8aa3b, v31
	v_mul_f32_e32 v24, 0xbfb8aa3b, v24
	v_mul_f32_e32 v25, 0xbfb8aa3b, v25
	v_mul_f32_e32 v26, 0xbfb8aa3b, v26
	v_mul_f32_e32 v27, 0xbfb8aa3b, v27
	v_exp_f32_e32 v28, v28
	v_exp_f32_e32 v29, v29
	v_exp_f32_e32 v30, v30
	v_exp_f32_e32 v31, v31
	v_exp_f32_e32 v24, v24
	v_exp_f32_e32 v25, v25
	s_waitcnt vmcnt(0) lgkmcnt(0)
	v_lshlrev_b32_e32 v118, 16, v104
	v_and_b32_e32 v119, 0xffff0000, v104
	v_lshlrev_b32_e32 v104, 16, v105
	v_and_b32_e32 v105, 0xffff0000, v105
	v_lshlrev_b32_e32 v120, 16, v108
	v_and_b32_e32 v121, 0xffff0000, v108
	v_lshlrev_b32_e32 v108, 16, v109
	v_and_b32_e32 v109, 0xffff0000, v109
	v_lshlrev_b32_e32 v124, 16, v106
	v_and_b32_e32 v125, 0xffff0000, v106
	v_lshlrev_b32_e32 v106, 16, v107
	v_and_b32_e32 v107, 0xffff0000, v107
	v_pk_mul_f32 v[118:119], v[118:119], s[14:15] op_sel_hi:[1,0]
	v_pk_mul_f32 v[104:105], v[104:105], s[14:15] op_sel_hi:[1,0]
	v_lshlrev_b32_e32 v126, 16, v110
	v_and_b32_e32 v127, 0xffff0000, v110
	v_lshlrev_b32_e32 v110, 16, v111
	v_and_b32_e32 v111, 0xffff0000, v111
	v_pk_mul_f32 v[124:125], v[124:125], s[14:15] op_sel_hi:[1,0]
	v_pk_mul_f32 v[106:107], v[106:107], s[14:15] op_sel_hi:[1,0]
	v_pk_fma_f32 v[96:97], v[96:97], v[120:121], v[118:119]
	v_pk_fma_f32 v[98:99], v[98:99], v[108:109], v[104:105]
	v_pk_fma_f32 v[100:101], v[100:101], v[126:127], v[124:125]
	v_pk_fma_f32 v[102:103], v[102:103], v[110:111], v[106:107]
	flat_store_dwordx4 v[122:123], v[96:99] offset:512
	flat_store_dwordx4 v[122:123], v[100:103] offset:528
	flat_load_dwordx4 v[96:99], v[116:117] nt
	v_lshl_add_u64 v[104:105], s[8:9], 0, v[114:115]
	flat_load_dwordx4 v[100:103], v[104:105] nt
	v_add_f32_e32 v106, 1.0, v88
	v_add_f32_e32 v107, 1.0, v89
	v_add_f32_e32 v108, 1.0, v90
	v_add_f32_e32 v109, 1.0, v91
	v_rcp_f32_e32 v88, v92
	v_rcp_f32_e32 v89, v93
	v_rcp_f32_e32 v90, v94
	v_rcp_f32_e32 v91, v95
	v_rcp_f32_e32 v92, v106
	v_rcp_f32_e32 v93, v107
	v_rcp_f32_e32 v94, v108
	v_rcp_f32_e32 v95, v109
	v_lshl_add_u64 v[106:107], v[112:113], 2, s[2:3]
	v_exp_f32_e32 v26, v26
	v_exp_f32_e32 v27, v27
	v_add_f32_e32 v28, 1.0, v28
	v_add_f32_e32 v29, 1.0, v29
	v_add_f32_e32 v30, 1.0, v30
	v_add_f32_e32 v31, 1.0, v31
	v_mul_f32_e32 v20, 0xbfb8aa3b, v20
	v_mul_f32_e32 v21, 0xbfb8aa3b, v21
	v_mul_f32_e32 v22, 0xbfb8aa3b, v22
	v_mul_f32_e32 v23, 0xbfb8aa3b, v23
	v_mul_f32_e32 v16, 0xbfb8aa3b, v16
	v_mul_f32_e32 v17, 0xbfb8aa3b, v17
	v_mul_f32_e32 v18, 0xbfb8aa3b, v18
	v_mul_f32_e32 v19, 0xbfb8aa3b, v19
	v_exp_f32_e32 v20, v20
	v_exp_f32_e32 v21, v21
	v_exp_f32_e32 v22, v22
	v_exp_f32_e32 v23, v23
	v_exp_f32_e32 v16, v16
	v_exp_f32_e32 v17, v17
	v_exp_f32_e32 v18, v18
	v_exp_f32_e32 v19, v19
	v_add_f32_e32 v20, 1.0, v20
	v_add_f32_e32 v21, 1.0, v21
	v_add_f32_e32 v22, 1.0, v22
	v_add_f32_e32 v23, 1.0, v23
	v_mul_f32_e32 v12, 0xbfb8aa3b, v12
	v_mul_f32_e32 v13, 0xbfb8aa3b, v13
	v_mul_f32_e32 v14, 0xbfb8aa3b, v14
	v_mul_f32_e32 v15, 0xbfb8aa3b, v15
	v_mul_f32_e32 v8, 0xbfb8aa3b, v8
	v_mul_f32_e32 v9, 0xbfb8aa3b, v9
	v_mul_f32_e32 v10, 0xbfb8aa3b, v10
	v_mul_f32_e32 v11, 0xbfb8aa3b, v11
	v_exp_f32_e32 v12, v12
	v_exp_f32_e32 v13, v13
	v_exp_f32_e32 v14, v14
	v_exp_f32_e32 v15, v15
	v_exp_f32_e32 v8, v8
	v_exp_f32_e32 v9, v9
	v_exp_f32_e32 v10, v10
	v_exp_f32_e32 v11, v11
	v_add_f32_e32 v12, 1.0, v12
	v_add_f32_e32 v13, 1.0, v13
	v_add_f32_e32 v14, 1.0, v14
	v_add_f32_e32 v15, 1.0, v15
	v_mul_f32_e32 v4, 0xbfb8aa3b, v4
	v_mul_f32_e32 v5, 0xbfb8aa3b, v5
	v_mul_f32_e32 v6, 0xbfb8aa3b, v6
	v_mul_f32_e32 v7, 0xbfb8aa3b, v7
	v_mul_f32_e32 v0, 0xbfb8aa3b, v0
	v_mul_f32_e32 v1, 0xbfb8aa3b, v1
	v_mul_f32_e32 v2, 0xbfb8aa3b, v2
	v_mul_f32_e32 v3, 0xbfb8aa3b, v3
	v_exp_f32_e32 v4, v4
	v_exp_f32_e32 v5, v5
	v_exp_f32_e32 v6, v6
	v_exp_f32_e32 v7, v7
	v_exp_f32_e32 v0, v0
	v_exp_f32_e32 v1, v1
	v_exp_f32_e32 v2, v2
	v_exp_f32_e32 v3, v3
	v_add_f32_e32 v4, 1.0, v4
	v_add_f32_e32 v5, 1.0, v5
	s_waitcnt vmcnt(0) lgkmcnt(0)
; __device__ __forceinline__ float bf_lo(unsigned u) { return __uint_as_float(u << 16); }
; __device__ __forceinline__ float bf_hi(unsigned u) { return __uint_as_float(u & 0xffff0000u); }
; __device__ __forceinline__ float fsigmoid(float x) { return __builtin_amdgcn_rcpf(1.0f + __builtin_amdgcn_exp2f(-LOG2E * x)); }
;     __device__ __forceinline__ void operator()(AccRef acc, const Unit& u, int wr, int wc, int fr, int fq) const {
;     ...
;                 for (int bj = 0; bj < 2; ++bj) {
;                     const u32x4 pv = *(const u32x4*)(pp + off + bj * HALF);
;                     const u32x4 hv = *(const u32x4*)(hb + off + bj * HALF);
;                     f32x4 r0, r1;
;                     r0[0] = bf_lo(hv.x); r0[1] = bf_hi(hv.x); r0[2] = bf_lo(hv.y); r0[3] = bf_hi(hv.y); r1[0] = bf_lo(hv.z); r1[1] = bf_hi(hv.z); r1[2] = bf_lo(hv.w); r1[3] = bf_hi(hv.w);
;                     const f32x4 a0 = acc[ai][bj][m][0], a1 = acc[ai][bj][m][1];
;                     f32x4 o0, o1;
;                     o0[0] = r0[0] * alpha + fsigmoid(a0[0]) * bf_lo(pv.x); o0[1] = r0[1] * alpha + fsigmoid(a0[1]) * bf_hi(pv.x);
;                     o0[2] = r0[2] * alpha + fsigmoid(a0[2]) * bf_lo(pv.y); o0[3] = r0[3] * alpha + fsigmoid(a0[3]) * bf_hi(pv.y);
;                     o1[0] = r1[0] * alpha + fsigmoid(a1[0]) * bf_lo(pv.z); o1[1] = r1[1] * alpha + fsigmoid(a1[1]) * bf_hi(pv.z);
;                     o1[2] = r1[2] * alpha + fsigmoid(a1[2]) * bf_lo(pv.w); o1[3] = r1[3] * alpha + fsigmoid(a1[3]) * bf_hi(pv.w);
;                     *(f32x4*)(out + off + bj * HALF) = o0; *(f32x4*)(out + off + bj * HALF + 4) = o1;
	v_lshlrev_b32_e32 v108, 16, v96
	v_and_b32_e32 v109, 0xffff0000, v96
	v_lshlrev_b32_e32 v96, 16, v97
	v_and_b32_e32 v97, 0xffff0000, v97
	v_lshlrev_b32_e32 v110, 16, v100
	v_and_b32_e32 v111, 0xffff0000, v100
	v_lshlrev_b32_e32 v100, 16, v101
	v_and_b32_e32 v101, 0xffff0000, v101
	v_lshlrev_b32_e32 v112, 16, v98
	v_and_b32_e32 v113, 0xffff0000, v98
	v_lshlrev_b32_e32 v98, 16, v99
	v_and_b32_e32 v99, 0xffff0000, v99
	v_pk_mul_f32 v[108:109], v[108:109], s[14:15] op_sel_hi:[1,0]
	v_pk_mul_f32 v[96:97], v[96:97], s[14:15] op_sel_hi:[1,0]
	v_lshlrev_b32_e32 v114, 16, v102
	v_and_b32_e32 v115, 0xffff0000, v102
	v_lshlrev_b32_e32 v102, 16, v103
	v_and_b32_e32 v103, 0xffff0000, v103
	v_pk_mul_f32 v[112:113], v[112:113], s[14:15] op_sel_hi:[1,0]
	v_pk_mul_f32 v[98:99], v[98:99], s[14:15] op_sel_hi:[1,0]
	v_pk_fma_f32 v[88:89], v[88:89], v[110:111], v[108:109]
	v_pk_fma_f32 v[90:91], v[90:91], v[100:101], v[96:97]
	v_pk_fma_f32 v[92:93], v[92:93], v[114:115], v[112:113]
	v_pk_fma_f32 v[94:95], v[94:95], v[102:103], v[98:99]
	flat_store_dwordx4 v[106:107], v[88:91]
	flat_store_dwordx4 v[106:107], v[92:95] offset:16
	flat_load_dwordx4 v[88:91], v[116:117] offset:256 nt
	s_nop 0
	flat_load_dwordx4 v[92:95], v[104:105] offset:256 nt
	v_add_f32_e32 v96, 1.0, v80
	v_add_f32_e32 v97, 1.0, v81
	v_add_f32_e32 v98, 1.0, v82
	v_add_f32_e32 v99, 1.0, v83
	v_rcp_f32_e32 v80, v84
	v_rcp_f32_e32 v81, v85
	v_rcp_f32_e32 v82, v86
	v_rcp_f32_e32 v83, v87
	v_rcp_f32_e32 v84, v96
	v_rcp_f32_e32 v85, v97
	v_rcp_f32_e32 v86, v98
	v_rcp_f32_e32 v87, v99
	v_lshl_add_u64 v[96:97], v[144:145], 0, s[20:21]
	v_lshlrev_b64 v[98:99], 1, v[96:97]
	v_lshl_add_u64 v[100:101], s[4:5], 0, v[98:99]
	v_add_f32_e32 v6, 1.0, v6
	v_add_f32_e32 v7, 1.0, v7
	s_andn2_b64 vcc, exec, s[0:1]
	s_mov_b64 s[0:1], -1
	s_waitcnt vmcnt(0) lgkmcnt(0)
	v_lshlrev_b32_e32 v102, 16, v88
	v_and_b32_e32 v103, 0xffff0000, v88
	v_lshlrev_b32_e32 v88, 16, v89
	v_and_b32_e32 v89, 0xffff0000, v89
	v_lshlrev_b32_e32 v104, 16, v92
	v_and_b32_e32 v105, 0xffff0000, v92
	v_lshlrev_b32_e32 v92, 16, v93
	v_and_b32_e32 v93, 0xffff0000, v93
	v_lshlrev_b32_e32 v108, 16, v90
	v_and_b32_e32 v109, 0xffff0000, v90
	v_lshlrev_b32_e32 v90, 16, v91
	v_and_b32_e32 v91, 0xffff0000, v91
	v_pk_mul_f32 v[102:103], v[102:103], s[14:15] op_sel_hi:[1,0]
	v_pk_mul_f32 v[88:89], v[88:89], s[14:15] op_sel_hi:[1,0]
	v_lshlrev_b32_e32 v110, 16, v94
	v_and_b32_e32 v111, 0xffff0000, v94
	v_lshlrev_b32_e32 v94, 16, v95
	v_and_b32_e32 v95, 0xffff0000, v95
	v_pk_mul_f32 v[108:109], v[108:109], s[14:15] op_sel_hi:[1,0]
	v_pk_mul_f32 v[90:91], v[90:91], s[14:15] op_sel_hi:[1,0]
	v_pk_fma_f32 v[80:81], v[80:81], v[104:105], v[102:103]
	v_pk_fma_f32 v[82:83], v[82:83], v[92:93], v[88:89]
	v_pk_fma_f32 v[84:85], v[84:85], v[110:111], v[108:109]
	v_pk_fma_f32 v[86:87], v[86:87], v[94:95], v[90:91]
	flat_store_dwordx4 v[106:107], v[80:83] offset:512
	flat_store_dwordx4 v[106:107], v[84:87] offset:528
	flat_load_dwordx4 v[80:83], v[100:101] nt
	v_lshl_add_u64 v[88:89], s[8:9], 0, v[98:99]
	flat_load_dwordx4 v[84:87], v[88:89] nt
	v_add_f32_e32 v90, 1.0, v72
	v_add_f32_e32 v91, 1.0, v73
	v_add_f32_e32 v92, 1.0, v74
	v_add_f32_e32 v93, 1.0, v75
	v_rcp_f32_e32 v72, v76
	v_rcp_f32_e32 v73, v77
	v_rcp_f32_e32 v74, v78
	v_rcp_f32_e32 v75, v79
	v_rcp_f32_e32 v76, v90
	v_rcp_f32_e32 v77, v91
	v_rcp_f32_e32 v78, v92
	v_rcp_f32_e32 v79, v93
	v_lshl_add_u64 v[90:91], v[96:97], 2, s[2:3]
	s_waitcnt vmcnt(0) lgkmcnt(0)
	v_lshlrev_b32_e32 v92, 16, v80
	v_and_b32_e32 v93, 0xffff0000, v80
	v_lshlrev_b32_e32 v80, 16, v81
	v_and_b32_e32 v81, 0xffff0000, v81
	v_lshlrev_b32_e32 v94, 16, v84
	v_and_b32_e32 v95, 0xffff0000, v84
	v_lshlrev_b32_e32 v84, 16, v85
	v_and_b32_e32 v85, 0xffff0000, v85
	v_lshlrev_b32_e32 v96, 16, v82
	v_and_b32_e32 v97, 0xffff0000, v82
	v_lshlrev_b32_e32 v82, 16, v83
	v_and_b32_e32 v83, 0xffff0000, v83
	v_pk_mul_f32 v[92:93], v[92:93], s[14:15] op_sel_hi:[1,0]
	v_pk_mul_f32 v[80:81], v[80:81], s[14:15] op_sel_hi:[1,0]
	v_lshlrev_b32_e32 v98, 16, v86
	v_and_b32_e32 v99, 0xffff0000, v86
	v_lshlrev_b32_e32 v86, 16, v87
	v_and_b32_e32 v87, 0xffff0000, v87
	v_pk_mul_f32 v[96:97], v[96:97], s[14:15] op_sel_hi:[1,0]
	v_pk_mul_f32 v[82:83], v[82:83], s[14:15] op_sel_hi:[1,0]
	v_pk_fma_f32 v[72:73], v[72:73], v[94:95], v[92:93]
	v_pk_fma_f32 v[74:75], v[74:75], v[84:85], v[80:81]
	v_pk_fma_f32 v[76:77], v[76:77], v[98:99], v[96:97]
	v_pk_fma_f32 v[78:79], v[78:79], v[86:87], v[82:83]
	flat_store_dwordx4 v[90:91], v[72:75]
	flat_store_dwordx4 v[90:91], v[76:79] offset:16
	flat_load_dwordx4 v[72:75], v[100:101] offset:256 nt
	s_nop 0
	flat_load_dwordx4 v[76:79], v[88:89] offset:256 nt
	v_add_f32_e32 v80, 1.0, v64
	v_add_f32_e32 v81, 1.0, v65
	v_add_f32_e32 v82, 1.0, v66
	v_add_f32_e32 v83, 1.0, v67
	v_rcp_f32_e32 v64, v68
	v_rcp_f32_e32 v65, v69
	v_rcp_f32_e32 v66, v70
	v_rcp_f32_e32 v67, v71
	v_rcp_f32_e32 v68, v80
	v_rcp_f32_e32 v69, v81
	v_rcp_f32_e32 v70, v82
	v_rcp_f32_e32 v71, v83
	v_lshl_add_u64 v[80:81], v[144:145], 0, s[22:23]
	v_lshlrev_b64 v[82:83], 1, v[80:81]
	v_lshl_add_u64 v[84:85], s[4:5], 0, v[82:83]
	s_waitcnt vmcnt(0) lgkmcnt(0)
; __device__ __forceinline__ float bf_lo(unsigned u) { return __uint_as_float(u << 16); }
; __device__ __forceinline__ float bf_hi(unsigned u) { return __uint_as_float(u & 0xffff0000u); }
; __device__ __forceinline__ float fsigmoid(float x) { return __builtin_amdgcn_rcpf(1.0f + __builtin_amdgcn_exp2f(-LOG2E * x)); }
;     __device__ __forceinline__ void operator()(AccRef acc, const Unit& u, int wr, int wc, int fr, int fq) const {
;     ...
;                 for (int bj = 0; bj < 2; ++bj) {
;                     const u32x4 pv = *(const u32x4*)(pp + off + bj * HALF);
;                     const u32x4 hv = *(const u32x4*)(hb + off + bj * HALF);
;                     f32x4 r0, r1;
;                     r0[0] = bf_lo(hv.x); r0[1] = bf_hi(hv.x); r0[2] = bf_lo(hv.y); r0[3] = bf_hi(hv.y); r1[0] = bf_lo(hv.z); r1[1] = bf_hi(hv.z); r1[2] = bf_lo(hv.w); r1[3] = bf_hi(hv.w);
;                     const f32x4 a0 = acc[ai][bj][m][0], a1 = acc[ai][bj][m][1];
;                     f32x4 o0, o1;
;                     o0[0] = r0[0] * alpha + fsigmoid(a0[0]) * bf_lo(pv.x); o0[1] = r0[1] * alpha + fsigmoid(a0[1]) * bf_hi(pv.x);
;                     o0[2] = r0[2] * alpha + fsigmoid(a0[2]) * bf_lo(pv.y); o0[3] = r0[3] * alpha + fsigmoid(a0[3]) * bf_hi(pv.y);
;                     o1[0] = r1[0] * alpha + fsigmoid(a1[0]) * bf_lo(pv.z); o1[1] = r1[1] * alpha + fsigmoid(a1[1]) * bf_hi(pv.z);
;                     o1[2] = r1[2] * alpha + fsigmoid(a1[2]) * bf_lo(pv.w); o1[3] = r1[3] * alpha + fsigmoid(a1[3]) * bf_hi(pv.w);
;                     *(f32x4*)(out + off + bj * HALF) = o0; *(f32x4*)(out + off + bj * HALF + 4) = o1;
	v_lshlrev_b32_e32 v86, 16, v72
	v_and_b32_e32 v87, 0xffff0000, v72
	v_lshlrev_b32_e32 v72, 16, v73
	v_and_b32_e32 v73, 0xffff0000, v73
	v_lshlrev_b32_e32 v88, 16, v76
	v_and_b32_e32 v89, 0xffff0000, v76
	v_lshlrev_b32_e32 v76, 16, v77
	v_and_b32_e32 v77, 0xffff0000, v77
	v_lshlrev_b32_e32 v92, 16, v74
	v_and_b32_e32 v93, 0xffff0000, v74
	v_lshlrev_b32_e32 v74, 16, v75
	v_and_b32_e32 v75, 0xffff0000, v75
	v_pk_mul_f32 v[86:87], v[86:87], s[14:15] op_sel_hi:[1,0]
	v_pk_mul_f32 v[72:73], v[72:73], s[14:15] op_sel_hi:[1,0]
	v_lshlrev_b32_e32 v94, 16, v78
	v_and_b32_e32 v95, 0xffff0000, v78
	v_lshlrev_b32_e32 v78, 16, v79
	v_and_b32_e32 v79, 0xffff0000, v79
	v_pk_mul_f32 v[92:93], v[92:93], s[14:15] op_sel_hi:[1,0]
	v_pk_mul_f32 v[74:75], v[74:75], s[14:15] op_sel_hi:[1,0]
	v_pk_fma_f32 v[64:65], v[64:65], v[88:89], v[86:87]
	v_pk_fma_f32 v[66:67], v[66:67], v[76:77], v[72:73]
	v_pk_fma_f32 v[68:69], v[68:69], v[94:95], v[92:93]
	v_pk_fma_f32 v[70:71], v[70:71], v[78:79], v[74:75]
	flat_store_dwordx4 v[90:91], v[64:67] offset:512
	flat_store_dwordx4 v[90:91], v[68:71] offset:528
	flat_load_dwordx4 v[64:67], v[84:85] nt
	v_lshl_add_u64 v[72:73], s[8:9], 0, v[82:83]
	flat_load_dwordx4 v[68:71], v[72:73] nt
	v_add_f32_e32 v74, 1.0, v56
	v_add_f32_e32 v75, 1.0, v57
	v_add_f32_e32 v76, 1.0, v58
	v_add_f32_e32 v77, 1.0, v59
	v_rcp_f32_e32 v56, v60
	v_rcp_f32_e32 v57, v61
	v_rcp_f32_e32 v58, v62
	v_rcp_f32_e32 v59, v63
	v_rcp_f32_e32 v60, v74
	v_rcp_f32_e32 v61, v75
	v_rcp_f32_e32 v62, v76
	v_rcp_f32_e32 v63, v77
	v_lshl_add_u64 v[74:75], v[80:81], 2, s[2:3]
	s_waitcnt vmcnt(0) lgkmcnt(0)
	v_lshlrev_b32_e32 v76, 16, v64
	v_and_b32_e32 v77, 0xffff0000, v64
	v_lshlrev_b32_e32 v64, 16, v65
	v_and_b32_e32 v65, 0xffff0000, v65
	v_lshlrev_b32_e32 v78, 16, v68
	v_and_b32_e32 v79, 0xffff0000, v68
	v_lshlrev_b32_e32 v68, 16, v69
	v_and_b32_e32 v69, 0xffff0000, v69
	v_lshlrev_b32_e32 v80, 16, v66
	v_and_b32_e32 v81, 0xffff0000, v66
	v_lshlrev_b32_e32 v66, 16, v67
	v_and_b32_e32 v67, 0xffff0000, v67
	v_pk_mul_f32 v[76:77], v[76:77], s[14:15] op_sel_hi:[1,0]
	v_pk_mul_f32 v[64:65], v[64:65], s[14:15] op_sel_hi:[1,0]
	v_lshlrev_b32_e32 v82, 16, v70
	v_and_b32_e32 v83, 0xffff0000, v70
	v_lshlrev_b32_e32 v70, 16, v71
	v_and_b32_e32 v71, 0xffff0000, v71
	v_pk_mul_f32 v[80:81], v[80:81], s[14:15] op_sel_hi:[1,0]
	v_pk_mul_f32 v[66:67], v[66:67], s[14:15] op_sel_hi:[1,0]
	v_pk_fma_f32 v[56:57], v[56:57], v[78:79], v[76:77]
	v_pk_fma_f32 v[58:59], v[58:59], v[68:69], v[64:65]
	v_pk_fma_f32 v[60:61], v[60:61], v[82:83], v[80:81]
	v_pk_fma_f32 v[62:63], v[62:63], v[70:71], v[66:67]
	flat_store_dwordx4 v[74:75], v[56:59]
	flat_store_dwordx4 v[74:75], v[60:63] offset:16
	flat_load_dwordx4 v[56:59], v[84:85] offset:256 nt
	s_nop 0
	flat_load_dwordx4 v[60:63], v[72:73] offset:256 nt
	v_add_f32_e32 v64, 1.0, v48
	v_add_f32_e32 v65, 1.0, v49
	v_add_f32_e32 v66, 1.0, v50
	v_add_f32_e32 v67, 1.0, v51
	v_rcp_f32_e32 v48, v52
	v_rcp_f32_e32 v49, v53
	v_rcp_f32_e32 v50, v54
	v_rcp_f32_e32 v51, v55
	v_rcp_f32_e32 v52, v64
	v_rcp_f32_e32 v53, v65
	v_rcp_f32_e32 v54, v66
	v_rcp_f32_e32 v55, v67
	v_lshl_add_u64 v[64:65], v[144:145], 0, s[24:25]
	v_lshlrev_b64 v[66:67], 1, v[64:65]
	v_lshl_add_u64 v[68:69], s[4:5], 0, v[66:67]
	s_waitcnt vmcnt(0) lgkmcnt(0)
	v_lshlrev_b32_e32 v70, 16, v56
	v_and_b32_e32 v71, 0xffff0000, v56
	v_lshlrev_b32_e32 v56, 16, v57
	v_and_b32_e32 v57, 0xffff0000, v57
	v_lshlrev_b32_e32 v72, 16, v60
	v_and_b32_e32 v73, 0xffff0000, v60
	v_lshlrev_b32_e32 v60, 16, v61
	v_and_b32_e32 v61, 0xffff0000, v61
	v_lshlrev_b32_e32 v76, 16, v58
	v_and_b32_e32 v77, 0xffff0000, v58
	v_lshlrev_b32_e32 v58, 16, v59
	v_and_b32_e32 v59, 0xffff0000, v59
	v_pk_mul_f32 v[70:71], v[70:71], s[14:15] op_sel_hi:[1,0]
	v_pk_mul_f32 v[56:57], v[56:57], s[14:15] op_sel_hi:[1,0]
	v_lshlrev_b32_e32 v78, 16, v62
	v_and_b32_e32 v79, 0xffff0000, v62
	v_lshlrev_b32_e32 v62, 16, v63
	v_and_b32_e32 v63, 0xffff0000, v63
	v_pk_mul_f32 v[76:77], v[76:77], s[14:15] op_sel_hi:[1,0]
	v_pk_mul_f32 v[58:59], v[58:59], s[14:15] op_sel_hi:[1,0]
	v_pk_fma_f32 v[48:49], v[48:49], v[72:73], v[70:71]
	v_pk_fma_f32 v[50:51], v[50:51], v[60:61], v[56:57]
	v_pk_fma_f32 v[52:53], v[52:53], v[78:79], v[76:77]
	v_pk_fma_f32 v[54:55], v[54:55], v[62:63], v[58:59]
	flat_store_dwordx4 v[74:75], v[48:51] offset:512
	flat_store_dwordx4 v[74:75], v[52:55] offset:528
	flat_load_dwordx4 v[48:51], v[68:69] nt
	v_lshl_add_u64 v[56:57], s[8:9], 0, v[66:67]
	flat_load_dwordx4 v[52:55], v[56:57] nt
	v_add_f32_e32 v58, 1.0, v40
	v_add_f32_e32 v59, 1.0, v41
	v_add_f32_e32 v60, 1.0, v42
	v_add_f32_e32 v61, 1.0, v43
	v_rcp_f32_e32 v40, v44
	v_rcp_f32_e32 v41, v45
	v_rcp_f32_e32 v42, v46
	v_rcp_f32_e32 v43, v47
	v_rcp_f32_e32 v44, v58
	v_rcp_f32_e32 v45, v59
	v_rcp_f32_e32 v46, v60
	v_rcp_f32_e32 v47, v61
	v_lshl_add_u64 v[58:59], v[64:65], 2, s[2:3]
	s_waitcnt vmcnt(0) lgkmcnt(0)
; __device__ __forceinline__ float bf_lo(unsigned u) { return __uint_as_float(u << 16); }
; __device__ __forceinline__ float bf_hi(unsigned u) { return __uint_as_float(u & 0xffff0000u); }
; __device__ __forceinline__ float fsigmoid(float x) { return __builtin_amdgcn_rcpf(1.0f + __builtin_amdgcn_exp2f(-LOG2E * x)); }
;     __device__ __forceinline__ void operator()(AccRef acc, const Unit& u, int wr, int wc, int fr, int fq) const {
;     ...
;                 for (int bj = 0; bj < 2; ++bj) {
;                     const u32x4 pv = *(const u32x4*)(pp + off + bj * HALF);
;                     const u32x4 hv = *(const u32x4*)(hb + off + bj * HALF);
;                     f32x4 r0, r1;
;                     r0[0] = bf_lo(hv.x); r0[1] = bf_hi(hv.x); r0[2] = bf_lo(hv.y); r0[3] = bf_hi(hv.y); r1[0] = bf_lo(hv.z); r1[1] = bf_hi(hv.z); r1[2] = bf_lo(hv.w); r1[3] = bf_hi(hv.w);
;                     const f32x4 a0 = acc[ai][bj][m][0], a1 = acc[ai][bj][m][1];
;                     f32x4 o0, o1;
;                     o0[0] = r0[0] * alpha + fsigmoid(a0[0]) * bf_lo(pv.x); o0[1] = r0[1] * alpha + fsigmoid(a0[1]) * bf_hi(pv.x);
;                     o0[2] = r0[2] * alpha + fsigmoid(a0[2]) * bf_lo(pv.y); o0[3] = r0[3] * alpha + fsigmoid(a0[3]) * bf_hi(pv.y);
;                     o1[0] = r1[0] * alpha + fsigmoid(a1[0]) * bf_lo(pv.z); o1[1] = r1[1] * alpha + fsigmoid(a1[1]) * bf_hi(pv.z);
;                     o1[2] = r1[2] * alpha + fsigmoid(a1[2]) * bf_lo(pv.w); o1[3] = r1[3] * alpha + fsigmoid(a1[3]) * bf_hi(pv.w);
;                     *(f32x4*)(out + off + bj * HALF) = o0; *(f32x4*)(out + off + bj * HALF + 4) = o1;
	v_lshlrev_b32_e32 v60, 16, v48
	v_and_b32_e32 v61, 0xffff0000, v48
	v_lshlrev_b32_e32 v48, 16, v49
	v_and_b32_e32 v49, 0xffff0000, v49
	v_lshlrev_b32_e32 v62, 16, v52
	v_and_b32_e32 v63, 0xffff0000, v52
	v_lshlrev_b32_e32 v52, 16, v53
	v_and_b32_e32 v53, 0xffff0000, v53
	v_lshlrev_b32_e32 v64, 16, v50
	v_and_b32_e32 v65, 0xffff0000, v50
	v_lshlrev_b32_e32 v50, 16, v51
	v_and_b32_e32 v51, 0xffff0000, v51
	v_pk_mul_f32 v[60:61], v[60:61], s[14:15] op_sel_hi:[1,0]
	v_pk_mul_f32 v[48:49], v[48:49], s[14:15] op_sel_hi:[1,0]
	v_lshlrev_b32_e32 v66, 16, v54
	v_and_b32_e32 v67, 0xffff0000, v54
	v_lshlrev_b32_e32 v54, 16, v55
	v_and_b32_e32 v55, 0xffff0000, v55
	v_pk_mul_f32 v[64:65], v[64:65], s[14:15] op_sel_hi:[1,0]
	v_pk_mul_f32 v[50:51], v[50:51], s[14:15] op_sel_hi:[1,0]
	v_pk_fma_f32 v[40:41], v[40:41], v[62:63], v[60:61]
	v_pk_fma_f32 v[42:43], v[42:43], v[52:53], v[48:49]
	v_pk_fma_f32 v[44:45], v[44:45], v[66:67], v[64:65]
	v_pk_fma_f32 v[46:47], v[46:47], v[54:55], v[50:51]
	flat_store_dwordx4 v[58:59], v[40:43]
	flat_store_dwordx4 v[58:59], v[44:47] offset:16
	flat_load_dwordx4 v[40:43], v[68:69] offset:256 nt
	s_nop 0
	flat_load_dwordx4 v[44:47], v[56:57] offset:256 nt
	v_add_f32_e32 v48, 1.0, v32
	v_add_f32_e32 v49, 1.0, v33
	v_add_f32_e32 v50, 1.0, v34
	v_add_f32_e32 v51, 1.0, v35
	v_rcp_f32_e32 v32, v36
	v_rcp_f32_e32 v33, v37
	v_rcp_f32_e32 v34, v38
	v_rcp_f32_e32 v35, v39
	v_rcp_f32_e32 v36, v48
	v_rcp_f32_e32 v37, v49
	v_rcp_f32_e32 v38, v50
	v_rcp_f32_e32 v39, v51
	v_lshl_add_u64 v[48:49], v[144:145], 0, s[26:27]
	v_lshlrev_b64 v[50:51], 1, v[48:49]
	v_lshl_add_u64 v[52:53], s[4:5], 0, v[50:51]
	s_waitcnt vmcnt(0) lgkmcnt(0)
	v_lshlrev_b32_e32 v54, 16, v40
	v_and_b32_e32 v55, 0xffff0000, v40
	v_lshlrev_b32_e32 v40, 16, v41
	v_and_b32_e32 v41, 0xffff0000, v41
	v_lshlrev_b32_e32 v56, 16, v44
	v_and_b32_e32 v57, 0xffff0000, v44
	v_lshlrev_b32_e32 v44, 16, v45
	v_and_b32_e32 v45, 0xffff0000, v45
	v_lshlrev_b32_e32 v60, 16, v42
	v_and_b32_e32 v61, 0xffff0000, v42
	v_lshlrev_b32_e32 v42, 16, v43
	v_and_b32_e32 v43, 0xffff0000, v43
	v_pk_mul_f32 v[54:55], v[54:55], s[14:15] op_sel_hi:[1,0]
	v_pk_mul_f32 v[40:41], v[40:41], s[14:15] op_sel_hi:[1,0]
	v_lshlrev_b32_e32 v62, 16, v46
	v_and_b32_e32 v63, 0xffff0000, v46
	v_lshlrev_b32_e32 v46, 16, v47
	v_and_b32_e32 v47, 0xffff0000, v47
	v_pk_mul_f32 v[60:61], v[60:61], s[14:15] op_sel_hi:[1,0]
	v_pk_mul_f32 v[42:43], v[42:43], s[14:15] op_sel_hi:[1,0]
	v_pk_fma_f32 v[32:33], v[32:33], v[56:57], v[54:55]
	v_pk_fma_f32 v[34:35], v[34:35], v[44:45], v[40:41]
	v_pk_fma_f32 v[36:37], v[36:37], v[62:63], v[60:61]
	v_pk_fma_f32 v[38:39], v[38:39], v[46:47], v[42:43]
	flat_store_dwordx4 v[58:59], v[32:35] offset:512
	flat_store_dwordx4 v[58:59], v[36:39] offset:528
	flat_load_dwordx4 v[32:35], v[52:53] nt
	v_lshl_add_u64 v[40:41], s[8:9], 0, v[50:51]
	flat_load_dwordx4 v[36:39], v[40:41] nt
	v_add_f32_e32 v42, 1.0, v24
	v_add_f32_e32 v43, 1.0, v25
	v_add_f32_e32 v44, 1.0, v26
	v_add_f32_e32 v45, 1.0, v27
	v_rcp_f32_e32 v24, v28
	v_rcp_f32_e32 v25, v29
	v_rcp_f32_e32 v26, v30
	v_rcp_f32_e32 v27, v31
	v_rcp_f32_e32 v28, v42
	v_rcp_f32_e32 v29, v43
	v_rcp_f32_e32 v30, v44
	v_rcp_f32_e32 v31, v45
	v_lshl_add_u64 v[42:43], v[48:49], 2, s[2:3]
	s_waitcnt vmcnt(0) lgkmcnt(0)
	v_lshlrev_b32_e32 v44, 16, v32
	v_and_b32_e32 v45, 0xffff0000, v32
	v_lshlrev_b32_e32 v32, 16, v33
	v_and_b32_e32 v33, 0xffff0000, v33
	v_lshlrev_b32_e32 v46, 16, v36
	v_and_b32_e32 v47, 0xffff0000, v36
	v_lshlrev_b32_e32 v36, 16, v37
	v_and_b32_e32 v37, 0xffff0000, v37
	v_lshlrev_b32_e32 v48, 16, v34
	v_and_b32_e32 v49, 0xffff0000, v34
	v_lshlrev_b32_e32 v34, 16, v35
	v_and_b32_e32 v35, 0xffff0000, v35
	v_pk_mul_f32 v[44:45], v[44:45], s[14:15] op_sel_hi:[1,0]
	v_pk_mul_f32 v[32:33], v[32:33], s[14:15] op_sel_hi:[1,0]
	v_lshlrev_b32_e32 v50, 16, v38
	v_and_b32_e32 v51, 0xffff0000, v38
	v_lshlrev_b32_e32 v38, 16, v39
	v_and_b32_e32 v39, 0xffff0000, v39
	v_pk_mul_f32 v[48:49], v[48:49], s[14:15] op_sel_hi:[1,0]
	v_pk_mul_f32 v[34:35], v[34:35], s[14:15] op_sel_hi:[1,0]
	v_pk_fma_f32 v[24:25], v[24:25], v[46:47], v[44:45]
	v_pk_fma_f32 v[26:27], v[26:27], v[36:37], v[32:33]
	v_pk_fma_f32 v[28:29], v[28:29], v[50:51], v[48:49]
	v_pk_fma_f32 v[30:31], v[30:31], v[38:39], v[34:35]
	flat_store_dwordx4 v[42:43], v[24:27]
	flat_store_dwordx4 v[42:43], v[28:31] offset:16
	flat_load_dwordx4 v[24:27], v[52:53] offset:256 nt
	s_nop 0
	flat_load_dwordx4 v[28:31], v[40:41] offset:256 nt
	v_add_f32_e32 v32, 1.0, v16
	v_add_f32_e32 v33, 1.0, v17
	v_add_f32_e32 v34, 1.0, v18
	v_add_f32_e32 v35, 1.0, v19
	v_rcp_f32_e32 v16, v20
	v_rcp_f32_e32 v17, v21
	v_rcp_f32_e32 v18, v22
	v_rcp_f32_e32 v19, v23
	v_rcp_f32_e32 v20, v32
	v_rcp_f32_e32 v21, v33
	v_rcp_f32_e32 v22, v34
	v_rcp_f32_e32 v23, v35
	v_lshl_add_u64 v[32:33], v[144:145], 0, s[28:29]
	v_lshlrev_b64 v[34:35], 1, v[32:33]
	v_lshl_add_u64 v[36:37], s[4:5], 0, v[34:35]
	s_waitcnt vmcnt(0) lgkmcnt(0)
; __device__ __forceinline__ float bf_lo(unsigned u) { return __uint_as_float(u << 16); }
; __device__ __forceinline__ float bf_hi(unsigned u) { return __uint_as_float(u & 0xffff0000u); }
; __device__ __forceinline__ float fsigmoid(float x) { return __builtin_amdgcn_rcpf(1.0f + __builtin_amdgcn_exp2f(-LOG2E * x)); }
;     __device__ __forceinline__ void operator()(AccRef acc, const Unit& u, int wr, int wc, int fr, int fq) const {
;     ...
;                 const int row = row0 + ai * HALF + m * 16;
;                 const size_t off = (size_t)row * D + col0;
; #pragma unroll
;                 for (int bj = 0; bj < 2; ++bj) {
;                     const u32x4 pv = *(const u32x4*)(pp + off + bj * HALF);
;                     const u32x4 hv = *(const u32x4*)(hb + off + bj * HALF);
;                     f32x4 r0, r1;
;                     r0[0] = bf_lo(hv.x); r0[1] = bf_hi(hv.x); r0[2] = bf_lo(hv.y); r0[3] = bf_hi(hv.y); r1[0] = bf_lo(hv.z); r1[1] = bf_hi(hv.z); r1[2] = bf_lo(hv.w); r1[3] = bf_hi(hv.w);
;                     const f32x4 a0 = acc[ai][bj][m][0], a1 = acc[ai][bj][m][1];
;                     f32x4 o0, o1;
;                     o0[0] = r0[0] * alpha + fsigmoid(a0[0]) * bf_lo(pv.x); o0[1] = r0[1] * alpha + fsigmoid(a0[1]) * bf_hi(pv.x);
;                     o0[2] = r0[2] * alpha + fsigmoid(a0[2]) * bf_lo(pv.y); o0[3] = r0[3] * alpha + fsigmoid(a0[3]) * bf_hi(pv.y);
;                     o1[0] = r1[0] * alpha + fsigmoid(a1[0]) * bf_lo(pv.z); o1[1] = r1[1] * alpha + fsigmoid(a1[1]) * bf_hi(pv.z);
;                     o1[2] = r1[2] * alpha + fsigmoid(a1[2]) * bf_lo(pv.w); o1[3] = r1[3] * alpha + fsigmoid(a1[3]) * bf_hi(pv.w);
;                     *(f32x4*)(out + off + bj * HALF) = o0; *(f32x4*)(out + off + bj * HALF + 4) = o1;
;                 }
;                 if (m & 1) asm volatile("" ::: "memory");
	v_lshlrev_b32_e32 v38, 16, v24
	v_and_b32_e32 v39, 0xffff0000, v24
	v_lshlrev_b32_e32 v24, 16, v25
	v_and_b32_e32 v25, 0xffff0000, v25
	v_lshlrev_b32_e32 v40, 16, v28
	v_and_b32_e32 v41, 0xffff0000, v28
	v_lshlrev_b32_e32 v28, 16, v29
	v_and_b32_e32 v29, 0xffff0000, v29
	v_lshlrev_b32_e32 v44, 16, v26
	v_and_b32_e32 v45, 0xffff0000, v26
	v_lshlrev_b32_e32 v26, 16, v27
	v_and_b32_e32 v27, 0xffff0000, v27
	v_pk_mul_f32 v[38:39], v[38:39], s[14:15] op_sel_hi:[1,0]
	v_pk_mul_f32 v[24:25], v[24:25], s[14:15] op_sel_hi:[1,0]
	v_lshlrev_b32_e32 v46, 16, v30
	v_and_b32_e32 v47, 0xffff0000, v30
	v_lshlrev_b32_e32 v30, 16, v31
	v_and_b32_e32 v31, 0xffff0000, v31
	v_pk_mul_f32 v[44:45], v[44:45], s[14:15] op_sel_hi:[1,0]
	v_pk_mul_f32 v[26:27], v[26:27], s[14:15] op_sel_hi:[1,0]
	v_pk_fma_f32 v[16:17], v[16:17], v[40:41], v[38:39]
	v_pk_fma_f32 v[18:19], v[18:19], v[28:29], v[24:25]
	v_pk_fma_f32 v[20:21], v[20:21], v[46:47], v[44:45]
	v_pk_fma_f32 v[22:23], v[22:23], v[30:31], v[26:27]
	flat_store_dwordx4 v[42:43], v[16:19] offset:512
	flat_store_dwordx4 v[42:43], v[20:23] offset:528
	flat_load_dwordx4 v[16:19], v[36:37] nt
	v_lshl_add_u64 v[24:25], s[8:9], 0, v[34:35]
	flat_load_dwordx4 v[20:23], v[24:25] nt
	v_add_f32_e32 v26, 1.0, v8
	v_add_f32_e32 v27, 1.0, v9
	v_add_f32_e32 v28, 1.0, v10
	v_add_f32_e32 v29, 1.0, v11
	v_rcp_f32_e32 v8, v12
	v_rcp_f32_e32 v9, v13
	v_rcp_f32_e32 v10, v14
	v_rcp_f32_e32 v11, v15
	v_rcp_f32_e32 v12, v26
	v_rcp_f32_e32 v13, v27
	v_rcp_f32_e32 v14, v28
	v_rcp_f32_e32 v15, v29
	v_lshl_add_u64 v[26:27], v[32:33], 2, s[2:3]
	s_waitcnt vmcnt(0) lgkmcnt(0)
	v_lshlrev_b32_e32 v28, 16, v16
	v_and_b32_e32 v29, 0xffff0000, v16
	v_lshlrev_b32_e32 v16, 16, v17
	v_and_b32_e32 v17, 0xffff0000, v17
	v_lshlrev_b32_e32 v30, 16, v20
	v_and_b32_e32 v31, 0xffff0000, v20
	v_lshlrev_b32_e32 v20, 16, v21
	v_and_b32_e32 v21, 0xffff0000, v21
	v_lshlrev_b32_e32 v32, 16, v18
	v_and_b32_e32 v33, 0xffff0000, v18
	v_lshlrev_b32_e32 v18, 16, v19
	v_and_b32_e32 v19, 0xffff0000, v19
	v_pk_mul_f32 v[28:29], v[28:29], s[14:15] op_sel_hi:[1,0]
	v_pk_mul_f32 v[16:17], v[16:17], s[14:15] op_sel_hi:[1,0]
	v_lshlrev_b32_e32 v34, 16, v22
	v_and_b32_e32 v35, 0xffff0000, v22
	v_lshlrev_b32_e32 v22, 16, v23
	v_and_b32_e32 v23, 0xffff0000, v23
	v_pk_mul_f32 v[32:33], v[32:33], s[14:15] op_sel_hi:[1,0]
	v_pk_mul_f32 v[18:19], v[18:19], s[14:15] op_sel_hi:[1,0]
	v_pk_fma_f32 v[8:9], v[8:9], v[30:31], v[28:29]
	v_pk_fma_f32 v[10:11], v[10:11], v[20:21], v[16:17]
	v_pk_fma_f32 v[12:13], v[12:13], v[34:35], v[32:33]
	v_pk_fma_f32 v[14:15], v[14:15], v[22:23], v[18:19]
	flat_store_dwordx4 v[26:27], v[8:11]
	flat_store_dwordx4 v[26:27], v[12:15] offset:16
	flat_load_dwordx4 v[8:11], v[36:37] offset:256 nt
	s_nop 0
	flat_load_dwordx4 v[12:15], v[24:25] offset:256 nt
	v_add_f32_e32 v16, 1.0, v0
	v_add_f32_e32 v17, 1.0, v1
	v_add_f32_e32 v18, 1.0, v2
	v_add_f32_e32 v19, 1.0, v3
	v_rcp_f32_e32 v0, v4
	v_rcp_f32_e32 v1, v5
	v_rcp_f32_e32 v2, v6
	v_rcp_f32_e32 v3, v7
	v_rcp_f32_e32 v4, v16
	v_rcp_f32_e32 v5, v17
	v_rcp_f32_e32 v6, v18
	v_rcp_f32_e32 v7, v19
	s_waitcnt vmcnt(0) lgkmcnt(0)
	v_lshlrev_b32_e32 v16, 16, v8
	v_and_b32_e32 v17, 0xffff0000, v8
	v_lshlrev_b32_e32 v8, 16, v9
	v_and_b32_e32 v9, 0xffff0000, v9
	v_lshlrev_b32_e32 v18, 16, v12
	v_and_b32_e32 v19, 0xffff0000, v12
	v_lshlrev_b32_e32 v12, 16, v13
	v_and_b32_e32 v13, 0xffff0000, v13
	v_lshlrev_b32_e32 v20, 16, v10
	v_and_b32_e32 v21, 0xffff0000, v10
	v_lshlrev_b32_e32 v10, 16, v11
	v_and_b32_e32 v11, 0xffff0000, v11
	v_pk_mul_f32 v[16:17], v[16:17], s[14:15] op_sel_hi:[1,0]
	v_pk_mul_f32 v[8:9], v[8:9], s[14:15] op_sel_hi:[1,0]
	v_lshlrev_b32_e32 v22, 16, v14
	v_and_b32_e32 v23, 0xffff0000, v14
	v_lshlrev_b32_e32 v14, 16, v15
	v_and_b32_e32 v15, 0xffff0000, v15
	v_pk_mul_f32 v[20:21], v[20:21], s[14:15] op_sel_hi:[1,0]
	v_pk_mul_f32 v[10:11], v[10:11], s[14:15] op_sel_hi:[1,0]
	v_pk_fma_f32 v[0:1], v[0:1], v[18:19], v[16:17]
	v_pk_fma_f32 v[2:3], v[2:3], v[12:13], v[8:9]
	v_pk_fma_f32 v[4:5], v[4:5], v[22:23], v[20:21]
	v_pk_fma_f32 v[6:7], v[6:7], v[14:15], v[10:11]
	flat_store_dwordx4 v[26:27], v[0:3] offset:512
	flat_store_dwordx4 v[26:27], v[4:7] offset:528
	s_cbranch_vccnz .LBB0_1091
	s_andn2_b64 vcc, exec, s[6:7]
	s_cbranch_vccnz .LBB0_1090
	s_barrier
	s_branch .LBB0_1090

; __device__ __forceinline__ void ln_phase(float* io, const float* g, const float* b, bf16_t* hb, float* stats, int gw, int NGW, int lane) {
;     ...
;     for (int row = gw; row < M; row += NGW) {
;         f32x4* xr = (f32x4*)(io + (size_t)row * D) + lane;
;         f32x4 v[8]; float s = 0.f;
; #pragma unroll
;         for (int j = 0; j < 8; ++j) { v[j] = xr[64 * j]; s += (v[j][0] + v[j][1]) + (v[j][2] + v[j][3]); }
;         const float mean = wave_sum(s, lane) * (1.f / D); float s2 = 0.f;
; #pragma unroll
;         for (int j = 0; j < 8; ++j) { v[j] = v[j] - mean; s2 += (v[j][0] * v[j][0] + v[j][1] * v[j][1]) + (v[j][2] * v[j][2] + v[j][3] * v[j][3]); }
.LBB0_1152:
	flat_load_dwordx4 v[84:87], v[96:97] nt
	flat_load_dwordx4 v[64:67], v[96:97] offset:1024 nt
	flat_load_dwordx4 v[92:95], v[96:97] offset:2048 nt
	flat_load_dwordx4 v[76:79], v[96:97] offset:3072 nt
	v_add_co_u32_e32 v98, vcc, s3, v96
	s_add_i32 s2, s2, s58
	s_nop 0
	v_addc_co_u32_e32 v99, vcc, 0, v97, vcc
	flat_load_dwordx4 v[72:75], v[98:99] nt
	flat_load_dwordx4 v[80:83], v[98:99] offset:1024 nt
	flat_load_dwordx4 v[88:91], v[98:99] offset:2048 nt
	flat_load_dwordx4 v[68:71], v[98:99] offset:3072 nt
	s_cmp_lt_i32 s2, 0x8000
	s_waitcnt vmcnt(0) lgkmcnt(0)
	v_mov_b32_e32 v108, v84
	v_mov_b32_e32 v109, v64
	v_mov_b32_e32 v110, v85
	v_mov_b32_e32 v111, v65
	v_mov_b32_e32 v112, v86
	v_mov_b32_e32 v113, v66
	v_mov_b32_e32 v114, v87
	v_mov_b32_e32 v115, v67
	v_mov_b32_e32 v116, v93
	v_mov_b32_e32 v117, v94
	v_mov_b32_e32 v118, v92
	v_mov_b32_e32 v119, v95
	v_pk_add_f32 v[108:109], v[108:109], v[110:111]
	v_pk_add_f32 v[110:111], v[112:113], v[114:115]
	v_pk_add_f32 v[112:113], v[116:117], v[118:119]
	v_pk_add_f32 v[108:109], v[108:109], v[110:111]
	v_pk_add_f32 v[110:111], v[112:113], v[112:113] op_sel:[0,1] op_sel_hi:[1,0]
	v_add_f32_e32 v108, 0, v108
	v_add_f32_e32 v120, v76, v77
	v_add_f32_e32 v122, v78, v79
	v_mov_b32_e32 v115, v72
	v_mov_b32_e32 v121, v74
	v_mov_b32_e32 v123, v75
	v_mov_b32_e32 v111, v73
	v_add_f32_e32 v114, v108, v109
	v_mov_b32_e32 v116, v81
	v_mov_b32_e32 v117, v82
	v_mov_b32_e32 v118, v80
	v_mov_b32_e32 v119, v83
	v_pk_add_f32 v[112:113], v[120:121], v[122:123]
	v_pk_add_f32 v[108:109], v[114:115], v[110:111]
	v_pk_add_f32 v[116:117], v[116:117], v[118:119]
	v_pk_add_f32 v[108:109], v[108:109], v[112:113]
	v_pk_add_f32 v[116:117], v[116:117], v[116:117] op_sel:[0,1] op_sel_hi:[1,0]
	v_pk_add_f32 v[108:109], v[108:109], v[108:109] op_sel:[0,1] op_sel_hi:[1,0]
	v_add_f32_e32 v124, v88, v89
	v_add_f32_e32 v126, v90, v91
	v_mov_b32_e32 v125, v70
	v_mov_b32_e32 v127, v71
	v_mov_b32_e32 v117, v69
	v_mov_b32_e32 v109, v68
	v_pk_add_f32 v[118:119], v[124:125], v[126:127]
	v_pk_add_f32 v[108:109], v[108:109], v[116:117]
	s_nop 0
	v_pk_add_f32 v[108:109], v[108:109], v[118:119]
	s_nop 0
	v_add_f32_e32 v108, v108, v109
	ds_bpermute_b32 v109, v100, v108
	s_waitcnt lgkmcnt(0)
	v_add_f32_e32 v108, v108, v109
	ds_bpermute_b32 v109, v101, v108
	s_waitcnt lgkmcnt(0)
	v_add_f32_e32 v108, v108, v109
	ds_bpermute_b32 v109, v102, v108
	s_waitcnt lgkmcnt(0)
	v_add_f32_e32 v108, v108, v109
	ds_bpermute_b32 v109, v103, v108
	s_waitcnt lgkmcnt(0)
	v_add_f32_e32 v108, v108, v109
	ds_bpermute_b32 v109, v104, v108
	s_waitcnt lgkmcnt(0)
	v_add_f32_e32 v108, v108, v109
	ds_bpermute_b32 v109, v105, v108
	s_waitcnt lgkmcnt(0)
	v_add_f32_e32 v129, v108, v109
	v_fmamk_f32 v87, v129, 0xba000000, v87
	v_fmamk_f32 v85, v129, 0xba000000, v85
	v_fmamk_f32 v67, v129, 0xba000000, v67
	v_fmamk_f32 v65, v129, 0xba000000, v65
	v_fmamk_f32 v86, v129, 0xba000000, v86
	v_fmac_f32_e32 v84, 0xba000000, v129
	v_fmamk_f32 v66, v129, 0xba000000, v66
	v_fmac_f32_e32 v64, 0xba000000, v129
	v_fmamk_f32 v93, v129, 0xba000000, v93
	v_fmamk_f32 v92, v129, 0xba000000, v92
	v_fmamk_f32 v95, v129, 0xba000000, v95
	v_fmac_f32_e32 v94, 0xba000000, v129
	v_fmamk_f32 v111, v129, 0xba000000, v81
	v_fmamk_f32 v110, v129, 0xba000000, v80
	v_mov_b32_e32 v80, v85
	v_mov_b32_e32 v81, v65
	v_mov_b32_e32 v114, v87
	v_mov_b32_e32 v115, v67
	v_fmamk_f32 v109, v129, 0xba000000, v75
	v_fmamk_f32 v108, v129, 0xba000000, v74
	v_mov_b32_e32 v74, v84
	v_mov_b32_e32 v75, v64
	v_mov_b32_e32 v112, v86
	v_mov_b32_e32 v113, v66
	v_pk_mul_f32 v[116:117], v[94:95], v[94:95]
	v_pk_mul_f32 v[118:119], v[92:93], v[92:93]
	v_pk_mul_f32 v[80:81], v[80:81], v[80:81]
	v_pk_mul_f32 v[114:115], v[114:115], v[114:115]
	v_fmamk_f32 v76, v129, 0xba000000, v76
	v_fmac_f32_e32 v78, 0xba000000, v129
	v_pk_mov_b32 v[132:133], v[118:119], v[116:117] op_sel:[1,0]
	v_mov_b32_e32 v119, v117
	v_pk_fma_f32 v[74:75], v[74:75], v[74:75], v[80:81]
	v_pk_fma_f32 v[80:81], v[112:113], v[112:113], v[114:115]
	v_fmamk_f32 v77, v129, 0xba000000, v77
	v_fmamk_f32 v79, v129, 0xba000000, v79
	v_mul_f32_e32 v120, v76, v76
	v_mul_f32_e32 v122, v78, v78
	v_pk_add_f32 v[112:113], v[132:133], v[118:119]
	v_pk_add_f32 v[74:75], v[74:75], v[80:81]
	v_fmamk_f32 v73, v129, 0xba000000, v73
	v_fmac_f32_e32 v72, 0xba000000, v129
	v_fmamk_f32 v83, v129, 0xba000000, v83
	v_fmac_f32_e32 v82, 0xba000000, v129
	v_pk_fma_f32 v[116:117], v[76:77], v[76:77], v[120:121] op_sel_hi:[1,1,0]
	v_pk_fma_f32 v[120:121], v[78:79], v[78:79], v[122:123] op_sel_hi:[1,1,0]
	v_pk_add_f32 v[80:81], v[112:113], v[112:113] op_sel_hi:[0,1]
	v_pk_add_f32 v[74:75], v[74:75], v[74:75] op_sel_hi:[0,1]
	v_pk_mul_f32 v[124:125], v[82:83], v[82:83]
	v_pk_mul_f32 v[126:127], v[110:111], v[110:111]
	v_mul_f32_e32 v116, v72, v72
	v_mul_f32_e32 v120, v73, v73
	v_mul_f32_e32 v80, v108, v108
	v_mul_f32_e32 v74, v109, v109
	v_fmamk_f32 v88, v129, 0xba000000, v88
	v_fmac_f32_e32 v90, 0xba000000, v129
	v_pk_mov_b32 v[122:123], v[126:127], v[124:125] op_sel:[1,0]
	v_mov_b32_e32 v127, v125
	v_pk_add_f32 v[112:113], v[116:117], v[120:121]
	v_pk_add_f32 v[74:75], v[80:81], v[74:75]
	v_fmamk_f32 v89, v129, 0xba000000, v89
	v_fmamk_f32 v91, v129, 0xba000000, v91
	v_mul_f32_e32 v128, v88, v88
	v_mul_f32_e32 v130, v90, v90
	v_pk_add_f32 v[114:115], v[122:123], v[126:127]
	v_pk_add_f32 v[74:75], v[112:113], v[74:75]
	v_pk_fma_f32 v[124:125], v[88:89], v[88:89], v[128:129] op_sel_hi:[1,1,0]
	v_pk_add_f32 v[114:115], v[114:115], v[114:115] op_sel_hi:[0,1]
	v_pk_add_f32 v[74:75], v[74:75], v[74:75] op_sel_hi:[0,1]
	v_pk_fma_f32 v[80:81], v[90:91], v[90:91], v[130:131] op_sel_hi:[1,1,0]
	v_fmamk_f32 v113, v129, 0xba000000, v71
	v_fmamk_f32 v112, v129, 0xba000000, v70
	v_fmamk_f32 v69, v129, 0xba000000, v69
	v_fmac_f32_e32 v68, 0xba000000, v129
	v_mul_f32_e32 v124, v68, v68
	v_mul_f32_e32 v80, v69, v69
	v_mul_f32_e32 v114, v112, v112
	v_mul_f32_e32 v74, v113, v113
	v_pk_add_f32 v[70:71], v[124:125], v[80:81]
	v_pk_add_f32 v[74:75], v[114:115], v[74:75]
	s_nop 0
	v_pk_add_f32 v[70:71], v[70:71], v[74:75]
	s_nop 0
	v_add_f32_e32 v70, v70, v71
	ds_bpermute_b32 v71, v100, v70
	s_waitcnt lgkmcnt(0)
; __device__ __forceinline__ unsigned cvt_pk_bf16(float lo, float hi) { unsigned r; asm volatile("s_nop 1\n\tv_cvt_pk_bf16_f32 %0, %1, %2" : "=v"(r) : "v"(lo), "v"(hi)); return r; }
; __device__ __forceinline__ void ln_phase(float* io, const float* g, const float* b, bf16_t* hb, float* stats, int gw, int NGW, int lane) {
;     ...
;         for (int j = 0; j < 8; ++j) { v[j] = v[j] - mean; s2 += (v[j][0] * v[j][0] + v[j][1] * v[j][1]) + (v[j][2] * v[j][2] + v[j][3] * v[j][3]); }
;         const float rstd = 1.0f / sqrtf(wave_sum(s2, lane) * (1.f / D) + 1e-5f);
; #pragma unroll
;         for (int j = 0; j < 8; ++j) v[j] = v[j] * rstd * gv[j] + bv[j];
;         if (stats) {
;             u32x2* o8 = (u32x2*)(hb + (size_t)row * D) + lane;
; #pragma unroll
;             for (int j = 0; j < 8; ++j) { u32x2 w; w.x = cvt_pk_bf16(v[j][0], v[j][1]); w.y = cvt_pk_bf16(v[j][2], v[j][3]); o8[64 * j] = w; }
;         } else {
; #pragma unroll
;             for (int j = 0; j < 8; ++j) xr[64 * j] = v[j];
	v_add_f32_e32 v70, v70, v71
	ds_bpermute_b32 v71, v101, v70
	s_waitcnt lgkmcnt(0)
	v_add_f32_e32 v70, v70, v71
	ds_bpermute_b32 v71, v102, v70
	s_waitcnt lgkmcnt(0)
	v_add_f32_e32 v70, v70, v71
	ds_bpermute_b32 v71, v103, v70
	s_waitcnt lgkmcnt(0)
	v_add_f32_e32 v70, v70, v71
	ds_bpermute_b32 v71, v104, v70
	s_waitcnt lgkmcnt(0)
	v_add_f32_e32 v70, v70, v71
	ds_bpermute_b32 v71, v105, v70
	s_waitcnt lgkmcnt(0)
	v_add_f32_e32 v70, v70, v71
	v_fmamk_f32 v70, v70, 0x3a000000, v106
	v_mul_f32_e32 v71, 0x4f800000, v70
	v_cmp_gt_f32_e32 vcc, s6, v70
	s_nop 1
	v_cndmask_b32_e32 v70, v70, v71, vcc
	v_sqrt_f32_e32 v71, v70
	s_nop 0
	v_add_u32_e32 v74, -1, v71
	v_add_u32_e32 v75, 1, v71
	v_fma_f32 v80, -v74, v71, v70
	v_fma_f32 v81, -v75, v71, v70
	v_cmp_ge_f32_e64 s[0:1], 0, v80
	s_nop 1
	v_cndmask_b32_e64 v71, v71, v74, s[0:1]
	v_cmp_lt_f32_e64 s[0:1], 0, v81
	s_nop 1
	v_cndmask_b32_e64 v71, v71, v75, s[0:1]
	v_mul_f32_e32 v74, 0x37800000, v71
	v_cndmask_b32_e32 v71, v71, v74, vcc
	v_cmp_class_f32_e32 vcc, v70, v107
	s_nop 1
	v_cndmask_b32_e32 v70, v71, v70, vcc
	v_div_scale_f32 v71, s[0:1], v70, v70, 1.0
	v_rcp_f32_e32 v74, v71
	v_div_scale_f32 v75, vcc, 1.0, v70, 1.0
	v_fma_f32 v80, -v71, v74, 1.0
	v_fmac_f32_e32 v74, v80, v74
	v_mul_f32_e32 v80, v75, v74
	v_fma_f32 v81, -v71, v80, v75
	v_fmac_f32_e32 v80, v81, v74
	v_fma_f32 v71, -v71, v80, v75
	v_div_fmas_f32 v71, v71, v74, v80
	v_div_fixup_f32 v114, v71, v70, 1.0
	v_pk_mul_f32 v[70:71], v[84:85], v[114:115] op_sel_hi:[1,0]
	v_pk_mul_f32 v[74:75], v[86:87], v[114:115] op_sel_hi:[1,0]
	v_pk_mul_f32 v[86:87], v[94:95], v[114:115] op_sel_hi:[1,0]
	v_pk_mul_f32 v[94:95], v[76:77], v[114:115] op_sel_hi:[1,0]
	v_pk_mul_f32 v[82:83], v[82:83], v[114:115] op_sel_hi:[1,0]
	v_pk_mul_f32 v[80:81], v[64:65], v[114:115] op_sel_hi:[1,0]
	v_pk_mul_f32 v[84:85], v[66:67], v[114:115] op_sel_hi:[1,0]
	v_pk_mul_f32 v[92:93], v[92:93], v[114:115] op_sel_hi:[1,0]
	v_pk_fma_f32 v[64:65], v[0:1], v[70:71], v[4:5]
	v_pk_mul_f32 v[70:71], v[78:79], v[114:115] op_sel_hi:[1,0]
	v_pk_fma_f32 v[78:79], v[24:25], v[94:95], v[28:29]
	v_pk_fma_f32 v[94:95], v[38:39], v[82:83], v[46:47]
	v_pk_mul_f32 v[82:83], v[88:89], v[114:115] op_sel_hi:[1,0]
	v_pk_mul_f32 v[88:89], v[90:91], v[114:115] op_sel_hi:[1,0]
	v_pk_fma_f32 v[66:67], v[2:3], v[74:75], v[6:7]
	v_pk_fma_f32 v[76:77], v[10:11], v[84:85], v[18:19]
	v_pk_fma_f32 v[74:75], v[8:9], v[80:81], v[16:17]
	v_pk_fma_f32 v[84:85], v[12:13], v[92:93], v[20:21]
	v_pk_fma_f32 v[80:81], v[26:27], v[70:71], v[30:31]
	v_pk_mul_f32 v[70:71], v[72:73], v[114:115] op_sel_hi:[1,0]
	v_pk_mul_f32 v[72:73], v[108:109], v[114:115] op_sel_hi:[1,0]
	v_pk_mul_f32 v[92:93], v[110:111], v[114:115] op_sel_hi:[1,0]
	v_pk_fma_f32 v[90:91], v[50:51], v[88:89], v[58:59]
	v_pk_fma_f32 v[88:89], v[48:49], v[82:83], v[56:57]
	v_pk_mul_f32 v[68:69], v[68:69], v[114:115] op_sel_hi:[1,0]
	v_pk_mul_f32 v[82:83], v[112:113], v[114:115] op_sel_hi:[1,0]
	v_pk_fma_f32 v[86:87], v[14:15], v[86:87], v[22:23]
	v_pk_fma_f32 v[72:73], v[34:35], v[72:73], v[42:43]
	v_pk_fma_f32 v[70:71], v[32:33], v[70:71], v[40:41]
	v_pk_fma_f32 v[92:93], v[36:37], v[92:93], v[44:45]
	v_pk_fma_f32 v[110:111], v[54:55], v[82:83], v[62:63]
	v_pk_fma_f32 v[108:109], v[52:53], v[68:69], v[60:61]
	flat_store_dwordx4 v[96:97], v[64:67]
	flat_store_dwordx4 v[96:97], v[74:77] offset:1024
	flat_store_dwordx4 v[96:97], v[84:87] offset:2048
	flat_store_dwordx4 v[96:97], v[78:81] offset:3072
	flat_store_dwordx4 v[98:99], v[70:73]
	flat_store_dwordx4 v[98:99], v[92:95] offset:1024
	flat_store_dwordx4 v[98:99], v[88:91] offset:2048
	flat_store_dwordx4 v[98:99], v[108:111] offset:3072
	v_lshl_add_u64 v[96:97], v[96:97], 0, s[4:5]
	s_cbranch_scc1 .LBB0_1152
